# hand-written GEMM K-loops (LDS-DMA 5-stage ring, swizzled LDS) for phases 1,4,6,9,13,15 plus software-pipelined hyena conv loop
# speedup vs baseline: 1.0310x; 1.0310x over previous
; DI int tid512() { int t = threadIdx_x_raw(); asm volatile("" : "+v"(t)); return t; }
; #define G_LOADA(kt_) { _Pragma("unroll") for (int i = 0; i < 4; ++i) ra[i] = al(lrow + 64 * i, (kt_) * 64 + lck * 8); }
; #define G_LOADB(kt_) { _Pragma("unroll") for (int i = 0; i < 4; ++i) rb[i] = bl(lrow + 64 * i, (kt_) * 64 + lck * 8); }
; #define G_STOREA(buf_) { bf16_t* nA = sA + (buf_) * 256 * GLD; _Pragma("unroll") for (int i = 0; i < 4; ++i) *(u32x4*)(nA + (lrow + 64 * i) * GLD + lck * 8) = ra[i]; }
; #define G_STOREB(buf_) { bf16_t* nB = sB + (buf_) * 256 * GLD; _Pragma("unroll") for (int i = 0; i < 4; ++i) *(u32x4*)(nB + (lrow + 64 * i) * GLD + lck * 8) = rb[i]; }
; template <class AL, class BL, class EP>
; DI void gemm_tile256(AL al, BL bl, EP ep, int K, char* smem) {
;     ...
;   const int tid = tid512(), lane = tid & 63, w = tid >> 6, wm = w >> 2, wn = w & 3, r = lane & 31, h = lane >> 5;
;   const int lrow = tid >> 3, lck = tid & 7;
;   f32x16 acc[4][2];
; #pragma unroll
;   for (int i = 0; i < 4; ++i)
; #pragma unroll
;     for (int j = 0; j < 2; ++j)
; #pragma unroll
;       for (int q = 0; q < 16; ++q) acc[i][j][q] = 0.f;
;   u32x4 ra[4], rb[4];
;   const int KT = K >> 6;
;     ...
;   G_LOADA(0); G_LOADB(0);
;   __syncthreads();
;   G_STOREA(0); G_STOREB(0);
;   if (KT > 1) G_LOADB(1);
;   __syncthreads();
;   DI u32x4 operator()(int r, int k) const {
;     int row = row0 + r;
;     row = row < nrows ? row : nrows - 1;
;     return ldg16(base + (size_t)row * ld + k);
;   }
.LBB0_154:
	s_cmp_gt_i32 s38, 1
	s_cbranch_scc1 .LBB0_164
	s_cmp_lg_u32 s38, 1
	s_mov_b64 s[0:1], -1
	s_cbranch_scc0 .LBB0_162
	v_mov_b32_e32 v32, v196
	s_nop 0
	v_ashrrev_i32_e32 v33, 3, v32
	v_add_u32_e32 v12, v33, v168
	v_add_u32_e32 v28, v33, v169
	v_lshlrev_b32_e32 v0, 4, v32
	v_add_u32_e32 v10, 0x80, v12
	v_add_u32_e32 v26, 0x80, v28
	v_and_b32_e32 v128, 0x70, v0
	v_min_i32_e32 v0, 0x7fff, v12
	v_min_i32_e32 v10, 0x7fff, v10
	v_min_i32_e32 v16, 0x79f, v28
	v_min_i32_e32 v26, 0x79f, v26
	v_ashrrev_i32_e32 v1, 31, v0
	v_ashrrev_i32_e32 v11, 31, v10
	v_ashrrev_i32_e32 v17, 31, v16
	v_ashrrev_i32_e32 v27, 31, v26
	v_lshl_add_u64 v[8:9], s[52:53], 0, v[128:129]
	v_lshlrev_b64 v[0:1], 11, v[0:1]
	v_lshlrev_b64 v[10:11], 11, v[10:11]
	v_lshl_add_u64 v[24:25], s[90:91], 0, v[128:129]
	v_lshlrev_b64 v[16:17], 11, v[16:17]
	v_lshlrev_b64 v[26:27], 11, v[26:27]
	v_lshl_add_u64 v[134:135], v[8:9], 0, v[0:1]
	v_add_u32_e32 v0, 64, v12
	v_lshl_add_u64 v[138:139], v[8:9], 0, v[10:11]
	v_add_u32_e32 v10, 0xc0, v12
	v_lshl_add_u64 v[142:143], v[24:25], 0, v[16:17]
	v_add_u32_e32 v16, 64, v28
	v_lshl_add_u64 v[146:147], v[24:25], 0, v[26:27]
	v_add_u32_e32 v26, 0xc0, v28
	v_min_i32_e32 v0, 0x7fff, v0
	v_min_i32_e32 v10, 0x7fff, v10
	v_min_i32_e32 v16, 0x79f, v16
	v_min_i32_e32 v26, 0x79f, v26
	v_ashrrev_i32_e32 v1, 31, v0
	v_ashrrev_i32_e32 v11, 31, v10
	v_ashrrev_i32_e32 v17, 31, v16
	v_ashrrev_i32_e32 v27, 31, v26
	v_lshlrev_b64 v[0:1], 11, v[0:1]
	v_lshlrev_b64 v[10:11], 11, v[10:11]
	v_lshlrev_b64 v[16:17], 11, v[16:17]
	v_lshlrev_b64 v[26:27], 11, v[26:27]
	v_lshl_add_u64 v[136:137], v[8:9], 0, v[0:1]
	v_lshl_add_u64 v[140:141], v[8:9], 0, v[10:11]
	v_lshl_add_u64 v[144:145], v[24:25], 0, v[16:17]
	v_lshl_add_u64 v[148:149], v[24:25], 0, v[26:27]
	v_mad_u64_u32 v[132:133], s[0:1], v33, s41, v[128:129]
	v_add_u32_e32 v173, 0x12000, v132
	v_bfe_u32 v128, v32, 6, 2
	v_add_u32_e32 v172, 0x1b000, v132
	v_and_b32_e32 v1, 31, v32
	v_ashrrev_i32_e32 v0, 1, v32
	v_and_or_b32 v133, v0, s42, v1
	v_lshrrev_b32_e32 v0, 2, v32
	v_and_b32_e32 v170, 8, v0
	v_lshlrev_b32_e32 v0, 1, v170
	v_mad_u64_u32 v[130:131], s[0:1], v133, s41, v[0:1]
	v_lshl_or_b32 v1, v128, 6, v1
	v_mul_u32_u24_e32 v1, 0x48, v1
	v_lshl_add_u32 v0, v1, 1, v0
	v_add_u32_e32 v171, 0x12000, v0
	v_add_u32_e32 v131, 0x1b000, v0
	s_nop 0
	s_nop 0
	s_nop 0
	s_nop 0
	s_nop 0
	s_nop 0
	v_lshrrev_b32_e32 v231, 6, v196
	s_mov_b32 s38, 64
	v_readfirstlane_b32 s32, v231
	s_mov_b32 s39, 0
	s_mov_b32 s48, 0x40000
	s_mov_b32 s49, 0
	v_bfe_u32 v240, v196, 2, 4
	s_lshl_b32 s54, s32, 3
	v_add_u32_e32 v240, s54, v240
	s_mov_b32 s54, 0x800
	v_mul_lo_u32 v240, v240, s54
	v_bfe_u32 v231, v196, 4, 2
	v_and_b32_e32 v241, 3, v196
	v_xor_b32_e32 v231, v241, v231
	v_lshl_add_u32 v240, v231, 4, v240
	v_mov_b32_e32 v241, 0
	v_readlane_b32 s50, v134, 0
	v_readlane_b32 s51, v135, 0
	s_nop 1
	v_lshl_add_u64 v[232:233], s[50:51], 0, v[240:241]
	v_lshl_add_u64 v[234:235], v[232:233], 0, s[48:49]
	v_readlane_b32 s50, v142, 0
	v_readlane_b32 s51, v143, 0
	s_nop 1
	v_lshl_add_u64 v[236:237], s[50:51], 0, v[240:241]
	v_lshl_add_u64 v[238:239], v[236:237], 0, s[48:49]
	v_and_b32_e32 v240, 31, v196
	v_bfe_u32 v231, v196, 2, 2
	v_bfe_u32 v241, v196, 5, 1
	v_xor_b32_e32 v231, v241, v231
	v_lshlrev_b32_e32 v231, 4, v231
	v_lshl_or_b32 v240, v240, 6, v231
	s_lshr_b32 s54, s32, 2
	s_lshl_b32 s54, s54, 13
	v_add_u32_e32 v132, s54, v240
	s_and_b32 s54, s32, 3
	s_lshl_b32 s54, s54, 12
	s_add_u32 s54, s54, 0x4000
	v_add_u32_e32 v197, s54, v240
	v_xor_b32_e32 v171, 0x20, v132
	v_xor_b32_e32 v198, 0x20, v197
	v_add_u32_e32 v199, 0x10000, v132
	v_add_u32_e32 v225, 0x10000, v197
	v_add_u32_e32 v227, 0x20000, v132
	v_add_u32_e32 v229, 0x20000, v197
	v_add_u32_e32 v224, 0x10000, v171
	v_add_u32_e32 v226, 0x10000, v198
	v_add_u32_e32 v228, 0x20000, v171
	v_add_u32_e32 v230, 0x20000, v198
	s_lshl_b32 s32, s32, 10
	s_waitcnt lgkmcnt(0)
	s_barrier
	s_add_u32 m0, s32, 0x0
	s_nop 0
	global_load_lds_dwordx4 v[232:233], off
	v_lshl_add_u64 v[232:233], v[232:233], 0, s[38:39]
	s_add_u32 m0, s32, 0x4000
	s_nop 0
	global_load_lds_dwordx4 v[236:237], off
	v_lshl_add_u64 v[236:237], v[236:237], 0, s[38:39]
	s_add_u32 m0, s32, 0x2000
	s_nop 0
	global_load_lds_dwordx4 v[234:235], off
	v_lshl_add_u64 v[234:235], v[234:235], 0, s[38:39]
	s_add_u32 m0, s32, 0x6000
	s_nop 0
	global_load_lds_dwordx4 v[238:239], off
	v_lshl_add_u64 v[238:239], v[238:239], 0, s[38:39]
	s_add_u32 m0, s32, 0x8000
	s_nop 0
	global_load_lds_dwordx4 v[232:233], off
	v_lshl_add_u64 v[232:233], v[232:233], 0, s[38:39]
	s_add_u32 m0, s32, 0xc000
	s_nop 0
	global_load_lds_dwordx4 v[236:237], off
	v_lshl_add_u64 v[236:237], v[236:237], 0, s[38:39]
	s_add_u32 m0, s32, 0xa000
	s_nop 0
	global_load_lds_dwordx4 v[234:235], off
	v_lshl_add_u64 v[234:235], v[234:235], 0, s[38:39]
	s_add_u32 m0, s32, 0xe000
	s_nop 0
	global_load_lds_dwordx4 v[238:239], off
	v_lshl_add_u64 v[238:239], v[238:239], 0, s[38:39]
	s_add_u32 m0, s32, 0x10000
	s_nop 0
	global_load_lds_dwordx4 v[232:233], off
	v_lshl_add_u64 v[232:233], v[232:233], 0, s[38:39]
	s_add_u32 m0, s32, 0x14000
	s_nop 0
	global_load_lds_dwordx4 v[236:237], off
	v_lshl_add_u64 v[236:237], v[236:237], 0, s[38:39]
	s_add_u32 m0, s32, 0x12000
	s_nop 0
	global_load_lds_dwordx4 v[234:235], off
	v_lshl_add_u64 v[234:235], v[234:235], 0, s[38:39]
	s_add_u32 m0, s32, 0x16000
	s_nop 0
	global_load_lds_dwordx4 v[238:239], off
	v_lshl_add_u64 v[238:239], v[238:239], 0, s[38:39]
	s_add_u32 m0, s32, 0x18000
	s_nop 0
	global_load_lds_dwordx4 v[232:233], off
	v_lshl_add_u64 v[232:233], v[232:233], 0, s[38:39]
	s_add_u32 m0, s32, 0x1c000
	s_nop 0
; #define G_LOADA(kt_) { _Pragma("unroll") for (int i = 0; i < 4; ++i) ra[i] = al(lrow + 64 * i, (kt_) * 64 + lck * 8); }
; #define G_LOADB(kt_) { _Pragma("unroll") for (int i = 0; i < 4; ++i) rb[i] = bl(lrow + 64 * i, (kt_) * 64 + lck * 8); }
; #define G_STOREA(buf_) { bf16_t* nA = sA + (buf_) * 256 * GLD; _Pragma("unroll") for (int i = 0; i < 4; ++i) *(u32x4*)(nA + (lrow + 64 * i) * GLD + lck * 8) = ra[i]; }
; #define G_STOREB(buf_) { bf16_t* nB = sB + (buf_) * 256 * GLD; _Pragma("unroll") for (int i = 0; i < 4; ++i) *(u32x4*)(nB + (lrow + 64 * i) * GLD + lck * 8) = rb[i]; }
; template <class AL, class BL, class EP>
; DI void gemm_tile256(AL al, BL bl, EP ep, int K, char* smem) {
;     ...
;   f32x16 acc[4][2];
; #pragma unroll
;   for (int i = 0; i < 4; ++i)
; #pragma unroll
;     for (int j = 0; j < 2; ++j)
; #pragma unroll
;       for (int q = 0; q < 16; ++q) acc[i][j][q] = 0.f;
;   u32x4 ra[4], rb[4];
;   const int KT = K >> 6;
;     ...
;   G_LOADA(0); G_LOADB(0);
;   __syncthreads();
;   G_STOREA(0); G_STOREB(0);
;   if (KT > 1) G_LOADB(1);
;   __syncthreads();
;   for (int kt = 0; kt < KT; kt += 2) {
;     G_STEP(0, kt);
;     if (kt + 1 >= KT) break;
;     G_STEP(1, kt + 1);
;   }
	global_load_lds_dwordx4 v[236:237], off
	v_lshl_add_u64 v[236:237], v[236:237], 0, s[38:39]
	s_add_u32 m0, s32, 0x1a000
	s_nop 0
	global_load_lds_dwordx4 v[234:235], off
	v_lshl_add_u64 v[234:235], v[234:235], 0, s[38:39]
	s_add_u32 m0, s32, 0x1e000
	s_nop 0
	global_load_lds_dwordx4 v[238:239], off
	v_lshl_add_u64 v[238:239], v[238:239], 0, s[38:39]
	s_add_u32 m0, s32, 0x20000
	s_nop 0
	global_load_lds_dwordx4 v[232:233], off
	v_lshl_add_u64 v[232:233], v[232:233], 0, s[38:39]
	s_add_u32 m0, s32, 0x24000
	s_nop 0
	global_load_lds_dwordx4 v[236:237], off
	v_lshl_add_u64 v[236:237], v[236:237], 0, s[38:39]
	v_mov_b64_e32 v[112:113], 0
	v_mov_b64_e32 v[114:115], 0
	v_mov_b64_e32 v[116:117], 0
	v_mov_b64_e32 v[118:119], 0
	v_mov_b64_e32 v[120:121], 0
	v_mov_b64_e32 v[122:123], 0
	v_mov_b64_e32 v[124:125], 0
	v_mov_b64_e32 v[126:127], 0
	v_mov_b64_e32 v[96:97], 0
	v_mov_b64_e32 v[98:99], 0
	v_mov_b64_e32 v[100:101], 0
	v_mov_b64_e32 v[102:103], 0
	v_mov_b64_e32 v[104:105], 0
	v_mov_b64_e32 v[106:107], 0
	v_mov_b64_e32 v[108:109], 0
	v_mov_b64_e32 v[110:111], 0
	v_mov_b64_e32 v[80:81], 0
	v_mov_b64_e32 v[82:83], 0
	v_mov_b64_e32 v[84:85], 0
	v_mov_b64_e32 v[86:87], 0
	v_mov_b64_e32 v[88:89], 0
	v_mov_b64_e32 v[90:91], 0
	v_mov_b64_e32 v[92:93], 0
	v_mov_b64_e32 v[94:95], 0
	v_mov_b64_e32 v[64:65], 0
	v_mov_b64_e32 v[66:67], 0
	v_mov_b64_e32 v[68:69], 0
	v_mov_b64_e32 v[70:71], 0
	v_mov_b64_e32 v[72:73], 0
	v_mov_b64_e32 v[74:75], 0
	v_mov_b64_e32 v[76:77], 0
	v_mov_b64_e32 v[78:79], 0
	v_mov_b64_e32 v[48:49], 0
	v_mov_b64_e32 v[50:51], 0
	v_mov_b64_e32 v[52:53], 0
	v_mov_b64_e32 v[54:55], 0
	v_mov_b64_e32 v[56:57], 0
	v_mov_b64_e32 v[58:59], 0
	v_mov_b64_e32 v[60:61], 0
	v_mov_b64_e32 v[62:63], 0
	v_mov_b64_e32 v[32:33], 0
	v_mov_b64_e32 v[34:35], 0
	v_mov_b64_e32 v[36:37], 0
	v_mov_b64_e32 v[38:39], 0
	v_mov_b64_e32 v[40:41], 0
	v_mov_b64_e32 v[42:43], 0
	v_mov_b64_e32 v[44:45], 0
	v_mov_b64_e32 v[46:47], 0
	v_mov_b64_e32 v[16:17], 0
	v_mov_b64_e32 v[18:19], 0
	v_mov_b64_e32 v[20:21], 0
	v_mov_b64_e32 v[22:23], 0
	v_mov_b64_e32 v[24:25], 0
	v_mov_b64_e32 v[26:27], 0
	v_mov_b64_e32 v[28:29], 0
	v_mov_b64_e32 v[30:31], 0
	v_mov_b64_e32 v[0:1], 0
	v_mov_b64_e32 v[2:3], 0
	v_mov_b64_e32 v[4:5], 0
	v_mov_b64_e32 v[6:7], 0
	v_mov_b64_e32 v[8:9], 0
	v_mov_b64_e32 v[10:11], 0
	v_mov_b64_e32 v[12:13], 0
	v_mov_b64_e32 v[14:15], 0
	s_mov_b32 s54, 5
	s_waitcnt vmcnt(14)
	s_barrier
	ds_read_b128 v[208:211], v197
	ds_read_b128 v[172:175], v132
	ds_read_b128 v[212:215], v197 offset:2048
	ds_read_b128 v[176:179], v132 offset:2048
	ds_read_b128 v[180:183], v132 offset:4096
	ds_read_b128 v[184:187], v132 offset:6144
.Lgk_ph1_loop:
	s_waitcnt lgkmcnt(0)
	v_mfma_f32_32x32x16_bf16 v[112:127], v[208:211], v[172:175], v[112:127]
	ds_read_b128 v[216:219], v198
	ds_read_b128 v[188:191], v171
	v_mfma_f32_32x32x16_bf16 v[96:111], v[212:215], v[172:175], v[96:111]
	ds_read_b128 v[220:223], v198 offset:2048
	ds_read_b128 v[192:195], v171 offset:2048
	v_mfma_f32_32x32x16_bf16 v[80:95], v[208:211], v[176:179], v[80:95]
	ds_read_b128 v[200:203], v171 offset:4096
	ds_read_b128 v[204:207], v171 offset:6144
	v_mfma_f32_32x32x16_bf16 v[64:79], v[212:215], v[176:179], v[64:79]
	s_add_u32 m0, s32, 0x22000
	s_nop 0
	global_load_lds_dwordx4 v[234:235], off
	v_lshl_add_u64 v[234:235], v[234:235], 0, s[38:39]
	v_mfma_f32_32x32x16_bf16 v[48:63], v[208:211], v[180:183], v[48:63]
	v_mfma_f32_32x32x16_bf16 v[32:47], v[212:215], v[180:183], v[32:47]
	v_mfma_f32_32x32x16_bf16 v[16:31], v[208:211], v[184:187], v[16:31]
	v_mfma_f32_32x32x16_bf16 v[0:15], v[212:215], v[184:187], v[0:15]
	s_add_u32 m0, s32, 0x26000
	s_nop 0
	global_load_lds_dwordx4 v[238:239], off
	v_lshl_add_u64 v[238:239], v[238:239], 0, s[38:39]
	s_waitcnt lgkmcnt(0)
	s_waitcnt vmcnt(12)
	s_barrier
	s_waitcnt lgkmcnt(0)
	v_mfma_f32_32x32x16_bf16 v[112:127], v[216:219], v[188:191], v[112:127]
	ds_read_b128 v[208:211], v197 offset:32768
	ds_read_b128 v[172:175], v132 offset:32768
	v_mfma_f32_32x32x16_bf16 v[96:111], v[220:223], v[188:191], v[96:111]
	ds_read_b128 v[212:215], v197 offset:34816
	ds_read_b128 v[176:179], v132 offset:34816
	v_mfma_f32_32x32x16_bf16 v[80:95], v[216:219], v[192:195], v[80:95]
	ds_read_b128 v[180:183], v132 offset:36864
	ds_read_b128 v[184:187], v132 offset:38912
	v_mfma_f32_32x32x16_bf16 v[64:79], v[220:223], v[192:195], v[64:79]
	s_add_u32 m0, s32, 0x0
	s_nop 0
	global_load_lds_dwordx4 v[232:233], off
	v_lshl_add_u64 v[232:233], v[232:233], 0, s[38:39]
	v_mfma_f32_32x32x16_bf16 v[48:63], v[216:219], v[200:203], v[48:63]
	v_mfma_f32_32x32x16_bf16 v[32:47], v[220:223], v[200:203], v[32:47]
	v_mfma_f32_32x32x16_bf16 v[16:31], v[216:219], v[204:207], v[16:31]
	v_mfma_f32_32x32x16_bf16 v[0:15], v[220:223], v[204:207], v[0:15]
	s_add_u32 m0, s32, 0x4000
	s_nop 0
	global_load_lds_dwordx4 v[236:237], off
	v_lshl_add_u64 v[236:237], v[236:237], 0, s[38:39]
	s_waitcnt lgkmcnt(0)
	v_mfma_f32_32x32x16_bf16 v[112:127], v[208:211], v[172:175], v[112:127]
	ds_read_b128 v[216:219], v198 offset:32768
	ds_read_b128 v[188:191], v171 offset:32768
	v_mfma_f32_32x32x16_bf16 v[96:111], v[212:215], v[172:175], v[96:111]
	ds_read_b128 v[220:223], v198 offset:34816
	ds_read_b128 v[192:195], v171 offset:34816
	v_mfma_f32_32x32x16_bf16 v[80:95], v[208:211], v[176:179], v[80:95]
	ds_read_b128 v[200:203], v171 offset:36864
	ds_read_b128 v[204:207], v171 offset:38912
	v_mfma_f32_32x32x16_bf16 v[64:79], v[212:215], v[176:179], v[64:79]
	s_add_u32 m0, s32, 0x2000
	s_nop 0
	global_load_lds_dwordx4 v[234:235], off
	v_lshl_add_u64 v[234:235], v[234:235], 0, s[38:39]
	v_mfma_f32_32x32x16_bf16 v[48:63], v[208:211], v[180:183], v[48:63]
	v_mfma_f32_32x32x16_bf16 v[32:47], v[212:215], v[180:183], v[32:47]
	v_mfma_f32_32x32x16_bf16 v[16:31], v[208:211], v[184:187], v[16:31]
	v_mfma_f32_32x32x16_bf16 v[0:15], v[212:215], v[184:187], v[0:15]
	s_add_u32 m0, s32, 0x6000
	s_nop 0
	global_load_lds_dwordx4 v[238:239], off
	v_lshl_add_u64 v[238:239], v[238:239], 0, s[38:39]
	s_waitcnt lgkmcnt(0)
	s_waitcnt vmcnt(12)
	s_barrier
; #define G_LOADA(kt_) { _Pragma("unroll") for (int i = 0; i < 4; ++i) ra[i] = al(lrow + 64 * i, (kt_) * 64 + lck * 8); }
; #define G_LOADB(kt_) { _Pragma("unroll") for (int i = 0; i < 4; ++i) rb[i] = bl(lrow + 64 * i, (kt_) * 64 + lck * 8); }
; #define G_STOREA(buf_) { bf16_t* nA = sA + (buf_) * 256 * GLD; _Pragma("unroll") for (int i = 0; i < 4; ++i) *(u32x4*)(nA + (lrow + 64 * i) * GLD + lck * 8) = ra[i]; }
; #define G_STOREB(buf_) { bf16_t* nB = sB + (buf_) * 256 * GLD; _Pragma("unroll") for (int i = 0; i < 4; ++i) *(u32x4*)(nB + (lrow + 64 * i) * GLD + lck * 8) = rb[i]; }
; template <class AL, class BL, class EP>
; DI void gemm_tile256(AL al, BL bl, EP ep, int K, char* smem) {
;     ...
;   G_LOADA(0); G_LOADB(0);
;   __syncthreads();
;   G_STOREA(0); G_STOREB(0);
;   if (KT > 1) G_LOADB(1);
;   __syncthreads();
;   for (int kt = 0; kt < KT; kt += 2) {
;     G_STEP(0, kt);
;     if (kt + 1 >= KT) break;
;     G_STEP(1, kt + 1);
;   }
	s_waitcnt lgkmcnt(0)
	v_mfma_f32_32x32x16_bf16 v[112:127], v[216:219], v[188:191], v[112:127]
	ds_read_b128 v[208:211], v225
	ds_read_b128 v[172:175], v199
	v_mfma_f32_32x32x16_bf16 v[96:111], v[220:223], v[188:191], v[96:111]
	ds_read_b128 v[212:215], v225 offset:2048
	ds_read_b128 v[176:179], v199 offset:2048
	v_mfma_f32_32x32x16_bf16 v[80:95], v[216:219], v[192:195], v[80:95]
	ds_read_b128 v[180:183], v199 offset:4096
	ds_read_b128 v[184:187], v199 offset:6144
	v_mfma_f32_32x32x16_bf16 v[64:79], v[220:223], v[192:195], v[64:79]
	s_add_u32 m0, s32, 0x8000
	s_nop 0
	global_load_lds_dwordx4 v[232:233], off
	v_lshl_add_u64 v[232:233], v[232:233], 0, s[38:39]
	v_mfma_f32_32x32x16_bf16 v[48:63], v[216:219], v[200:203], v[48:63]
	v_mfma_f32_32x32x16_bf16 v[32:47], v[220:223], v[200:203], v[32:47]
	v_mfma_f32_32x32x16_bf16 v[16:31], v[216:219], v[204:207], v[16:31]
	v_mfma_f32_32x32x16_bf16 v[0:15], v[220:223], v[204:207], v[0:15]
	s_add_u32 m0, s32, 0xc000
	s_nop 0
	global_load_lds_dwordx4 v[236:237], off
	v_lshl_add_u64 v[236:237], v[236:237], 0, s[38:39]
	s_waitcnt lgkmcnt(0)
	v_mfma_f32_32x32x16_bf16 v[112:127], v[208:211], v[172:175], v[112:127]
	ds_read_b128 v[216:219], v226
	ds_read_b128 v[188:191], v224
	v_mfma_f32_32x32x16_bf16 v[96:111], v[212:215], v[172:175], v[96:111]
	ds_read_b128 v[220:223], v226 offset:2048
	ds_read_b128 v[192:195], v224 offset:2048
	v_mfma_f32_32x32x16_bf16 v[80:95], v[208:211], v[176:179], v[80:95]
	ds_read_b128 v[200:203], v224 offset:4096
	ds_read_b128 v[204:207], v224 offset:6144
	v_mfma_f32_32x32x16_bf16 v[64:79], v[212:215], v[176:179], v[64:79]
	s_add_u32 m0, s32, 0xa000
	s_nop 0
	global_load_lds_dwordx4 v[234:235], off
	v_lshl_add_u64 v[234:235], v[234:235], 0, s[38:39]
	v_mfma_f32_32x32x16_bf16 v[48:63], v[208:211], v[180:183], v[48:63]
	v_mfma_f32_32x32x16_bf16 v[32:47], v[212:215], v[180:183], v[32:47]
	v_mfma_f32_32x32x16_bf16 v[16:31], v[208:211], v[184:187], v[16:31]
	v_mfma_f32_32x32x16_bf16 v[0:15], v[212:215], v[184:187], v[0:15]
	s_add_u32 m0, s32, 0xe000
	s_nop 0
	global_load_lds_dwordx4 v[238:239], off
	v_lshl_add_u64 v[238:239], v[238:239], 0, s[38:39]
	s_waitcnt lgkmcnt(0)
	s_waitcnt vmcnt(12)
	s_barrier
	s_waitcnt lgkmcnt(0)
	v_mfma_f32_32x32x16_bf16 v[112:127], v[216:219], v[188:191], v[112:127]
	ds_read_b128 v[208:211], v225 offset:32768
	ds_read_b128 v[172:175], v199 offset:32768
	v_mfma_f32_32x32x16_bf16 v[96:111], v[220:223], v[188:191], v[96:111]
	ds_read_b128 v[212:215], v225 offset:34816
	ds_read_b128 v[176:179], v199 offset:34816
	v_mfma_f32_32x32x16_bf16 v[80:95], v[216:219], v[192:195], v[80:95]
	ds_read_b128 v[180:183], v199 offset:36864
	ds_read_b128 v[184:187], v199 offset:38912
	v_mfma_f32_32x32x16_bf16 v[64:79], v[220:223], v[192:195], v[64:79]
	s_add_u32 m0, s32, 0x10000
	s_nop 0
	global_load_lds_dwordx4 v[232:233], off
	v_lshl_add_u64 v[232:233], v[232:233], 0, s[38:39]
	v_mfma_f32_32x32x16_bf16 v[48:63], v[216:219], v[200:203], v[48:63]
	v_mfma_f32_32x32x16_bf16 v[32:47], v[220:223], v[200:203], v[32:47]
	v_mfma_f32_32x32x16_bf16 v[16:31], v[216:219], v[204:207], v[16:31]
	v_mfma_f32_32x32x16_bf16 v[0:15], v[220:223], v[204:207], v[0:15]
	s_add_u32 m0, s32, 0x14000
	s_nop 0
	global_load_lds_dwordx4 v[236:237], off
	v_lshl_add_u64 v[236:237], v[236:237], 0, s[38:39]
	s_waitcnt lgkmcnt(0)
	v_mfma_f32_32x32x16_bf16 v[112:127], v[208:211], v[172:175], v[112:127]
	ds_read_b128 v[216:219], v226 offset:32768
	ds_read_b128 v[188:191], v224 offset:32768
	v_mfma_f32_32x32x16_bf16 v[96:111], v[212:215], v[172:175], v[96:111]
	ds_read_b128 v[220:223], v226 offset:34816
	ds_read_b128 v[192:195], v224 offset:34816
	v_mfma_f32_32x32x16_bf16 v[80:95], v[208:211], v[176:179], v[80:95]
	ds_read_b128 v[200:203], v224 offset:36864
	ds_read_b128 v[204:207], v224 offset:38912
	v_mfma_f32_32x32x16_bf16 v[64:79], v[212:215], v[176:179], v[64:79]
	s_add_u32 m0, s32, 0x12000
	s_nop 0
	global_load_lds_dwordx4 v[234:235], off
	v_lshl_add_u64 v[234:235], v[234:235], 0, s[38:39]
	v_mfma_f32_32x32x16_bf16 v[48:63], v[208:211], v[180:183], v[48:63]
	v_mfma_f32_32x32x16_bf16 v[32:47], v[212:215], v[180:183], v[32:47]
	v_mfma_f32_32x32x16_bf16 v[16:31], v[208:211], v[184:187], v[16:31]
	v_mfma_f32_32x32x16_bf16 v[0:15], v[212:215], v[184:187], v[0:15]
	s_add_u32 m0, s32, 0x16000
	s_nop 0
	global_load_lds_dwordx4 v[238:239], off
	v_lshl_add_u64 v[238:239], v[238:239], 0, s[38:39]
	s_waitcnt lgkmcnt(0)
	s_waitcnt vmcnt(12)
	s_barrier
	s_waitcnt lgkmcnt(0)
	v_mfma_f32_32x32x16_bf16 v[112:127], v[216:219], v[188:191], v[112:127]
	ds_read_b128 v[208:211], v229
	ds_read_b128 v[172:175], v227
	v_mfma_f32_32x32x16_bf16 v[96:111], v[220:223], v[188:191], v[96:111]
	ds_read_b128 v[212:215], v229 offset:2048
	ds_read_b128 v[176:179], v227 offset:2048
	v_mfma_f32_32x32x16_bf16 v[80:95], v[216:219], v[192:195], v[80:95]
	ds_read_b128 v[180:183], v227 offset:4096
	ds_read_b128 v[184:187], v227 offset:6144
	v_mfma_f32_32x32x16_bf16 v[64:79], v[220:223], v[192:195], v[64:79]
	s_add_u32 m0, s32, 0x18000
	s_nop 0
	global_load_lds_dwordx4 v[232:233], off
	v_lshl_add_u64 v[232:233], v[232:233], 0, s[38:39]
	v_mfma_f32_32x32x16_bf16 v[48:63], v[216:219], v[200:203], v[48:63]
	v_mfma_f32_32x32x16_bf16 v[32:47], v[220:223], v[200:203], v[32:47]
	v_mfma_f32_32x32x16_bf16 v[16:31], v[216:219], v[204:207], v[16:31]
	v_mfma_f32_32x32x16_bf16 v[0:15], v[220:223], v[204:207], v[0:15]
	s_add_u32 m0, s32, 0x1c000
	s_nop 0
	global_load_lds_dwordx4 v[236:237], off
	v_lshl_add_u64 v[236:237], v[236:237], 0, s[38:39]
	s_waitcnt lgkmcnt(0)
	v_mfma_f32_32x32x16_bf16 v[112:127], v[208:211], v[172:175], v[112:127]
	ds_read_b128 v[216:219], v230
	ds_read_b128 v[188:191], v228
	v_mfma_f32_32x32x16_bf16 v[96:111], v[212:215], v[172:175], v[96:111]
	ds_read_b128 v[220:223], v230 offset:2048
	ds_read_b128 v[192:195], v228 offset:2048
	v_mfma_f32_32x32x16_bf16 v[80:95], v[208:211], v[176:179], v[80:95]
	ds_read_b128 v[200:203], v228 offset:4096
	ds_read_b128 v[204:207], v228 offset:6144
	v_mfma_f32_32x32x16_bf16 v[64:79], v[212:215], v[176:179], v[64:79]
	s_add_u32 m0, s32, 0x1a000
	s_nop 0
	global_load_lds_dwordx4 v[234:235], off
	v_lshl_add_u64 v[234:235], v[234:235], 0, s[38:39]
	v_mfma_f32_32x32x16_bf16 v[48:63], v[208:211], v[180:183], v[48:63]
	v_mfma_f32_32x32x16_bf16 v[32:47], v[212:215], v[180:183], v[32:47]
	v_mfma_f32_32x32x16_bf16 v[16:31], v[208:211], v[184:187], v[16:31]
	v_mfma_f32_32x32x16_bf16 v[0:15], v[212:215], v[184:187], v[0:15]
	s_add_u32 m0, s32, 0x1e000
	s_nop 0
	global_load_lds_dwordx4 v[238:239], off
	v_lshl_add_u64 v[238:239], v[238:239], 0, s[38:39]
	s_waitcnt lgkmcnt(0)
	s_waitcnt vmcnt(12)
	s_barrier
; #define G_LOADA(kt_) { _Pragma("unroll") for (int i = 0; i < 4; ++i) ra[i] = al(lrow + 64 * i, (kt_) * 64 + lck * 8); }
; #define G_LOADB(kt_) { _Pragma("unroll") for (int i = 0; i < 4; ++i) rb[i] = bl(lrow + 64 * i, (kt_) * 64 + lck * 8); }
; #define G_STOREA(buf_) { bf16_t* nA = sA + (buf_) * 256 * GLD; _Pragma("unroll") for (int i = 0; i < 4; ++i) *(u32x4*)(nA + (lrow + 64 * i) * GLD + lck * 8) = ra[i]; }
; #define G_STOREB(buf_) { bf16_t* nB = sB + (buf_) * 256 * GLD; _Pragma("unroll") for (int i = 0; i < 4; ++i) *(u32x4*)(nB + (lrow + 64 * i) * GLD + lck * 8) = rb[i]; }
; template <class AL, class BL, class EP>
; DI void gemm_tile256(AL al, BL bl, EP ep, int K, char* smem) {
;     ...
;   G_LOADA(0); G_LOADB(0);
;   __syncthreads();
;   G_STOREA(0); G_STOREB(0);
;   if (KT > 1) G_LOADB(1);
;   __syncthreads();
;   for (int kt = 0; kt < KT; kt += 2) {
;     G_STEP(0, kt);
;     if (kt + 1 >= KT) break;
;     G_STEP(1, kt + 1);
;   }
	s_waitcnt lgkmcnt(0)
	v_mfma_f32_32x32x16_bf16 v[112:127], v[216:219], v[188:191], v[112:127]
	ds_read_b128 v[208:211], v197
	ds_read_b128 v[172:175], v132
	v_mfma_f32_32x32x16_bf16 v[96:111], v[220:223], v[188:191], v[96:111]
	ds_read_b128 v[212:215], v197 offset:2048
	ds_read_b128 v[176:179], v132 offset:2048
	v_mfma_f32_32x32x16_bf16 v[80:95], v[216:219], v[192:195], v[80:95]
	ds_read_b128 v[180:183], v132 offset:4096
	ds_read_b128 v[184:187], v132 offset:6144
	v_mfma_f32_32x32x16_bf16 v[64:79], v[220:223], v[192:195], v[64:79]
	s_add_u32 m0, s32, 0x20000
	s_nop 0
	global_load_lds_dwordx4 v[232:233], off
	v_lshl_add_u64 v[232:233], v[232:233], 0, s[38:39]
	v_mfma_f32_32x32x16_bf16 v[48:63], v[216:219], v[200:203], v[48:63]
	v_mfma_f32_32x32x16_bf16 v[32:47], v[220:223], v[200:203], v[32:47]
	v_mfma_f32_32x32x16_bf16 v[16:31], v[216:219], v[204:207], v[16:31]
	v_mfma_f32_32x32x16_bf16 v[0:15], v[220:223], v[204:207], v[0:15]
	s_add_u32 m0, s32, 0x24000
	s_nop 0
	global_load_lds_dwordx4 v[236:237], off
	v_lshl_add_u64 v[236:237], v[236:237], 0, s[38:39]
	s_sub_u32 s54, s54, 1
	s_cmp_lg_u32 s54, 0
	s_cbranch_scc1 .Lgk_ph1_loop
	s_waitcnt lgkmcnt(0)
	v_mfma_f32_32x32x16_bf16 v[112:127], v[208:211], v[172:175], v[112:127]
	ds_read_b128 v[216:219], v198
	ds_read_b128 v[188:191], v171
	v_mfma_f32_32x32x16_bf16 v[96:111], v[212:215], v[172:175], v[96:111]
	ds_read_b128 v[220:223], v198 offset:2048
	ds_read_b128 v[192:195], v171 offset:2048
	v_mfma_f32_32x32x16_bf16 v[80:95], v[208:211], v[176:179], v[80:95]
	ds_read_b128 v[200:203], v171 offset:4096
	ds_read_b128 v[204:207], v171 offset:6144
	v_mfma_f32_32x32x16_bf16 v[64:79], v[212:215], v[176:179], v[64:79]
	s_add_u32 m0, s32, 0x22000
	s_nop 0
	global_load_lds_dwordx4 v[234:235], off
	v_lshl_add_u64 v[234:235], v[234:235], 0, s[38:39]
	v_mfma_f32_32x32x16_bf16 v[48:63], v[208:211], v[180:183], v[48:63]
	v_mfma_f32_32x32x16_bf16 v[32:47], v[212:215], v[180:183], v[32:47]
	v_mfma_f32_32x32x16_bf16 v[16:31], v[208:211], v[184:187], v[16:31]
	v_mfma_f32_32x32x16_bf16 v[0:15], v[212:215], v[184:187], v[0:15]
	s_add_u32 m0, s32, 0x26000
	s_nop 0
	global_load_lds_dwordx4 v[238:239], off
	v_lshl_add_u64 v[238:239], v[238:239], 0, s[38:39]
	s_waitcnt lgkmcnt(0)
	s_waitcnt vmcnt(12)
	s_barrier
	s_waitcnt lgkmcnt(0)
	v_mfma_f32_32x32x16_bf16 v[112:127], v[216:219], v[188:191], v[112:127]
	ds_read_b128 v[208:211], v197 offset:32768
	ds_read_b128 v[172:175], v132 offset:32768
	v_mfma_f32_32x32x16_bf16 v[96:111], v[220:223], v[188:191], v[96:111]
	ds_read_b128 v[212:215], v197 offset:34816
	ds_read_b128 v[176:179], v132 offset:34816
	v_mfma_f32_32x32x16_bf16 v[80:95], v[216:219], v[192:195], v[80:95]
	ds_read_b128 v[180:183], v132 offset:36864
	ds_read_b128 v[184:187], v132 offset:38912
	v_mfma_f32_32x32x16_bf16 v[64:79], v[220:223], v[192:195], v[64:79]
	s_add_u32 m0, s32, 0x0
	s_nop 0
	global_load_lds_dwordx4 v[232:233], off
	v_lshl_add_u64 v[232:233], v[232:233], 0, s[38:39]
	v_mfma_f32_32x32x16_bf16 v[48:63], v[216:219], v[200:203], v[48:63]
	v_mfma_f32_32x32x16_bf16 v[32:47], v[220:223], v[200:203], v[32:47]
	v_mfma_f32_32x32x16_bf16 v[16:31], v[216:219], v[204:207], v[16:31]
	v_mfma_f32_32x32x16_bf16 v[0:15], v[220:223], v[204:207], v[0:15]
	s_add_u32 m0, s32, 0x4000
	s_nop 0
	global_load_lds_dwordx4 v[236:237], off
	v_lshl_add_u64 v[236:237], v[236:237], 0, s[38:39]
	s_waitcnt lgkmcnt(0)
	v_mfma_f32_32x32x16_bf16 v[112:127], v[208:211], v[172:175], v[112:127]
	ds_read_b128 v[216:219], v198 offset:32768
	ds_read_b128 v[188:191], v171 offset:32768
	v_mfma_f32_32x32x16_bf16 v[96:111], v[212:215], v[172:175], v[96:111]
	ds_read_b128 v[220:223], v198 offset:34816
	ds_read_b128 v[192:195], v171 offset:34816
	v_mfma_f32_32x32x16_bf16 v[80:95], v[208:211], v[176:179], v[80:95]
	ds_read_b128 v[200:203], v171 offset:36864
	ds_read_b128 v[204:207], v171 offset:38912
	v_mfma_f32_32x32x16_bf16 v[64:79], v[212:215], v[176:179], v[64:79]
	s_add_u32 m0, s32, 0x2000
	s_nop 0
	global_load_lds_dwordx4 v[234:235], off
	v_lshl_add_u64 v[234:235], v[234:235], 0, s[38:39]
	v_mfma_f32_32x32x16_bf16 v[48:63], v[208:211], v[180:183], v[48:63]
	v_mfma_f32_32x32x16_bf16 v[32:47], v[212:215], v[180:183], v[32:47]
	v_mfma_f32_32x32x16_bf16 v[16:31], v[208:211], v[184:187], v[16:31]
	v_mfma_f32_32x32x16_bf16 v[0:15], v[212:215], v[184:187], v[0:15]
	s_add_u32 m0, s32, 0x6000
	s_nop 0
	global_load_lds_dwordx4 v[238:239], off
	v_lshl_add_u64 v[238:239], v[238:239], 0, s[38:39]
	s_waitcnt lgkmcnt(0)
	s_waitcnt vmcnt(12)
	s_barrier
	s_waitcnt lgkmcnt(0)
	v_mfma_f32_32x32x16_bf16 v[112:127], v[216:219], v[188:191], v[112:127]
	ds_read_b128 v[208:211], v225
	ds_read_b128 v[172:175], v199
	v_mfma_f32_32x32x16_bf16 v[96:111], v[220:223], v[188:191], v[96:111]
	ds_read_b128 v[212:215], v225 offset:2048
	ds_read_b128 v[176:179], v199 offset:2048
	v_mfma_f32_32x32x16_bf16 v[80:95], v[216:219], v[192:195], v[80:95]
	ds_read_b128 v[180:183], v199 offset:4096
	ds_read_b128 v[184:187], v199 offset:6144
	v_mfma_f32_32x32x16_bf16 v[64:79], v[220:223], v[192:195], v[64:79]
	s_add_u32 m0, s32, 0x8000
	s_nop 0
	global_load_lds_dwordx4 v[232:233], off
	v_lshl_add_u64 v[232:233], v[232:233], 0, s[38:39]
	v_mfma_f32_32x32x16_bf16 v[48:63], v[216:219], v[200:203], v[48:63]
	v_mfma_f32_32x32x16_bf16 v[32:47], v[220:223], v[200:203], v[32:47]
	v_mfma_f32_32x32x16_bf16 v[16:31], v[216:219], v[204:207], v[16:31]
	v_mfma_f32_32x32x16_bf16 v[0:15], v[220:223], v[204:207], v[0:15]
	s_add_u32 m0, s32, 0xc000
	s_nop 0
	global_load_lds_dwordx4 v[236:237], off
	v_lshl_add_u64 v[236:237], v[236:237], 0, s[38:39]
	s_waitcnt lgkmcnt(0)
	v_mfma_f32_32x32x16_bf16 v[112:127], v[208:211], v[172:175], v[112:127]
	ds_read_b128 v[216:219], v226
	ds_read_b128 v[188:191], v224
	v_mfma_f32_32x32x16_bf16 v[96:111], v[212:215], v[172:175], v[96:111]
	ds_read_b128 v[220:223], v226 offset:2048
	ds_read_b128 v[192:195], v224 offset:2048
	v_mfma_f32_32x32x16_bf16 v[80:95], v[208:211], v[176:179], v[80:95]
	ds_read_b128 v[200:203], v224 offset:4096
	ds_read_b128 v[204:207], v224 offset:6144
	v_mfma_f32_32x32x16_bf16 v[64:79], v[212:215], v[176:179], v[64:79]
	s_add_u32 m0, s32, 0xa000
	s_nop 0
	global_load_lds_dwordx4 v[234:235], off
	v_lshl_add_u64 v[234:235], v[234:235], 0, s[38:39]
	v_mfma_f32_32x32x16_bf16 v[48:63], v[208:211], v[180:183], v[48:63]
	v_mfma_f32_32x32x16_bf16 v[32:47], v[212:215], v[180:183], v[32:47]
	v_mfma_f32_32x32x16_bf16 v[16:31], v[208:211], v[184:187], v[16:31]
	v_mfma_f32_32x32x16_bf16 v[0:15], v[212:215], v[184:187], v[0:15]
	s_add_u32 m0, s32, 0xe000
	s_nop 0
	global_load_lds_dwordx4 v[238:239], off
	v_lshl_add_u64 v[238:239], v[238:239], 0, s[38:39]
	s_waitcnt lgkmcnt(0)
	s_waitcnt vmcnt(12)
	s_barrier
; #define G_LOADA(kt_) { _Pragma("unroll") for (int i = 0; i < 4; ++i) ra[i] = al(lrow + 64 * i, (kt_) * 64 + lck * 8); }
; #define G_LOADB(kt_) { _Pragma("unroll") for (int i = 0; i < 4; ++i) rb[i] = bl(lrow + 64 * i, (kt_) * 64 + lck * 8); }
; #define G_STOREA(buf_) { bf16_t* nA = sA + (buf_) * 256 * GLD; _Pragma("unroll") for (int i = 0; i < 4; ++i) *(u32x4*)(nA + (lrow + 64 * i) * GLD + lck * 8) = ra[i]; }
; #define G_STOREB(buf_) { bf16_t* nB = sB + (buf_) * 256 * GLD; _Pragma("unroll") for (int i = 0; i < 4; ++i) *(u32x4*)(nB + (lrow + 64 * i) * GLD + lck * 8) = rb[i]; }
; template <class AL, class BL, class EP>
; DI void gemm_tile256(AL al, BL bl, EP ep, int K, char* smem) {
;     ...
;   G_LOADA(0); G_LOADB(0);
;   __syncthreads();
;   G_STOREA(0); G_STOREB(0);
;   if (KT > 1) G_LOADB(1);
;   __syncthreads();
;   for (int kt = 0; kt < KT; kt += 2) {
;     G_STEP(0, kt);
;     if (kt + 1 >= KT) break;
;     G_STEP(1, kt + 1);
;   }
	s_waitcnt lgkmcnt(0)
	v_mfma_f32_32x32x16_bf16 v[112:127], v[216:219], v[188:191], v[112:127]
	ds_read_b128 v[208:211], v225 offset:32768
	ds_read_b128 v[172:175], v199 offset:32768
	v_mfma_f32_32x32x16_bf16 v[96:111], v[220:223], v[188:191], v[96:111]
	ds_read_b128 v[212:215], v225 offset:34816
	ds_read_b128 v[176:179], v199 offset:34816
	v_mfma_f32_32x32x16_bf16 v[80:95], v[216:219], v[192:195], v[80:95]
	ds_read_b128 v[180:183], v199 offset:36864
	ds_read_b128 v[184:187], v199 offset:38912
	v_mfma_f32_32x32x16_bf16 v[64:79], v[220:223], v[192:195], v[64:79]
	v_mfma_f32_32x32x16_bf16 v[48:63], v[216:219], v[200:203], v[48:63]
	v_mfma_f32_32x32x16_bf16 v[32:47], v[220:223], v[200:203], v[32:47]
	v_mfma_f32_32x32x16_bf16 v[16:31], v[216:219], v[204:207], v[16:31]
	v_mfma_f32_32x32x16_bf16 v[0:15], v[220:223], v[204:207], v[0:15]
	s_waitcnt lgkmcnt(0)
	v_mfma_f32_32x32x16_bf16 v[112:127], v[208:211], v[172:175], v[112:127]
	ds_read_b128 v[216:219], v226 offset:32768
	ds_read_b128 v[188:191], v224 offset:32768
	v_mfma_f32_32x32x16_bf16 v[96:111], v[212:215], v[172:175], v[96:111]
	ds_read_b128 v[220:223], v226 offset:34816
	ds_read_b128 v[192:195], v224 offset:34816
	v_mfma_f32_32x32x16_bf16 v[80:95], v[208:211], v[176:179], v[80:95]
	ds_read_b128 v[200:203], v224 offset:36864
	ds_read_b128 v[204:207], v224 offset:38912
	v_mfma_f32_32x32x16_bf16 v[64:79], v[212:215], v[176:179], v[64:79]
	v_mfma_f32_32x32x16_bf16 v[48:63], v[208:211], v[180:183], v[48:63]
	v_mfma_f32_32x32x16_bf16 v[32:47], v[212:215], v[180:183], v[32:47]
	v_mfma_f32_32x32x16_bf16 v[16:31], v[208:211], v[184:187], v[16:31]
	v_mfma_f32_32x32x16_bf16 v[0:15], v[212:215], v[184:187], v[0:15]
	s_waitcnt lgkmcnt(0)
	s_waitcnt vmcnt(8)
	s_barrier
	s_waitcnt lgkmcnt(0)
	v_mfma_f32_32x32x16_bf16 v[112:127], v[216:219], v[188:191], v[112:127]
	ds_read_b128 v[208:211], v229
	ds_read_b128 v[172:175], v227
	v_mfma_f32_32x32x16_bf16 v[96:111], v[220:223], v[188:191], v[96:111]
	ds_read_b128 v[212:215], v229 offset:2048
	ds_read_b128 v[176:179], v227 offset:2048
	v_mfma_f32_32x32x16_bf16 v[80:95], v[216:219], v[192:195], v[80:95]
	ds_read_b128 v[180:183], v227 offset:4096
	ds_read_b128 v[184:187], v227 offset:6144
	v_mfma_f32_32x32x16_bf16 v[64:79], v[220:223], v[192:195], v[64:79]
	v_mfma_f32_32x32x16_bf16 v[48:63], v[216:219], v[200:203], v[48:63]
	v_mfma_f32_32x32x16_bf16 v[32:47], v[220:223], v[200:203], v[32:47]
	v_mfma_f32_32x32x16_bf16 v[16:31], v[216:219], v[204:207], v[16:31]
	v_mfma_f32_32x32x16_bf16 v[0:15], v[220:223], v[204:207], v[0:15]
	s_waitcnt lgkmcnt(0)
	v_mfma_f32_32x32x16_bf16 v[112:127], v[208:211], v[172:175], v[112:127]
	ds_read_b128 v[216:219], v230
	ds_read_b128 v[188:191], v228
	v_mfma_f32_32x32x16_bf16 v[96:111], v[212:215], v[172:175], v[96:111]
	ds_read_b128 v[220:223], v230 offset:2048
	ds_read_b128 v[192:195], v228 offset:2048
	v_mfma_f32_32x32x16_bf16 v[80:95], v[208:211], v[176:179], v[80:95]
	ds_read_b128 v[200:203], v228 offset:4096
	ds_read_b128 v[204:207], v228 offset:6144
	v_mfma_f32_32x32x16_bf16 v[64:79], v[212:215], v[176:179], v[64:79]
	v_mfma_f32_32x32x16_bf16 v[48:63], v[208:211], v[180:183], v[48:63]
	v_mfma_f32_32x32x16_bf16 v[32:47], v[212:215], v[180:183], v[32:47]
	v_mfma_f32_32x32x16_bf16 v[16:31], v[208:211], v[184:187], v[16:31]
	v_mfma_f32_32x32x16_bf16 v[0:15], v[212:215], v[184:187], v[0:15]
	s_waitcnt lgkmcnt(0)
	s_waitcnt vmcnt(4)
	s_barrier
	s_waitcnt lgkmcnt(0)
	v_mfma_f32_32x32x16_bf16 v[112:127], v[216:219], v[188:191], v[112:127]
	ds_read_b128 v[208:211], v197
	ds_read_b128 v[172:175], v132
	v_mfma_f32_32x32x16_bf16 v[96:111], v[220:223], v[188:191], v[96:111]
	ds_read_b128 v[212:215], v197 offset:2048
	ds_read_b128 v[176:179], v132 offset:2048
	v_mfma_f32_32x32x16_bf16 v[80:95], v[216:219], v[192:195], v[80:95]
	ds_read_b128 v[180:183], v132 offset:4096
	ds_read_b128 v[184:187], v132 offset:6144
	v_mfma_f32_32x32x16_bf16 v[64:79], v[220:223], v[192:195], v[64:79]
	v_mfma_f32_32x32x16_bf16 v[48:63], v[216:219], v[200:203], v[48:63]
	v_mfma_f32_32x32x16_bf16 v[32:47], v[220:223], v[200:203], v[32:47]
	v_mfma_f32_32x32x16_bf16 v[16:31], v[216:219], v[204:207], v[16:31]
	v_mfma_f32_32x32x16_bf16 v[0:15], v[220:223], v[204:207], v[0:15]
	s_waitcnt lgkmcnt(0)
	v_mfma_f32_32x32x16_bf16 v[112:127], v[208:211], v[172:175], v[112:127]
	ds_read_b128 v[216:219], v198
	ds_read_b128 v[188:191], v171
	v_mfma_f32_32x32x16_bf16 v[96:111], v[212:215], v[172:175], v[96:111]
	ds_read_b128 v[220:223], v198 offset:2048
	ds_read_b128 v[192:195], v171 offset:2048
	v_mfma_f32_32x32x16_bf16 v[80:95], v[208:211], v[176:179], v[80:95]
	ds_read_b128 v[200:203], v171 offset:4096
	ds_read_b128 v[204:207], v171 offset:6144
	v_mfma_f32_32x32x16_bf16 v[64:79], v[212:215], v[176:179], v[64:79]
	v_mfma_f32_32x32x16_bf16 v[48:63], v[208:211], v[180:183], v[48:63]
	v_mfma_f32_32x32x16_bf16 v[32:47], v[212:215], v[180:183], v[32:47]
	v_mfma_f32_32x32x16_bf16 v[16:31], v[208:211], v[184:187], v[16:31]
	v_mfma_f32_32x32x16_bf16 v[0:15], v[212:215], v[184:187], v[0:15]
	s_waitcnt lgkmcnt(0)
	s_waitcnt vmcnt(0)
	s_barrier
; DI unsigned pack2(float a, float b) { f2_t f = {a, b}; bf2_t r = __builtin_convertvector(f, bf2_t); return __builtin_bit_cast(unsigned, r); }
; template <class AL, class BL, class EP>
; DI void gemm_tile256(AL al, BL bl, EP ep, int K, char* smem) {
;     ...
;   if constexpr (EP::kBf16) {
;     bf16_t* sCb = (bf16_t*)smem;
; #pragma unroll
;     for (int i = 0; i < 4; ++i)
; #pragma unroll
;       for (int j = 0; j < 2; ++j)
; #pragma unroll
;         for (int g = 0; g < 4; ++g) {
;           u32x2 v = {pack2(acc[i][j][4 * g], acc[i][j][4 * g + 1]), pack2(acc[i][j][4 * g + 2], acc[i][j][4 * g + 3])};
;           *(u32x2*)(sCb + (128 * wm + 32 * i + r) * BLD + 64 * wn + 32 * j + 8 * g + 4 * h) = v;
;         }
;     __syncthreads();
;     ep(sCb);
	s_waitcnt lgkmcnt(0)
	v_mfma_f32_32x32x16_bf16 v[112:127], v[216:219], v[188:191], v[112:127]
	ds_read_b128 v[208:211], v197 offset:32768
	ds_read_b128 v[172:175], v132 offset:32768
	v_mfma_f32_32x32x16_bf16 v[96:111], v[220:223], v[188:191], v[96:111]
	ds_read_b128 v[212:215], v197 offset:34816
	ds_read_b128 v[176:179], v132 offset:34816
	v_mfma_f32_32x32x16_bf16 v[80:95], v[216:219], v[192:195], v[80:95]
	ds_read_b128 v[180:183], v132 offset:36864
	ds_read_b128 v[184:187], v132 offset:38912
	v_mfma_f32_32x32x16_bf16 v[64:79], v[220:223], v[192:195], v[64:79]
	v_mfma_f32_32x32x16_bf16 v[48:63], v[216:219], v[200:203], v[48:63]
	v_mfma_f32_32x32x16_bf16 v[32:47], v[220:223], v[200:203], v[32:47]
	v_mfma_f32_32x32x16_bf16 v[16:31], v[216:219], v[204:207], v[16:31]
	v_mfma_f32_32x32x16_bf16 v[0:15], v[220:223], v[204:207], v[0:15]
	s_waitcnt lgkmcnt(0)
	v_mfma_f32_32x32x16_bf16 v[112:127], v[208:211], v[172:175], v[112:127]
	ds_read_b128 v[216:219], v198 offset:32768
	ds_read_b128 v[188:191], v171 offset:32768
	v_mfma_f32_32x32x16_bf16 v[96:111], v[212:215], v[172:175], v[96:111]
	ds_read_b128 v[220:223], v198 offset:34816
	ds_read_b128 v[192:195], v171 offset:34816
	v_mfma_f32_32x32x16_bf16 v[80:95], v[208:211], v[176:179], v[80:95]
	ds_read_b128 v[200:203], v171 offset:36864
	ds_read_b128 v[204:207], v171 offset:38912
	v_mfma_f32_32x32x16_bf16 v[64:79], v[212:215], v[176:179], v[64:79]
	v_mfma_f32_32x32x16_bf16 v[48:63], v[208:211], v[180:183], v[48:63]
	v_mfma_f32_32x32x16_bf16 v[32:47], v[212:215], v[180:183], v[32:47]
	v_mfma_f32_32x32x16_bf16 v[16:31], v[208:211], v[184:187], v[16:31]
	v_mfma_f32_32x32x16_bf16 v[0:15], v[212:215], v[184:187], v[0:15]
	s_waitcnt lgkmcnt(0)
	s_waitcnt lgkmcnt(0)
	v_mfma_f32_32x32x16_bf16 v[112:127], v[216:219], v[188:191], v[112:127]
	v_mfma_f32_32x32x16_bf16 v[96:111], v[220:223], v[188:191], v[96:111]
	v_mfma_f32_32x32x16_bf16 v[80:95], v[216:219], v[192:195], v[80:95]
	v_mfma_f32_32x32x16_bf16 v[64:79], v[220:223], v[192:195], v[64:79]
	v_mfma_f32_32x32x16_bf16 v[48:63], v[216:219], v[200:203], v[48:63]
	v_mfma_f32_32x32x16_bf16 v[32:47], v[220:223], v[200:203], v[32:47]
	v_mfma_f32_32x32x16_bf16 v[16:31], v[216:219], v[204:207], v[16:31]
	v_mfma_f32_32x32x16_bf16 v[0:15], v[220:223], v[204:207], v[0:15]
	s_nop 15
	s_nop 3
	v_lshl_or_b32 v128, v128, 7, v170
	s_waitcnt lgkmcnt(4)
	v_mad_u64_u32 v[130:131], s[0:1], v133, s43, v[128:129]
	s_waitcnt lgkmcnt(0)
	s_barrier
	s_nop 8
	v_cvt_pk_bf16_f32 v112, v112, v113
	v_cvt_pk_bf16_f32 v113, v114, v115
	v_cvt_pk_bf16_f32 v114, v116, v117
	v_cvt_pk_bf16_f32 v115, v118, v119
	ds_write2_b64 v130, v[112:113], v[114:115] offset1:2
	v_cvt_pk_bf16_f32 v112, v120, v121
	v_cvt_pk_bf16_f32 v113, v122, v123
	v_cvt_pk_bf16_f32 v114, v124, v125
	s_nop 3
	v_cvt_pk_bf16_f32 v16, v16, v17
	v_cvt_pk_bf16_f32 v17, v18, v19
	v_cvt_pk_bf16_f32 v18, v20, v21
	v_add_u32_e32 v20, 0xc000, v130
	v_cvt_pk_bf16_f32 v19, v22, v23
	v_cvt_pk_bf16_f32 v115, v126, v127
	ds_write2_b64 v20, v[16:17], v[18:19] offset0:192 offset1:194
	v_cvt_pk_bf16_f32 v0, v0, v1
	v_cvt_pk_bf16_f32 v1, v2, v3
	v_cvt_pk_bf16_f32 v2, v4, v5
	v_cvt_pk_bf16_f32 v3, v6, v7
	ds_write2_b64 v20, v[0:1], v[2:3] offset0:200 offset1:202
	v_cvt_pk_bf16_f32 v0, v8, v9
	v_cvt_pk_bf16_f32 v1, v10, v11
	s_nop 3
	v_cvt_pk_bf16_f32 v96, v96, v97
	v_cvt_pk_bf16_f32 v97, v98, v99
	v_cvt_pk_bf16_f32 v98, v100, v101
	v_cvt_pk_bf16_f32 v99, v102, v103
	v_cvt_pk_bf16_f32 v2, v12, v13
	v_cvt_pk_bf16_f32 v3, v14, v15
	ds_write2_b64 v130, v[96:97], v[98:99] offset0:8 offset1:10
	v_cvt_pk_bf16_f32 v80, v80, v81
	v_cvt_pk_bf16_f32 v81, v82, v83
	v_cvt_pk_bf16_f32 v82, v84, v85
	v_cvt_pk_bf16_f32 v83, v86, v87
	v_add_u32_e32 v84, 0x4000, v130
	v_cvt_pk_bf16_f32 v96, v104, v105
	v_cvt_pk_bf16_f32 v97, v106, v107
	s_nop 3
	v_cvt_pk_bf16_f32 v64, v64, v65
	v_cvt_pk_bf16_f32 v65, v66, v67
	v_cvt_pk_bf16_f32 v66, v68, v69
	v_cvt_pk_bf16_f32 v67, v70, v71
	v_cvt_pk_bf16_f32 v98, v108, v109
	v_cvt_pk_bf16_f32 v99, v110, v111
	ds_write2_b64 v84, v[80:81], v[82:83] offset0:64 offset1:66
	v_cvt_pk_bf16_f32 v48, v48, v49
	v_cvt_pk_bf16_f32 v49, v50, v51
	v_cvt_pk_bf16_f32 v50, v52, v53
	v_cvt_pk_bf16_f32 v51, v54, v55
	v_add_u32_e32 v52, 0x8000, v130
	v_cvt_pk_bf16_f32 v80, v88, v89
	v_cvt_pk_bf16_f32 v81, v90, v91
	s_nop 4
	v_cvt_pk_bf16_f32 v32, v32, v33
	v_cvt_pk_bf16_f32 v33, v34, v35
	v_cvt_pk_bf16_f32 v34, v36, v37
	v_cvt_pk_bf16_f32 v35, v38, v39
	v_cvt_pk_bf16_f32 v82, v92, v93
	v_cvt_pk_bf16_f32 v83, v94, v95
	ds_write2_b64 v84, v[64:65], v[66:67] offset0:72 offset1:74
	v_cvt_pk_bf16_f32 v64, v72, v73
	v_cvt_pk_bf16_f32 v65, v74, v75
	v_cvt_pk_bf16_f32 v66, v76, v77
	v_cvt_pk_bf16_f32 v67, v78, v79
	ds_write2_b64 v52, v[48:49], v[50:51] offset0:128 offset1:130
	v_cvt_pk_bf16_f32 v48, v56, v57
	v_cvt_pk_bf16_f32 v49, v58, v59
	v_cvt_pk_bf16_f32 v50, v60, v61
	v_cvt_pk_bf16_f32 v51, v62, v63
	ds_write2_b64 v52, v[32:33], v[34:35] offset0:136 offset1:138
	v_cvt_pk_bf16_f32 v32, v40, v41
	v_cvt_pk_bf16_f32 v33, v42, v43
	v_cvt_pk_bf16_f32 v34, v44, v45
	v_cvt_pk_bf16_f32 v35, v46, v47
	v_cvt_pk_bf16_f32 v16, v24, v25
	v_cvt_pk_bf16_f32 v17, v26, v27
	v_cvt_pk_bf16_f32 v18, v28, v29
	v_cvt_pk_bf16_f32 v19, v30, v31
	ds_write2_b64 v20, v[0:1], v[2:3] offset0:204 offset1:206
	v_mov_b32_e32 v2, v196
	ds_write2_b64 v130, v[112:113], v[114:115] offset0:4 offset1:6
	ds_write2_b64 v130, v[96:97], v[98:99] offset0:12 offset1:14
	ds_write2_b64 v84, v[80:81], v[82:83] offset0:68 offset1:70
	ds_write2_b64 v84, v[64:65], v[66:67] offset0:76 offset1:78
	ds_write2_b64 v52, v[48:49], v[50:51] offset0:132 offset1:134
	ds_write2_b64 v52, v[32:33], v[34:35] offset0:140 offset1:142
	ds_write2_b64 v20, v[16:17], v[18:19] offset0:196 offset1:198
	s_waitcnt lgkmcnt(0)
	s_barrier
	s_nop 0
	v_cmp_gt_i32_e32 vcc, s44, v2
	s_and_saveexec_b64 s[0:1], vcc
	s_cbranch_execz .LBB0_161
	v_lshlrev_b32_e32 v3, 3, v2
	s_mov_b64 s[2:3], 0
	s_branch .LBB0_159

; DI int tid512() { int t = threadIdx_x_raw(); asm volatile("" : "+v"(t)); return t; }
; #define G_LOADA(kt_) { _Pragma("unroll") for (int i = 0; i < 4; ++i) ra[i] = al(lrow + 64 * i, (kt_) * 64 + lck * 8); }
; #define G_LOADB(kt_) { _Pragma("unroll") for (int i = 0; i < 4; ++i) rb[i] = bl(lrow + 64 * i, (kt_) * 64 + lck * 8); }
; #define G_STOREA(buf_) { bf16_t* nA = sA + (buf_) * 256 * GLD; _Pragma("unroll") for (int i = 0; i < 4; ++i) *(u32x4*)(nA + (lrow + 64 * i) * GLD + lck * 8) = ra[i]; }
; #define G_STOREB(buf_) { bf16_t* nB = sB + (buf_) * 256 * GLD; _Pragma("unroll") for (int i = 0; i < 4; ++i) *(u32x4*)(nB + (lrow + 64 * i) * GLD + lck * 8) = rb[i]; }
; template <class AL, class BL, class EP>
; DI void gemm_tile256(AL al, BL bl, EP ep, int K, char* smem) {
;     ...
;   const int tid = tid512(), lane = tid & 63, w = tid >> 6, wm = w >> 2, wn = w & 3, r = lane & 31, h = lane >> 5;
;   const int lrow = tid >> 3, lck = tid & 7;
;   f32x16 acc[4][2];
; #pragma unroll
;   for (int i = 0; i < 4; ++i)
; #pragma unroll
;     for (int j = 0; j < 2; ++j)
; #pragma unroll
;       for (int q = 0; q < 16; ++q) acc[i][j][q] = 0.f;
;   u32x4 ra[4], rb[4];
;   const int KT = K >> 6;
;     ...
;   G_LOADA(0); G_LOADB(0);
;   __syncthreads();
;   G_STOREA(0); G_STOREB(0);
;   if (KT > 1) G_LOADB(1);
;   __syncthreads();
;   DI u32x4 operator()(int r, int k) const {
;     int row = row0 + r;
;     row = row < nrows ? row : nrows - 1;
;     return ldg16(base + (size_t)row * ld + k);
;   }
.LBB0_438:
	s_cmp_lg_u32 s6, 1
	s_mov_b64 s[2:3], -1
	s_cbranch_scc0 .LBB0_445
	v_mov_b32_e32 v32, v196
	s_nop 0
	v_ashrrev_i32_e32 v33, 3, v32
	v_add_u32_e32 v12, s18, v33
	v_add_u32_e32 v28, s17, v33
	v_lshlrev_b32_e32 v0, 4, v32
	v_add_u32_e32 v10, 0x80, v12
	v_add_u32_e32 v26, 0x80, v28
	v_and_b32_e32 v128, 0x70, v0
	v_min_i32_e32 v0, 0x7fff, v12
	v_min_i32_e32 v10, 0x7fff, v10
	v_min_i32_e32 v16, 0x3ff, v28
	v_min_i32_e32 v26, 0x3ff, v26
	v_ashrrev_i32_e32 v1, 31, v0
	v_ashrrev_i32_e32 v11, 31, v10
	v_ashrrev_i32_e32 v17, 31, v16
	v_ashrrev_i32_e32 v27, 31, v26
	v_lshl_add_u64 v[8:9], s[38:39], 0, v[128:129]
	v_lshlrev_b64 v[0:1], 11, v[0:1]
	v_lshlrev_b64 v[10:11], 11, v[10:11]
	v_lshl_add_u64 v[24:25], s[0:1], 0, v[128:129]
	v_lshlrev_b64 v[16:17], 11, v[16:17]
	v_lshlrev_b64 v[26:27], 11, v[26:27]
	v_lshl_add_u64 v[134:135], v[8:9], 0, v[0:1]
	v_add_u32_e32 v0, 64, v12
	v_lshl_add_u64 v[138:139], v[8:9], 0, v[10:11]
	v_add_u32_e32 v10, 0xc0, v12
	v_lshl_add_u64 v[142:143], v[24:25], 0, v[16:17]
	v_add_u32_e32 v16, 64, v28
	v_lshl_add_u64 v[146:147], v[24:25], 0, v[26:27]
	v_add_u32_e32 v26, 0xc0, v28
	v_min_i32_e32 v0, 0x7fff, v0
	v_min_i32_e32 v10, 0x7fff, v10
	v_min_i32_e32 v16, 0x3ff, v16
	v_min_i32_e32 v26, 0x3ff, v26
	v_ashrrev_i32_e32 v1, 31, v0
	v_ashrrev_i32_e32 v11, 31, v10
	v_ashrrev_i32_e32 v17, 31, v16
	v_ashrrev_i32_e32 v27, 31, v26
	v_lshlrev_b64 v[0:1], 11, v[0:1]
	v_lshlrev_b64 v[10:11], 11, v[10:11]
	v_lshlrev_b64 v[16:17], 11, v[16:17]
	v_lshlrev_b64 v[26:27], 11, v[26:27]
	v_lshl_add_u64 v[136:137], v[8:9], 0, v[0:1]
	v_lshl_add_u64 v[140:141], v[8:9], 0, v[10:11]
	v_lshl_add_u64 v[144:145], v[24:25], 0, v[16:17]
	v_lshl_add_u64 v[148:149], v[24:25], 0, v[26:27]
	v_mad_u64_u32 v[132:133], s[2:3], v33, s11, v[128:129]
	v_add_u32_e32 v153, 0x12000, v132
	v_bfe_u32 v128, v32, 6, 2
	v_add_u32_e32 v152, 0x1b000, v132
	v_and_b32_e32 v1, 31, v32
	v_ashrrev_i32_e32 v0, 1, v32
	v_and_or_b32 v133, v0, s12, v1
	v_lshrrev_b32_e32 v0, 2, v32
	v_and_b32_e32 v150, 8, v0
	v_lshlrev_b32_e32 v0, 1, v150
	v_mad_u64_u32 v[130:131], s[2:3], v133, s11, v[0:1]
	v_lshl_or_b32 v1, v128, 6, v1
	v_mul_u32_u24_e32 v1, 0x48, v1
	v_lshl_add_u32 v0, v1, 1, v0
	v_add_u32_e32 v151, 0x12000, v0
	v_add_u32_e32 v131, 0x1b000, v0
	s_nop 0
	s_nop 0
	s_nop 0
	s_nop 0
	s_nop 0
	s_nop 0
	v_lshrrev_b32_e32 v222, 6, v196
	s_mov_b32 s4, 64
	v_readfirstlane_b32 s19, v222
	s_mov_b32 s5, 0
	s_mov_b32 s6, 0x40000
	s_mov_b32 s7, 0
	v_bfe_u32 v220, v196, 2, 4
	s_lshl_b32 s23, s19, 3
	v_add_u32_e32 v220, s23, v220
	s_mov_b32 s23, 0x800
	v_mul_lo_u32 v220, v220, s23
	v_bfe_u32 v222, v196, 4, 2
	v_and_b32_e32 v221, 3, v196
	v_xor_b32_e32 v222, v221, v222
	v_lshl_add_u32 v220, v222, 4, v220
	v_mov_b32_e32 v221, 0
	v_readlane_b32 s20, v134, 0
	v_readlane_b32 s21, v135, 0
	s_nop 1
	v_lshl_add_u64 v[212:213], s[20:21], 0, v[220:221]
	v_lshl_add_u64 v[214:215], v[212:213], 0, s[6:7]
	v_readlane_b32 s20, v142, 0
	v_readlane_b32 s21, v143, 0
	s_nop 1
	v_lshl_add_u64 v[216:217], s[20:21], 0, v[220:221]
	v_lshl_add_u64 v[218:219], v[216:217], 0, s[6:7]
	v_and_b32_e32 v220, 31, v196
	v_bfe_u32 v222, v196, 2, 2
	v_bfe_u32 v221, v196, 5, 1
	v_xor_b32_e32 v222, v221, v222
	v_lshlrev_b32_e32 v222, 4, v222
	v_lshl_or_b32 v220, v220, 6, v222
	s_lshr_b32 s23, s19, 2
	s_lshl_b32 s23, s23, 13
	v_add_u32_e32 v132, s23, v220
	s_and_b32 s23, s19, 3
	s_lshl_b32 s23, s23, 12
	s_add_u32 s23, s23, 0x4000
	v_add_u32_e32 v198, s23, v220
	v_xor_b32_e32 v151, 0x20, v132
	v_xor_b32_e32 v199, 0x20, v198
	v_add_u32_e32 v204, 0x10000, v132
	v_add_u32_e32 v206, 0x10000, v198
	v_add_u32_e32 v208, 0x20000, v132
	v_add_u32_e32 v210, 0x20000, v198
	v_add_u32_e32 v205, 0x10000, v151
	v_add_u32_e32 v207, 0x10000, v199
	v_add_u32_e32 v209, 0x20000, v151
	v_add_u32_e32 v211, 0x20000, v199
	s_lshl_b32 s19, s19, 10
	s_waitcnt lgkmcnt(0)
	s_barrier
	s_add_u32 m0, s19, 0x0
	s_nop 0
	global_load_lds_dwordx4 v[212:213], off
	v_lshl_add_u64 v[212:213], v[212:213], 0, s[4:5]
	s_add_u32 m0, s19, 0x4000
	s_nop 0
	global_load_lds_dwordx4 v[216:217], off
	v_lshl_add_u64 v[216:217], v[216:217], 0, s[4:5]
	s_add_u32 m0, s19, 0x2000
	s_nop 0
	global_load_lds_dwordx4 v[214:215], off
	v_lshl_add_u64 v[214:215], v[214:215], 0, s[4:5]
	s_add_u32 m0, s19, 0x6000
	s_nop 0
	global_load_lds_dwordx4 v[218:219], off
	v_lshl_add_u64 v[218:219], v[218:219], 0, s[4:5]
	s_add_u32 m0, s19, 0x8000
	s_nop 0
	global_load_lds_dwordx4 v[212:213], off
	v_lshl_add_u64 v[212:213], v[212:213], 0, s[4:5]
	s_add_u32 m0, s19, 0xc000
	s_nop 0
	global_load_lds_dwordx4 v[216:217], off
	v_lshl_add_u64 v[216:217], v[216:217], 0, s[4:5]
	s_add_u32 m0, s19, 0xa000
	s_nop 0
	global_load_lds_dwordx4 v[214:215], off
	v_lshl_add_u64 v[214:215], v[214:215], 0, s[4:5]
	s_add_u32 m0, s19, 0xe000
	s_nop 0
	global_load_lds_dwordx4 v[218:219], off
	v_lshl_add_u64 v[218:219], v[218:219], 0, s[4:5]
	s_add_u32 m0, s19, 0x10000
	s_nop 0
	global_load_lds_dwordx4 v[212:213], off
	v_lshl_add_u64 v[212:213], v[212:213], 0, s[4:5]
	s_add_u32 m0, s19, 0x14000
	s_nop 0
	global_load_lds_dwordx4 v[216:217], off
	v_lshl_add_u64 v[216:217], v[216:217], 0, s[4:5]
	s_add_u32 m0, s19, 0x12000
	s_nop 0
	global_load_lds_dwordx4 v[214:215], off
	v_lshl_add_u64 v[214:215], v[214:215], 0, s[4:5]
	s_add_u32 m0, s19, 0x16000
	s_nop 0
	global_load_lds_dwordx4 v[218:219], off
	v_lshl_add_u64 v[218:219], v[218:219], 0, s[4:5]
	s_add_u32 m0, s19, 0x18000
	s_nop 0
	global_load_lds_dwordx4 v[212:213], off
	v_lshl_add_u64 v[212:213], v[212:213], 0, s[4:5]
	s_add_u32 m0, s19, 0x1c000
	s_nop 0
	global_load_lds_dwordx4 v[216:217], off
	v_lshl_add_u64 v[216:217], v[216:217], 0, s[4:5]
; #define G_LOADA(kt_) { _Pragma("unroll") for (int i = 0; i < 4; ++i) ra[i] = al(lrow + 64 * i, (kt_) * 64 + lck * 8); }
; #define G_LOADB(kt_) { _Pragma("unroll") for (int i = 0; i < 4; ++i) rb[i] = bl(lrow + 64 * i, (kt_) * 64 + lck * 8); }
; #define G_STOREA(buf_) { bf16_t* nA = sA + (buf_) * 256 * GLD; _Pragma("unroll") for (int i = 0; i < 4; ++i) *(u32x4*)(nA + (lrow + 64 * i) * GLD + lck * 8) = ra[i]; }
; #define G_STOREB(buf_) { bf16_t* nB = sB + (buf_) * 256 * GLD; _Pragma("unroll") for (int i = 0; i < 4; ++i) *(u32x4*)(nB + (lrow + 64 * i) * GLD + lck * 8) = rb[i]; }
; template <class AL, class BL, class EP>
; DI void gemm_tile256(AL al, BL bl, EP ep, int K, char* smem) {
;     ...
;   f32x16 acc[4][2];
; #pragma unroll
;   for (int i = 0; i < 4; ++i)
; #pragma unroll
;     for (int j = 0; j < 2; ++j)
; #pragma unroll
;       for (int q = 0; q < 16; ++q) acc[i][j][q] = 0.f;
;   u32x4 ra[4], rb[4];
;   const int KT = K >> 6;
;     ...
;   G_LOADA(0); G_LOADB(0);
;   __syncthreads();
;   G_STOREA(0); G_STOREB(0);
;   if (KT > 1) G_LOADB(1);
;   __syncthreads();
;   for (int kt = 0; kt < KT; kt += 2) {
;     G_STEP(0, kt);
;     if (kt + 1 >= KT) break;
;     G_STEP(1, kt + 1);
;   }
	s_add_u32 m0, s19, 0x1a000
	s_nop 0
	global_load_lds_dwordx4 v[214:215], off
	v_lshl_add_u64 v[214:215], v[214:215], 0, s[4:5]
	s_add_u32 m0, s19, 0x1e000
	s_nop 0
	global_load_lds_dwordx4 v[218:219], off
	v_lshl_add_u64 v[218:219], v[218:219], 0, s[4:5]
	s_add_u32 m0, s19, 0x20000
	s_nop 0
	global_load_lds_dwordx4 v[212:213], off
	v_lshl_add_u64 v[212:213], v[212:213], 0, s[4:5]
	s_add_u32 m0, s19, 0x24000
	s_nop 0
	global_load_lds_dwordx4 v[216:217], off
	v_lshl_add_u64 v[216:217], v[216:217], 0, s[4:5]
	v_mov_b64_e32 v[112:113], 0
	v_mov_b64_e32 v[114:115], 0
	v_mov_b64_e32 v[116:117], 0
	v_mov_b64_e32 v[118:119], 0
	v_mov_b64_e32 v[120:121], 0
	v_mov_b64_e32 v[122:123], 0
	v_mov_b64_e32 v[124:125], 0
	v_mov_b64_e32 v[126:127], 0
	v_mov_b64_e32 v[96:97], 0
	v_mov_b64_e32 v[98:99], 0
	v_mov_b64_e32 v[100:101], 0
	v_mov_b64_e32 v[102:103], 0
	v_mov_b64_e32 v[104:105], 0
	v_mov_b64_e32 v[106:107], 0
	v_mov_b64_e32 v[108:109], 0
	v_mov_b64_e32 v[110:111], 0
	v_mov_b64_e32 v[80:81], 0
	v_mov_b64_e32 v[82:83], 0
	v_mov_b64_e32 v[84:85], 0
	v_mov_b64_e32 v[86:87], 0
	v_mov_b64_e32 v[88:89], 0
	v_mov_b64_e32 v[90:91], 0
	v_mov_b64_e32 v[92:93], 0
	v_mov_b64_e32 v[94:95], 0
	v_mov_b64_e32 v[64:65], 0
	v_mov_b64_e32 v[66:67], 0
	v_mov_b64_e32 v[68:69], 0
	v_mov_b64_e32 v[70:71], 0
	v_mov_b64_e32 v[72:73], 0
	v_mov_b64_e32 v[74:75], 0
	v_mov_b64_e32 v[76:77], 0
	v_mov_b64_e32 v[78:79], 0
	v_mov_b64_e32 v[48:49], 0
	v_mov_b64_e32 v[50:51], 0
	v_mov_b64_e32 v[52:53], 0
	v_mov_b64_e32 v[54:55], 0
	v_mov_b64_e32 v[56:57], 0
	v_mov_b64_e32 v[58:59], 0
	v_mov_b64_e32 v[60:61], 0
	v_mov_b64_e32 v[62:63], 0
	v_mov_b64_e32 v[32:33], 0
	v_mov_b64_e32 v[34:35], 0
	v_mov_b64_e32 v[36:37], 0
	v_mov_b64_e32 v[38:39], 0
	v_mov_b64_e32 v[40:41], 0
	v_mov_b64_e32 v[42:43], 0
	v_mov_b64_e32 v[44:45], 0
	v_mov_b64_e32 v[46:47], 0
	v_mov_b64_e32 v[16:17], 0
	v_mov_b64_e32 v[18:19], 0
	v_mov_b64_e32 v[20:21], 0
	v_mov_b64_e32 v[22:23], 0
	v_mov_b64_e32 v[24:25], 0
	v_mov_b64_e32 v[26:27], 0
	v_mov_b64_e32 v[28:29], 0
	v_mov_b64_e32 v[30:31], 0
	v_mov_b64_e32 v[0:1], 0
	v_mov_b64_e32 v[2:3], 0
	v_mov_b64_e32 v[4:5], 0
	v_mov_b64_e32 v[6:7], 0
	v_mov_b64_e32 v[8:9], 0
	v_mov_b64_e32 v[10:11], 0
	v_mov_b64_e32 v[12:13], 0
	v_mov_b64_e32 v[14:15], 0
	s_mov_b32 s23, 5
	s_waitcnt vmcnt(14)
	s_barrier
	ds_read_b128 v[184:187], v198
	ds_read_b128 v[152:155], v132
	ds_read_b128 v[188:191], v198 offset:2048
	ds_read_b128 v[156:159], v132 offset:2048
	ds_read_b128 v[160:163], v132 offset:4096
	ds_read_b128 v[164:167], v132 offset:6144
.Lgk_ph4_loop:
	s_waitcnt lgkmcnt(0)
	v_mfma_f32_32x32x16_bf16 v[112:127], v[184:187], v[152:155], v[112:127]
	ds_read_b128 v[192:195], v199
	ds_read_b128 v[168:171], v151
	v_mfma_f32_32x32x16_bf16 v[96:111], v[188:191], v[152:155], v[96:111]
	ds_read_b128 v[200:203], v199 offset:2048
	ds_read_b128 v[172:175], v151 offset:2048
	v_mfma_f32_32x32x16_bf16 v[80:95], v[184:187], v[156:159], v[80:95]
	ds_read_b128 v[176:179], v151 offset:4096
	ds_read_b128 v[180:183], v151 offset:6144
	v_mfma_f32_32x32x16_bf16 v[64:79], v[188:191], v[156:159], v[64:79]
	s_add_u32 m0, s19, 0x22000
	s_nop 0
	global_load_lds_dwordx4 v[214:215], off
	v_lshl_add_u64 v[214:215], v[214:215], 0, s[4:5]
	v_mfma_f32_32x32x16_bf16 v[48:63], v[184:187], v[160:163], v[48:63]
	v_mfma_f32_32x32x16_bf16 v[32:47], v[188:191], v[160:163], v[32:47]
	v_mfma_f32_32x32x16_bf16 v[16:31], v[184:187], v[164:167], v[16:31]
	v_mfma_f32_32x32x16_bf16 v[0:15], v[188:191], v[164:167], v[0:15]
	s_add_u32 m0, s19, 0x26000
	s_nop 0
	global_load_lds_dwordx4 v[218:219], off
	v_lshl_add_u64 v[218:219], v[218:219], 0, s[4:5]
	s_waitcnt lgkmcnt(0)
	s_waitcnt vmcnt(12)
	s_barrier
	s_waitcnt lgkmcnt(0)
	v_mfma_f32_32x32x16_bf16 v[112:127], v[192:195], v[168:171], v[112:127]
	ds_read_b128 v[184:187], v198 offset:32768
	ds_read_b128 v[152:155], v132 offset:32768
	v_mfma_f32_32x32x16_bf16 v[96:111], v[200:203], v[168:171], v[96:111]
	ds_read_b128 v[188:191], v198 offset:34816
	ds_read_b128 v[156:159], v132 offset:34816
	v_mfma_f32_32x32x16_bf16 v[80:95], v[192:195], v[172:175], v[80:95]
	ds_read_b128 v[160:163], v132 offset:36864
	ds_read_b128 v[164:167], v132 offset:38912
	v_mfma_f32_32x32x16_bf16 v[64:79], v[200:203], v[172:175], v[64:79]
	s_add_u32 m0, s19, 0x0
	s_nop 0
	global_load_lds_dwordx4 v[212:213], off
	v_lshl_add_u64 v[212:213], v[212:213], 0, s[4:5]
	v_mfma_f32_32x32x16_bf16 v[48:63], v[192:195], v[176:179], v[48:63]
	v_mfma_f32_32x32x16_bf16 v[32:47], v[200:203], v[176:179], v[32:47]
	v_mfma_f32_32x32x16_bf16 v[16:31], v[192:195], v[180:183], v[16:31]
	v_mfma_f32_32x32x16_bf16 v[0:15], v[200:203], v[180:183], v[0:15]
	s_add_u32 m0, s19, 0x4000
	s_nop 0
	global_load_lds_dwordx4 v[216:217], off
	v_lshl_add_u64 v[216:217], v[216:217], 0, s[4:5]
	s_waitcnt lgkmcnt(0)
	v_mfma_f32_32x32x16_bf16 v[112:127], v[184:187], v[152:155], v[112:127]
	ds_read_b128 v[192:195], v199 offset:32768
	ds_read_b128 v[168:171], v151 offset:32768
	v_mfma_f32_32x32x16_bf16 v[96:111], v[188:191], v[152:155], v[96:111]
	ds_read_b128 v[200:203], v199 offset:34816
	ds_read_b128 v[172:175], v151 offset:34816
	v_mfma_f32_32x32x16_bf16 v[80:95], v[184:187], v[156:159], v[80:95]
	ds_read_b128 v[176:179], v151 offset:36864
	ds_read_b128 v[180:183], v151 offset:38912
	v_mfma_f32_32x32x16_bf16 v[64:79], v[188:191], v[156:159], v[64:79]
	s_add_u32 m0, s19, 0x2000
	s_nop 0
	global_load_lds_dwordx4 v[214:215], off
	v_lshl_add_u64 v[214:215], v[214:215], 0, s[4:5]
	v_mfma_f32_32x32x16_bf16 v[48:63], v[184:187], v[160:163], v[48:63]
	v_mfma_f32_32x32x16_bf16 v[32:47], v[188:191], v[160:163], v[32:47]
	v_mfma_f32_32x32x16_bf16 v[16:31], v[184:187], v[164:167], v[16:31]
	v_mfma_f32_32x32x16_bf16 v[0:15], v[188:191], v[164:167], v[0:15]
	s_add_u32 m0, s19, 0x6000
	s_nop 0
	global_load_lds_dwordx4 v[218:219], off
	v_lshl_add_u64 v[218:219], v[218:219], 0, s[4:5]
	s_waitcnt lgkmcnt(0)
	s_waitcnt vmcnt(12)
	s_barrier
; #define G_LOADA(kt_) { _Pragma("unroll") for (int i = 0; i < 4; ++i) ra[i] = al(lrow + 64 * i, (kt_) * 64 + lck * 8); }
; #define G_LOADB(kt_) { _Pragma("unroll") for (int i = 0; i < 4; ++i) rb[i] = bl(lrow + 64 * i, (kt_) * 64 + lck * 8); }
; #define G_STOREA(buf_) { bf16_t* nA = sA + (buf_) * 256 * GLD; _Pragma("unroll") for (int i = 0; i < 4; ++i) *(u32x4*)(nA + (lrow + 64 * i) * GLD + lck * 8) = ra[i]; }
; #define G_STOREB(buf_) { bf16_t* nB = sB + (buf_) * 256 * GLD; _Pragma("unroll") for (int i = 0; i < 4; ++i) *(u32x4*)(nB + (lrow + 64 * i) * GLD + lck * 8) = rb[i]; }
; template <class AL, class BL, class EP>
; DI void gemm_tile256(AL al, BL bl, EP ep, int K, char* smem) {
;     ...
;   G_LOADA(0); G_LOADB(0);
;   __syncthreads();
;   G_STOREA(0); G_STOREB(0);
;   if (KT > 1) G_LOADB(1);
;   __syncthreads();
;   for (int kt = 0; kt < KT; kt += 2) {
;     G_STEP(0, kt);
;     if (kt + 1 >= KT) break;
;     G_STEP(1, kt + 1);
;   }
	s_waitcnt lgkmcnt(0)
	v_mfma_f32_32x32x16_bf16 v[112:127], v[192:195], v[168:171], v[112:127]
	ds_read_b128 v[184:187], v206
	ds_read_b128 v[152:155], v204
	v_mfma_f32_32x32x16_bf16 v[96:111], v[200:203], v[168:171], v[96:111]
	ds_read_b128 v[188:191], v206 offset:2048
	ds_read_b128 v[156:159], v204 offset:2048
	v_mfma_f32_32x32x16_bf16 v[80:95], v[192:195], v[172:175], v[80:95]
	ds_read_b128 v[160:163], v204 offset:4096
	ds_read_b128 v[164:167], v204 offset:6144
	v_mfma_f32_32x32x16_bf16 v[64:79], v[200:203], v[172:175], v[64:79]
	s_add_u32 m0, s19, 0x8000
	s_nop 0
	global_load_lds_dwordx4 v[212:213], off
	v_lshl_add_u64 v[212:213], v[212:213], 0, s[4:5]
	v_mfma_f32_32x32x16_bf16 v[48:63], v[192:195], v[176:179], v[48:63]
	v_mfma_f32_32x32x16_bf16 v[32:47], v[200:203], v[176:179], v[32:47]
	v_mfma_f32_32x32x16_bf16 v[16:31], v[192:195], v[180:183], v[16:31]
	v_mfma_f32_32x32x16_bf16 v[0:15], v[200:203], v[180:183], v[0:15]
	s_add_u32 m0, s19, 0xc000
	s_nop 0
	global_load_lds_dwordx4 v[216:217], off
	v_lshl_add_u64 v[216:217], v[216:217], 0, s[4:5]
	s_waitcnt lgkmcnt(0)
	v_mfma_f32_32x32x16_bf16 v[112:127], v[184:187], v[152:155], v[112:127]
	ds_read_b128 v[192:195], v207
	ds_read_b128 v[168:171], v205
	v_mfma_f32_32x32x16_bf16 v[96:111], v[188:191], v[152:155], v[96:111]
	ds_read_b128 v[200:203], v207 offset:2048
	ds_read_b128 v[172:175], v205 offset:2048
	v_mfma_f32_32x32x16_bf16 v[80:95], v[184:187], v[156:159], v[80:95]
	ds_read_b128 v[176:179], v205 offset:4096
	ds_read_b128 v[180:183], v205 offset:6144
	v_mfma_f32_32x32x16_bf16 v[64:79], v[188:191], v[156:159], v[64:79]
	s_add_u32 m0, s19, 0xa000
	s_nop 0
	global_load_lds_dwordx4 v[214:215], off
	v_lshl_add_u64 v[214:215], v[214:215], 0, s[4:5]
	v_mfma_f32_32x32x16_bf16 v[48:63], v[184:187], v[160:163], v[48:63]
	v_mfma_f32_32x32x16_bf16 v[32:47], v[188:191], v[160:163], v[32:47]
	v_mfma_f32_32x32x16_bf16 v[16:31], v[184:187], v[164:167], v[16:31]
	v_mfma_f32_32x32x16_bf16 v[0:15], v[188:191], v[164:167], v[0:15]
	s_add_u32 m0, s19, 0xe000
	s_nop 0
	global_load_lds_dwordx4 v[218:219], off
	v_lshl_add_u64 v[218:219], v[218:219], 0, s[4:5]
	s_waitcnt lgkmcnt(0)
	s_waitcnt vmcnt(12)
	s_barrier
	s_waitcnt lgkmcnt(0)
	v_mfma_f32_32x32x16_bf16 v[112:127], v[192:195], v[168:171], v[112:127]
	ds_read_b128 v[184:187], v206 offset:32768
	ds_read_b128 v[152:155], v204 offset:32768
	v_mfma_f32_32x32x16_bf16 v[96:111], v[200:203], v[168:171], v[96:111]
	ds_read_b128 v[188:191], v206 offset:34816
	ds_read_b128 v[156:159], v204 offset:34816
	v_mfma_f32_32x32x16_bf16 v[80:95], v[192:195], v[172:175], v[80:95]
	ds_read_b128 v[160:163], v204 offset:36864
	ds_read_b128 v[164:167], v204 offset:38912
	v_mfma_f32_32x32x16_bf16 v[64:79], v[200:203], v[172:175], v[64:79]
	s_add_u32 m0, s19, 0x10000
	s_nop 0
	global_load_lds_dwordx4 v[212:213], off
	v_lshl_add_u64 v[212:213], v[212:213], 0, s[4:5]
	v_mfma_f32_32x32x16_bf16 v[48:63], v[192:195], v[176:179], v[48:63]
	v_mfma_f32_32x32x16_bf16 v[32:47], v[200:203], v[176:179], v[32:47]
	v_mfma_f32_32x32x16_bf16 v[16:31], v[192:195], v[180:183], v[16:31]
	v_mfma_f32_32x32x16_bf16 v[0:15], v[200:203], v[180:183], v[0:15]
	s_add_u32 m0, s19, 0x14000
	s_nop 0
	global_load_lds_dwordx4 v[216:217], off
	v_lshl_add_u64 v[216:217], v[216:217], 0, s[4:5]
	s_waitcnt lgkmcnt(0)
	v_mfma_f32_32x32x16_bf16 v[112:127], v[184:187], v[152:155], v[112:127]
	ds_read_b128 v[192:195], v207 offset:32768
	ds_read_b128 v[168:171], v205 offset:32768
	v_mfma_f32_32x32x16_bf16 v[96:111], v[188:191], v[152:155], v[96:111]
	ds_read_b128 v[200:203], v207 offset:34816
	ds_read_b128 v[172:175], v205 offset:34816
	v_mfma_f32_32x32x16_bf16 v[80:95], v[184:187], v[156:159], v[80:95]
	ds_read_b128 v[176:179], v205 offset:36864
	ds_read_b128 v[180:183], v205 offset:38912
	v_mfma_f32_32x32x16_bf16 v[64:79], v[188:191], v[156:159], v[64:79]
	s_add_u32 m0, s19, 0x12000
	s_nop 0
	global_load_lds_dwordx4 v[214:215], off
	v_lshl_add_u64 v[214:215], v[214:215], 0, s[4:5]
	v_mfma_f32_32x32x16_bf16 v[48:63], v[184:187], v[160:163], v[48:63]
	v_mfma_f32_32x32x16_bf16 v[32:47], v[188:191], v[160:163], v[32:47]
	v_mfma_f32_32x32x16_bf16 v[16:31], v[184:187], v[164:167], v[16:31]
	v_mfma_f32_32x32x16_bf16 v[0:15], v[188:191], v[164:167], v[0:15]
	s_add_u32 m0, s19, 0x16000
	s_nop 0
	global_load_lds_dwordx4 v[218:219], off
	v_lshl_add_u64 v[218:219], v[218:219], 0, s[4:5]
	s_waitcnt lgkmcnt(0)
	s_waitcnt vmcnt(12)
	s_barrier
	s_waitcnt lgkmcnt(0)
	v_mfma_f32_32x32x16_bf16 v[112:127], v[192:195], v[168:171], v[112:127]
	ds_read_b128 v[184:187], v210
	ds_read_b128 v[152:155], v208
	v_mfma_f32_32x32x16_bf16 v[96:111], v[200:203], v[168:171], v[96:111]
	ds_read_b128 v[188:191], v210 offset:2048
	ds_read_b128 v[156:159], v208 offset:2048
	v_mfma_f32_32x32x16_bf16 v[80:95], v[192:195], v[172:175], v[80:95]
	ds_read_b128 v[160:163], v208 offset:4096
	ds_read_b128 v[164:167], v208 offset:6144
	v_mfma_f32_32x32x16_bf16 v[64:79], v[200:203], v[172:175], v[64:79]
	s_add_u32 m0, s19, 0x18000
	s_nop 0
	global_load_lds_dwordx4 v[212:213], off
	v_lshl_add_u64 v[212:213], v[212:213], 0, s[4:5]
	v_mfma_f32_32x32x16_bf16 v[48:63], v[192:195], v[176:179], v[48:63]
	v_mfma_f32_32x32x16_bf16 v[32:47], v[200:203], v[176:179], v[32:47]
	v_mfma_f32_32x32x16_bf16 v[16:31], v[192:195], v[180:183], v[16:31]
	v_mfma_f32_32x32x16_bf16 v[0:15], v[200:203], v[180:183], v[0:15]
	s_add_u32 m0, s19, 0x1c000
	s_nop 0
	global_load_lds_dwordx4 v[216:217], off
	v_lshl_add_u64 v[216:217], v[216:217], 0, s[4:5]
	s_waitcnt lgkmcnt(0)
	v_mfma_f32_32x32x16_bf16 v[112:127], v[184:187], v[152:155], v[112:127]
	ds_read_b128 v[192:195], v211
	ds_read_b128 v[168:171], v209
	v_mfma_f32_32x32x16_bf16 v[96:111], v[188:191], v[152:155], v[96:111]
	ds_read_b128 v[200:203], v211 offset:2048
	ds_read_b128 v[172:175], v209 offset:2048
	v_mfma_f32_32x32x16_bf16 v[80:95], v[184:187], v[156:159], v[80:95]
	ds_read_b128 v[176:179], v209 offset:4096
	ds_read_b128 v[180:183], v209 offset:6144
	v_mfma_f32_32x32x16_bf16 v[64:79], v[188:191], v[156:159], v[64:79]
	s_add_u32 m0, s19, 0x1a000
	s_nop 0
	global_load_lds_dwordx4 v[214:215], off
	v_lshl_add_u64 v[214:215], v[214:215], 0, s[4:5]
	v_mfma_f32_32x32x16_bf16 v[48:63], v[184:187], v[160:163], v[48:63]
	v_mfma_f32_32x32x16_bf16 v[32:47], v[188:191], v[160:163], v[32:47]
	v_mfma_f32_32x32x16_bf16 v[16:31], v[184:187], v[164:167], v[16:31]
	v_mfma_f32_32x32x16_bf16 v[0:15], v[188:191], v[164:167], v[0:15]
	s_add_u32 m0, s19, 0x1e000
	s_nop 0
	global_load_lds_dwordx4 v[218:219], off
	v_lshl_add_u64 v[218:219], v[218:219], 0, s[4:5]
	s_waitcnt lgkmcnt(0)
	s_waitcnt vmcnt(12)
	s_barrier
; #define G_LOADA(kt_) { _Pragma("unroll") for (int i = 0; i < 4; ++i) ra[i] = al(lrow + 64 * i, (kt_) * 64 + lck * 8); }
; #define G_LOADB(kt_) { _Pragma("unroll") for (int i = 0; i < 4; ++i) rb[i] = bl(lrow + 64 * i, (kt_) * 64 + lck * 8); }
; #define G_STOREA(buf_) { bf16_t* nA = sA + (buf_) * 256 * GLD; _Pragma("unroll") for (int i = 0; i < 4; ++i) *(u32x4*)(nA + (lrow + 64 * i) * GLD + lck * 8) = ra[i]; }
; #define G_STOREB(buf_) { bf16_t* nB = sB + (buf_) * 256 * GLD; _Pragma("unroll") for (int i = 0; i < 4; ++i) *(u32x4*)(nB + (lrow + 64 * i) * GLD + lck * 8) = rb[i]; }
; template <class AL, class BL, class EP>
; DI void gemm_tile256(AL al, BL bl, EP ep, int K, char* smem) {
;     ...
;   G_LOADA(0); G_LOADB(0);
;   __syncthreads();
;   G_STOREA(0); G_STOREB(0);
;   if (KT > 1) G_LOADB(1);
;   __syncthreads();
;   for (int kt = 0; kt < KT; kt += 2) {
;     G_STEP(0, kt);
;     if (kt + 1 >= KT) break;
;     G_STEP(1, kt + 1);
;   }
	s_waitcnt lgkmcnt(0)
	v_mfma_f32_32x32x16_bf16 v[112:127], v[192:195], v[168:171], v[112:127]
	ds_read_b128 v[184:187], v198
	ds_read_b128 v[152:155], v132
	v_mfma_f32_32x32x16_bf16 v[96:111], v[200:203], v[168:171], v[96:111]
	ds_read_b128 v[188:191], v198 offset:2048
	ds_read_b128 v[156:159], v132 offset:2048
	v_mfma_f32_32x32x16_bf16 v[80:95], v[192:195], v[172:175], v[80:95]
	ds_read_b128 v[160:163], v132 offset:4096
	ds_read_b128 v[164:167], v132 offset:6144
	v_mfma_f32_32x32x16_bf16 v[64:79], v[200:203], v[172:175], v[64:79]
	s_add_u32 m0, s19, 0x20000
	s_nop 0
	global_load_lds_dwordx4 v[212:213], off
	v_lshl_add_u64 v[212:213], v[212:213], 0, s[4:5]
	v_mfma_f32_32x32x16_bf16 v[48:63], v[192:195], v[176:179], v[48:63]
	v_mfma_f32_32x32x16_bf16 v[32:47], v[200:203], v[176:179], v[32:47]
	v_mfma_f32_32x32x16_bf16 v[16:31], v[192:195], v[180:183], v[16:31]
	v_mfma_f32_32x32x16_bf16 v[0:15], v[200:203], v[180:183], v[0:15]
	s_add_u32 m0, s19, 0x24000
	s_nop 0
	global_load_lds_dwordx4 v[216:217], off
	v_lshl_add_u64 v[216:217], v[216:217], 0, s[4:5]
	s_sub_u32 s23, s23, 1
	s_cmp_lg_u32 s23, 0
	s_cbranch_scc1 .Lgk_ph4_loop
	s_waitcnt lgkmcnt(0)
	v_mfma_f32_32x32x16_bf16 v[112:127], v[184:187], v[152:155], v[112:127]
	ds_read_b128 v[192:195], v199
	ds_read_b128 v[168:171], v151
	v_mfma_f32_32x32x16_bf16 v[96:111], v[188:191], v[152:155], v[96:111]
	ds_read_b128 v[200:203], v199 offset:2048
	ds_read_b128 v[172:175], v151 offset:2048
	v_mfma_f32_32x32x16_bf16 v[80:95], v[184:187], v[156:159], v[80:95]
	ds_read_b128 v[176:179], v151 offset:4096
	ds_read_b128 v[180:183], v151 offset:6144
	v_mfma_f32_32x32x16_bf16 v[64:79], v[188:191], v[156:159], v[64:79]
	s_add_u32 m0, s19, 0x22000
	s_nop 0
	global_load_lds_dwordx4 v[214:215], off
	v_lshl_add_u64 v[214:215], v[214:215], 0, s[4:5]
	v_mfma_f32_32x32x16_bf16 v[48:63], v[184:187], v[160:163], v[48:63]
	v_mfma_f32_32x32x16_bf16 v[32:47], v[188:191], v[160:163], v[32:47]
	v_mfma_f32_32x32x16_bf16 v[16:31], v[184:187], v[164:167], v[16:31]
	v_mfma_f32_32x32x16_bf16 v[0:15], v[188:191], v[164:167], v[0:15]
	s_add_u32 m0, s19, 0x26000
	s_nop 0
	global_load_lds_dwordx4 v[218:219], off
	v_lshl_add_u64 v[218:219], v[218:219], 0, s[4:5]
	s_waitcnt lgkmcnt(0)
	s_waitcnt vmcnt(12)
	s_barrier
	s_waitcnt lgkmcnt(0)
	v_mfma_f32_32x32x16_bf16 v[112:127], v[192:195], v[168:171], v[112:127]
	ds_read_b128 v[184:187], v198 offset:32768
	ds_read_b128 v[152:155], v132 offset:32768
	v_mfma_f32_32x32x16_bf16 v[96:111], v[200:203], v[168:171], v[96:111]
	ds_read_b128 v[188:191], v198 offset:34816
	ds_read_b128 v[156:159], v132 offset:34816
	v_mfma_f32_32x32x16_bf16 v[80:95], v[192:195], v[172:175], v[80:95]
	ds_read_b128 v[160:163], v132 offset:36864
	ds_read_b128 v[164:167], v132 offset:38912
	v_mfma_f32_32x32x16_bf16 v[64:79], v[200:203], v[172:175], v[64:79]
	s_add_u32 m0, s19, 0x0
	s_nop 0
	global_load_lds_dwordx4 v[212:213], off
	v_lshl_add_u64 v[212:213], v[212:213], 0, s[4:5]
	v_mfma_f32_32x32x16_bf16 v[48:63], v[192:195], v[176:179], v[48:63]
	v_mfma_f32_32x32x16_bf16 v[32:47], v[200:203], v[176:179], v[32:47]
	v_mfma_f32_32x32x16_bf16 v[16:31], v[192:195], v[180:183], v[16:31]
	v_mfma_f32_32x32x16_bf16 v[0:15], v[200:203], v[180:183], v[0:15]
	s_add_u32 m0, s19, 0x4000
	s_nop 0
	global_load_lds_dwordx4 v[216:217], off
	v_lshl_add_u64 v[216:217], v[216:217], 0, s[4:5]
	s_waitcnt lgkmcnt(0)
	v_mfma_f32_32x32x16_bf16 v[112:127], v[184:187], v[152:155], v[112:127]
	ds_read_b128 v[192:195], v199 offset:32768
	ds_read_b128 v[168:171], v151 offset:32768
	v_mfma_f32_32x32x16_bf16 v[96:111], v[188:191], v[152:155], v[96:111]
	ds_read_b128 v[200:203], v199 offset:34816
	ds_read_b128 v[172:175], v151 offset:34816
	v_mfma_f32_32x32x16_bf16 v[80:95], v[184:187], v[156:159], v[80:95]
	ds_read_b128 v[176:179], v151 offset:36864
	ds_read_b128 v[180:183], v151 offset:38912
	v_mfma_f32_32x32x16_bf16 v[64:79], v[188:191], v[156:159], v[64:79]
	s_add_u32 m0, s19, 0x2000
	s_nop 0
	global_load_lds_dwordx4 v[214:215], off
	v_lshl_add_u64 v[214:215], v[214:215], 0, s[4:5]
	v_mfma_f32_32x32x16_bf16 v[48:63], v[184:187], v[160:163], v[48:63]
	v_mfma_f32_32x32x16_bf16 v[32:47], v[188:191], v[160:163], v[32:47]
	v_mfma_f32_32x32x16_bf16 v[16:31], v[184:187], v[164:167], v[16:31]
	v_mfma_f32_32x32x16_bf16 v[0:15], v[188:191], v[164:167], v[0:15]
	s_add_u32 m0, s19, 0x6000
	s_nop 0
	global_load_lds_dwordx4 v[218:219], off
	v_lshl_add_u64 v[218:219], v[218:219], 0, s[4:5]
	s_waitcnt lgkmcnt(0)
	s_waitcnt vmcnt(12)
	s_barrier
	s_waitcnt lgkmcnt(0)
	v_mfma_f32_32x32x16_bf16 v[112:127], v[192:195], v[168:171], v[112:127]
	ds_read_b128 v[184:187], v206
	ds_read_b128 v[152:155], v204
	v_mfma_f32_32x32x16_bf16 v[96:111], v[200:203], v[168:171], v[96:111]
	ds_read_b128 v[188:191], v206 offset:2048
	ds_read_b128 v[156:159], v204 offset:2048
	v_mfma_f32_32x32x16_bf16 v[80:95], v[192:195], v[172:175], v[80:95]
	ds_read_b128 v[160:163], v204 offset:4096
	ds_read_b128 v[164:167], v204 offset:6144
	v_mfma_f32_32x32x16_bf16 v[64:79], v[200:203], v[172:175], v[64:79]
	s_add_u32 m0, s19, 0x8000
	s_nop 0
	global_load_lds_dwordx4 v[212:213], off
	v_lshl_add_u64 v[212:213], v[212:213], 0, s[4:5]
	v_mfma_f32_32x32x16_bf16 v[48:63], v[192:195], v[176:179], v[48:63]
	v_mfma_f32_32x32x16_bf16 v[32:47], v[200:203], v[176:179], v[32:47]
	v_mfma_f32_32x32x16_bf16 v[16:31], v[192:195], v[180:183], v[16:31]
	v_mfma_f32_32x32x16_bf16 v[0:15], v[200:203], v[180:183], v[0:15]
	s_add_u32 m0, s19, 0xc000
	s_nop 0
	global_load_lds_dwordx4 v[216:217], off
	v_lshl_add_u64 v[216:217], v[216:217], 0, s[4:5]
	s_waitcnt lgkmcnt(0)
	v_mfma_f32_32x32x16_bf16 v[112:127], v[184:187], v[152:155], v[112:127]
	ds_read_b128 v[192:195], v207
	ds_read_b128 v[168:171], v205
	v_mfma_f32_32x32x16_bf16 v[96:111], v[188:191], v[152:155], v[96:111]
	ds_read_b128 v[200:203], v207 offset:2048
	ds_read_b128 v[172:175], v205 offset:2048
	v_mfma_f32_32x32x16_bf16 v[80:95], v[184:187], v[156:159], v[80:95]
	ds_read_b128 v[176:179], v205 offset:4096
	ds_read_b128 v[180:183], v205 offset:6144
	v_mfma_f32_32x32x16_bf16 v[64:79], v[188:191], v[156:159], v[64:79]
	s_add_u32 m0, s19, 0xa000
	s_nop 0
	global_load_lds_dwordx4 v[214:215], off
	v_lshl_add_u64 v[214:215], v[214:215], 0, s[4:5]
	v_mfma_f32_32x32x16_bf16 v[48:63], v[184:187], v[160:163], v[48:63]
	v_mfma_f32_32x32x16_bf16 v[32:47], v[188:191], v[160:163], v[32:47]
	v_mfma_f32_32x32x16_bf16 v[16:31], v[184:187], v[164:167], v[16:31]
	v_mfma_f32_32x32x16_bf16 v[0:15], v[188:191], v[164:167], v[0:15]
	s_add_u32 m0, s19, 0xe000
	s_nop 0
	global_load_lds_dwordx4 v[218:219], off
	v_lshl_add_u64 v[218:219], v[218:219], 0, s[4:5]
	s_waitcnt lgkmcnt(0)
	s_waitcnt vmcnt(12)
	s_barrier
; #define G_LOADA(kt_) { _Pragma("unroll") for (int i = 0; i < 4; ++i) ra[i] = al(lrow + 64 * i, (kt_) * 64 + lck * 8); }
; #define G_LOADB(kt_) { _Pragma("unroll") for (int i = 0; i < 4; ++i) rb[i] = bl(lrow + 64 * i, (kt_) * 64 + lck * 8); }
; #define G_STOREA(buf_) { bf16_t* nA = sA + (buf_) * 256 * GLD; _Pragma("unroll") for (int i = 0; i < 4; ++i) *(u32x4*)(nA + (lrow + 64 * i) * GLD + lck * 8) = ra[i]; }
; #define G_STOREB(buf_) { bf16_t* nB = sB + (buf_) * 256 * GLD; _Pragma("unroll") for (int i = 0; i < 4; ++i) *(u32x4*)(nB + (lrow + 64 * i) * GLD + lck * 8) = rb[i]; }
; template <class AL, class BL, class EP>
; DI void gemm_tile256(AL al, BL bl, EP ep, int K, char* smem) {
;     ...
;   G_LOADA(0); G_LOADB(0);
;   __syncthreads();
;   G_STOREA(0); G_STOREB(0);
;   if (KT > 1) G_LOADB(1);
;   __syncthreads();
;   for (int kt = 0; kt < KT; kt += 2) {
;     G_STEP(0, kt);
;     if (kt + 1 >= KT) break;
;     G_STEP(1, kt + 1);
;   }
	s_waitcnt lgkmcnt(0)
	v_mfma_f32_32x32x16_bf16 v[112:127], v[192:195], v[168:171], v[112:127]
	ds_read_b128 v[184:187], v206 offset:32768
	ds_read_b128 v[152:155], v204 offset:32768
	v_mfma_f32_32x32x16_bf16 v[96:111], v[200:203], v[168:171], v[96:111]
	ds_read_b128 v[188:191], v206 offset:34816
	ds_read_b128 v[156:159], v204 offset:34816
	v_mfma_f32_32x32x16_bf16 v[80:95], v[192:195], v[172:175], v[80:95]
	ds_read_b128 v[160:163], v204 offset:36864
	ds_read_b128 v[164:167], v204 offset:38912
	v_mfma_f32_32x32x16_bf16 v[64:79], v[200:203], v[172:175], v[64:79]
	v_mfma_f32_32x32x16_bf16 v[48:63], v[192:195], v[176:179], v[48:63]
	v_mfma_f32_32x32x16_bf16 v[32:47], v[200:203], v[176:179], v[32:47]
	v_mfma_f32_32x32x16_bf16 v[16:31], v[192:195], v[180:183], v[16:31]
	v_mfma_f32_32x32x16_bf16 v[0:15], v[200:203], v[180:183], v[0:15]
	s_waitcnt lgkmcnt(0)
	v_mfma_f32_32x32x16_bf16 v[112:127], v[184:187], v[152:155], v[112:127]
	ds_read_b128 v[192:195], v207 offset:32768
	ds_read_b128 v[168:171], v205 offset:32768
	v_mfma_f32_32x32x16_bf16 v[96:111], v[188:191], v[152:155], v[96:111]
	ds_read_b128 v[200:203], v207 offset:34816
	ds_read_b128 v[172:175], v205 offset:34816
	v_mfma_f32_32x32x16_bf16 v[80:95], v[184:187], v[156:159], v[80:95]
	ds_read_b128 v[176:179], v205 offset:36864
	ds_read_b128 v[180:183], v205 offset:38912
	v_mfma_f32_32x32x16_bf16 v[64:79], v[188:191], v[156:159], v[64:79]
	v_mfma_f32_32x32x16_bf16 v[48:63], v[184:187], v[160:163], v[48:63]
	v_mfma_f32_32x32x16_bf16 v[32:47], v[188:191], v[160:163], v[32:47]
	v_mfma_f32_32x32x16_bf16 v[16:31], v[184:187], v[164:167], v[16:31]
	v_mfma_f32_32x32x16_bf16 v[0:15], v[188:191], v[164:167], v[0:15]
	s_waitcnt lgkmcnt(0)
	s_waitcnt vmcnt(8)
	s_barrier
	s_waitcnt lgkmcnt(0)
	v_mfma_f32_32x32x16_bf16 v[112:127], v[192:195], v[168:171], v[112:127]
	ds_read_b128 v[184:187], v210
	ds_read_b128 v[152:155], v208
	v_mfma_f32_32x32x16_bf16 v[96:111], v[200:203], v[168:171], v[96:111]
	ds_read_b128 v[188:191], v210 offset:2048
	ds_read_b128 v[156:159], v208 offset:2048
	v_mfma_f32_32x32x16_bf16 v[80:95], v[192:195], v[172:175], v[80:95]
	ds_read_b128 v[160:163], v208 offset:4096
	ds_read_b128 v[164:167], v208 offset:6144
	v_mfma_f32_32x32x16_bf16 v[64:79], v[200:203], v[172:175], v[64:79]
	v_mfma_f32_32x32x16_bf16 v[48:63], v[192:195], v[176:179], v[48:63]
	v_mfma_f32_32x32x16_bf16 v[32:47], v[200:203], v[176:179], v[32:47]
	v_mfma_f32_32x32x16_bf16 v[16:31], v[192:195], v[180:183], v[16:31]
	v_mfma_f32_32x32x16_bf16 v[0:15], v[200:203], v[180:183], v[0:15]
	s_waitcnt lgkmcnt(0)
	v_mfma_f32_32x32x16_bf16 v[112:127], v[184:187], v[152:155], v[112:127]
	ds_read_b128 v[192:195], v211
	ds_read_b128 v[168:171], v209
	v_mfma_f32_32x32x16_bf16 v[96:111], v[188:191], v[152:155], v[96:111]
	ds_read_b128 v[200:203], v211 offset:2048
	ds_read_b128 v[172:175], v209 offset:2048
	v_mfma_f32_32x32x16_bf16 v[80:95], v[184:187], v[156:159], v[80:95]
	ds_read_b128 v[176:179], v209 offset:4096
	ds_read_b128 v[180:183], v209 offset:6144
	v_mfma_f32_32x32x16_bf16 v[64:79], v[188:191], v[156:159], v[64:79]
	v_mfma_f32_32x32x16_bf16 v[48:63], v[184:187], v[160:163], v[48:63]
	v_mfma_f32_32x32x16_bf16 v[32:47], v[188:191], v[160:163], v[32:47]
	v_mfma_f32_32x32x16_bf16 v[16:31], v[184:187], v[164:167], v[16:31]
	v_mfma_f32_32x32x16_bf16 v[0:15], v[188:191], v[164:167], v[0:15]
	s_waitcnt lgkmcnt(0)
	s_waitcnt vmcnt(4)
	s_barrier
	s_waitcnt lgkmcnt(0)
	v_mfma_f32_32x32x16_bf16 v[112:127], v[192:195], v[168:171], v[112:127]
	ds_read_b128 v[184:187], v198
	ds_read_b128 v[152:155], v132
	v_mfma_f32_32x32x16_bf16 v[96:111], v[200:203], v[168:171], v[96:111]
	ds_read_b128 v[188:191], v198 offset:2048
	ds_read_b128 v[156:159], v132 offset:2048
	v_mfma_f32_32x32x16_bf16 v[80:95], v[192:195], v[172:175], v[80:95]
	ds_read_b128 v[160:163], v132 offset:4096
	ds_read_b128 v[164:167], v132 offset:6144
	v_mfma_f32_32x32x16_bf16 v[64:79], v[200:203], v[172:175], v[64:79]
	v_mfma_f32_32x32x16_bf16 v[48:63], v[192:195], v[176:179], v[48:63]
	v_mfma_f32_32x32x16_bf16 v[32:47], v[200:203], v[176:179], v[32:47]
	v_mfma_f32_32x32x16_bf16 v[16:31], v[192:195], v[180:183], v[16:31]
	v_mfma_f32_32x32x16_bf16 v[0:15], v[200:203], v[180:183], v[0:15]
	s_waitcnt lgkmcnt(0)
	v_mfma_f32_32x32x16_bf16 v[112:127], v[184:187], v[152:155], v[112:127]
	ds_read_b128 v[192:195], v199
	ds_read_b128 v[168:171], v151
	v_mfma_f32_32x32x16_bf16 v[96:111], v[188:191], v[152:155], v[96:111]
	ds_read_b128 v[200:203], v199 offset:2048
	ds_read_b128 v[172:175], v151 offset:2048
	v_mfma_f32_32x32x16_bf16 v[80:95], v[184:187], v[156:159], v[80:95]
	ds_read_b128 v[176:179], v151 offset:4096
	ds_read_b128 v[180:183], v151 offset:6144
	v_mfma_f32_32x32x16_bf16 v[64:79], v[188:191], v[156:159], v[64:79]
	v_mfma_f32_32x32x16_bf16 v[48:63], v[184:187], v[160:163], v[48:63]
	v_mfma_f32_32x32x16_bf16 v[32:47], v[188:191], v[160:163], v[32:47]
	v_mfma_f32_32x32x16_bf16 v[16:31], v[184:187], v[164:167], v[16:31]
	v_mfma_f32_32x32x16_bf16 v[0:15], v[188:191], v[164:167], v[0:15]
	s_waitcnt lgkmcnt(0)
	s_waitcnt vmcnt(0)
	s_barrier
; DI unsigned pack2(float a, float b) { f2_t f = {a, b}; bf2_t r = __builtin_convertvector(f, bf2_t); return __builtin_bit_cast(unsigned, r); }
; template <class AL, class BL, class EP>
; DI void gemm_tile256(AL al, BL bl, EP ep, int K, char* smem) {
;     ...
;   if constexpr (EP::kBf16) {
;     bf16_t* sCb = (bf16_t*)smem;
; #pragma unroll
;     for (int i = 0; i < 4; ++i)
; #pragma unroll
;       for (int j = 0; j < 2; ++j)
; #pragma unroll
;         for (int g = 0; g < 4; ++g) {
;           u32x2 v = {pack2(acc[i][j][4 * g], acc[i][j][4 * g + 1]), pack2(acc[i][j][4 * g + 2], acc[i][j][4 * g + 3])};
;           *(u32x2*)(sCb + (128 * wm + 32 * i + r) * BLD + 64 * wn + 32 * j + 8 * g + 4 * h) = v;
;         }
;     __syncthreads();
;     ep(sCb);
	s_waitcnt lgkmcnt(0)
	v_mfma_f32_32x32x16_bf16 v[112:127], v[192:195], v[168:171], v[112:127]
	ds_read_b128 v[184:187], v198 offset:32768
	ds_read_b128 v[152:155], v132 offset:32768
	v_mfma_f32_32x32x16_bf16 v[96:111], v[200:203], v[168:171], v[96:111]
	ds_read_b128 v[188:191], v198 offset:34816
	ds_read_b128 v[156:159], v132 offset:34816
	v_mfma_f32_32x32x16_bf16 v[80:95], v[192:195], v[172:175], v[80:95]
	ds_read_b128 v[160:163], v132 offset:36864
	ds_read_b128 v[164:167], v132 offset:38912
	v_mfma_f32_32x32x16_bf16 v[64:79], v[200:203], v[172:175], v[64:79]
	v_mfma_f32_32x32x16_bf16 v[48:63], v[192:195], v[176:179], v[48:63]
	v_mfma_f32_32x32x16_bf16 v[32:47], v[200:203], v[176:179], v[32:47]
	v_mfma_f32_32x32x16_bf16 v[16:31], v[192:195], v[180:183], v[16:31]
	v_mfma_f32_32x32x16_bf16 v[0:15], v[200:203], v[180:183], v[0:15]
	s_waitcnt lgkmcnt(0)
	v_mfma_f32_32x32x16_bf16 v[112:127], v[184:187], v[152:155], v[112:127]
	ds_read_b128 v[192:195], v199 offset:32768
	ds_read_b128 v[168:171], v151 offset:32768
	v_mfma_f32_32x32x16_bf16 v[96:111], v[188:191], v[152:155], v[96:111]
	ds_read_b128 v[200:203], v199 offset:34816
	ds_read_b128 v[172:175], v151 offset:34816
	v_mfma_f32_32x32x16_bf16 v[80:95], v[184:187], v[156:159], v[80:95]
	ds_read_b128 v[176:179], v151 offset:36864
	ds_read_b128 v[180:183], v151 offset:38912
	v_mfma_f32_32x32x16_bf16 v[64:79], v[188:191], v[156:159], v[64:79]
	v_mfma_f32_32x32x16_bf16 v[48:63], v[184:187], v[160:163], v[48:63]
	v_mfma_f32_32x32x16_bf16 v[32:47], v[188:191], v[160:163], v[32:47]
	v_mfma_f32_32x32x16_bf16 v[16:31], v[184:187], v[164:167], v[16:31]
	v_mfma_f32_32x32x16_bf16 v[0:15], v[188:191], v[164:167], v[0:15]
	s_waitcnt lgkmcnt(0)
	s_waitcnt lgkmcnt(0)
	v_mfma_f32_32x32x16_bf16 v[112:127], v[192:195], v[168:171], v[112:127]
	v_mfma_f32_32x32x16_bf16 v[96:111], v[200:203], v[168:171], v[96:111]
	v_mfma_f32_32x32x16_bf16 v[80:95], v[192:195], v[172:175], v[80:95]
	v_mfma_f32_32x32x16_bf16 v[64:79], v[200:203], v[172:175], v[64:79]
	v_mfma_f32_32x32x16_bf16 v[48:63], v[192:195], v[176:179], v[48:63]
	v_mfma_f32_32x32x16_bf16 v[32:47], v[200:203], v[176:179], v[32:47]
	v_mfma_f32_32x32x16_bf16 v[16:31], v[192:195], v[180:183], v[16:31]
	v_mfma_f32_32x32x16_bf16 v[0:15], v[200:203], v[180:183], v[0:15]
	s_nop 15
	s_nop 3
	v_lshl_or_b32 v128, v128, 7, v150
	s_waitcnt lgkmcnt(4)
	v_mad_u64_u32 v[130:131], s[2:3], v133, s13, v[128:129]
	s_waitcnt lgkmcnt(0)
	s_barrier
	s_nop 8
	v_cvt_pk_bf16_f32 v112, v112, v113
	v_cvt_pk_bf16_f32 v113, v114, v115
	v_cvt_pk_bf16_f32 v114, v116, v117
	v_cvt_pk_bf16_f32 v115, v118, v119
	ds_write2_b64 v130, v[112:113], v[114:115] offset1:2
	v_cvt_pk_bf16_f32 v112, v120, v121
	v_cvt_pk_bf16_f32 v113, v122, v123
	v_cvt_pk_bf16_f32 v114, v124, v125
	s_nop 3
	v_cvt_pk_bf16_f32 v16, v16, v17
	v_cvt_pk_bf16_f32 v17, v18, v19
	v_cvt_pk_bf16_f32 v18, v20, v21
	v_add_u32_e32 v20, 0xc000, v130
	v_cvt_pk_bf16_f32 v19, v22, v23
	v_cvt_pk_bf16_f32 v115, v126, v127
	ds_write2_b64 v20, v[16:17], v[18:19] offset0:192 offset1:194
	v_cvt_pk_bf16_f32 v0, v0, v1
	v_cvt_pk_bf16_f32 v1, v2, v3
	v_cvt_pk_bf16_f32 v2, v4, v5
	v_cvt_pk_bf16_f32 v3, v6, v7
	ds_write2_b64 v20, v[0:1], v[2:3] offset0:200 offset1:202
	v_cvt_pk_bf16_f32 v0, v8, v9
	v_cvt_pk_bf16_f32 v1, v10, v11
	s_nop 3
	v_cvt_pk_bf16_f32 v96, v96, v97
	v_cvt_pk_bf16_f32 v97, v98, v99
	v_cvt_pk_bf16_f32 v98, v100, v101
	v_cvt_pk_bf16_f32 v99, v102, v103
	v_cvt_pk_bf16_f32 v2, v12, v13
	v_cvt_pk_bf16_f32 v3, v14, v15
	ds_write2_b64 v130, v[96:97], v[98:99] offset0:8 offset1:10
	v_cvt_pk_bf16_f32 v80, v80, v81
	v_cvt_pk_bf16_f32 v81, v82, v83
	v_cvt_pk_bf16_f32 v82, v84, v85
	v_cvt_pk_bf16_f32 v83, v86, v87
	v_add_u32_e32 v84, 0x4000, v130
	v_cvt_pk_bf16_f32 v96, v104, v105
	v_cvt_pk_bf16_f32 v97, v106, v107
	s_nop 3
	v_cvt_pk_bf16_f32 v64, v64, v65
	v_cvt_pk_bf16_f32 v65, v66, v67
	v_cvt_pk_bf16_f32 v66, v68, v69
	v_cvt_pk_bf16_f32 v67, v70, v71
	v_cvt_pk_bf16_f32 v98, v108, v109
	v_cvt_pk_bf16_f32 v99, v110, v111
	ds_write2_b64 v84, v[80:81], v[82:83] offset0:64 offset1:66
	v_cvt_pk_bf16_f32 v48, v48, v49
	v_cvt_pk_bf16_f32 v49, v50, v51
	v_cvt_pk_bf16_f32 v50, v52, v53
	v_cvt_pk_bf16_f32 v51, v54, v55
	v_add_u32_e32 v52, 0x8000, v130
	v_cvt_pk_bf16_f32 v80, v88, v89
	v_cvt_pk_bf16_f32 v81, v90, v91
	s_nop 4
	v_cvt_pk_bf16_f32 v32, v32, v33
	v_cvt_pk_bf16_f32 v33, v34, v35
	v_cvt_pk_bf16_f32 v34, v36, v37
	v_cvt_pk_bf16_f32 v35, v38, v39
	v_cvt_pk_bf16_f32 v82, v92, v93
	v_cvt_pk_bf16_f32 v83, v94, v95
	ds_write2_b64 v84, v[64:65], v[66:67] offset0:72 offset1:74
	v_cvt_pk_bf16_f32 v64, v72, v73
	v_cvt_pk_bf16_f32 v65, v74, v75
	v_cvt_pk_bf16_f32 v66, v76, v77
	v_cvt_pk_bf16_f32 v67, v78, v79
	ds_write2_b64 v52, v[48:49], v[50:51] offset0:128 offset1:130
	v_cvt_pk_bf16_f32 v48, v56, v57
	v_cvt_pk_bf16_f32 v49, v58, v59
	v_cvt_pk_bf16_f32 v50, v60, v61
	v_cvt_pk_bf16_f32 v51, v62, v63
	ds_write2_b64 v52, v[32:33], v[34:35] offset0:136 offset1:138
	v_cvt_pk_bf16_f32 v32, v40, v41
	v_cvt_pk_bf16_f32 v33, v42, v43
	v_cvt_pk_bf16_f32 v34, v44, v45
	v_cvt_pk_bf16_f32 v35, v46, v47
	v_cvt_pk_bf16_f32 v16, v24, v25
	v_cvt_pk_bf16_f32 v17, v26, v27
	v_cvt_pk_bf16_f32 v18, v28, v29
	v_cvt_pk_bf16_f32 v19, v30, v31
	ds_write2_b64 v20, v[0:1], v[2:3] offset0:204 offset1:206
	v_mov_b32_e32 v2, v196
	ds_write2_b64 v130, v[112:113], v[114:115] offset0:4 offset1:6
	ds_write2_b64 v130, v[96:97], v[98:99] offset0:12 offset1:14
	ds_write2_b64 v84, v[80:81], v[82:83] offset0:68 offset1:70
	ds_write2_b64 v84, v[64:65], v[66:67] offset0:76 offset1:78
	ds_write2_b64 v52, v[48:49], v[50:51] offset0:132 offset1:134
	ds_write2_b64 v52, v[32:33], v[34:35] offset0:140 offset1:142
	ds_write2_b64 v20, v[16:17], v[18:19] offset0:196 offset1:198
	s_waitcnt lgkmcnt(0)
	s_barrier
	s_nop 0
	v_cmp_gt_i32_e32 vcc, s14, v2
	s_and_saveexec_b64 s[2:3], vcc
	s_cbranch_execz .LBB0_444
	v_lshlrev_b32_e32 v3, 3, v2
	s_mov_b64 s[4:5], 0
	s_branch .LBB0_442

; DI int tid512() { int t = threadIdx_x_raw(); asm volatile("" : "+v"(t)); return t; }
; #define G_LOADA(kt_) { _Pragma("unroll") for (int i = 0; i < 4; ++i) ra[i] = al(lrow + 64 * i, (kt_) * 64 + lck * 8); }
; #define G_LOADB(kt_) { _Pragma("unroll") for (int i = 0; i < 4; ++i) rb[i] = bl(lrow + 64 * i, (kt_) * 64 + lck * 8); }
; #define G_STOREA(buf_) { bf16_t* nA = sA + (buf_) * 256 * GLD; _Pragma("unroll") for (int i = 0; i < 4; ++i) *(u32x4*)(nA + (lrow + 64 * i) * GLD + lck * 8) = ra[i]; }
; #define G_STOREB(buf_) { bf16_t* nB = sB + (buf_) * 256 * GLD; _Pragma("unroll") for (int i = 0; i < 4; ++i) *(u32x4*)(nB + (lrow + 64 * i) * GLD + lck * 8) = rb[i]; }
; template <class AL, class BL, class EP>
; DI void gemm_tile256(AL al, BL bl, EP ep, int K, char* smem) {
;     ...
;   const int tid = tid512(), lane = tid & 63, w = tid >> 6, wm = w >> 2, wn = w & 3, r = lane & 31, h = lane >> 5;
;   const int lrow = tid >> 3, lck = tid & 7;
;   f32x16 acc[4][2];
; #pragma unroll
;   for (int i = 0; i < 4; ++i)
; #pragma unroll
;     for (int j = 0; j < 2; ++j)
; #pragma unroll
;       for (int q = 0; q < 16; ++q) acc[i][j][q] = 0.f;
;   u32x4 ra[4], rb[4];
;   const int KT = K >> 6;
;     ...
;   G_LOADA(0); G_LOADB(0);
;   __syncthreads();
;   G_STOREA(0); G_STOREB(0);
;   if (KT > 1) G_LOADB(1);
;   __syncthreads();
;   DI u32x4 operator()(int r, int k) const {
;     int row = row0 + r;
;     row = row < nrows ? row : nrows - 1;
;     return ldg16(base + (size_t)row * ld + k);
;   }
.LBB0_541:
	v_cmp_ne_u32_e32 vcc, 1, v0
	s_mov_b64 s[0:1], -1
	s_cbranch_vccz .LBB0_556
	v_mov_b32_e32 v32, v196
	s_nop 0
	v_ashrrev_i32_e32 v33, 3, v32
	v_lshl_add_u32 v12, v130, 8, v33
	v_lshlrev_b32_e32 v0, 4, v32
	v_add_u32_e32 v10, 0x80, v12
	v_lshl_add_u32 v28, v131, 8, v33
	v_and_b32_e32 v128, 0x70, v0
	v_min_i32_e32 v0, 0x7fff, v12
	v_min_i32_e32 v10, 0x7fff, v10
	v_add_u32_e32 v26, 0x80, v28
	v_ashrrev_i32_e32 v1, 31, v0
	v_ashrrev_i32_e32 v11, 31, v10
	v_min_i32_e32 v16, 0x15ff, v28
	v_min_i32_e32 v26, 0x15ff, v26
	v_lshl_add_u64 v[8:9], s[84:85], 0, v[128:129]
	v_lshlrev_b64 v[0:1], 11, v[0:1]
	v_lshlrev_b64 v[10:11], 11, v[10:11]
	v_ashrrev_i32_e32 v17, 31, v16
	v_ashrrev_i32_e32 v27, 31, v26
	v_lshl_add_u64 v[136:137], v[8:9], 0, v[0:1]
	v_add_u32_e32 v0, 64, v12
	v_lshl_add_u64 v[140:141], v[8:9], 0, v[10:11]
	v_add_u32_e32 v10, 0xc0, v12
	v_lshlrev_b64 v[190:191], 11, v[16:17]
	v_add_u32_e32 v16, 64, v28
	v_lshlrev_b64 v[194:195], 11, v[26:27]
	v_add_u32_e32 v26, 0xc0, v28
	v_min_i32_e32 v0, 0x7fff, v0
	v_min_i32_e32 v10, 0x7fff, v10
	v_min_i32_e32 v16, 0x15ff, v16
	v_min_i32_e32 v26, 0x15ff, v26
	v_ashrrev_i32_e32 v1, 31, v0
	v_ashrrev_i32_e32 v11, 31, v10
	v_lshl_add_u64 v[24:25], s[2:3], 0, v[128:129]
	v_ashrrev_i32_e32 v17, 31, v16
	v_ashrrev_i32_e32 v27, 31, v26
	v_lshlrev_b64 v[0:1], 11, v[0:1]
	v_lshlrev_b64 v[10:11], 11, v[10:11]
	v_lshl_add_u64 v[144:145], v[24:25], 0, v[190:191]
	v_lshlrev_b64 v[192:193], 11, v[16:17]
	v_lshl_add_u64 v[148:149], v[24:25], 0, v[194:195]
	v_lshlrev_b64 v[198:199], 11, v[26:27]
	v_lshl_add_u64 v[138:139], v[8:9], 0, v[0:1]
	v_lshl_add_u64 v[142:143], v[8:9], 0, v[10:11]
	v_lshl_add_u64 v[146:147], v[24:25], 0, v[192:193]
	v_lshl_add_u64 v[150:151], v[24:25], 0, v[198:199]
	v_mad_u64_u32 v[134:135], s[0:1], v33, s19, v[128:129]
	v_add_u32_e32 v157, 0x12000, v134
	v_bfe_u32 v135, v32, 6, 2
	v_add_u32_e32 v156, 0x1b000, v134
	v_and_b32_e32 v1, 31, v32
	v_ashrrev_i32_e32 v0, 1, v32
	v_and_or_b32 v153, v0, s20, v1
	v_lshrrev_b32_e32 v0, 2, v32
	v_and_b32_e32 v154, 8, v0
	v_lshlrev_b32_e32 v0, 1, v154
	v_mad_u64_u32 v[132:133], s[0:1], v153, s19, v[0:1]
	v_lshl_or_b32 v1, v135, 6, v1
	v_mul_u32_u24_e32 v1, 0x48, v1
	v_lshl_add_u32 v0, v1, 1, v0
	v_add_u32_e32 v155, 0x12000, v0
	v_add_u32_e32 v133, 0x1b000, v0
	v_lshl_add_u64 v[198:199], s[2:3], 0, v[198:199]
	v_or_b32_e32 v128, 0x100, v128
	v_lshl_add_u64 v[192:193], s[2:3], 0, v[192:193]
	v_lshl_add_u64 v[190:191], s[2:3], 0, v[190:191]
	v_lshl_add_u64 v[206:207], v[198:199], 0, v[128:129]
	v_lshl_add_u64 v[194:195], s[2:3], 0, v[194:195]
	v_lshl_add_u64 v[198:199], v[192:193], 0, v[128:129]
	v_lshl_add_u64 v[190:191], v[190:191], 0, v[128:129]
	v_lshl_add_u64 v[194:195], v[194:195], 0, v[128:129]
	s_nop 0
	s_nop 0
	s_nop 0
	s_nop 0
	s_nop 0
	s_nop 0
	s_nop 0
	s_nop 0
	s_nop 0
	v_lshrrev_b32_e32 v226, 6, v196
	s_mov_b32 s10, 64
	v_readfirstlane_b32 s29, v226
	s_mov_b32 s11, 0
	s_mov_b32 s14, 0x40000
	s_mov_b32 s15, 0
	v_bfe_u32 v224, v196, 2, 4
	s_lshl_b32 s30, s29, 3
	v_add_u32_e32 v224, s30, v224
	s_mov_b32 s30, 0x800
	v_mul_lo_u32 v224, v224, s30
	v_bfe_u32 v226, v196, 4, 2
	v_and_b32_e32 v225, 3, v196
	v_xor_b32_e32 v226, v225, v226
	v_lshl_add_u32 v224, v226, 4, v224
	v_mov_b32_e32 v225, 0
	v_readlane_b32 s16, v136, 0
	v_readlane_b32 s17, v137, 0
	s_nop 1
	v_lshl_add_u64 v[216:217], s[16:17], 0, v[224:225]
	v_lshl_add_u64 v[218:219], v[216:217], 0, s[14:15]
	v_readlane_b32 s16, v144, 0
	v_readlane_b32 s17, v145, 0
	s_nop 1
	v_lshl_add_u64 v[220:221], s[16:17], 0, v[224:225]
	v_lshl_add_u64 v[222:223], v[220:221], 0, s[14:15]
	v_and_b32_e32 v224, 31, v196
	v_bfe_u32 v226, v196, 2, 2
	v_bfe_u32 v225, v196, 5, 1
	v_xor_b32_e32 v226, v225, v226
	v_lshlrev_b32_e32 v226, 4, v226
	v_lshl_or_b32 v224, v224, 6, v226
	s_lshr_b32 s30, s29, 2
	s_lshl_b32 s30, s30, 13
	v_add_u32_e32 v134, s30, v224
	s_and_b32 s30, s29, 3
	s_lshl_b32 s30, s30, 12
	s_add_u32 s30, s30, 0x4000
	v_add_u32_e32 v198, s30, v224
	v_xor_b32_e32 v155, 0x20, v134
	v_xor_b32_e32 v199, 0x20, v198
	v_add_u32_e32 v208, 0x10000, v134
	v_add_u32_e32 v210, 0x10000, v198
	v_add_u32_e32 v212, 0x20000, v134
	v_add_u32_e32 v214, 0x20000, v198
	v_add_u32_e32 v209, 0x10000, v155
	v_add_u32_e32 v211, 0x10000, v199
	v_add_u32_e32 v213, 0x20000, v155
	v_add_u32_e32 v215, 0x20000, v199
	s_lshl_b32 s29, s29, 10
	s_waitcnt lgkmcnt(0)
	s_barrier
; #define G_LOADA(kt_) { _Pragma("unroll") for (int i = 0; i < 4; ++i) ra[i] = al(lrow + 64 * i, (kt_) * 64 + lck * 8); }
; #define G_LOADB(kt_) { _Pragma("unroll") for (int i = 0; i < 4; ++i) rb[i] = bl(lrow + 64 * i, (kt_) * 64 + lck * 8); }
; #define G_STOREA(buf_) { bf16_t* nA = sA + (buf_) * 256 * GLD; _Pragma("unroll") for (int i = 0; i < 4; ++i) *(u32x4*)(nA + (lrow + 64 * i) * GLD + lck * 8) = ra[i]; }
; #define G_STOREB(buf_) { bf16_t* nB = sB + (buf_) * 256 * GLD; _Pragma("unroll") for (int i = 0; i < 4; ++i) *(u32x4*)(nB + (lrow + 64 * i) * GLD + lck * 8) = rb[i]; }
; template <class AL, class BL, class EP>
; DI void gemm_tile256(AL al, BL bl, EP ep, int K, char* smem) {
;     ...
;   f32x16 acc[4][2];
; #pragma unroll
;   for (int i = 0; i < 4; ++i)
; #pragma unroll
;     for (int j = 0; j < 2; ++j)
; #pragma unroll
;       for (int q = 0; q < 16; ++q) acc[i][j][q] = 0.f;
;   u32x4 ra[4], rb[4];
;   const int KT = K >> 6;
;     ...
;   G_LOADA(0); G_LOADB(0);
;   __syncthreads();
;   G_STOREA(0); G_STOREB(0);
;   if (KT > 1) G_LOADB(1);
;   __syncthreads();
;   for (int kt = 0; kt < KT; kt += 2) {
;     G_STEP(0, kt);
;     if (kt + 1 >= KT) break;
;     G_STEP(1, kt + 1);
;   }
	s_add_u32 m0, s29, 0x0
	s_nop 0
	global_load_lds_dwordx4 v[216:217], off
	v_lshl_add_u64 v[216:217], v[216:217], 0, s[10:11]
	s_add_u32 m0, s29, 0x4000
	s_nop 0
	global_load_lds_dwordx4 v[220:221], off
	v_lshl_add_u64 v[220:221], v[220:221], 0, s[10:11]
	s_add_u32 m0, s29, 0x2000
	s_nop 0
	global_load_lds_dwordx4 v[218:219], off
	v_lshl_add_u64 v[218:219], v[218:219], 0, s[10:11]
	s_add_u32 m0, s29, 0x6000
	s_nop 0
	global_load_lds_dwordx4 v[222:223], off
	v_lshl_add_u64 v[222:223], v[222:223], 0, s[10:11]
	s_add_u32 m0, s29, 0x8000
	s_nop 0
	global_load_lds_dwordx4 v[216:217], off
	v_lshl_add_u64 v[216:217], v[216:217], 0, s[10:11]
	s_add_u32 m0, s29, 0xc000
	s_nop 0
	global_load_lds_dwordx4 v[220:221], off
	v_lshl_add_u64 v[220:221], v[220:221], 0, s[10:11]
	s_add_u32 m0, s29, 0xa000
	s_nop 0
	global_load_lds_dwordx4 v[218:219], off
	v_lshl_add_u64 v[218:219], v[218:219], 0, s[10:11]
	s_add_u32 m0, s29, 0xe000
	s_nop 0
	global_load_lds_dwordx4 v[222:223], off
	v_lshl_add_u64 v[222:223], v[222:223], 0, s[10:11]
	s_add_u32 m0, s29, 0x10000
	s_nop 0
	global_load_lds_dwordx4 v[216:217], off
	v_lshl_add_u64 v[216:217], v[216:217], 0, s[10:11]
	s_add_u32 m0, s29, 0x14000
	s_nop 0
	global_load_lds_dwordx4 v[220:221], off
	v_lshl_add_u64 v[220:221], v[220:221], 0, s[10:11]
	s_add_u32 m0, s29, 0x12000
	s_nop 0
	global_load_lds_dwordx4 v[218:219], off
	v_lshl_add_u64 v[218:219], v[218:219], 0, s[10:11]
	s_add_u32 m0, s29, 0x16000
	s_nop 0
	global_load_lds_dwordx4 v[222:223], off
	v_lshl_add_u64 v[222:223], v[222:223], 0, s[10:11]
	s_add_u32 m0, s29, 0x18000
	s_nop 0
	global_load_lds_dwordx4 v[216:217], off
	v_lshl_add_u64 v[216:217], v[216:217], 0, s[10:11]
	s_add_u32 m0, s29, 0x1c000
	s_nop 0
	global_load_lds_dwordx4 v[220:221], off
	v_lshl_add_u64 v[220:221], v[220:221], 0, s[10:11]
	s_add_u32 m0, s29, 0x1a000
	s_nop 0
	global_load_lds_dwordx4 v[218:219], off
	v_lshl_add_u64 v[218:219], v[218:219], 0, s[10:11]
	s_add_u32 m0, s29, 0x1e000
	s_nop 0
	global_load_lds_dwordx4 v[222:223], off
	v_lshl_add_u64 v[222:223], v[222:223], 0, s[10:11]
	s_add_u32 m0, s29, 0x20000
	s_nop 0
	global_load_lds_dwordx4 v[216:217], off
	v_lshl_add_u64 v[216:217], v[216:217], 0, s[10:11]
	s_add_u32 m0, s29, 0x24000
	s_nop 0
	global_load_lds_dwordx4 v[220:221], off
	v_lshl_add_u64 v[220:221], v[220:221], 0, s[10:11]
	v_mov_b64_e32 v[112:113], 0
	v_mov_b64_e32 v[114:115], 0
	v_mov_b64_e32 v[116:117], 0
	v_mov_b64_e32 v[118:119], 0
	v_mov_b64_e32 v[120:121], 0
	v_mov_b64_e32 v[122:123], 0
	v_mov_b64_e32 v[124:125], 0
	v_mov_b64_e32 v[126:127], 0
	v_mov_b64_e32 v[96:97], 0
	v_mov_b64_e32 v[98:99], 0
	v_mov_b64_e32 v[100:101], 0
	v_mov_b64_e32 v[102:103], 0
	v_mov_b64_e32 v[104:105], 0
	v_mov_b64_e32 v[106:107], 0
	v_mov_b64_e32 v[108:109], 0
	v_mov_b64_e32 v[110:111], 0
	v_mov_b64_e32 v[80:81], 0
	v_mov_b64_e32 v[82:83], 0
	v_mov_b64_e32 v[84:85], 0
	v_mov_b64_e32 v[86:87], 0
	v_mov_b64_e32 v[88:89], 0
	v_mov_b64_e32 v[90:91], 0
	v_mov_b64_e32 v[92:93], 0
	v_mov_b64_e32 v[94:95], 0
	v_mov_b64_e32 v[64:65], 0
	v_mov_b64_e32 v[66:67], 0
	v_mov_b64_e32 v[68:69], 0
	v_mov_b64_e32 v[70:71], 0
	v_mov_b64_e32 v[72:73], 0
	v_mov_b64_e32 v[74:75], 0
	v_mov_b64_e32 v[76:77], 0
	v_mov_b64_e32 v[78:79], 0
	v_mov_b64_e32 v[48:49], 0
	v_mov_b64_e32 v[50:51], 0
	v_mov_b64_e32 v[52:53], 0
	v_mov_b64_e32 v[54:55], 0
	v_mov_b64_e32 v[56:57], 0
	v_mov_b64_e32 v[58:59], 0
	v_mov_b64_e32 v[60:61], 0
	v_mov_b64_e32 v[62:63], 0
	v_mov_b64_e32 v[32:33], 0
	v_mov_b64_e32 v[34:35], 0
	v_mov_b64_e32 v[36:37], 0
	v_mov_b64_e32 v[38:39], 0
	v_mov_b64_e32 v[40:41], 0
	v_mov_b64_e32 v[42:43], 0
	v_mov_b64_e32 v[44:45], 0
	v_mov_b64_e32 v[46:47], 0
	v_mov_b64_e32 v[16:17], 0
	v_mov_b64_e32 v[18:19], 0
	v_mov_b64_e32 v[20:21], 0
	v_mov_b64_e32 v[22:23], 0
	v_mov_b64_e32 v[24:25], 0
	v_mov_b64_e32 v[26:27], 0
	v_mov_b64_e32 v[28:29], 0
	v_mov_b64_e32 v[30:31], 0
	v_mov_b64_e32 v[0:1], 0
	v_mov_b64_e32 v[2:3], 0
	v_mov_b64_e32 v[4:5], 0
	v_mov_b64_e32 v[6:7], 0
	v_mov_b64_e32 v[8:9], 0
	v_mov_b64_e32 v[10:11], 0
	v_mov_b64_e32 v[12:13], 0
	v_mov_b64_e32 v[14:15], 0
	s_mov_b32 s30, 5
	s_waitcnt vmcnt(14)
	s_barrier
	ds_read_b128 v[188:191], v198
	ds_read_b128 v[156:159], v134
	ds_read_b128 v[192:195], v198 offset:2048
	ds_read_b128 v[160:163], v134 offset:2048
	ds_read_b128 v[164:167], v134 offset:4096
	ds_read_b128 v[168:171], v134 offset:6144
; #define G_LOADA(kt_) { _Pragma("unroll") for (int i = 0; i < 4; ++i) ra[i] = al(lrow + 64 * i, (kt_) * 64 + lck * 8); }
; #define G_LOADB(kt_) { _Pragma("unroll") for (int i = 0; i < 4; ++i) rb[i] = bl(lrow + 64 * i, (kt_) * 64 + lck * 8); }
; #define G_STOREA(buf_) { bf16_t* nA = sA + (buf_) * 256 * GLD; _Pragma("unroll") for (int i = 0; i < 4; ++i) *(u32x4*)(nA + (lrow + 64 * i) * GLD + lck * 8) = ra[i]; }
; #define G_STOREB(buf_) { bf16_t* nB = sB + (buf_) * 256 * GLD; _Pragma("unroll") for (int i = 0; i < 4; ++i) *(u32x4*)(nB + (lrow + 64 * i) * GLD + lck * 8) = rb[i]; }
; template <class AL, class BL, class EP>
; DI void gemm_tile256(AL al, BL bl, EP ep, int K, char* smem) {
;     ...
;   G_LOADA(0); G_LOADB(0);
;   __syncthreads();
;   G_STOREA(0); G_STOREB(0);
;   if (KT > 1) G_LOADB(1);
;   __syncthreads();
;   for (int kt = 0; kt < KT; kt += 2) {
;     G_STEP(0, kt);
;     if (kt + 1 >= KT) break;
;     G_STEP(1, kt + 1);
;   }
.Lgk_ph6_loop:
	s_waitcnt lgkmcnt(0)
	v_mfma_f32_32x32x16_bf16 v[112:127], v[188:191], v[156:159], v[112:127]
	ds_read_b128 v[200:203], v199
	ds_read_b128 v[172:175], v155
	v_mfma_f32_32x32x16_bf16 v[96:111], v[192:195], v[156:159], v[96:111]
	ds_read_b128 v[204:207], v199 offset:2048
	ds_read_b128 v[176:179], v155 offset:2048
	v_mfma_f32_32x32x16_bf16 v[80:95], v[188:191], v[160:163], v[80:95]
	ds_read_b128 v[180:183], v155 offset:4096
	ds_read_b128 v[184:187], v155 offset:6144
	v_mfma_f32_32x32x16_bf16 v[64:79], v[192:195], v[160:163], v[64:79]
	s_add_u32 m0, s29, 0x22000
	s_nop 0
	global_load_lds_dwordx4 v[218:219], off
	v_lshl_add_u64 v[218:219], v[218:219], 0, s[10:11]
	v_mfma_f32_32x32x16_bf16 v[48:63], v[188:191], v[164:167], v[48:63]
	v_mfma_f32_32x32x16_bf16 v[32:47], v[192:195], v[164:167], v[32:47]
	v_mfma_f32_32x32x16_bf16 v[16:31], v[188:191], v[168:171], v[16:31]
	v_mfma_f32_32x32x16_bf16 v[0:15], v[192:195], v[168:171], v[0:15]
	s_add_u32 m0, s29, 0x26000
	s_nop 0
	global_load_lds_dwordx4 v[222:223], off
	v_lshl_add_u64 v[222:223], v[222:223], 0, s[10:11]
	s_waitcnt lgkmcnt(0)
	s_waitcnt vmcnt(12)
	s_barrier
	s_waitcnt lgkmcnt(0)
	v_mfma_f32_32x32x16_bf16 v[112:127], v[200:203], v[172:175], v[112:127]
	ds_read_b128 v[188:191], v198 offset:32768
	ds_read_b128 v[156:159], v134 offset:32768
	v_mfma_f32_32x32x16_bf16 v[96:111], v[204:207], v[172:175], v[96:111]
	ds_read_b128 v[192:195], v198 offset:34816
	ds_read_b128 v[160:163], v134 offset:34816
	v_mfma_f32_32x32x16_bf16 v[80:95], v[200:203], v[176:179], v[80:95]
	ds_read_b128 v[164:167], v134 offset:36864
	ds_read_b128 v[168:171], v134 offset:38912
	v_mfma_f32_32x32x16_bf16 v[64:79], v[204:207], v[176:179], v[64:79]
	s_add_u32 m0, s29, 0x0
	s_nop 0
	global_load_lds_dwordx4 v[216:217], off
	v_lshl_add_u64 v[216:217], v[216:217], 0, s[10:11]
	v_mfma_f32_32x32x16_bf16 v[48:63], v[200:203], v[180:183], v[48:63]
	v_mfma_f32_32x32x16_bf16 v[32:47], v[204:207], v[180:183], v[32:47]
	v_mfma_f32_32x32x16_bf16 v[16:31], v[200:203], v[184:187], v[16:31]
	v_mfma_f32_32x32x16_bf16 v[0:15], v[204:207], v[184:187], v[0:15]
	s_add_u32 m0, s29, 0x4000
	s_nop 0
	global_load_lds_dwordx4 v[220:221], off
	v_lshl_add_u64 v[220:221], v[220:221], 0, s[10:11]
	s_waitcnt lgkmcnt(0)
	v_mfma_f32_32x32x16_bf16 v[112:127], v[188:191], v[156:159], v[112:127]
	ds_read_b128 v[200:203], v199 offset:32768
	ds_read_b128 v[172:175], v155 offset:32768
	v_mfma_f32_32x32x16_bf16 v[96:111], v[192:195], v[156:159], v[96:111]
	ds_read_b128 v[204:207], v199 offset:34816
	ds_read_b128 v[176:179], v155 offset:34816
	v_mfma_f32_32x32x16_bf16 v[80:95], v[188:191], v[160:163], v[80:95]
	ds_read_b128 v[180:183], v155 offset:36864
	ds_read_b128 v[184:187], v155 offset:38912
	v_mfma_f32_32x32x16_bf16 v[64:79], v[192:195], v[160:163], v[64:79]
	s_add_u32 m0, s29, 0x2000
	s_nop 0
	global_load_lds_dwordx4 v[218:219], off
	v_lshl_add_u64 v[218:219], v[218:219], 0, s[10:11]
	v_mfma_f32_32x32x16_bf16 v[48:63], v[188:191], v[164:167], v[48:63]
	v_mfma_f32_32x32x16_bf16 v[32:47], v[192:195], v[164:167], v[32:47]
	v_mfma_f32_32x32x16_bf16 v[16:31], v[188:191], v[168:171], v[16:31]
	v_mfma_f32_32x32x16_bf16 v[0:15], v[192:195], v[168:171], v[0:15]
	s_add_u32 m0, s29, 0x6000
	s_nop 0
	global_load_lds_dwordx4 v[222:223], off
	v_lshl_add_u64 v[222:223], v[222:223], 0, s[10:11]
	s_waitcnt lgkmcnt(0)
	s_waitcnt vmcnt(12)
	s_barrier
	s_waitcnt lgkmcnt(0)
	v_mfma_f32_32x32x16_bf16 v[112:127], v[200:203], v[172:175], v[112:127]
	ds_read_b128 v[188:191], v210
	ds_read_b128 v[156:159], v208
	v_mfma_f32_32x32x16_bf16 v[96:111], v[204:207], v[172:175], v[96:111]
	ds_read_b128 v[192:195], v210 offset:2048
	ds_read_b128 v[160:163], v208 offset:2048
	v_mfma_f32_32x32x16_bf16 v[80:95], v[200:203], v[176:179], v[80:95]
	ds_read_b128 v[164:167], v208 offset:4096
	ds_read_b128 v[168:171], v208 offset:6144
	v_mfma_f32_32x32x16_bf16 v[64:79], v[204:207], v[176:179], v[64:79]
	s_add_u32 m0, s29, 0x8000
	s_nop 0
	global_load_lds_dwordx4 v[216:217], off
	v_lshl_add_u64 v[216:217], v[216:217], 0, s[10:11]
	v_mfma_f32_32x32x16_bf16 v[48:63], v[200:203], v[180:183], v[48:63]
	v_mfma_f32_32x32x16_bf16 v[32:47], v[204:207], v[180:183], v[32:47]
	v_mfma_f32_32x32x16_bf16 v[16:31], v[200:203], v[184:187], v[16:31]
	v_mfma_f32_32x32x16_bf16 v[0:15], v[204:207], v[184:187], v[0:15]
	s_add_u32 m0, s29, 0xc000
	s_nop 0
	global_load_lds_dwordx4 v[220:221], off
	v_lshl_add_u64 v[220:221], v[220:221], 0, s[10:11]
	s_waitcnt lgkmcnt(0)
	v_mfma_f32_32x32x16_bf16 v[112:127], v[188:191], v[156:159], v[112:127]
	ds_read_b128 v[200:203], v211
	ds_read_b128 v[172:175], v209
	v_mfma_f32_32x32x16_bf16 v[96:111], v[192:195], v[156:159], v[96:111]
	ds_read_b128 v[204:207], v211 offset:2048
	ds_read_b128 v[176:179], v209 offset:2048
	v_mfma_f32_32x32x16_bf16 v[80:95], v[188:191], v[160:163], v[80:95]
	ds_read_b128 v[180:183], v209 offset:4096
	ds_read_b128 v[184:187], v209 offset:6144
	v_mfma_f32_32x32x16_bf16 v[64:79], v[192:195], v[160:163], v[64:79]
	s_add_u32 m0, s29, 0xa000
	s_nop 0
	global_load_lds_dwordx4 v[218:219], off
	v_lshl_add_u64 v[218:219], v[218:219], 0, s[10:11]
	v_mfma_f32_32x32x16_bf16 v[48:63], v[188:191], v[164:167], v[48:63]
	v_mfma_f32_32x32x16_bf16 v[32:47], v[192:195], v[164:167], v[32:47]
	v_mfma_f32_32x32x16_bf16 v[16:31], v[188:191], v[168:171], v[16:31]
	v_mfma_f32_32x32x16_bf16 v[0:15], v[192:195], v[168:171], v[0:15]
	s_add_u32 m0, s29, 0xe000
	s_nop 0
	global_load_lds_dwordx4 v[222:223], off
	v_lshl_add_u64 v[222:223], v[222:223], 0, s[10:11]
	s_waitcnt lgkmcnt(0)
	s_waitcnt vmcnt(12)
	s_barrier
; #define G_LOADA(kt_) { _Pragma("unroll") for (int i = 0; i < 4; ++i) ra[i] = al(lrow + 64 * i, (kt_) * 64 + lck * 8); }
; #define G_LOADB(kt_) { _Pragma("unroll") for (int i = 0; i < 4; ++i) rb[i] = bl(lrow + 64 * i, (kt_) * 64 + lck * 8); }
; #define G_STOREA(buf_) { bf16_t* nA = sA + (buf_) * 256 * GLD; _Pragma("unroll") for (int i = 0; i < 4; ++i) *(u32x4*)(nA + (lrow + 64 * i) * GLD + lck * 8) = ra[i]; }
; #define G_STOREB(buf_) { bf16_t* nB = sB + (buf_) * 256 * GLD; _Pragma("unroll") for (int i = 0; i < 4; ++i) *(u32x4*)(nB + (lrow + 64 * i) * GLD + lck * 8) = rb[i]; }
; template <class AL, class BL, class EP>
; DI void gemm_tile256(AL al, BL bl, EP ep, int K, char* smem) {
;     ...
;   G_LOADA(0); G_LOADB(0);
;   __syncthreads();
;   G_STOREA(0); G_STOREB(0);
;   if (KT > 1) G_LOADB(1);
;   __syncthreads();
;   for (int kt = 0; kt < KT; kt += 2) {
;     G_STEP(0, kt);
;     if (kt + 1 >= KT) break;
;     G_STEP(1, kt + 1);
;   }
	s_waitcnt lgkmcnt(0)
	v_mfma_f32_32x32x16_bf16 v[112:127], v[200:203], v[172:175], v[112:127]
	ds_read_b128 v[188:191], v210 offset:32768
	ds_read_b128 v[156:159], v208 offset:32768
	v_mfma_f32_32x32x16_bf16 v[96:111], v[204:207], v[172:175], v[96:111]
	ds_read_b128 v[192:195], v210 offset:34816
	ds_read_b128 v[160:163], v208 offset:34816
	v_mfma_f32_32x32x16_bf16 v[80:95], v[200:203], v[176:179], v[80:95]
	ds_read_b128 v[164:167], v208 offset:36864
	ds_read_b128 v[168:171], v208 offset:38912
	v_mfma_f32_32x32x16_bf16 v[64:79], v[204:207], v[176:179], v[64:79]
	s_add_u32 m0, s29, 0x10000
	s_nop 0
	global_load_lds_dwordx4 v[216:217], off
	v_lshl_add_u64 v[216:217], v[216:217], 0, s[10:11]
	v_mfma_f32_32x32x16_bf16 v[48:63], v[200:203], v[180:183], v[48:63]
	v_mfma_f32_32x32x16_bf16 v[32:47], v[204:207], v[180:183], v[32:47]
	v_mfma_f32_32x32x16_bf16 v[16:31], v[200:203], v[184:187], v[16:31]
	v_mfma_f32_32x32x16_bf16 v[0:15], v[204:207], v[184:187], v[0:15]
	s_add_u32 m0, s29, 0x14000
	s_nop 0
	global_load_lds_dwordx4 v[220:221], off
	v_lshl_add_u64 v[220:221], v[220:221], 0, s[10:11]
	s_waitcnt lgkmcnt(0)
	v_mfma_f32_32x32x16_bf16 v[112:127], v[188:191], v[156:159], v[112:127]
	ds_read_b128 v[200:203], v211 offset:32768
	ds_read_b128 v[172:175], v209 offset:32768
	v_mfma_f32_32x32x16_bf16 v[96:111], v[192:195], v[156:159], v[96:111]
	ds_read_b128 v[204:207], v211 offset:34816
	ds_read_b128 v[176:179], v209 offset:34816
	v_mfma_f32_32x32x16_bf16 v[80:95], v[188:191], v[160:163], v[80:95]
	ds_read_b128 v[180:183], v209 offset:36864
	ds_read_b128 v[184:187], v209 offset:38912
	v_mfma_f32_32x32x16_bf16 v[64:79], v[192:195], v[160:163], v[64:79]
	s_add_u32 m0, s29, 0x12000
	s_nop 0
	global_load_lds_dwordx4 v[218:219], off
	v_lshl_add_u64 v[218:219], v[218:219], 0, s[10:11]
	v_mfma_f32_32x32x16_bf16 v[48:63], v[188:191], v[164:167], v[48:63]
	v_mfma_f32_32x32x16_bf16 v[32:47], v[192:195], v[164:167], v[32:47]
	v_mfma_f32_32x32x16_bf16 v[16:31], v[188:191], v[168:171], v[16:31]
	v_mfma_f32_32x32x16_bf16 v[0:15], v[192:195], v[168:171], v[0:15]
	s_add_u32 m0, s29, 0x16000
	s_nop 0
	global_load_lds_dwordx4 v[222:223], off
	v_lshl_add_u64 v[222:223], v[222:223], 0, s[10:11]
	s_waitcnt lgkmcnt(0)
	s_waitcnt vmcnt(12)
	s_barrier
	s_waitcnt lgkmcnt(0)
	v_mfma_f32_32x32x16_bf16 v[112:127], v[200:203], v[172:175], v[112:127]
	ds_read_b128 v[188:191], v214
	ds_read_b128 v[156:159], v212
	v_mfma_f32_32x32x16_bf16 v[96:111], v[204:207], v[172:175], v[96:111]
	ds_read_b128 v[192:195], v214 offset:2048
	ds_read_b128 v[160:163], v212 offset:2048
	v_mfma_f32_32x32x16_bf16 v[80:95], v[200:203], v[176:179], v[80:95]
	ds_read_b128 v[164:167], v212 offset:4096
	ds_read_b128 v[168:171], v212 offset:6144
	v_mfma_f32_32x32x16_bf16 v[64:79], v[204:207], v[176:179], v[64:79]
	s_add_u32 m0, s29, 0x18000
	s_nop 0
	global_load_lds_dwordx4 v[216:217], off
	v_lshl_add_u64 v[216:217], v[216:217], 0, s[10:11]
	v_mfma_f32_32x32x16_bf16 v[48:63], v[200:203], v[180:183], v[48:63]
	v_mfma_f32_32x32x16_bf16 v[32:47], v[204:207], v[180:183], v[32:47]
	v_mfma_f32_32x32x16_bf16 v[16:31], v[200:203], v[184:187], v[16:31]
	v_mfma_f32_32x32x16_bf16 v[0:15], v[204:207], v[184:187], v[0:15]
	s_add_u32 m0, s29, 0x1c000
	s_nop 0
	global_load_lds_dwordx4 v[220:221], off
	v_lshl_add_u64 v[220:221], v[220:221], 0, s[10:11]
	s_waitcnt lgkmcnt(0)
	v_mfma_f32_32x32x16_bf16 v[112:127], v[188:191], v[156:159], v[112:127]
	ds_read_b128 v[200:203], v215
	ds_read_b128 v[172:175], v213
	v_mfma_f32_32x32x16_bf16 v[96:111], v[192:195], v[156:159], v[96:111]
	ds_read_b128 v[204:207], v215 offset:2048
	ds_read_b128 v[176:179], v213 offset:2048
	v_mfma_f32_32x32x16_bf16 v[80:95], v[188:191], v[160:163], v[80:95]
	ds_read_b128 v[180:183], v213 offset:4096
	ds_read_b128 v[184:187], v213 offset:6144
	v_mfma_f32_32x32x16_bf16 v[64:79], v[192:195], v[160:163], v[64:79]
	s_add_u32 m0, s29, 0x1a000
	s_nop 0
	global_load_lds_dwordx4 v[218:219], off
	v_lshl_add_u64 v[218:219], v[218:219], 0, s[10:11]
	v_mfma_f32_32x32x16_bf16 v[48:63], v[188:191], v[164:167], v[48:63]
	v_mfma_f32_32x32x16_bf16 v[32:47], v[192:195], v[164:167], v[32:47]
	v_mfma_f32_32x32x16_bf16 v[16:31], v[188:191], v[168:171], v[16:31]
	v_mfma_f32_32x32x16_bf16 v[0:15], v[192:195], v[168:171], v[0:15]
	s_add_u32 m0, s29, 0x1e000
	s_nop 0
	global_load_lds_dwordx4 v[222:223], off
	v_lshl_add_u64 v[222:223], v[222:223], 0, s[10:11]
	s_waitcnt lgkmcnt(0)
	s_waitcnt vmcnt(12)
	s_barrier
	s_waitcnt lgkmcnt(0)
	v_mfma_f32_32x32x16_bf16 v[112:127], v[200:203], v[172:175], v[112:127]
	ds_read_b128 v[188:191], v198
	ds_read_b128 v[156:159], v134
	v_mfma_f32_32x32x16_bf16 v[96:111], v[204:207], v[172:175], v[96:111]
	ds_read_b128 v[192:195], v198 offset:2048
	ds_read_b128 v[160:163], v134 offset:2048
	v_mfma_f32_32x32x16_bf16 v[80:95], v[200:203], v[176:179], v[80:95]
	ds_read_b128 v[164:167], v134 offset:4096
	ds_read_b128 v[168:171], v134 offset:6144
	v_mfma_f32_32x32x16_bf16 v[64:79], v[204:207], v[176:179], v[64:79]
	s_add_u32 m0, s29, 0x20000
	s_nop 0
	global_load_lds_dwordx4 v[216:217], off
	v_lshl_add_u64 v[216:217], v[216:217], 0, s[10:11]
	v_mfma_f32_32x32x16_bf16 v[48:63], v[200:203], v[180:183], v[48:63]
	v_mfma_f32_32x32x16_bf16 v[32:47], v[204:207], v[180:183], v[32:47]
	v_mfma_f32_32x32x16_bf16 v[16:31], v[200:203], v[184:187], v[16:31]
	v_mfma_f32_32x32x16_bf16 v[0:15], v[204:207], v[184:187], v[0:15]
	s_add_u32 m0, s29, 0x24000
	s_nop 0
	global_load_lds_dwordx4 v[220:221], off
	v_lshl_add_u64 v[220:221], v[220:221], 0, s[10:11]
	s_sub_u32 s30, s30, 1
	s_cmp_lg_u32 s30, 0
	s_cbranch_scc1 .Lgk_ph6_loop
; #define G_LOADA(kt_) { _Pragma("unroll") for (int i = 0; i < 4; ++i) ra[i] = al(lrow + 64 * i, (kt_) * 64 + lck * 8); }
; #define G_LOADB(kt_) { _Pragma("unroll") for (int i = 0; i < 4; ++i) rb[i] = bl(lrow + 64 * i, (kt_) * 64 + lck * 8); }
; #define G_STOREA(buf_) { bf16_t* nA = sA + (buf_) * 256 * GLD; _Pragma("unroll") for (int i = 0; i < 4; ++i) *(u32x4*)(nA + (lrow + 64 * i) * GLD + lck * 8) = ra[i]; }
; #define G_STOREB(buf_) { bf16_t* nB = sB + (buf_) * 256 * GLD; _Pragma("unroll") for (int i = 0; i < 4; ++i) *(u32x4*)(nB + (lrow + 64 * i) * GLD + lck * 8) = rb[i]; }
; template <class AL, class BL, class EP>
; DI void gemm_tile256(AL al, BL bl, EP ep, int K, char* smem) {
;     ...
;   G_LOADA(0); G_LOADB(0);
;   __syncthreads();
;   G_STOREA(0); G_STOREB(0);
;   if (KT > 1) G_LOADB(1);
;   __syncthreads();
;   for (int kt = 0; kt < KT; kt += 2) {
;     G_STEP(0, kt);
;     if (kt + 1 >= KT) break;
;     G_STEP(1, kt + 1);
;   }
	s_waitcnt lgkmcnt(0)
	v_mfma_f32_32x32x16_bf16 v[112:127], v[188:191], v[156:159], v[112:127]
	ds_read_b128 v[200:203], v199
	ds_read_b128 v[172:175], v155
	v_mfma_f32_32x32x16_bf16 v[96:111], v[192:195], v[156:159], v[96:111]
	ds_read_b128 v[204:207], v199 offset:2048
	ds_read_b128 v[176:179], v155 offset:2048
	v_mfma_f32_32x32x16_bf16 v[80:95], v[188:191], v[160:163], v[80:95]
	ds_read_b128 v[180:183], v155 offset:4096
	ds_read_b128 v[184:187], v155 offset:6144
	v_mfma_f32_32x32x16_bf16 v[64:79], v[192:195], v[160:163], v[64:79]
	s_add_u32 m0, s29, 0x22000
	s_nop 0
	global_load_lds_dwordx4 v[218:219], off
	v_lshl_add_u64 v[218:219], v[218:219], 0, s[10:11]
	v_mfma_f32_32x32x16_bf16 v[48:63], v[188:191], v[164:167], v[48:63]
	v_mfma_f32_32x32x16_bf16 v[32:47], v[192:195], v[164:167], v[32:47]
	v_mfma_f32_32x32x16_bf16 v[16:31], v[188:191], v[168:171], v[16:31]
	v_mfma_f32_32x32x16_bf16 v[0:15], v[192:195], v[168:171], v[0:15]
	s_add_u32 m0, s29, 0x26000
	s_nop 0
	global_load_lds_dwordx4 v[222:223], off
	v_lshl_add_u64 v[222:223], v[222:223], 0, s[10:11]
	s_waitcnt lgkmcnt(0)
	s_waitcnt vmcnt(12)
	s_barrier
	s_waitcnt lgkmcnt(0)
	v_mfma_f32_32x32x16_bf16 v[112:127], v[200:203], v[172:175], v[112:127]
	ds_read_b128 v[188:191], v198 offset:32768
	ds_read_b128 v[156:159], v134 offset:32768
	v_mfma_f32_32x32x16_bf16 v[96:111], v[204:207], v[172:175], v[96:111]
	ds_read_b128 v[192:195], v198 offset:34816
	ds_read_b128 v[160:163], v134 offset:34816
	v_mfma_f32_32x32x16_bf16 v[80:95], v[200:203], v[176:179], v[80:95]
	ds_read_b128 v[164:167], v134 offset:36864
	ds_read_b128 v[168:171], v134 offset:38912
	v_mfma_f32_32x32x16_bf16 v[64:79], v[204:207], v[176:179], v[64:79]
	s_add_u32 m0, s29, 0x0
	s_nop 0
	global_load_lds_dwordx4 v[216:217], off
	v_lshl_add_u64 v[216:217], v[216:217], 0, s[10:11]
	v_mfma_f32_32x32x16_bf16 v[48:63], v[200:203], v[180:183], v[48:63]
	v_mfma_f32_32x32x16_bf16 v[32:47], v[204:207], v[180:183], v[32:47]
	v_mfma_f32_32x32x16_bf16 v[16:31], v[200:203], v[184:187], v[16:31]
	v_mfma_f32_32x32x16_bf16 v[0:15], v[204:207], v[184:187], v[0:15]
	s_add_u32 m0, s29, 0x4000
	s_nop 0
	global_load_lds_dwordx4 v[220:221], off
	v_lshl_add_u64 v[220:221], v[220:221], 0, s[10:11]
	s_waitcnt lgkmcnt(0)
	v_mfma_f32_32x32x16_bf16 v[112:127], v[188:191], v[156:159], v[112:127]
	ds_read_b128 v[200:203], v199 offset:32768
	ds_read_b128 v[172:175], v155 offset:32768
	v_mfma_f32_32x32x16_bf16 v[96:111], v[192:195], v[156:159], v[96:111]
	ds_read_b128 v[204:207], v199 offset:34816
	ds_read_b128 v[176:179], v155 offset:34816
	v_mfma_f32_32x32x16_bf16 v[80:95], v[188:191], v[160:163], v[80:95]
	ds_read_b128 v[180:183], v155 offset:36864
	ds_read_b128 v[184:187], v155 offset:38912
	v_mfma_f32_32x32x16_bf16 v[64:79], v[192:195], v[160:163], v[64:79]
	s_add_u32 m0, s29, 0x2000
	s_nop 0
	global_load_lds_dwordx4 v[218:219], off
	v_lshl_add_u64 v[218:219], v[218:219], 0, s[10:11]
	v_mfma_f32_32x32x16_bf16 v[48:63], v[188:191], v[164:167], v[48:63]
	v_mfma_f32_32x32x16_bf16 v[32:47], v[192:195], v[164:167], v[32:47]
	v_mfma_f32_32x32x16_bf16 v[16:31], v[188:191], v[168:171], v[16:31]
	v_mfma_f32_32x32x16_bf16 v[0:15], v[192:195], v[168:171], v[0:15]
	s_add_u32 m0, s29, 0x6000
	s_nop 0
	global_load_lds_dwordx4 v[222:223], off
	v_lshl_add_u64 v[222:223], v[222:223], 0, s[10:11]
	s_waitcnt lgkmcnt(0)
	s_waitcnt vmcnt(12)
	s_barrier
	s_waitcnt lgkmcnt(0)
	v_mfma_f32_32x32x16_bf16 v[112:127], v[200:203], v[172:175], v[112:127]
	ds_read_b128 v[188:191], v210
	ds_read_b128 v[156:159], v208
	v_mfma_f32_32x32x16_bf16 v[96:111], v[204:207], v[172:175], v[96:111]
	ds_read_b128 v[192:195], v210 offset:2048
	ds_read_b128 v[160:163], v208 offset:2048
	v_mfma_f32_32x32x16_bf16 v[80:95], v[200:203], v[176:179], v[80:95]
	ds_read_b128 v[164:167], v208 offset:4096
	ds_read_b128 v[168:171], v208 offset:6144
	v_mfma_f32_32x32x16_bf16 v[64:79], v[204:207], v[176:179], v[64:79]
	s_add_u32 m0, s29, 0x8000
	s_nop 0
	global_load_lds_dwordx4 v[216:217], off
	v_lshl_add_u64 v[216:217], v[216:217], 0, s[10:11]
	v_mfma_f32_32x32x16_bf16 v[48:63], v[200:203], v[180:183], v[48:63]
	v_mfma_f32_32x32x16_bf16 v[32:47], v[204:207], v[180:183], v[32:47]
	v_mfma_f32_32x32x16_bf16 v[16:31], v[200:203], v[184:187], v[16:31]
	v_mfma_f32_32x32x16_bf16 v[0:15], v[204:207], v[184:187], v[0:15]
	s_add_u32 m0, s29, 0xc000
	s_nop 0
	global_load_lds_dwordx4 v[220:221], off
	v_lshl_add_u64 v[220:221], v[220:221], 0, s[10:11]
	s_waitcnt lgkmcnt(0)
	v_mfma_f32_32x32x16_bf16 v[112:127], v[188:191], v[156:159], v[112:127]
	ds_read_b128 v[200:203], v211
	ds_read_b128 v[172:175], v209
	v_mfma_f32_32x32x16_bf16 v[96:111], v[192:195], v[156:159], v[96:111]
	ds_read_b128 v[204:207], v211 offset:2048
	ds_read_b128 v[176:179], v209 offset:2048
	v_mfma_f32_32x32x16_bf16 v[80:95], v[188:191], v[160:163], v[80:95]
	ds_read_b128 v[180:183], v209 offset:4096
	ds_read_b128 v[184:187], v209 offset:6144
	v_mfma_f32_32x32x16_bf16 v[64:79], v[192:195], v[160:163], v[64:79]
	s_add_u32 m0, s29, 0xa000
	s_nop 0
	global_load_lds_dwordx4 v[218:219], off
	v_lshl_add_u64 v[218:219], v[218:219], 0, s[10:11]
	v_mfma_f32_32x32x16_bf16 v[48:63], v[188:191], v[164:167], v[48:63]
	v_mfma_f32_32x32x16_bf16 v[32:47], v[192:195], v[164:167], v[32:47]
	v_mfma_f32_32x32x16_bf16 v[16:31], v[188:191], v[168:171], v[16:31]
	v_mfma_f32_32x32x16_bf16 v[0:15], v[192:195], v[168:171], v[0:15]
	s_add_u32 m0, s29, 0xe000
	s_nop 0
	global_load_lds_dwordx4 v[222:223], off
	v_lshl_add_u64 v[222:223], v[222:223], 0, s[10:11]
	s_waitcnt lgkmcnt(0)
	s_waitcnt vmcnt(12)
	s_barrier
; #define G_LOADA(kt_) { _Pragma("unroll") for (int i = 0; i < 4; ++i) ra[i] = al(lrow + 64 * i, (kt_) * 64 + lck * 8); }
; #define G_LOADB(kt_) { _Pragma("unroll") for (int i = 0; i < 4; ++i) rb[i] = bl(lrow + 64 * i, (kt_) * 64 + lck * 8); }
; #define G_STOREA(buf_) { bf16_t* nA = sA + (buf_) * 256 * GLD; _Pragma("unroll") for (int i = 0; i < 4; ++i) *(u32x4*)(nA + (lrow + 64 * i) * GLD + lck * 8) = ra[i]; }
; #define G_STOREB(buf_) { bf16_t* nB = sB + (buf_) * 256 * GLD; _Pragma("unroll") for (int i = 0; i < 4; ++i) *(u32x4*)(nB + (lrow + 64 * i) * GLD + lck * 8) = rb[i]; }
; template <class AL, class BL, class EP>
; DI void gemm_tile256(AL al, BL bl, EP ep, int K, char* smem) {
;     ...
;   G_LOADA(0); G_LOADB(0);
;   __syncthreads();
;   G_STOREA(0); G_STOREB(0);
;   if (KT > 1) G_LOADB(1);
;   __syncthreads();
;   for (int kt = 0; kt < KT; kt += 2) {
;     G_STEP(0, kt);
;     if (kt + 1 >= KT) break;
;     G_STEP(1, kt + 1);
;   }
	s_waitcnt lgkmcnt(0)
	v_mfma_f32_32x32x16_bf16 v[112:127], v[200:203], v[172:175], v[112:127]
	ds_read_b128 v[188:191], v210 offset:32768
	ds_read_b128 v[156:159], v208 offset:32768
	v_mfma_f32_32x32x16_bf16 v[96:111], v[204:207], v[172:175], v[96:111]
	ds_read_b128 v[192:195], v210 offset:34816
	ds_read_b128 v[160:163], v208 offset:34816
	v_mfma_f32_32x32x16_bf16 v[80:95], v[200:203], v[176:179], v[80:95]
	ds_read_b128 v[164:167], v208 offset:36864
	ds_read_b128 v[168:171], v208 offset:38912
	v_mfma_f32_32x32x16_bf16 v[64:79], v[204:207], v[176:179], v[64:79]
	v_mfma_f32_32x32x16_bf16 v[48:63], v[200:203], v[180:183], v[48:63]
	v_mfma_f32_32x32x16_bf16 v[32:47], v[204:207], v[180:183], v[32:47]
	v_mfma_f32_32x32x16_bf16 v[16:31], v[200:203], v[184:187], v[16:31]
	v_mfma_f32_32x32x16_bf16 v[0:15], v[204:207], v[184:187], v[0:15]
	s_waitcnt lgkmcnt(0)
	v_mfma_f32_32x32x16_bf16 v[112:127], v[188:191], v[156:159], v[112:127]
	ds_read_b128 v[200:203], v211 offset:32768
	ds_read_b128 v[172:175], v209 offset:32768
	v_mfma_f32_32x32x16_bf16 v[96:111], v[192:195], v[156:159], v[96:111]
	ds_read_b128 v[204:207], v211 offset:34816
	ds_read_b128 v[176:179], v209 offset:34816
	v_mfma_f32_32x32x16_bf16 v[80:95], v[188:191], v[160:163], v[80:95]
	ds_read_b128 v[180:183], v209 offset:36864
	ds_read_b128 v[184:187], v209 offset:38912
	v_mfma_f32_32x32x16_bf16 v[64:79], v[192:195], v[160:163], v[64:79]
	v_mfma_f32_32x32x16_bf16 v[48:63], v[188:191], v[164:167], v[48:63]
	v_mfma_f32_32x32x16_bf16 v[32:47], v[192:195], v[164:167], v[32:47]
	v_mfma_f32_32x32x16_bf16 v[16:31], v[188:191], v[168:171], v[16:31]
	v_mfma_f32_32x32x16_bf16 v[0:15], v[192:195], v[168:171], v[0:15]
	s_waitcnt lgkmcnt(0)
	s_waitcnt vmcnt(8)
	s_barrier
	s_waitcnt lgkmcnt(0)
	v_mfma_f32_32x32x16_bf16 v[112:127], v[200:203], v[172:175], v[112:127]
	ds_read_b128 v[188:191], v214
	ds_read_b128 v[156:159], v212
	v_mfma_f32_32x32x16_bf16 v[96:111], v[204:207], v[172:175], v[96:111]
	ds_read_b128 v[192:195], v214 offset:2048
	ds_read_b128 v[160:163], v212 offset:2048
	v_mfma_f32_32x32x16_bf16 v[80:95], v[200:203], v[176:179], v[80:95]
	ds_read_b128 v[164:167], v212 offset:4096
	ds_read_b128 v[168:171], v212 offset:6144
	v_mfma_f32_32x32x16_bf16 v[64:79], v[204:207], v[176:179], v[64:79]
	v_mfma_f32_32x32x16_bf16 v[48:63], v[200:203], v[180:183], v[48:63]
	v_mfma_f32_32x32x16_bf16 v[32:47], v[204:207], v[180:183], v[32:47]
	v_mfma_f32_32x32x16_bf16 v[16:31], v[200:203], v[184:187], v[16:31]
	v_mfma_f32_32x32x16_bf16 v[0:15], v[204:207], v[184:187], v[0:15]
	s_waitcnt lgkmcnt(0)
	v_mfma_f32_32x32x16_bf16 v[112:127], v[188:191], v[156:159], v[112:127]
	ds_read_b128 v[200:203], v215
	ds_read_b128 v[172:175], v213
	v_mfma_f32_32x32x16_bf16 v[96:111], v[192:195], v[156:159], v[96:111]
	ds_read_b128 v[204:207], v215 offset:2048
	ds_read_b128 v[176:179], v213 offset:2048
	v_mfma_f32_32x32x16_bf16 v[80:95], v[188:191], v[160:163], v[80:95]
	ds_read_b128 v[180:183], v213 offset:4096
	ds_read_b128 v[184:187], v213 offset:6144
	v_mfma_f32_32x32x16_bf16 v[64:79], v[192:195], v[160:163], v[64:79]
	v_mfma_f32_32x32x16_bf16 v[48:63], v[188:191], v[164:167], v[48:63]
	v_mfma_f32_32x32x16_bf16 v[32:47], v[192:195], v[164:167], v[32:47]
	v_mfma_f32_32x32x16_bf16 v[16:31], v[188:191], v[168:171], v[16:31]
	v_mfma_f32_32x32x16_bf16 v[0:15], v[192:195], v[168:171], v[0:15]
	s_waitcnt lgkmcnt(0)
	s_waitcnt vmcnt(4)
	s_barrier
	s_waitcnt lgkmcnt(0)
	v_mfma_f32_32x32x16_bf16 v[112:127], v[200:203], v[172:175], v[112:127]
	ds_read_b128 v[188:191], v198
	ds_read_b128 v[156:159], v134
	v_mfma_f32_32x32x16_bf16 v[96:111], v[204:207], v[172:175], v[96:111]
	ds_read_b128 v[192:195], v198 offset:2048
	ds_read_b128 v[160:163], v134 offset:2048
	v_mfma_f32_32x32x16_bf16 v[80:95], v[200:203], v[176:179], v[80:95]
	ds_read_b128 v[164:167], v134 offset:4096
	ds_read_b128 v[168:171], v134 offset:6144
	v_mfma_f32_32x32x16_bf16 v[64:79], v[204:207], v[176:179], v[64:79]
	v_mfma_f32_32x32x16_bf16 v[48:63], v[200:203], v[180:183], v[48:63]
	v_mfma_f32_32x32x16_bf16 v[32:47], v[204:207], v[180:183], v[32:47]
	v_mfma_f32_32x32x16_bf16 v[16:31], v[200:203], v[184:187], v[16:31]
	v_mfma_f32_32x32x16_bf16 v[0:15], v[204:207], v[184:187], v[0:15]
	s_waitcnt lgkmcnt(0)
	v_mfma_f32_32x32x16_bf16 v[112:127], v[188:191], v[156:159], v[112:127]
	ds_read_b128 v[200:203], v199
	ds_read_b128 v[172:175], v155
	v_mfma_f32_32x32x16_bf16 v[96:111], v[192:195], v[156:159], v[96:111]
	ds_read_b128 v[204:207], v199 offset:2048
	ds_read_b128 v[176:179], v155 offset:2048
	v_mfma_f32_32x32x16_bf16 v[80:95], v[188:191], v[160:163], v[80:95]
	ds_read_b128 v[180:183], v155 offset:4096
	ds_read_b128 v[184:187], v155 offset:6144
	v_mfma_f32_32x32x16_bf16 v[64:79], v[192:195], v[160:163], v[64:79]
	v_mfma_f32_32x32x16_bf16 v[48:63], v[188:191], v[164:167], v[48:63]
	v_mfma_f32_32x32x16_bf16 v[32:47], v[192:195], v[164:167], v[32:47]
	v_mfma_f32_32x32x16_bf16 v[16:31], v[188:191], v[168:171], v[16:31]
	v_mfma_f32_32x32x16_bf16 v[0:15], v[192:195], v[168:171], v[0:15]
	s_waitcnt lgkmcnt(0)
	s_waitcnt vmcnt(0)
	s_barrier
; #define G_LOADA(kt_) { _Pragma("unroll") for (int i = 0; i < 4; ++i) ra[i] = al(lrow + 64 * i, (kt_) * 64 + lck * 8); }
; #define G_LOADB(kt_) { _Pragma("unroll") for (int i = 0; i < 4; ++i) rb[i] = bl(lrow + 64 * i, (kt_) * 64 + lck * 8); }
; #define G_STOREA(buf_) { bf16_t* nA = sA + (buf_) * 256 * GLD; _Pragma("unroll") for (int i = 0; i < 4; ++i) *(u32x4*)(nA + (lrow + 64 * i) * GLD + lck * 8) = ra[i]; }
; #define G_STOREB(buf_) { bf16_t* nB = sB + (buf_) * 256 * GLD; _Pragma("unroll") for (int i = 0; i < 4; ++i) *(u32x4*)(nB + (lrow + 64 * i) * GLD + lck * 8) = rb[i]; }
; template <class AL, class BL, class EP>
; DI void gemm_tile256(AL al, BL bl, EP ep, int K, char* smem) {
;     ...
;   G_LOADA(0); G_LOADB(0);
;   __syncthreads();
;   G_STOREA(0); G_STOREB(0);
;   if (KT > 1) G_LOADB(1);
;   __syncthreads();
;   for (int kt = 0; kt < KT; kt += 2) {
;     G_STEP(0, kt);
;     if (kt + 1 >= KT) break;
;     G_STEP(1, kt + 1);
;   }
	s_waitcnt lgkmcnt(0)
	v_mfma_f32_32x32x16_bf16 v[112:127], v[200:203], v[172:175], v[112:127]
	ds_read_b128 v[188:191], v198 offset:32768
	ds_read_b128 v[156:159], v134 offset:32768
	v_mfma_f32_32x32x16_bf16 v[96:111], v[204:207], v[172:175], v[96:111]
	ds_read_b128 v[192:195], v198 offset:34816
	ds_read_b128 v[160:163], v134 offset:34816
	v_mfma_f32_32x32x16_bf16 v[80:95], v[200:203], v[176:179], v[80:95]
	ds_read_b128 v[164:167], v134 offset:36864
	ds_read_b128 v[168:171], v134 offset:38912
	v_mfma_f32_32x32x16_bf16 v[64:79], v[204:207], v[176:179], v[64:79]
	v_mfma_f32_32x32x16_bf16 v[48:63], v[200:203], v[180:183], v[48:63]
	v_mfma_f32_32x32x16_bf16 v[32:47], v[204:207], v[180:183], v[32:47]
	v_mfma_f32_32x32x16_bf16 v[16:31], v[200:203], v[184:187], v[16:31]
	v_mfma_f32_32x32x16_bf16 v[0:15], v[204:207], v[184:187], v[0:15]
	s_waitcnt lgkmcnt(0)
	v_mfma_f32_32x32x16_bf16 v[112:127], v[188:191], v[156:159], v[112:127]
	ds_read_b128 v[200:203], v199 offset:32768
	ds_read_b128 v[172:175], v155 offset:32768
	v_mfma_f32_32x32x16_bf16 v[96:111], v[192:195], v[156:159], v[96:111]
	ds_read_b128 v[204:207], v199 offset:34816
	ds_read_b128 v[176:179], v155 offset:34816
	v_mfma_f32_32x32x16_bf16 v[80:95], v[188:191], v[160:163], v[80:95]
	ds_read_b128 v[180:183], v155 offset:36864
	ds_read_b128 v[184:187], v155 offset:38912
	v_mfma_f32_32x32x16_bf16 v[64:79], v[192:195], v[160:163], v[64:79]
	v_mfma_f32_32x32x16_bf16 v[48:63], v[188:191], v[164:167], v[48:63]
	v_mfma_f32_32x32x16_bf16 v[32:47], v[192:195], v[164:167], v[32:47]
	v_mfma_f32_32x32x16_bf16 v[16:31], v[188:191], v[168:171], v[16:31]
	v_mfma_f32_32x32x16_bf16 v[0:15], v[192:195], v[168:171], v[0:15]
	s_waitcnt lgkmcnt(0)
	s_waitcnt lgkmcnt(0)
	v_mfma_f32_32x32x16_bf16 v[112:127], v[200:203], v[172:175], v[112:127]
	v_mfma_f32_32x32x16_bf16 v[96:111], v[204:207], v[172:175], v[96:111]
	v_mfma_f32_32x32x16_bf16 v[80:95], v[200:203], v[176:179], v[80:95]
	v_mfma_f32_32x32x16_bf16 v[64:79], v[204:207], v[176:179], v[64:79]
	v_mfma_f32_32x32x16_bf16 v[48:63], v[200:203], v[180:183], v[48:63]
	v_mfma_f32_32x32x16_bf16 v[32:47], v[204:207], v[180:183], v[32:47]
	v_mfma_f32_32x32x16_bf16 v[16:31], v[200:203], v[184:187], v[16:31]
	v_mfma_f32_32x32x16_bf16 v[0:15], v[204:207], v[184:187], v[0:15]
	s_nop 15
	s_nop 3
	s_waitcnt lgkmcnt(4)
	v_lshl_or_b32 v128, v135, 7, v154
	v_mad_u64_u32 v[132:133], s[0:1], v153, s21, v[128:129]
	s_waitcnt lgkmcnt(0)
	s_barrier
; DI unsigned pack2(float a, float b) { f2_t f = {a, b}; bf2_t r = __builtin_convertvector(f, bf2_t); return __builtin_bit_cast(unsigned, r); }
; DI int tid512() { int t = threadIdx_x_raw(); asm volatile("" : "+v"(t)); return t; }
; template <class AL, class BL, class EP>
; DI void gemm_tile256(AL al, BL bl, EP ep, int K, char* smem) {
;     ...
;   if constexpr (EP::kBf16) {
;     bf16_t* sCb = (bf16_t*)smem;
; #pragma unroll
;     for (int i = 0; i < 4; ++i)
; #pragma unroll
;       for (int j = 0; j < 2; ++j)
; #pragma unroll
;         for (int g = 0; g < 4; ++g) {
;           u32x2 v = {pack2(acc[i][j][4 * g], acc[i][j][4 * g + 1]), pack2(acc[i][j][4 * g + 2], acc[i][j][4 * g + 3])};
;           *(u32x2*)(sCb + (128 * wm + 32 * i + r) * BLD + 64 * wn + 32 * j + 8 * g + 4 * h) = v;
;         }
;   DI void operator()(const bf16_t* sCb) const {
;     const int t = tid512(), hf = (t >> 3) & 1, c8 = (t & 7) * 8;
;     const int cb = c0 + 64 * hf;
;     const bf16_t* base = sCb + 128 * hf;
;     float w0[8], w1[8], w2[8];
;     ld8f(conv + cb + c8, w0); ld8f(conv + DFF + cb + c8, w1); ld8f(conv + 2 * DFF + cb + c8, w2);
	v_lshlrev_b32_e32 v131, 7, v131
	s_nop 5
	v_cvt_pk_bf16_f32 v112, v112, v113
	v_cvt_pk_bf16_f32 v113, v114, v115
	v_cvt_pk_bf16_f32 v114, v116, v117
	v_cvt_pk_bf16_f32 v115, v118, v119
	ds_write2_b64 v132, v[112:113], v[114:115] offset1:2
	v_cvt_pk_bf16_f32 v112, v120, v121
	v_cvt_pk_bf16_f32 v113, v122, v123
	v_cvt_pk_bf16_f32 v96, v96, v97
	v_cvt_pk_bf16_f32 v97, v98, v99
	v_cvt_pk_bf16_f32 v98, v100, v101
	v_cvt_pk_bf16_f32 v99, v102, v103
	v_cvt_pk_bf16_f32 v114, v124, v125
	v_cvt_pk_bf16_f32 v115, v126, v127
	ds_write2_b64 v132, v[96:97], v[98:99] offset0:8 offset1:10
	s_nop 3
	v_cvt_pk_bf16_f32 v80, v80, v81
	v_cvt_pk_bf16_f32 v81, v82, v83
	v_cvt_pk_bf16_f32 v82, v84, v85
	v_cvt_pk_bf16_f32 v83, v86, v87
	v_add_u32_e32 v84, 0x4000, v132
	v_cvt_pk_bf16_f32 v96, v104, v105
	v_cvt_pk_bf16_f32 v97, v106, v107
	v_cvt_pk_bf16_f32 v64, v64, v65
	v_cvt_pk_bf16_f32 v65, v66, v67
	v_cvt_pk_bf16_f32 v66, v68, v69
	v_cvt_pk_bf16_f32 v67, v70, v71
	v_cvt_pk_bf16_f32 v98, v108, v109
	v_cvt_pk_bf16_f32 v99, v110, v111
	ds_write2_b64 v84, v[80:81], v[82:83] offset0:64 offset1:66
	s_nop 3
	v_cvt_pk_bf16_f32 v48, v48, v49
	v_cvt_pk_bf16_f32 v49, v50, v51
	v_cvt_pk_bf16_f32 v50, v52, v53
	v_cvt_pk_bf16_f32 v51, v54, v55
	v_add_u32_e32 v52, 0x8000, v132
	v_cvt_pk_bf16_f32 v80, v88, v89
	v_cvt_pk_bf16_f32 v81, v90, v91
	v_cvt_pk_bf16_f32 v32, v32, v33
	v_cvt_pk_bf16_f32 v33, v34, v35
	v_cvt_pk_bf16_f32 v34, v36, v37
	v_cvt_pk_bf16_f32 v35, v38, v39
	v_cvt_pk_bf16_f32 v82, v92, v93
	v_cvt_pk_bf16_f32 v83, v94, v95
	ds_write2_b64 v84, v[64:65], v[66:67] offset0:72 offset1:74
	s_nop 3
	v_cvt_pk_bf16_f32 v16, v16, v17
	v_cvt_pk_bf16_f32 v17, v18, v19
	v_cvt_pk_bf16_f32 v18, v20, v21
	v_cvt_pk_bf16_f32 v19, v22, v23
	v_add_u32_e32 v20, 0xc000, v132
	v_cvt_pk_bf16_f32 v64, v72, v73
	v_cvt_pk_bf16_f32 v65, v74, v75
	s_nop 0
	v_cvt_pk_bf16_f32 v0, v0, v1
	v_cvt_pk_bf16_f32 v1, v2, v3
	v_cvt_pk_bf16_f32 v2, v4, v5
	v_cvt_pk_bf16_f32 v3, v6, v7
	v_cvt_pk_bf16_f32 v66, v76, v77
	v_cvt_pk_bf16_f32 v67, v78, v79
	ds_write2_b64 v52, v[48:49], v[50:51] offset0:128 offset1:130
	v_cvt_pk_bf16_f32 v48, v56, v57
	v_cvt_pk_bf16_f32 v49, v58, v59
	v_cvt_pk_bf16_f32 v50, v60, v61
	v_cvt_pk_bf16_f32 v51, v62, v63
	ds_write2_b64 v52, v[32:33], v[34:35] offset0:136 offset1:138
	v_cvt_pk_bf16_f32 v32, v40, v41
	v_cvt_pk_bf16_f32 v33, v42, v43
	v_cvt_pk_bf16_f32 v34, v44, v45
	v_cvt_pk_bf16_f32 v35, v46, v47
	ds_write2_b64 v20, v[16:17], v[18:19] offset0:192 offset1:194
	v_cvt_pk_bf16_f32 v16, v24, v25
	v_cvt_pk_bf16_f32 v17, v26, v27
	v_cvt_pk_bf16_f32 v18, v28, v29
	v_cvt_pk_bf16_f32 v19, v30, v31
	ds_write2_b64 v20, v[0:1], v[2:3] offset0:200 offset1:202
	v_cvt_pk_bf16_f32 v0, v8, v9
	v_cvt_pk_bf16_f32 v1, v10, v11
	v_cvt_pk_bf16_f32 v2, v12, v13
	v_cvt_pk_bf16_f32 v3, v14, v15
	v_mov_b32_e32 v29, v196
	ds_write2_b64 v132, v[112:113], v[114:115] offset0:4 offset1:6
	ds_write2_b64 v132, v[96:97], v[98:99] offset0:12 offset1:14
	ds_write2_b64 v84, v[80:81], v[82:83] offset0:68 offset1:70
	ds_write2_b64 v84, v[64:65], v[66:67] offset0:76 offset1:78
	ds_write2_b64 v52, v[48:49], v[50:51] offset0:132 offset1:134
	ds_write2_b64 v52, v[32:33], v[34:35] offset0:140 offset1:142
	ds_write2_b64 v20, v[16:17], v[18:19] offset0:196 offset1:198
	ds_write2_b64 v20, v[0:1], v[2:3] offset0:204 offset1:206
	s_waitcnt lgkmcnt(0)
	s_barrier
	s_nop 0
	v_bfe_u32 v0, v29, 3, 1
	v_lshlrev_b32_e32 v30, 6, v0
	v_lshlrev_b32_e32 v1, 3, v29
	v_or_b32_e32 v24, v30, v131
	v_ashrrev_i32_e32 v26, 4, v29
	v_and_b32_e32 v27, 56, v1
	v_lshlrev_b32_e32 v28, 8, v0
	v_ashrrev_i32_e32 v25, 31, v24
	v_cmp_gt_i32_e32 vcc, s23, v26
	s_and_saveexec_b64 s[0:1], vcc
	s_cbranch_execz .LBB0_545
	v_lshlrev_b64 v[16:17], 2, v[24:25]
	v_lshl_add_u64 v[0:1], s[6:7], 0, v[16:17]
	v_lshlrev_b32_e32 v128, 2, v27
	v_lshl_add_u64 v[8:9], s[4:5], 0, v[16:17]
	v_lshl_add_u64 v[16:17], s[86:87], 0, v[16:17]
	v_lshl_add_u64 v[4:5], v[0:1], 0, v[128:129]
	v_lshl_add_u64 v[12:13], v[8:9], 0, v[128:129]
	v_lshl_add_u64 v[20:21], v[16:17], 0, v[128:129]
	global_load_dwordx4 v[0:3], v[4:5], off
	s_nop 0
	global_load_dwordx4 v[4:7], v[4:5], off offset:16
	s_nop 0
	global_load_dwordx4 v[8:11], v[12:13], off
	s_nop 0
	global_load_dwordx4 v[12:15], v[12:13], off offset:16
	s_nop 0
	global_load_dwordx4 v[16:19], v[20:21], off
	s_nop 0
	global_load_dwordx4 v[20:23], v[20:21], off offset:16
	v_lshlrev_b32_e32 v33, 4, v29
	v_mad_i64_i32 v[34:35], s[14:15], v26, s24, 0
	v_mul_lo_u32 v31, v26, s21
	v_and_b32_e32 v36, 0x70, v33
	v_mad_i64_i32 v[34:35], s[14:15], v130, s25, v[34:35]
	v_add_u32_e32 v30, v131, v30
	v_add3_u32 v33, v31, v28, v36
	v_or_b32_e32 v34, v34, v36
	v_ashrrev_i32_e32 v31, 31, v30
	v_readlane_b32 s10, v246, 51
	v_lshl_add_u64 v[30:31], v[30:31], 1, v[34:35]
	v_readlane_b32 s11, v246, 52
	v_subrev_u32_e32 v32, 32, v26
	s_mov_b64 s[14:15], 0
	v_lshl_add_u64 v[30:31], s[10:11], 0, v[30:31]
	s_waitcnt vmcnt(0)

; DI int tid512() { int t = threadIdx_x_raw(); asm volatile("" : "+v"(t)); return t; }
; template <class AL, class BL, class EP>
; DI void gemm_tile256(AL al, BL bl, EP ep, int K, char* smem) {
;     ...
;   const int tid = tid512(), lane = tid & 63, w = tid >> 6, wm = w >> 2, wn = w & 3, r = lane & 31, h = lane >> 5;
;   const int lrow = tid >> 3, lck = tid & 7;
; DI void phase_in1_256(const Sched& sc, const Params& p, char* smem) {
;     ...
;     LoadRows al{H, 1024, mt * 256, T};
;     LoadRows bl{Wt, 1024, nt * 256, 3584};
.LBB0_765:
	v_cmp_ne_u32_e32 vcc, 1, v0
	s_mov_b64 s[4:5], -1
	s_cbranch_vccz .LBB0_797
	v_mov_b32_e32 v32, v196
	s_nop 0
	v_ashrrev_i32_e32 v33, 3, v32
	v_add_u32_e32 v12, s52, v33
	v_lshlrev_b32_e32 v0, 4, v32
	v_add_u32_e32 v10, 0x80, v12
	v_lshl_add_u32 v28, s20, 8, v33
	v_and_b32_e32 v128, 0x70, v0
	v_min_i32_e32 v0, 0x7fff, v12
	v_min_i32_e32 v10, 0x7fff, v10
	v_add_u32_e32 v26, 0x80, v28
	v_ashrrev_i32_e32 v1, 31, v0
	v_ashrrev_i32_e32 v11, 31, v10
	v_min_i32_e32 v16, 0xdff, v28
	v_min_i32_e32 v26, 0xdff, v26
	v_lshl_add_u64 v[8:9], s[84:85], 0, v[128:129]
	v_lshlrev_b64 v[0:1], 11, v[0:1]
	v_lshlrev_b64 v[10:11], 11, v[10:11]
	v_ashrrev_i32_e32 v17, 31, v16
	v_ashrrev_i32_e32 v27, 31, v26
	v_lshl_add_u64 v[134:135], v[8:9], 0, v[0:1]
	v_add_u32_e32 v0, 64, v12
	v_lshl_add_u64 v[138:139], v[8:9], 0, v[10:11]
	v_add_u32_e32 v10, 0xc0, v12
	v_lshlrev_b64 v[188:189], 11, v[16:17]
	v_add_u32_e32 v16, 64, v28
	v_lshlrev_b64 v[192:193], 11, v[26:27]
	v_add_u32_e32 v26, 0xc0, v28
	v_min_i32_e32 v0, 0x7fff, v0
	v_min_i32_e32 v10, 0x7fff, v10
	v_min_i32_e32 v16, 0xdff, v16
	v_min_i32_e32 v26, 0xdff, v26
	v_ashrrev_i32_e32 v1, 31, v0
	v_ashrrev_i32_e32 v11, 31, v10
	v_lshl_add_u64 v[24:25], s[0:1], 0, v[128:129]
	v_ashrrev_i32_e32 v17, 31, v16
	v_ashrrev_i32_e32 v27, 31, v26
	v_lshlrev_b64 v[0:1], 11, v[0:1]
	v_lshlrev_b64 v[10:11], 11, v[10:11]
	v_lshl_add_u64 v[142:143], v[24:25], 0, v[188:189]
	v_lshlrev_b64 v[190:191], 11, v[16:17]
	v_lshl_add_u64 v[146:147], v[24:25], 0, v[192:193]
	v_lshlrev_b64 v[194:195], 11, v[26:27]
	v_lshl_add_u64 v[136:137], v[8:9], 0, v[0:1]
	v_lshl_add_u64 v[140:141], v[8:9], 0, v[10:11]
	v_lshl_add_u64 v[144:145], v[24:25], 0, v[190:191]
	v_lshl_add_u64 v[148:149], v[24:25], 0, v[194:195]
	v_mad_u64_u32 v[132:133], s[4:5], v33, s44, v[128:129]
	v_add_u32_e32 v155, 0x12000, v132
	v_bfe_u32 v133, v32, 6, 2
	v_add_u32_e32 v154, 0x1b000, v132
	v_and_b32_e32 v1, 31, v32
	v_ashrrev_i32_e32 v0, 1, v32
	v_and_or_b32 v151, v0, s45, v1
	v_lshrrev_b32_e32 v0, 2, v32
	v_and_b32_e32 v152, 8, v0
	v_lshlrev_b32_e32 v0, 1, v152
	v_mad_u64_u32 v[130:131], s[4:5], v151, s44, v[0:1]
	v_lshl_or_b32 v1, v133, 6, v1
	v_mul_u32_u24_e32 v1, 0x48, v1
	v_lshl_add_u32 v0, v1, 1, v0
	v_add_u32_e32 v153, 0x12000, v0
	v_add_u32_e32 v131, 0x1b000, v0
	v_lshl_add_u64 v[194:195], s[0:1], 0, v[194:195]
	v_or_b32_e32 v128, 0x100, v128
	v_lshl_add_u64 v[192:193], s[0:1], 0, v[192:193]
	v_lshl_add_u64 v[190:191], s[0:1], 0, v[190:191]
	v_lshl_add_u64 v[188:189], s[0:1], 0, v[188:189]
	v_lshl_add_u64 v[202:203], v[194:195], 0, v[128:129]
	v_lshl_add_u64 v[198:199], v[192:193], 0, v[128:129]
	v_lshl_add_u64 v[192:193], v[190:191], 0, v[128:129]
	v_lshl_add_u64 v[188:189], v[188:189], 0, v[128:129]
	s_nop 0
	s_nop 0
	s_nop 0
	s_nop 0
	s_nop 0
	s_nop 0
	s_nop 0
	s_nop 0
	s_nop 0
	v_lshrrev_b32_e32 v224, 6, v196
	s_mov_b32 s6, 64
	v_readfirstlane_b32 s21, v224
	s_mov_b32 s7, 0
	s_mov_b32 s10, 0x40000
	s_mov_b32 s11, 0
	v_bfe_u32 v222, v196, 2, 4
	s_lshl_b32 s25, s21, 3
	v_add_u32_e32 v222, s25, v222
	s_mov_b32 s25, 0x800
	v_mul_lo_u32 v222, v222, s25
	v_bfe_u32 v224, v196, 4, 2
	v_and_b32_e32 v223, 3, v196
	v_xor_b32_e32 v224, v223, v224
	v_lshl_add_u32 v222, v224, 4, v222
	v_mov_b32_e32 v223, 0
	v_readlane_b32 s22, v134, 0
	v_readlane_b32 s23, v135, 0
	s_nop 1
	v_lshl_add_u64 v[214:215], s[22:23], 0, v[222:223]
	v_lshl_add_u64 v[216:217], v[214:215], 0, s[10:11]
	v_readlane_b32 s22, v142, 0
	v_readlane_b32 s23, v143, 0
	s_nop 1
	v_lshl_add_u64 v[218:219], s[22:23], 0, v[222:223]
	v_lshl_add_u64 v[220:221], v[218:219], 0, s[10:11]
	v_and_b32_e32 v222, 31, v196
	v_bfe_u32 v224, v196, 2, 2
	v_bfe_u32 v223, v196, 5, 1
	v_xor_b32_e32 v224, v223, v224
	v_lshlrev_b32_e32 v224, 4, v224
	v_lshl_or_b32 v222, v222, 6, v224
	s_lshr_b32 s25, s21, 2
	s_lshl_b32 s25, s25, 13
	v_add_u32_e32 v132, s25, v222
	s_and_b32 s25, s21, 3
	s_lshl_b32 s25, s25, 12
	s_add_u32 s25, s25, 0x4000
	v_add_u32_e32 v154, s25, v222
	v_xor_b32_e32 v153, 0x20, v132
	v_xor_b32_e32 v155, 0x20, v154
	v_add_u32_e32 v198, 0x10000, v132
	v_add_u32_e32 v208, 0x10000, v154
	v_add_u32_e32 v210, 0x20000, v132
	v_add_u32_e32 v212, 0x20000, v154
	v_add_u32_e32 v199, 0x10000, v153
	v_add_u32_e32 v209, 0x10000, v155
	v_add_u32_e32 v211, 0x20000, v153
	v_add_u32_e32 v213, 0x20000, v155
	s_lshl_b32 s21, s21, 10
	s_waitcnt lgkmcnt(0)
	s_barrier
; #define G_LOADA(kt_) { _Pragma("unroll") for (int i = 0; i < 4; ++i) ra[i] = al(lrow + 64 * i, (kt_) * 64 + lck * 8); }
; #define G_LOADB(kt_) { _Pragma("unroll") for (int i = 0; i < 4; ++i) rb[i] = bl(lrow + 64 * i, (kt_) * 64 + lck * 8); }
; #define G_STOREA(buf_) { bf16_t* nA = sA + (buf_) * 256 * GLD; _Pragma("unroll") for (int i = 0; i < 4; ++i) *(u32x4*)(nA + (lrow + 64 * i) * GLD + lck * 8) = ra[i]; }
; #define G_STOREB(buf_) { bf16_t* nB = sB + (buf_) * 256 * GLD; _Pragma("unroll") for (int i = 0; i < 4; ++i) *(u32x4*)(nB + (lrow + 64 * i) * GLD + lck * 8) = rb[i]; }
; template <class AL, class BL, class EP>
; DI void gemm_tile256(AL al, BL bl, EP ep, int K, char* smem) {
;     ...
;   f32x16 acc[4][2];
; #pragma unroll
;   for (int i = 0; i < 4; ++i)
; #pragma unroll
;     for (int j = 0; j < 2; ++j)
; #pragma unroll
;       for (int q = 0; q < 16; ++q) acc[i][j][q] = 0.f;
;   u32x4 ra[4], rb[4];
;   const int KT = K >> 6;
;     ...
;   G_LOADA(0); G_LOADB(0);
;   __syncthreads();
;   G_STOREA(0); G_STOREB(0);
;   if (KT > 1) G_LOADB(1);
;   __syncthreads();
	s_add_u32 m0, s21, 0x0
	s_nop 0
	global_load_lds_dwordx4 v[214:215], off
	v_lshl_add_u64 v[214:215], v[214:215], 0, s[6:7]
	s_add_u32 m0, s21, 0x4000
	s_nop 0
	global_load_lds_dwordx4 v[218:219], off
	v_lshl_add_u64 v[218:219], v[218:219], 0, s[6:7]
	s_add_u32 m0, s21, 0x2000
	s_nop 0
	global_load_lds_dwordx4 v[216:217], off
	v_lshl_add_u64 v[216:217], v[216:217], 0, s[6:7]
	s_add_u32 m0, s21, 0x6000
	s_nop 0
	global_load_lds_dwordx4 v[220:221], off
	v_lshl_add_u64 v[220:221], v[220:221], 0, s[6:7]
	s_add_u32 m0, s21, 0x8000
	s_nop 0
	global_load_lds_dwordx4 v[214:215], off
	v_lshl_add_u64 v[214:215], v[214:215], 0, s[6:7]
	s_add_u32 m0, s21, 0xc000
	s_nop 0
	global_load_lds_dwordx4 v[218:219], off
	v_lshl_add_u64 v[218:219], v[218:219], 0, s[6:7]
	s_add_u32 m0, s21, 0xa000
	s_nop 0
	global_load_lds_dwordx4 v[216:217], off
	v_lshl_add_u64 v[216:217], v[216:217], 0, s[6:7]
	s_add_u32 m0, s21, 0xe000
	s_nop 0
	global_load_lds_dwordx4 v[220:221], off
	v_lshl_add_u64 v[220:221], v[220:221], 0, s[6:7]
	s_add_u32 m0, s21, 0x10000
	s_nop 0
	global_load_lds_dwordx4 v[214:215], off
	v_lshl_add_u64 v[214:215], v[214:215], 0, s[6:7]
	s_add_u32 m0, s21, 0x14000
	s_nop 0
	global_load_lds_dwordx4 v[218:219], off
	v_lshl_add_u64 v[218:219], v[218:219], 0, s[6:7]
	s_add_u32 m0, s21, 0x12000
	s_nop 0
	global_load_lds_dwordx4 v[216:217], off
	v_lshl_add_u64 v[216:217], v[216:217], 0, s[6:7]
	s_add_u32 m0, s21, 0x16000
	s_nop 0
	global_load_lds_dwordx4 v[220:221], off
	v_lshl_add_u64 v[220:221], v[220:221], 0, s[6:7]
	s_add_u32 m0, s21, 0x18000
	s_nop 0
	global_load_lds_dwordx4 v[214:215], off
	v_lshl_add_u64 v[214:215], v[214:215], 0, s[6:7]
	s_add_u32 m0, s21, 0x1c000
	s_nop 0
	global_load_lds_dwordx4 v[218:219], off
	v_lshl_add_u64 v[218:219], v[218:219], 0, s[6:7]
	s_add_u32 m0, s21, 0x1a000
	s_nop 0
	global_load_lds_dwordx4 v[216:217], off
	v_lshl_add_u64 v[216:217], v[216:217], 0, s[6:7]
	s_add_u32 m0, s21, 0x1e000
	s_nop 0
	global_load_lds_dwordx4 v[220:221], off
	v_lshl_add_u64 v[220:221], v[220:221], 0, s[6:7]
	s_add_u32 m0, s21, 0x20000
	s_nop 0
	global_load_lds_dwordx4 v[214:215], off
	v_lshl_add_u64 v[214:215], v[214:215], 0, s[6:7]
	s_add_u32 m0, s21, 0x24000
	s_nop 0
	global_load_lds_dwordx4 v[218:219], off
	v_lshl_add_u64 v[218:219], v[218:219], 0, s[6:7]
	v_mov_b64_e32 v[112:113], 0
	v_mov_b64_e32 v[114:115], 0
	v_mov_b64_e32 v[116:117], 0
	v_mov_b64_e32 v[118:119], 0
	v_mov_b64_e32 v[120:121], 0
	v_mov_b64_e32 v[122:123], 0
	v_mov_b64_e32 v[124:125], 0
	v_mov_b64_e32 v[126:127], 0
	v_mov_b64_e32 v[96:97], 0
	v_mov_b64_e32 v[98:99], 0
	v_mov_b64_e32 v[100:101], 0
	v_mov_b64_e32 v[102:103], 0
	v_mov_b64_e32 v[104:105], 0
	v_mov_b64_e32 v[106:107], 0
	v_mov_b64_e32 v[108:109], 0
	v_mov_b64_e32 v[110:111], 0
	v_mov_b64_e32 v[80:81], 0
	v_mov_b64_e32 v[82:83], 0
	v_mov_b64_e32 v[84:85], 0
	v_mov_b64_e32 v[86:87], 0
	v_mov_b64_e32 v[88:89], 0
	v_mov_b64_e32 v[90:91], 0
	v_mov_b64_e32 v[92:93], 0
	v_mov_b64_e32 v[94:95], 0
	v_mov_b64_e32 v[64:65], 0
	v_mov_b64_e32 v[66:67], 0
	v_mov_b64_e32 v[68:69], 0
	v_mov_b64_e32 v[70:71], 0
	v_mov_b64_e32 v[72:73], 0
	v_mov_b64_e32 v[74:75], 0
	v_mov_b64_e32 v[76:77], 0
	v_mov_b64_e32 v[78:79], 0
	v_mov_b64_e32 v[48:49], 0
	v_mov_b64_e32 v[50:51], 0
	v_mov_b64_e32 v[52:53], 0
	v_mov_b64_e32 v[54:55], 0
	v_mov_b64_e32 v[56:57], 0
	v_mov_b64_e32 v[58:59], 0
	v_mov_b64_e32 v[60:61], 0
	v_mov_b64_e32 v[62:63], 0
	v_mov_b64_e32 v[32:33], 0
	v_mov_b64_e32 v[34:35], 0
	v_mov_b64_e32 v[36:37], 0
	v_mov_b64_e32 v[38:39], 0
	v_mov_b64_e32 v[40:41], 0
	v_mov_b64_e32 v[42:43], 0
	v_mov_b64_e32 v[44:45], 0
	v_mov_b64_e32 v[46:47], 0
	v_mov_b64_e32 v[16:17], 0
	v_mov_b64_e32 v[18:19], 0
	v_mov_b64_e32 v[20:21], 0
	v_mov_b64_e32 v[22:23], 0
	v_mov_b64_e32 v[24:25], 0
	v_mov_b64_e32 v[26:27], 0
	v_mov_b64_e32 v[28:29], 0
	v_mov_b64_e32 v[30:31], 0
	v_mov_b64_e32 v[0:1], 0
	v_mov_b64_e32 v[2:3], 0
	v_mov_b64_e32 v[4:5], 0
	v_mov_b64_e32 v[6:7], 0
	v_mov_b64_e32 v[8:9], 0
	v_mov_b64_e32 v[10:11], 0
	v_mov_b64_e32 v[12:13], 0
	v_mov_b64_e32 v[14:15], 0
	s_mov_b32 s25, 5
	s_waitcnt vmcnt(14)
	s_barrier
	ds_read_b128 v[188:191], v154
	ds_read_b128 v[156:159], v132
	ds_read_b128 v[192:195], v154 offset:2048
	ds_read_b128 v[160:163], v132 offset:2048
	ds_read_b128 v[164:167], v132 offset:4096
	ds_read_b128 v[168:171], v132 offset:6144
.Lgk_ph9_loop:
	s_waitcnt lgkmcnt(0)
	v_mfma_f32_32x32x16_bf16 v[112:127], v[188:191], v[156:159], v[112:127]
	ds_read_b128 v[200:203], v155
	ds_read_b128 v[172:175], v153
	v_mfma_f32_32x32x16_bf16 v[96:111], v[192:195], v[156:159], v[96:111]
	ds_read_b128 v[204:207], v155 offset:2048
	ds_read_b128 v[176:179], v153 offset:2048
	v_mfma_f32_32x32x16_bf16 v[80:95], v[188:191], v[160:163], v[80:95]
	ds_read_b128 v[180:183], v153 offset:4096
	ds_read_b128 v[184:187], v153 offset:6144
	v_mfma_f32_32x32x16_bf16 v[64:79], v[192:195], v[160:163], v[64:79]
	s_add_u32 m0, s21, 0x22000
	s_nop 0
	global_load_lds_dwordx4 v[216:217], off
	v_lshl_add_u64 v[216:217], v[216:217], 0, s[6:7]
	v_mfma_f32_32x32x16_bf16 v[48:63], v[188:191], v[164:167], v[48:63]
	v_mfma_f32_32x32x16_bf16 v[32:47], v[192:195], v[164:167], v[32:47]
	v_mfma_f32_32x32x16_bf16 v[16:31], v[188:191], v[168:171], v[16:31]
	v_mfma_f32_32x32x16_bf16 v[0:15], v[192:195], v[168:171], v[0:15]
	s_add_u32 m0, s21, 0x26000
	s_nop 0
	global_load_lds_dwordx4 v[220:221], off
	v_lshl_add_u64 v[220:221], v[220:221], 0, s[6:7]
	s_waitcnt lgkmcnt(0)
	s_waitcnt vmcnt(12)
	s_barrier
	s_waitcnt lgkmcnt(0)
	v_mfma_f32_32x32x16_bf16 v[112:127], v[200:203], v[172:175], v[112:127]
	ds_read_b128 v[188:191], v154 offset:32768
	ds_read_b128 v[156:159], v132 offset:32768
	v_mfma_f32_32x32x16_bf16 v[96:111], v[204:207], v[172:175], v[96:111]
	ds_read_b128 v[192:195], v154 offset:34816
	ds_read_b128 v[160:163], v132 offset:34816
	v_mfma_f32_32x32x16_bf16 v[80:95], v[200:203], v[176:179], v[80:95]
	ds_read_b128 v[164:167], v132 offset:36864
	ds_read_b128 v[168:171], v132 offset:38912
	v_mfma_f32_32x32x16_bf16 v[64:79], v[204:207], v[176:179], v[64:79]
	s_add_u32 m0, s21, 0x0
	s_nop 0
	global_load_lds_dwordx4 v[214:215], off
	v_lshl_add_u64 v[214:215], v[214:215], 0, s[6:7]
	v_mfma_f32_32x32x16_bf16 v[48:63], v[200:203], v[180:183], v[48:63]
	v_mfma_f32_32x32x16_bf16 v[32:47], v[204:207], v[180:183], v[32:47]
	v_mfma_f32_32x32x16_bf16 v[16:31], v[200:203], v[184:187], v[16:31]
	v_mfma_f32_32x32x16_bf16 v[0:15], v[204:207], v[184:187], v[0:15]
	s_add_u32 m0, s21, 0x4000
	s_nop 0
	global_load_lds_dwordx4 v[218:219], off
	v_lshl_add_u64 v[218:219], v[218:219], 0, s[6:7]
	s_waitcnt lgkmcnt(0)
	v_mfma_f32_32x32x16_bf16 v[112:127], v[188:191], v[156:159], v[112:127]
	ds_read_b128 v[200:203], v155 offset:32768
	ds_read_b128 v[172:175], v153 offset:32768
	v_mfma_f32_32x32x16_bf16 v[96:111], v[192:195], v[156:159], v[96:111]
	ds_read_b128 v[204:207], v155 offset:34816
	ds_read_b128 v[176:179], v153 offset:34816
	v_mfma_f32_32x32x16_bf16 v[80:95], v[188:191], v[160:163], v[80:95]
	ds_read_b128 v[180:183], v153 offset:36864
	ds_read_b128 v[184:187], v153 offset:38912
	v_mfma_f32_32x32x16_bf16 v[64:79], v[192:195], v[160:163], v[64:79]
	s_add_u32 m0, s21, 0x2000
	s_nop 0
	global_load_lds_dwordx4 v[216:217], off
	v_lshl_add_u64 v[216:217], v[216:217], 0, s[6:7]
	v_mfma_f32_32x32x16_bf16 v[48:63], v[188:191], v[164:167], v[48:63]
	v_mfma_f32_32x32x16_bf16 v[32:47], v[192:195], v[164:167], v[32:47]
	v_mfma_f32_32x32x16_bf16 v[16:31], v[188:191], v[168:171], v[16:31]
	v_mfma_f32_32x32x16_bf16 v[0:15], v[192:195], v[168:171], v[0:15]
	s_add_u32 m0, s21, 0x6000
	s_nop 0
	global_load_lds_dwordx4 v[220:221], off
	v_lshl_add_u64 v[220:221], v[220:221], 0, s[6:7]
	s_waitcnt lgkmcnt(0)
	s_waitcnt vmcnt(12)
	s_barrier
	s_waitcnt lgkmcnt(0)
	v_mfma_f32_32x32x16_bf16 v[112:127], v[200:203], v[172:175], v[112:127]
	ds_read_b128 v[188:191], v208
	ds_read_b128 v[156:159], v198
	v_mfma_f32_32x32x16_bf16 v[96:111], v[204:207], v[172:175], v[96:111]
	ds_read_b128 v[192:195], v208 offset:2048
	ds_read_b128 v[160:163], v198 offset:2048
	v_mfma_f32_32x32x16_bf16 v[80:95], v[200:203], v[176:179], v[80:95]
	ds_read_b128 v[164:167], v198 offset:4096
	ds_read_b128 v[168:171], v198 offset:6144
	v_mfma_f32_32x32x16_bf16 v[64:79], v[204:207], v[176:179], v[64:79]
	s_add_u32 m0, s21, 0x8000
	s_nop 0
	global_load_lds_dwordx4 v[214:215], off
	v_lshl_add_u64 v[214:215], v[214:215], 0, s[6:7]
	v_mfma_f32_32x32x16_bf16 v[48:63], v[200:203], v[180:183], v[48:63]
	v_mfma_f32_32x32x16_bf16 v[32:47], v[204:207], v[180:183], v[32:47]
	v_mfma_f32_32x32x16_bf16 v[16:31], v[200:203], v[184:187], v[16:31]
	v_mfma_f32_32x32x16_bf16 v[0:15], v[204:207], v[184:187], v[0:15]
	s_add_u32 m0, s21, 0xc000
	s_nop 0
	global_load_lds_dwordx4 v[218:219], off
	v_lshl_add_u64 v[218:219], v[218:219], 0, s[6:7]
	s_waitcnt lgkmcnt(0)
	v_mfma_f32_32x32x16_bf16 v[112:127], v[188:191], v[156:159], v[112:127]
	ds_read_b128 v[200:203], v209
	ds_read_b128 v[172:175], v199
	v_mfma_f32_32x32x16_bf16 v[96:111], v[192:195], v[156:159], v[96:111]
	ds_read_b128 v[204:207], v209 offset:2048
	ds_read_b128 v[176:179], v199 offset:2048
	v_mfma_f32_32x32x16_bf16 v[80:95], v[188:191], v[160:163], v[80:95]
	ds_read_b128 v[180:183], v199 offset:4096
	ds_read_b128 v[184:187], v199 offset:6144
	v_mfma_f32_32x32x16_bf16 v[64:79], v[192:195], v[160:163], v[64:79]
	s_add_u32 m0, s21, 0xa000
	s_nop 0
	global_load_lds_dwordx4 v[216:217], off
	v_lshl_add_u64 v[216:217], v[216:217], 0, s[6:7]
	v_mfma_f32_32x32x16_bf16 v[48:63], v[188:191], v[164:167], v[48:63]
	v_mfma_f32_32x32x16_bf16 v[32:47], v[192:195], v[164:167], v[32:47]
	v_mfma_f32_32x32x16_bf16 v[16:31], v[188:191], v[168:171], v[16:31]
	v_mfma_f32_32x32x16_bf16 v[0:15], v[192:195], v[168:171], v[0:15]
	s_add_u32 m0, s21, 0xe000
	s_nop 0
	global_load_lds_dwordx4 v[220:221], off
	v_lshl_add_u64 v[220:221], v[220:221], 0, s[6:7]
	s_waitcnt lgkmcnt(0)
	s_waitcnt vmcnt(12)
	s_barrier
	s_waitcnt lgkmcnt(0)
	v_mfma_f32_32x32x16_bf16 v[112:127], v[200:203], v[172:175], v[112:127]
	ds_read_b128 v[188:191], v208 offset:32768
	ds_read_b128 v[156:159], v198 offset:32768
	v_mfma_f32_32x32x16_bf16 v[96:111], v[204:207], v[172:175], v[96:111]
	ds_read_b128 v[192:195], v208 offset:34816
	ds_read_b128 v[160:163], v198 offset:34816
	v_mfma_f32_32x32x16_bf16 v[80:95], v[200:203], v[176:179], v[80:95]
	ds_read_b128 v[164:167], v198 offset:36864
	ds_read_b128 v[168:171], v198 offset:38912
	v_mfma_f32_32x32x16_bf16 v[64:79], v[204:207], v[176:179], v[64:79]
	s_add_u32 m0, s21, 0x10000
	s_nop 0
	global_load_lds_dwordx4 v[214:215], off
	v_lshl_add_u64 v[214:215], v[214:215], 0, s[6:7]
	v_mfma_f32_32x32x16_bf16 v[48:63], v[200:203], v[180:183], v[48:63]
	v_mfma_f32_32x32x16_bf16 v[32:47], v[204:207], v[180:183], v[32:47]
	v_mfma_f32_32x32x16_bf16 v[16:31], v[200:203], v[184:187], v[16:31]
	v_mfma_f32_32x32x16_bf16 v[0:15], v[204:207], v[184:187], v[0:15]
	s_add_u32 m0, s21, 0x14000
	s_nop 0
	global_load_lds_dwordx4 v[218:219], off
	v_lshl_add_u64 v[218:219], v[218:219], 0, s[6:7]
	s_waitcnt lgkmcnt(0)
	v_mfma_f32_32x32x16_bf16 v[112:127], v[188:191], v[156:159], v[112:127]
	ds_read_b128 v[200:203], v209 offset:32768
	ds_read_b128 v[172:175], v199 offset:32768
	v_mfma_f32_32x32x16_bf16 v[96:111], v[192:195], v[156:159], v[96:111]
	ds_read_b128 v[204:207], v209 offset:34816
	ds_read_b128 v[176:179], v199 offset:34816
	v_mfma_f32_32x32x16_bf16 v[80:95], v[188:191], v[160:163], v[80:95]
	ds_read_b128 v[180:183], v199 offset:36864
	ds_read_b128 v[184:187], v199 offset:38912
	v_mfma_f32_32x32x16_bf16 v[64:79], v[192:195], v[160:163], v[64:79]
	s_add_u32 m0, s21, 0x12000
	s_nop 0
	global_load_lds_dwordx4 v[216:217], off
	v_lshl_add_u64 v[216:217], v[216:217], 0, s[6:7]
	v_mfma_f32_32x32x16_bf16 v[48:63], v[188:191], v[164:167], v[48:63]
	v_mfma_f32_32x32x16_bf16 v[32:47], v[192:195], v[164:167], v[32:47]
	v_mfma_f32_32x32x16_bf16 v[16:31], v[188:191], v[168:171], v[16:31]
	v_mfma_f32_32x32x16_bf16 v[0:15], v[192:195], v[168:171], v[0:15]
	s_add_u32 m0, s21, 0x16000
	s_nop 0
	global_load_lds_dwordx4 v[220:221], off
	v_lshl_add_u64 v[220:221], v[220:221], 0, s[6:7]
	s_waitcnt lgkmcnt(0)
	s_waitcnt vmcnt(12)
	s_barrier
	s_waitcnt lgkmcnt(0)
	v_mfma_f32_32x32x16_bf16 v[112:127], v[200:203], v[172:175], v[112:127]
	ds_read_b128 v[188:191], v212
	ds_read_b128 v[156:159], v210
	v_mfma_f32_32x32x16_bf16 v[96:111], v[204:207], v[172:175], v[96:111]
	ds_read_b128 v[192:195], v212 offset:2048
	ds_read_b128 v[160:163], v210 offset:2048
	v_mfma_f32_32x32x16_bf16 v[80:95], v[200:203], v[176:179], v[80:95]
	ds_read_b128 v[164:167], v210 offset:4096
	ds_read_b128 v[168:171], v210 offset:6144
	v_mfma_f32_32x32x16_bf16 v[64:79], v[204:207], v[176:179], v[64:79]
	s_add_u32 m0, s21, 0x18000
	s_nop 0
	global_load_lds_dwordx4 v[214:215], off
	v_lshl_add_u64 v[214:215], v[214:215], 0, s[6:7]
	v_mfma_f32_32x32x16_bf16 v[48:63], v[200:203], v[180:183], v[48:63]
	v_mfma_f32_32x32x16_bf16 v[32:47], v[204:207], v[180:183], v[32:47]
	v_mfma_f32_32x32x16_bf16 v[16:31], v[200:203], v[184:187], v[16:31]
	v_mfma_f32_32x32x16_bf16 v[0:15], v[204:207], v[184:187], v[0:15]
	s_add_u32 m0, s21, 0x1c000
	s_nop 0
	global_load_lds_dwordx4 v[218:219], off
	v_lshl_add_u64 v[218:219], v[218:219], 0, s[6:7]
	s_waitcnt lgkmcnt(0)
	v_mfma_f32_32x32x16_bf16 v[112:127], v[188:191], v[156:159], v[112:127]
	ds_read_b128 v[200:203], v213
	ds_read_b128 v[172:175], v211
	v_mfma_f32_32x32x16_bf16 v[96:111], v[192:195], v[156:159], v[96:111]
	ds_read_b128 v[204:207], v213 offset:2048
	ds_read_b128 v[176:179], v211 offset:2048
	v_mfma_f32_32x32x16_bf16 v[80:95], v[188:191], v[160:163], v[80:95]
	ds_read_b128 v[180:183], v211 offset:4096
	ds_read_b128 v[184:187], v211 offset:6144
	v_mfma_f32_32x32x16_bf16 v[64:79], v[192:195], v[160:163], v[64:79]
	s_add_u32 m0, s21, 0x1a000
	s_nop 0
	global_load_lds_dwordx4 v[216:217], off
	v_lshl_add_u64 v[216:217], v[216:217], 0, s[6:7]
	v_mfma_f32_32x32x16_bf16 v[48:63], v[188:191], v[164:167], v[48:63]
	v_mfma_f32_32x32x16_bf16 v[32:47], v[192:195], v[164:167], v[32:47]
	v_mfma_f32_32x32x16_bf16 v[16:31], v[188:191], v[168:171], v[16:31]
	v_mfma_f32_32x32x16_bf16 v[0:15], v[192:195], v[168:171], v[0:15]
	s_add_u32 m0, s21, 0x1e000
	s_nop 0
	global_load_lds_dwordx4 v[220:221], off
	v_lshl_add_u64 v[220:221], v[220:221], 0, s[6:7]
	s_waitcnt lgkmcnt(0)
	s_waitcnt vmcnt(12)
	s_barrier
	s_waitcnt lgkmcnt(0)
	v_mfma_f32_32x32x16_bf16 v[112:127], v[200:203], v[172:175], v[112:127]
	ds_read_b128 v[188:191], v154
	ds_read_b128 v[156:159], v132
	v_mfma_f32_32x32x16_bf16 v[96:111], v[204:207], v[172:175], v[96:111]
	ds_read_b128 v[192:195], v154 offset:2048
	ds_read_b128 v[160:163], v132 offset:2048
	v_mfma_f32_32x32x16_bf16 v[80:95], v[200:203], v[176:179], v[80:95]
	ds_read_b128 v[164:167], v132 offset:4096
	ds_read_b128 v[168:171], v132 offset:6144
	v_mfma_f32_32x32x16_bf16 v[64:79], v[204:207], v[176:179], v[64:79]
	s_add_u32 m0, s21, 0x20000
	s_nop 0
	global_load_lds_dwordx4 v[214:215], off
	v_lshl_add_u64 v[214:215], v[214:215], 0, s[6:7]
	v_mfma_f32_32x32x16_bf16 v[48:63], v[200:203], v[180:183], v[48:63]
	v_mfma_f32_32x32x16_bf16 v[32:47], v[204:207], v[180:183], v[32:47]
	v_mfma_f32_32x32x16_bf16 v[16:31], v[200:203], v[184:187], v[16:31]
	v_mfma_f32_32x32x16_bf16 v[0:15], v[204:207], v[184:187], v[0:15]
	s_add_u32 m0, s21, 0x24000
	s_nop 0
	global_load_lds_dwordx4 v[218:219], off
	v_lshl_add_u64 v[218:219], v[218:219], 0, s[6:7]
	s_sub_u32 s25, s25, 1
	s_cmp_lg_u32 s25, 0
	s_cbranch_scc1 .Lgk_ph9_loop
; #define G_LOADA(kt_) { _Pragma("unroll") for (int i = 0; i < 4; ++i) ra[i] = al(lrow + 64 * i, (kt_) * 64 + lck * 8); }
; #define G_LOADB(kt_) { _Pragma("unroll") for (int i = 0; i < 4; ++i) rb[i] = bl(lrow + 64 * i, (kt_) * 64 + lck * 8); }
; #define G_STOREA(buf_) { bf16_t* nA = sA + (buf_) * 256 * GLD; _Pragma("unroll") for (int i = 0; i < 4; ++i) *(u32x4*)(nA + (lrow + 64 * i) * GLD + lck * 8) = ra[i]; }
; #define G_STOREB(buf_) { bf16_t* nB = sB + (buf_) * 256 * GLD; _Pragma("unroll") for (int i = 0; i < 4; ++i) *(u32x4*)(nB + (lrow + 64 * i) * GLD + lck * 8) = rb[i]; }
; template <class AL, class BL, class EP>
; DI void gemm_tile256(AL al, BL bl, EP ep, int K, char* smem) {
;     ...
;   G_LOADA(0); G_LOADB(0);
;   __syncthreads();
;   G_STOREA(0); G_STOREB(0);
;   if (KT > 1) G_LOADB(1);
;   __syncthreads();
;   for (int kt = 0; kt < KT; kt += 2) {
;     G_STEP(0, kt);
;     if (kt + 1 >= KT) break;
;     G_STEP(1, kt + 1);
;   }
	s_waitcnt lgkmcnt(0)
	v_mfma_f32_32x32x16_bf16 v[112:127], v[188:191], v[156:159], v[112:127]
	ds_read_b128 v[200:203], v155
	ds_read_b128 v[172:175], v153
	v_mfma_f32_32x32x16_bf16 v[96:111], v[192:195], v[156:159], v[96:111]
	ds_read_b128 v[204:207], v155 offset:2048
	ds_read_b128 v[176:179], v153 offset:2048
	v_mfma_f32_32x32x16_bf16 v[80:95], v[188:191], v[160:163], v[80:95]
	ds_read_b128 v[180:183], v153 offset:4096
	ds_read_b128 v[184:187], v153 offset:6144
	v_mfma_f32_32x32x16_bf16 v[64:79], v[192:195], v[160:163], v[64:79]
	s_add_u32 m0, s21, 0x22000
	s_nop 0
	global_load_lds_dwordx4 v[216:217], off
	v_lshl_add_u64 v[216:217], v[216:217], 0, s[6:7]
	v_mfma_f32_32x32x16_bf16 v[48:63], v[188:191], v[164:167], v[48:63]
	v_mfma_f32_32x32x16_bf16 v[32:47], v[192:195], v[164:167], v[32:47]
	v_mfma_f32_32x32x16_bf16 v[16:31], v[188:191], v[168:171], v[16:31]
	v_mfma_f32_32x32x16_bf16 v[0:15], v[192:195], v[168:171], v[0:15]
	s_add_u32 m0, s21, 0x26000
	s_nop 0
	global_load_lds_dwordx4 v[220:221], off
	v_lshl_add_u64 v[220:221], v[220:221], 0, s[6:7]
	s_waitcnt lgkmcnt(0)
	s_waitcnt vmcnt(12)
	s_barrier
	s_waitcnt lgkmcnt(0)
	v_mfma_f32_32x32x16_bf16 v[112:127], v[200:203], v[172:175], v[112:127]
	ds_read_b128 v[188:191], v154 offset:32768
	ds_read_b128 v[156:159], v132 offset:32768
	v_mfma_f32_32x32x16_bf16 v[96:111], v[204:207], v[172:175], v[96:111]
	ds_read_b128 v[192:195], v154 offset:34816
	ds_read_b128 v[160:163], v132 offset:34816
	v_mfma_f32_32x32x16_bf16 v[80:95], v[200:203], v[176:179], v[80:95]
	ds_read_b128 v[164:167], v132 offset:36864
	ds_read_b128 v[168:171], v132 offset:38912
	v_mfma_f32_32x32x16_bf16 v[64:79], v[204:207], v[176:179], v[64:79]
	s_add_u32 m0, s21, 0x0
	s_nop 0
	global_load_lds_dwordx4 v[214:215], off
	v_lshl_add_u64 v[214:215], v[214:215], 0, s[6:7]
	v_mfma_f32_32x32x16_bf16 v[48:63], v[200:203], v[180:183], v[48:63]
	v_mfma_f32_32x32x16_bf16 v[32:47], v[204:207], v[180:183], v[32:47]
	v_mfma_f32_32x32x16_bf16 v[16:31], v[200:203], v[184:187], v[16:31]
	v_mfma_f32_32x32x16_bf16 v[0:15], v[204:207], v[184:187], v[0:15]
	s_add_u32 m0, s21, 0x4000
	s_nop 0
	global_load_lds_dwordx4 v[218:219], off
	v_lshl_add_u64 v[218:219], v[218:219], 0, s[6:7]
	s_waitcnt lgkmcnt(0)
	v_mfma_f32_32x32x16_bf16 v[112:127], v[188:191], v[156:159], v[112:127]
	ds_read_b128 v[200:203], v155 offset:32768
	ds_read_b128 v[172:175], v153 offset:32768
	v_mfma_f32_32x32x16_bf16 v[96:111], v[192:195], v[156:159], v[96:111]
	ds_read_b128 v[204:207], v155 offset:34816
	ds_read_b128 v[176:179], v153 offset:34816
	v_mfma_f32_32x32x16_bf16 v[80:95], v[188:191], v[160:163], v[80:95]
	ds_read_b128 v[180:183], v153 offset:36864
	ds_read_b128 v[184:187], v153 offset:38912
	v_mfma_f32_32x32x16_bf16 v[64:79], v[192:195], v[160:163], v[64:79]
	s_add_u32 m0, s21, 0x2000
	s_nop 0
	global_load_lds_dwordx4 v[216:217], off
	v_lshl_add_u64 v[216:217], v[216:217], 0, s[6:7]
	v_mfma_f32_32x32x16_bf16 v[48:63], v[188:191], v[164:167], v[48:63]
	v_mfma_f32_32x32x16_bf16 v[32:47], v[192:195], v[164:167], v[32:47]
	v_mfma_f32_32x32x16_bf16 v[16:31], v[188:191], v[168:171], v[16:31]
	v_mfma_f32_32x32x16_bf16 v[0:15], v[192:195], v[168:171], v[0:15]
	s_add_u32 m0, s21, 0x6000
	s_nop 0
	global_load_lds_dwordx4 v[220:221], off
	v_lshl_add_u64 v[220:221], v[220:221], 0, s[6:7]
	s_waitcnt lgkmcnt(0)
	s_waitcnt vmcnt(12)
	s_barrier
	s_waitcnt lgkmcnt(0)
	v_mfma_f32_32x32x16_bf16 v[112:127], v[200:203], v[172:175], v[112:127]
	ds_read_b128 v[188:191], v208
	ds_read_b128 v[156:159], v198
	v_mfma_f32_32x32x16_bf16 v[96:111], v[204:207], v[172:175], v[96:111]
	ds_read_b128 v[192:195], v208 offset:2048
	ds_read_b128 v[160:163], v198 offset:2048
	v_mfma_f32_32x32x16_bf16 v[80:95], v[200:203], v[176:179], v[80:95]
	ds_read_b128 v[164:167], v198 offset:4096
	ds_read_b128 v[168:171], v198 offset:6144
	v_mfma_f32_32x32x16_bf16 v[64:79], v[204:207], v[176:179], v[64:79]
	s_add_u32 m0, s21, 0x8000
	s_nop 0
	global_load_lds_dwordx4 v[214:215], off
	v_lshl_add_u64 v[214:215], v[214:215], 0, s[6:7]
	v_mfma_f32_32x32x16_bf16 v[48:63], v[200:203], v[180:183], v[48:63]
	v_mfma_f32_32x32x16_bf16 v[32:47], v[204:207], v[180:183], v[32:47]
	v_mfma_f32_32x32x16_bf16 v[16:31], v[200:203], v[184:187], v[16:31]
	v_mfma_f32_32x32x16_bf16 v[0:15], v[204:207], v[184:187], v[0:15]
	s_add_u32 m0, s21, 0xc000
	s_nop 0
	global_load_lds_dwordx4 v[218:219], off
	v_lshl_add_u64 v[218:219], v[218:219], 0, s[6:7]
	s_waitcnt lgkmcnt(0)
	v_mfma_f32_32x32x16_bf16 v[112:127], v[188:191], v[156:159], v[112:127]
	ds_read_b128 v[200:203], v209
	ds_read_b128 v[172:175], v199
	v_mfma_f32_32x32x16_bf16 v[96:111], v[192:195], v[156:159], v[96:111]
	ds_read_b128 v[204:207], v209 offset:2048
	ds_read_b128 v[176:179], v199 offset:2048
	v_mfma_f32_32x32x16_bf16 v[80:95], v[188:191], v[160:163], v[80:95]
	ds_read_b128 v[180:183], v199 offset:4096
	ds_read_b128 v[184:187], v199 offset:6144
	v_mfma_f32_32x32x16_bf16 v[64:79], v[192:195], v[160:163], v[64:79]
	s_add_u32 m0, s21, 0xa000
	s_nop 0
	global_load_lds_dwordx4 v[216:217], off
	v_lshl_add_u64 v[216:217], v[216:217], 0, s[6:7]
	v_mfma_f32_32x32x16_bf16 v[48:63], v[188:191], v[164:167], v[48:63]
	v_mfma_f32_32x32x16_bf16 v[32:47], v[192:195], v[164:167], v[32:47]
	v_mfma_f32_32x32x16_bf16 v[16:31], v[188:191], v[168:171], v[16:31]
	v_mfma_f32_32x32x16_bf16 v[0:15], v[192:195], v[168:171], v[0:15]
	s_add_u32 m0, s21, 0xe000
	s_nop 0
	global_load_lds_dwordx4 v[220:221], off
	v_lshl_add_u64 v[220:221], v[220:221], 0, s[6:7]
	s_waitcnt lgkmcnt(0)
	s_waitcnt vmcnt(12)
	s_barrier
; #define G_LOADA(kt_) { _Pragma("unroll") for (int i = 0; i < 4; ++i) ra[i] = al(lrow + 64 * i, (kt_) * 64 + lck * 8); }
; #define G_LOADB(kt_) { _Pragma("unroll") for (int i = 0; i < 4; ++i) rb[i] = bl(lrow + 64 * i, (kt_) * 64 + lck * 8); }
; #define G_STOREA(buf_) { bf16_t* nA = sA + (buf_) * 256 * GLD; _Pragma("unroll") for (int i = 0; i < 4; ++i) *(u32x4*)(nA + (lrow + 64 * i) * GLD + lck * 8) = ra[i]; }
; #define G_STOREB(buf_) { bf16_t* nB = sB + (buf_) * 256 * GLD; _Pragma("unroll") for (int i = 0; i < 4; ++i) *(u32x4*)(nB + (lrow + 64 * i) * GLD + lck * 8) = rb[i]; }
; template <class AL, class BL, class EP>
; DI void gemm_tile256(AL al, BL bl, EP ep, int K, char* smem) {
;     ...
;   G_LOADA(0); G_LOADB(0);
;   __syncthreads();
;   G_STOREA(0); G_STOREB(0);
;   if (KT > 1) G_LOADB(1);
;   __syncthreads();
;   for (int kt = 0; kt < KT; kt += 2) {
;     G_STEP(0, kt);
;     if (kt + 1 >= KT) break;
;     G_STEP(1, kt + 1);
;   }
	s_waitcnt lgkmcnt(0)
	v_mfma_f32_32x32x16_bf16 v[112:127], v[200:203], v[172:175], v[112:127]
	ds_read_b128 v[188:191], v208 offset:32768
	ds_read_b128 v[156:159], v198 offset:32768
	v_mfma_f32_32x32x16_bf16 v[96:111], v[204:207], v[172:175], v[96:111]
	ds_read_b128 v[192:195], v208 offset:34816
	ds_read_b128 v[160:163], v198 offset:34816
	v_mfma_f32_32x32x16_bf16 v[80:95], v[200:203], v[176:179], v[80:95]
	ds_read_b128 v[164:167], v198 offset:36864
	ds_read_b128 v[168:171], v198 offset:38912
	v_mfma_f32_32x32x16_bf16 v[64:79], v[204:207], v[176:179], v[64:79]
	v_mfma_f32_32x32x16_bf16 v[48:63], v[200:203], v[180:183], v[48:63]
	v_mfma_f32_32x32x16_bf16 v[32:47], v[204:207], v[180:183], v[32:47]
	v_mfma_f32_32x32x16_bf16 v[16:31], v[200:203], v[184:187], v[16:31]
	v_mfma_f32_32x32x16_bf16 v[0:15], v[204:207], v[184:187], v[0:15]
	s_waitcnt lgkmcnt(0)
	v_mfma_f32_32x32x16_bf16 v[112:127], v[188:191], v[156:159], v[112:127]
	ds_read_b128 v[200:203], v209 offset:32768
	ds_read_b128 v[172:175], v199 offset:32768
	v_mfma_f32_32x32x16_bf16 v[96:111], v[192:195], v[156:159], v[96:111]
	ds_read_b128 v[204:207], v209 offset:34816
	ds_read_b128 v[176:179], v199 offset:34816
	v_mfma_f32_32x32x16_bf16 v[80:95], v[188:191], v[160:163], v[80:95]
	ds_read_b128 v[180:183], v199 offset:36864
	ds_read_b128 v[184:187], v199 offset:38912
	v_mfma_f32_32x32x16_bf16 v[64:79], v[192:195], v[160:163], v[64:79]
	v_mfma_f32_32x32x16_bf16 v[48:63], v[188:191], v[164:167], v[48:63]
	v_mfma_f32_32x32x16_bf16 v[32:47], v[192:195], v[164:167], v[32:47]
	v_mfma_f32_32x32x16_bf16 v[16:31], v[188:191], v[168:171], v[16:31]
	v_mfma_f32_32x32x16_bf16 v[0:15], v[192:195], v[168:171], v[0:15]
	s_waitcnt lgkmcnt(0)
	s_waitcnt vmcnt(8)
	s_barrier
	s_waitcnt lgkmcnt(0)
	v_mfma_f32_32x32x16_bf16 v[112:127], v[200:203], v[172:175], v[112:127]
	ds_read_b128 v[188:191], v212
	ds_read_b128 v[156:159], v210
	v_mfma_f32_32x32x16_bf16 v[96:111], v[204:207], v[172:175], v[96:111]
	ds_read_b128 v[192:195], v212 offset:2048
	ds_read_b128 v[160:163], v210 offset:2048
	v_mfma_f32_32x32x16_bf16 v[80:95], v[200:203], v[176:179], v[80:95]
	ds_read_b128 v[164:167], v210 offset:4096
	ds_read_b128 v[168:171], v210 offset:6144
	v_mfma_f32_32x32x16_bf16 v[64:79], v[204:207], v[176:179], v[64:79]
	v_mfma_f32_32x32x16_bf16 v[48:63], v[200:203], v[180:183], v[48:63]
	v_mfma_f32_32x32x16_bf16 v[32:47], v[204:207], v[180:183], v[32:47]
	v_mfma_f32_32x32x16_bf16 v[16:31], v[200:203], v[184:187], v[16:31]
	v_mfma_f32_32x32x16_bf16 v[0:15], v[204:207], v[184:187], v[0:15]
	s_waitcnt lgkmcnt(0)
	v_mfma_f32_32x32x16_bf16 v[112:127], v[188:191], v[156:159], v[112:127]
	ds_read_b128 v[200:203], v213
	ds_read_b128 v[172:175], v211
	v_mfma_f32_32x32x16_bf16 v[96:111], v[192:195], v[156:159], v[96:111]
	ds_read_b128 v[204:207], v213 offset:2048
	ds_read_b128 v[176:179], v211 offset:2048
	v_mfma_f32_32x32x16_bf16 v[80:95], v[188:191], v[160:163], v[80:95]
	ds_read_b128 v[180:183], v211 offset:4096
	ds_read_b128 v[184:187], v211 offset:6144
	v_mfma_f32_32x32x16_bf16 v[64:79], v[192:195], v[160:163], v[64:79]
	v_mfma_f32_32x32x16_bf16 v[48:63], v[188:191], v[164:167], v[48:63]
	v_mfma_f32_32x32x16_bf16 v[32:47], v[192:195], v[164:167], v[32:47]
	v_mfma_f32_32x32x16_bf16 v[16:31], v[188:191], v[168:171], v[16:31]
	v_mfma_f32_32x32x16_bf16 v[0:15], v[192:195], v[168:171], v[0:15]
	s_waitcnt lgkmcnt(0)
	s_waitcnt vmcnt(4)
	s_barrier
	s_waitcnt lgkmcnt(0)
	v_mfma_f32_32x32x16_bf16 v[112:127], v[200:203], v[172:175], v[112:127]
	ds_read_b128 v[188:191], v154
	ds_read_b128 v[156:159], v132
	v_mfma_f32_32x32x16_bf16 v[96:111], v[204:207], v[172:175], v[96:111]
	ds_read_b128 v[192:195], v154 offset:2048
	ds_read_b128 v[160:163], v132 offset:2048
	v_mfma_f32_32x32x16_bf16 v[80:95], v[200:203], v[176:179], v[80:95]
	ds_read_b128 v[164:167], v132 offset:4096
	ds_read_b128 v[168:171], v132 offset:6144
	v_mfma_f32_32x32x16_bf16 v[64:79], v[204:207], v[176:179], v[64:79]
	v_mfma_f32_32x32x16_bf16 v[48:63], v[200:203], v[180:183], v[48:63]
	v_mfma_f32_32x32x16_bf16 v[32:47], v[204:207], v[180:183], v[32:47]
	v_mfma_f32_32x32x16_bf16 v[16:31], v[200:203], v[184:187], v[16:31]
	v_mfma_f32_32x32x16_bf16 v[0:15], v[204:207], v[184:187], v[0:15]
	s_waitcnt lgkmcnt(0)
	v_mfma_f32_32x32x16_bf16 v[112:127], v[188:191], v[156:159], v[112:127]
	ds_read_b128 v[200:203], v155
	ds_read_b128 v[172:175], v153
	v_mfma_f32_32x32x16_bf16 v[96:111], v[192:195], v[156:159], v[96:111]
	ds_read_b128 v[204:207], v155 offset:2048
	ds_read_b128 v[176:179], v153 offset:2048
	v_mfma_f32_32x32x16_bf16 v[80:95], v[188:191], v[160:163], v[80:95]
	ds_read_b128 v[180:183], v153 offset:4096
	ds_read_b128 v[184:187], v153 offset:6144
	v_mfma_f32_32x32x16_bf16 v[64:79], v[192:195], v[160:163], v[64:79]
	v_mfma_f32_32x32x16_bf16 v[48:63], v[188:191], v[164:167], v[48:63]
	v_mfma_f32_32x32x16_bf16 v[32:47], v[192:195], v[164:167], v[32:47]
	v_mfma_f32_32x32x16_bf16 v[16:31], v[188:191], v[168:171], v[16:31]
	v_mfma_f32_32x32x16_bf16 v[0:15], v[192:195], v[168:171], v[0:15]
	s_waitcnt lgkmcnt(0)
	s_waitcnt vmcnt(0)
	s_barrier
; DI unsigned pack2(float a, float b) { f2_t f = {a, b}; bf2_t r = __builtin_convertvector(f, bf2_t); return __builtin_bit_cast(unsigned, r); }
; DI int tid512() { int t = threadIdx_x_raw(); asm volatile("" : "+v"(t)); return t; }
; template <class AL, class BL, class EP>
; DI void gemm_tile256(AL al, BL bl, EP ep, int K, char* smem) {
;     ...
;   if constexpr (EP::kBf16) {
;     bf16_t* sCb = (bf16_t*)smem;
; #pragma unroll
;     for (int i = 0; i < 4; ++i)
; #pragma unroll
;       for (int j = 0; j < 2; ++j)
; #pragma unroll
;         for (int g = 0; g < 4; ++g) {
;           u32x2 v = {pack2(acc[i][j][4 * g], acc[i][j][4 * g + 1]), pack2(acc[i][j][4 * g + 2], acc[i][j][4 * g + 3])};
;           *(u32x2*)(sCb + (128 * wm + 32 * i + r) * BLD + 64 * wn + 32 * j + 8 * g + 4 * h) = v;
;         }
;     __syncthreads();
;   DI void operator()(bf16_t* sCb) const {
;     const int b = m0 >> 12, s0 = m0 & 4095;
;     char* ws = p->ws;
;     if (nt2 < 4) {
;       const float2* rope = (const float2*)(ws + OFF_ROPER);
;       const float sc = (nt2 >= 2) ? 0.08838834764831845f : 1.f;
;       for (int id = tid512(); id < 256 * 128; id += 512) {
;         int row = id >> 7, hf = (id >> 6) & 1, i = id & 63;
;         float2 cs = rope[(size_t)(s0 + row) * 64 + i];
	s_waitcnt lgkmcnt(0)
	v_mfma_f32_32x32x16_bf16 v[112:127], v[200:203], v[172:175], v[112:127]
	ds_read_b128 v[188:191], v154 offset:32768
	ds_read_b128 v[156:159], v132 offset:32768
	v_mfma_f32_32x32x16_bf16 v[96:111], v[204:207], v[172:175], v[96:111]
	ds_read_b128 v[192:195], v154 offset:34816
	ds_read_b128 v[160:163], v132 offset:34816
	v_mfma_f32_32x32x16_bf16 v[80:95], v[200:203], v[176:179], v[80:95]
	ds_read_b128 v[164:167], v132 offset:36864
	ds_read_b128 v[168:171], v132 offset:38912
	v_mfma_f32_32x32x16_bf16 v[64:79], v[204:207], v[176:179], v[64:79]
	v_mfma_f32_32x32x16_bf16 v[48:63], v[200:203], v[180:183], v[48:63]
	v_mfma_f32_32x32x16_bf16 v[32:47], v[204:207], v[180:183], v[32:47]
	v_mfma_f32_32x32x16_bf16 v[16:31], v[200:203], v[184:187], v[16:31]
	v_mfma_f32_32x32x16_bf16 v[0:15], v[204:207], v[184:187], v[0:15]
	s_waitcnt lgkmcnt(0)
	v_mfma_f32_32x32x16_bf16 v[112:127], v[188:191], v[156:159], v[112:127]
	ds_read_b128 v[200:203], v155 offset:32768
	ds_read_b128 v[172:175], v153 offset:32768
	v_mfma_f32_32x32x16_bf16 v[96:111], v[192:195], v[156:159], v[96:111]
	ds_read_b128 v[204:207], v155 offset:34816
	ds_read_b128 v[176:179], v153 offset:34816
	v_mfma_f32_32x32x16_bf16 v[80:95], v[188:191], v[160:163], v[80:95]
	ds_read_b128 v[180:183], v153 offset:36864
	ds_read_b128 v[184:187], v153 offset:38912
	v_mfma_f32_32x32x16_bf16 v[64:79], v[192:195], v[160:163], v[64:79]
	v_mfma_f32_32x32x16_bf16 v[48:63], v[188:191], v[164:167], v[48:63]
	v_mfma_f32_32x32x16_bf16 v[32:47], v[192:195], v[164:167], v[32:47]
	v_mfma_f32_32x32x16_bf16 v[16:31], v[188:191], v[168:171], v[16:31]
	v_mfma_f32_32x32x16_bf16 v[0:15], v[192:195], v[168:171], v[0:15]
	s_waitcnt lgkmcnt(0)
	s_waitcnt lgkmcnt(0)
	v_mfma_f32_32x32x16_bf16 v[112:127], v[200:203], v[172:175], v[112:127]
	v_mfma_f32_32x32x16_bf16 v[96:111], v[204:207], v[172:175], v[96:111]
	v_mfma_f32_32x32x16_bf16 v[80:95], v[200:203], v[176:179], v[80:95]
	v_mfma_f32_32x32x16_bf16 v[64:79], v[204:207], v[176:179], v[64:79]
	v_mfma_f32_32x32x16_bf16 v[48:63], v[200:203], v[180:183], v[48:63]
	v_mfma_f32_32x32x16_bf16 v[32:47], v[204:207], v[180:183], v[32:47]
	v_mfma_f32_32x32x16_bf16 v[16:31], v[200:203], v[184:187], v[16:31]
	v_mfma_f32_32x32x16_bf16 v[0:15], v[204:207], v[184:187], v[0:15]
	s_nop 15
	s_nop 3
	v_lshl_or_b32 v128, v133, 7, v152
	s_waitcnt lgkmcnt(4)
	v_mad_u64_u32 v[130:131], s[4:5], v151, s46, v[128:129]
	s_and_b32 s24, s52, 0xf00
	s_waitcnt lgkmcnt(0)
	s_barrier
	s_cmp_gt_i32 s20, 3
	s_nop 5
	v_cvt_pk_bf16_f32 v112, v112, v113
	v_cvt_pk_bf16_f32 v113, v114, v115
	v_cvt_pk_bf16_f32 v114, v116, v117
	v_cvt_pk_bf16_f32 v115, v118, v119
	ds_write2_b64 v130, v[112:113], v[114:115] offset1:2
	v_cvt_pk_bf16_f32 v112, v120, v121
	v_cvt_pk_bf16_f32 v113, v122, v123
	v_cvt_pk_bf16_f32 v96, v96, v97
	v_cvt_pk_bf16_f32 v97, v98, v99
	v_cvt_pk_bf16_f32 v98, v100, v101
	v_cvt_pk_bf16_f32 v99, v102, v103
	v_cvt_pk_bf16_f32 v114, v124, v125
	v_cvt_pk_bf16_f32 v115, v126, v127
	ds_write2_b64 v130, v[96:97], v[98:99] offset0:8 offset1:10
	s_nop 3
	v_cvt_pk_bf16_f32 v80, v80, v81
	v_cvt_pk_bf16_f32 v81, v82, v83
	v_cvt_pk_bf16_f32 v82, v84, v85
	v_cvt_pk_bf16_f32 v83, v86, v87
	v_add_u32_e32 v84, 0x4000, v130
	v_cvt_pk_bf16_f32 v96, v104, v105
	v_cvt_pk_bf16_f32 v97, v106, v107
	v_cvt_pk_bf16_f32 v64, v64, v65
	v_cvt_pk_bf16_f32 v65, v66, v67
	v_cvt_pk_bf16_f32 v66, v68, v69
	v_cvt_pk_bf16_f32 v67, v70, v71
	v_cvt_pk_bf16_f32 v98, v108, v109
	v_cvt_pk_bf16_f32 v99, v110, v111
	ds_write2_b64 v84, v[80:81], v[82:83] offset0:64 offset1:66
	s_nop 3
	v_cvt_pk_bf16_f32 v48, v48, v49
	v_cvt_pk_bf16_f32 v49, v50, v51
	v_cvt_pk_bf16_f32 v50, v52, v53
	v_cvt_pk_bf16_f32 v51, v54, v55
	v_add_u32_e32 v52, 0x8000, v130
	v_cvt_pk_bf16_f32 v80, v88, v89
	v_cvt_pk_bf16_f32 v81, v90, v91
	v_cvt_pk_bf16_f32 v32, v32, v33
	v_cvt_pk_bf16_f32 v33, v34, v35
	v_cvt_pk_bf16_f32 v34, v36, v37
	v_cvt_pk_bf16_f32 v35, v38, v39
	v_cvt_pk_bf16_f32 v82, v92, v93
	v_cvt_pk_bf16_f32 v83, v94, v95
	ds_write2_b64 v84, v[64:65], v[66:67] offset0:72 offset1:74
	s_nop 3
	v_cvt_pk_bf16_f32 v16, v16, v17
	v_cvt_pk_bf16_f32 v17, v18, v19
	v_cvt_pk_bf16_f32 v18, v20, v21
	v_cvt_pk_bf16_f32 v19, v22, v23
	v_add_u32_e32 v20, 0xc000, v130
	v_cvt_pk_bf16_f32 v64, v72, v73
	v_cvt_pk_bf16_f32 v65, v74, v75
	s_nop 0
	v_cvt_pk_bf16_f32 v0, v0, v1
	v_cvt_pk_bf16_f32 v1, v2, v3
	v_cvt_pk_bf16_f32 v2, v4, v5
	v_cvt_pk_bf16_f32 v3, v6, v7
	v_cvt_pk_bf16_f32 v66, v76, v77
	v_cvt_pk_bf16_f32 v67, v78, v79
	ds_write2_b64 v52, v[48:49], v[50:51] offset0:128 offset1:130
	v_cvt_pk_bf16_f32 v48, v56, v57
	v_cvt_pk_bf16_f32 v49, v58, v59
	v_cvt_pk_bf16_f32 v50, v60, v61
	v_cvt_pk_bf16_f32 v51, v62, v63
	ds_write2_b64 v52, v[32:33], v[34:35] offset0:136 offset1:138
	v_cvt_pk_bf16_f32 v32, v40, v41
	v_cvt_pk_bf16_f32 v33, v42, v43
	v_cvt_pk_bf16_f32 v34, v44, v45
	v_cvt_pk_bf16_f32 v35, v46, v47
	ds_write2_b64 v20, v[16:17], v[18:19] offset0:192 offset1:194
	v_cvt_pk_bf16_f32 v16, v24, v25
	v_cvt_pk_bf16_f32 v17, v26, v27
	v_cvt_pk_bf16_f32 v18, v28, v29
	v_cvt_pk_bf16_f32 v19, v30, v31
	ds_write2_b64 v20, v[0:1], v[2:3] offset0:200 offset1:202
	v_cvt_pk_bf16_f32 v0, v8, v9
	v_cvt_pk_bf16_f32 v1, v10, v11
	v_cvt_pk_bf16_f32 v2, v12, v13
	v_cvt_pk_bf16_f32 v3, v14, v15
	ds_write2_b64 v130, v[112:113], v[114:115] offset0:4 offset1:6
	ds_write2_b64 v130, v[96:97], v[98:99] offset0:12 offset1:14
	ds_write2_b64 v84, v[80:81], v[82:83] offset0:68 offset1:70
	ds_write2_b64 v84, v[64:65], v[66:67] offset0:76 offset1:78
	ds_write2_b64 v52, v[48:49], v[50:51] offset0:132 offset1:134
	ds_write2_b64 v52, v[32:33], v[34:35] offset0:140 offset1:142
	ds_write2_b64 v20, v[16:17], v[18:19] offset0:196 offset1:198
	ds_write2_b64 v20, v[0:1], v[2:3] offset0:204 offset1:206
	s_waitcnt lgkmcnt(0)
	s_barrier
	s_cbranch_scc1 .LBB0_771
	v_mov_b32_e32 v2, v196
	s_nop 0
	v_cmp_gt_i32_e32 vcc, s47, v2
	s_and_saveexec_b64 s[4:5], vcc
	s_cbranch_execz .LBB0_770
	s_cmp_gt_i32 s20, 1
	v_and_b32_e32 v4, 63, v2
	s_cselect_b64 vcc, -1, 0
	v_lshlrev_b32_e32 v128, 3, v4
	v_cndmask_b32_e32 v3, 1.0, v150, vcc
	v_lshl_add_u64 v[0:1], s[2:3], 0, v[128:129]
	v_lshlrev_b32_e32 v5, 1, v2
	s_mov_b64 s[6:7], 0

; DI void hyena_conv_unit(const Params& p, int item, char* smem) {
;     ...
;   const bf16_t* G = (const bf16_t*)(p.ws + OFF_FILT) + (size_t)c * 8192;
;   __syncthreads();
;   for (int x = tid; x < 8192; x += 256) {
;     bf16_t v = G[8191 - x];
;     sG0[x] = v;
;     if (x >= 1) sG1[x - 1] = v;
;   }
;   if (tid == 0) sG1[8191] = 0;
.LBB0_913:
	s_or_b64 exec, exec, s[0:1]
	v_xor_b32_e32 v4, 0x18ff, v0
	v_xor_b32_e32 v5, 0x19ff, v0
	v_xor_b32_e32 v6, 0x1aff, v0
	v_xor_b32_e32 v7, 0x1bff, v0
	v_xor_b32_e32 v8, 0x14ff, v0
	v_xor_b32_e32 v9, 0x15ff, v0
	v_xor_b32_e32 v10, 0x16ff, v0
	v_xor_b32_e32 v11, 0x17ff, v0
	v_xor_b32_e32 v12, 0x10ff, v0
	v_xor_b32_e32 v13, 0x11ff, v0
	v_xor_b32_e32 v14, 0x12ff, v0
	v_xor_b32_e32 v15, 0x13ff, v0
	v_xor_b32_e32 v16, 0xcff, v0
	v_xor_b32_e32 v17, 0xdff, v0
	v_xor_b32_e32 v18, 0xeff, v0
	v_xor_b32_e32 v19, 0xfff, v0
	v_xor_b32_e32 v20, 0x8ff, v0
	v_xor_b32_e32 v21, 0x9ff, v0
	v_xor_b32_e32 v22, 0xaff, v0
	v_xor_b32_e32 v23, 0xbff, v0
	v_xor_b32_e32 v24, 0x4ff, v0
	v_xor_b32_e32 v25, 0x5ff, v0
	v_xor_b32_e32 v26, 0x6ff, v0
	v_xor_b32_e32 v27, 0x7ff, v0
	v_xor_b32_e32 v28, 0xff, v0
	v_xor_b32_e32 v29, 0x1ff, v0
	v_xor_b32_e32 v30, 0x2ff, v0
	v_xor_b32_e32 v31, 0x3ff, v0
	v_lshlrev_b32_e32 v7, 1, v7
	v_lshlrev_b32_e32 v6, 1, v6
	v_lshlrev_b32_e32 v5, 1, v5
	v_lshlrev_b32_e32 v4, 1, v4
	v_lshlrev_b32_e32 v11, 1, v11
	v_lshlrev_b32_e32 v10, 1, v10
	v_lshlrev_b32_e32 v9, 1, v9
	v_lshlrev_b32_e32 v8, 1, v8
	v_lshlrev_b32_e32 v15, 1, v15
	v_lshlrev_b32_e32 v14, 1, v14
	v_lshlrev_b32_e32 v13, 1, v13
	v_lshlrev_b32_e32 v12, 1, v12
	v_lshlrev_b32_e32 v19, 1, v19
	v_lshlrev_b32_e32 v18, 1, v18
	v_lshlrev_b32_e32 v17, 1, v17
	v_lshlrev_b32_e32 v16, 1, v16
	v_lshlrev_b32_e32 v23, 1, v23
	v_lshlrev_b32_e32 v22, 1, v22
	v_lshlrev_b32_e32 v21, 1, v21
	v_lshlrev_b32_e32 v20, 1, v20
	v_lshlrev_b32_e32 v27, 1, v27
	v_lshlrev_b32_e32 v26, 1, v26
	v_lshlrev_b32_e32 v25, 1, v25
	v_lshlrev_b32_e32 v24, 1, v24
	v_lshlrev_b32_e32 v31, 1, v31
	v_lshlrev_b32_e32 v30, 1, v30
	v_lshlrev_b32_e32 v29, 1, v29
	v_lshlrev_b32_e32 v28, 1, v28
	global_load_ushort v7, v7, s[22:23]
	s_nop 0
	global_load_ushort v6, v6, s[22:23]
	s_nop 0
	global_load_ushort v5, v5, s[22:23]
	s_nop 0
	global_load_ushort v4, v4, s[22:23]
	s_nop 0
	global_load_ushort v11, v11, s[22:23]
	s_nop 0
	global_load_ushort v10, v10, s[22:23]
	s_nop 0
	global_load_ushort v9, v9, s[22:23]
	s_nop 0
	global_load_ushort v8, v8, s[22:23]
	s_nop 0
	global_load_ushort v15, v15, s[22:23]
	s_nop 0
	global_load_ushort v14, v14, s[22:23]
	s_nop 0
	global_load_ushort v13, v13, s[22:23]
	s_nop 0
	global_load_ushort v12, v12, s[22:23]
	s_nop 0
	global_load_ushort v19, v19, s[22:23]
	s_nop 0
	global_load_ushort v18, v18, s[22:23]
	s_nop 0
	global_load_ushort v17, v17, s[22:23]
	s_nop 0
	global_load_ushort v16, v16, s[22:23]
	s_nop 0
	global_load_ushort v23, v23, s[22:23]
	s_nop 0
	global_load_ushort v22, v22, s[22:23]
	s_nop 0
	global_load_ushort v21, v21, s[22:23]
	s_nop 0
	global_load_ushort v20, v20, s[22:23]
	s_nop 0
	global_load_ushort v27, v27, s[22:23]
	s_nop 0
	global_load_ushort v26, v26, s[22:23]
	s_nop 0
	global_load_ushort v25, v25, s[22:23]
	s_nop 0
	global_load_ushort v24, v24, s[22:23]
	s_nop 0
	global_load_ushort v31, v31, s[22:23]
	s_nop 0
	global_load_ushort v30, v30, s[22:23]
	s_nop 0
	global_load_ushort v29, v29, s[22:23]
	s_nop 0
	global_load_ushort v28, v28, s[22:23]
	v_cmp_eq_u32_e32 vcc, 0, v0
	s_waitcnt vmcnt(27)
	ds_write_b16 v3, v7 offset:2048
	s_waitcnt vmcnt(26)
	ds_write_b16 v3, v6 offset:2560
	s_waitcnt vmcnt(25)
	ds_write_b16 v3, v5 offset:3072
	s_waitcnt vmcnt(24)
	ds_write_b16 v3, v4 offset:3584
	ds_write_b16 v3, v7 offset:18446
	ds_write_b16 v3, v6 offset:18958
	ds_write_b16 v3, v5 offset:19470
	ds_write_b16 v3, v4 offset:19982
	s_waitcnt vmcnt(23)
	ds_write_b16 v3, v11 offset:4096
	s_waitcnt vmcnt(22)
	ds_write_b16 v3, v10 offset:4608
	s_waitcnt vmcnt(21)
	ds_write_b16 v3, v9 offset:5120
	s_waitcnt vmcnt(20)
	ds_write_b16 v3, v8 offset:5632
	ds_write_b16 v3, v11 offset:20494
	ds_write_b16 v3, v10 offset:21006
	ds_write_b16 v3, v9 offset:21518
	ds_write_b16 v3, v8 offset:22030
	s_waitcnt vmcnt(19)
	ds_write_b16 v3, v15 offset:6144
	s_waitcnt vmcnt(18)
	ds_write_b16 v3, v14 offset:6656
	s_waitcnt vmcnt(17)
	ds_write_b16 v3, v13 offset:7168
	s_waitcnt vmcnt(16)
	ds_write_b16 v3, v12 offset:7680
	ds_write_b16 v3, v15 offset:22542
	ds_write_b16 v3, v14 offset:23054
	ds_write_b16 v3, v13 offset:23566
	ds_write_b16 v3, v12 offset:24078
	s_waitcnt vmcnt(15)
	ds_write_b16 v3, v19 offset:8192
	s_waitcnt vmcnt(14)
	ds_write_b16 v3, v18 offset:8704
	s_waitcnt vmcnt(13)
	ds_write_b16 v3, v17 offset:9216
	s_waitcnt vmcnt(12)
	ds_write_b16 v3, v16 offset:9728
	ds_write_b16 v3, v19 offset:24590
	ds_write_b16 v3, v18 offset:25102
	ds_write_b16 v3, v17 offset:25614
	ds_write_b16 v3, v16 offset:26126
	s_waitcnt vmcnt(11)
	ds_write_b16 v3, v23 offset:10240
	s_waitcnt vmcnt(10)
	ds_write_b16 v3, v22 offset:10752
	s_waitcnt vmcnt(9)
	ds_write_b16 v3, v21 offset:11264
	s_waitcnt vmcnt(8)
	ds_write_b16 v3, v20 offset:11776
	ds_write_b16 v3, v23 offset:26638
	ds_write_b16 v3, v22 offset:27150
	ds_write_b16 v3, v21 offset:27662
	ds_write_b16 v3, v20 offset:28174
	s_waitcnt vmcnt(7)
	ds_write_b16 v3, v27 offset:12288
	s_waitcnt vmcnt(6)
	ds_write_b16 v3, v26 offset:12800
	s_waitcnt vmcnt(5)
	ds_write_b16 v3, v25 offset:13312
	s_waitcnt vmcnt(4)
	ds_write_b16 v3, v24 offset:13824
	ds_write_b16 v3, v27 offset:28686
	ds_write_b16 v3, v26 offset:29198
	ds_write_b16 v3, v25 offset:29710
	ds_write_b16 v3, v24 offset:30222
	s_waitcnt vmcnt(3)
	ds_write_b16 v3, v31 offset:14336
	s_waitcnt vmcnt(2)
	ds_write_b16 v3, v30 offset:14848
	s_waitcnt vmcnt(1)
	ds_write_b16 v3, v29 offset:15360
	s_waitcnt vmcnt(0)
; DI void hyena_conv_unit(const Params& p, int item, char* smem) {
;     ...
;   {
;     const bf16_t* ub = (const bf16_t*)(p.hbuf + HB_UT) + ((size_t)c * 8 + b) * 4096;
;     bf16_t* su = sU + w * 64 * 72;
; #pragma unroll
;     for (int i = 0; i < 8; ++i) { int id = lane + 64 * i; int row = id >> 3, ck = id & 7; *(u32x4*)(su + row * 72 + ck * 8) = ldg16(ub + row * 64 + ck * 8); }
;   }
;   __syncthreads();
;   const int n = lane & 15, g = lane >> 4;
;   const bf16_t* su = sU + w * 64 * 72;
;   f32x4 acc[4][4];
; #pragma unroll
;   for (int i = 0; i < 4; ++i)
; #pragma unroll
;     for (int j = 0; j < 4; ++j) { acc[i][j][0] = 0.f; acc[i][j][1] = 0.f; acc[i][j][2] = 0.f; acc[i][j][3] = 0.f; }
;     ...
;           u32x4 a = zero4();
;           if (s1 >= 0 && s1 < 64) a = *(const u32x4*)(su + s1 * 72 + 32 * kk + 8 * g);
	ds_write_b16 v3, v28 offset:15872
	ds_write_b16 v3, v31 offset:30734
	ds_write_b16 v3, v30 offset:31246
	ds_write_b16 v3, v29 offset:31758
	ds_write_b16 v3, v28 offset:32270
	s_and_saveexec_b64 s[0:1], vcc
	v_mov_b32_e32 v3, s27
	ds_write_b16 v3, v1 offset:32782
	s_or_b64 exec, exec, s[0:1]
	s_lshl_b32 s0, s26, 2
	v_lshrrev_b32_e32 v3, 6, v0
	v_and_or_b32 v3, s0, 4, v3
	s_lshl_b64 s[0:1], s[20:21], 15
	v_lshl_or_b32 v88, v3, 12, s0
	v_mov_b32_e32 v89, s1
	v_lshlrev_b32_e32 v0, 4, v0
	v_lshl_add_u64 v[4:5], v[88:89], 1, s[84:85]
	v_and_b32_e32 v0, 0x70, v0
	v_bfe_u32 v10, v2, 3, 3
	v_and_b32_e32 v12, 0xc0, v2
	v_mov_b32_e32 v13, s27
	v_lshl_add_u64 v[4:5], v[4:5], 0, v[0:1]
	v_lshlrev_b32_e32 v6, 7, v10
	v_mov_b32_e32 v7, v1
	v_mad_u32_u24 v3, v12, s55, v13
	v_lshl_add_u64 v[8:9], v[4:5], 0, v[6:7]
	v_mul_u32_u24_e32 v7, 0x90, v10
	v_add3_u32 v106, v3, v0, v7
	v_or_b32_e32 v0, 0x400, v6
	v_lshl_add_u64 v[10:11], v[4:5], 0, v[0:1]
	v_or_b32_e32 v0, 0x800, v6
	global_load_dwordx4 v[64:67], v[8:9], off
	global_load_dwordx4 v[68:71], v[10:11], off
	v_lshl_add_u64 v[8:9], v[4:5], 0, v[0:1]
	v_or_b32_e32 v0, 0xc00, v6
	v_lshl_add_u64 v[10:11], v[4:5], 0, v[0:1]
	v_or_b32_e32 v0, 0x1000, v6
	global_load_dwordx4 v[72:75], v[8:9], off
	global_load_dwordx4 v[76:79], v[10:11], off
	v_lshl_add_u64 v[8:9], v[4:5], 0, v[0:1]
	v_or_b32_e32 v0, 0x1400, v6
	v_lshl_add_u64 v[10:11], v[4:5], 0, v[0:1]
	v_or_b32_e32 v0, 0x1800, v6
	global_load_dwordx4 v[80:83], v[8:9], off
	global_load_dwordx4 v[84:87], v[10:11], off
	v_lshl_add_u64 v[8:9], v[4:5], 0, v[0:1]
	v_or_b32_e32 v0, 0x1c00, v6
	v_lshl_add_u64 v[4:5], v[4:5], 0, v[0:1]
	global_load_dwordx4 v[98:101], v[8:9], off
	global_load_dwordx4 v[102:105], v[4:5], off
	v_and_b32_e32 v93, 15, v2
	v_and_b32_e32 v0, 1, v2
	v_and_b32_e32 v5, 48, v2
	v_mov_b32_e32 v4, s28
	v_cmp_eq_u32_e32 vcc, 0, v0
	v_mul_u32_u24_e32 v6, 0x90, v93
	v_lshl_or_b32 v0, v0, 1, v5
	v_lshlrev_b32_e32 v7, 1, v93
	v_bfe_u32 v94, v2, 4, 2
	v_mov_b32_e32 v2, v1
	v_mov_b32_e32 v3, v1
	v_cndmask_b32_e32 v4, v13, v4, vcc
	v_mad_u32_u24 v6, v12, s55, v6
	v_sub_u32_e32 v0, v0, v7
	v_add3_u32 v96, v6, v5, s33
	v_add3_u32 v97, v4, v0, s10
	v_mov_b32_e32 v0, v1
	v_mov_b64_e32 v[6:7], v[2:3]
	v_mov_b64_e32 v[10:11], v[2:3]
	v_mov_b64_e32 v[14:15], v[2:3]
	v_mov_b64_e32 v[18:19], v[2:3]
	v_mov_b64_e32 v[22:23], v[2:3]
	v_mov_b64_e32 v[26:27], v[2:3]
	v_mov_b64_e32 v[30:31], v[2:3]
	v_mov_b64_e32 v[34:35], v[2:3]
	v_mov_b64_e32 v[38:39], v[2:3]
	v_mov_b64_e32 v[42:43], v[2:3]
	v_mov_b64_e32 v[46:47], v[2:3]
	v_mov_b64_e32 v[50:51], v[2:3]
	v_mov_b64_e32 v[54:55], v[2:3]
	v_mov_b64_e32 v[58:59], v[2:3]
	v_mov_b64_e32 v[62:63], v[2:3]
	s_movk_i32 s24, 0xffc1
	v_add_u32_e32 v95, 0x6f, v93
	v_mov_b64_e32 v[4:5], v[0:1]
	v_mov_b64_e32 v[8:9], v[0:1]
	v_mov_b64_e32 v[12:13], v[0:1]
	v_mov_b64_e32 v[16:17], v[0:1]
	v_mov_b64_e32 v[20:21], v[0:1]
	v_mov_b64_e32 v[24:25], v[0:1]
	v_mov_b64_e32 v[28:29], v[0:1]
	v_mov_b64_e32 v[32:33], v[0:1]
	v_mov_b64_e32 v[36:37], v[0:1]
	v_mov_b64_e32 v[40:41], v[0:1]
	v_mov_b64_e32 v[44:45], v[0:1]
	v_mov_b64_e32 v[48:49], v[0:1]
	v_mov_b64_e32 v[52:53], v[0:1]
	v_mov_b64_e32 v[56:57], v[0:1]
	v_mov_b64_e32 v[60:61], v[0:1]
	s_waitcnt vmcnt(7)
	ds_write_b128 v106, v[64:67] offset:32800
	s_waitcnt vmcnt(6)
	ds_write_b128 v106, v[68:71] offset:33952
	s_waitcnt vmcnt(5)
	ds_write_b128 v106, v[72:75] offset:35104
	s_waitcnt vmcnt(4)
	ds_write_b128 v106, v[76:79] offset:36256
	s_waitcnt vmcnt(3)
	ds_write_b128 v106, v[80:83] offset:37408
	s_waitcnt vmcnt(2)
	ds_write_b128 v106, v[84:87] offset:38560
	s_waitcnt vmcnt(1)
	ds_write_b128 v106, v[98:101] offset:39712
	s_waitcnt vmcnt(0)
	ds_write_b128 v106, v[102:105] offset:40864
	v_mov_b64_e32 v[66:67], v[2:3]
	v_mov_b64_e32 v[64:65], v[0:1]
	s_waitcnt lgkmcnt(0)
	s_barrier
	v_mov_b32_e32 v80, 0
	v_mov_b32_e32 v81, 0
	v_mov_b32_e32 v82, 0
	v_mov_b32_e32 v83, 0
	v_and_b32_e32 v84, 7, v196
	v_lshlrev_b32_e32 v84, 4, v84
	s_add_u32 s22, s27, 0x11020
	v_add_u32_e32 v84, s22, v84
	ds_write_b128 v84, v[80:83]
	s_sub_u32 s23, s22, 0
	v_mov_b32_e32 v68, s23
	s_sub_u32 s23, s22, 2304
	v_mov_b32_e32 v69, s23
	s_sub_u32 s23, s22, 4608
	v_mov_b32_e32 v70, s23
	s_sub_u32 s23, s22, 6912
	v_mov_b32_e32 v71, s23
	s_waitcnt lgkmcnt(0)
	ds_read2_b32 v[172:173], v97 offset0:40 offset1:41
	ds_read2_b32 v[174:175], v97 offset0:42 offset1:43
	ds_read2_b32 v[176:177], v97 offset0:32 offset1:33
	ds_read2_b32 v[178:179], v97 offset0:34 offset1:35
	ds_read2_b32 v[180:181], v97 offset0:24 offset1:25
	ds_read2_b32 v[182:183], v97 offset0:26 offset1:27
	ds_read2_b32 v[184:185], v97 offset0:16 offset1:17
	ds_read2_b32 v[186:187], v97 offset0:18 offset1:19
	ds_read2_b32 v[188:189], v97 offset0:8 offset1:9
	ds_read2_b32 v[190:191], v97 offset0:10 offset1:11
	ds_read2_b32 v[192:193], v97 offset0:0 offset1:1
	ds_read2_b32 v[194:195], v97 offset0:2 offset1:3
	v_add_u32_e32 v72, 0xffffffd0, v95
	v_cmp_gt_u32_e64 s[0:1], 64, v72
	s_nop 1
	v_cndmask_b32_e64 v76, v68, v96, s[0:1]
	ds_read_b128 v[132:135], v76 offset:0
	ds_read_b128 v[136:139], v76 offset:64
	s_mov_b32 s24, 7
; #define MFMA16(a, b, c) __builtin_amdgcn_mfma_f32_16x16x32_bf16(__builtin_bit_cast(bf16x8, (a)), __builtin_bit_cast(bf16x8, (b)), (c), 0, 0, 0)
; DI void hyena_conv_unit(const Params& p, int item, char* smem) {
;     ...
;   for (int d = -63; d <= 63; ++d) {
; #pragma unroll
;     for (int kk = 0; kk < 2; ++kk) {
;       u32x4 bfr[4];
; #pragma unroll
;       for (int nn = 0; nn < 4; ++nn) bfr[nn] = bfrag(4 * d + nn - 2 * kk);
; #pragma unroll
;       for (int rb = 0; rb < 4; ++rb) {
;         if (d >= 16 * rb - 63 && d <= 16 * rb + 15) {
;           int t1 = 16 * rb + n, s1 = t1 - d;
;           u32x4 a = zero4();
;           if (s1 >= 0 && s1 < 64) a = *(const u32x4*)(su + s1 * 72 + 32 * kk + 8 * g);
; #pragma unroll
;           for (int nn = 0; nn < 4; ++nn) acc[rb][nn] = MFMA16(a, bfr[nn], acc[rb][nn]);
;         }
;       }
;     }
;   }
.Lconv_seg0:
	s_waitcnt lgkmcnt(0)
	v_add_u32_e32 v97, 0xffffff80, v97
	v_add_u32_e32 v96, 0xffffff70, v96
	v_add_u32_e32 v95, -1, v95
	ds_read2_b32 v[164:165], v97 offset0:24 offset1:25
	ds_read2_b32 v[166:167], v97 offset0:26 offset1:27
	ds_read2_b32 v[168:169], v97 offset0:16 offset1:17
	ds_read2_b32 v[170:171], v97 offset0:18 offset1:19
	v_add_u32_e32 v72, 0xffffffd0, v95
	v_cmp_gt_u32_e64 s[0:1], 64, v72
	v_mfma_f32_16x16x32_bf16 v[64:67], v[132:135], v[180:183], v[64:67]
	v_mfma_f32_16x16x32_bf16 v[60:63], v[132:135], v[184:187], v[60:63]
	v_mfma_f32_16x16x32_bf16 v[64:67], v[136:139], v[172:175], v[64:67]
	v_mfma_f32_16x16x32_bf16 v[60:63], v[136:139], v[176:179], v[60:63]
	v_cndmask_b32_e64 v76, v68, v96, s[0:1]
	ds_read_b128 v[100:103], v76 offset:0
	ds_read_b128 v[104:107], v76 offset:64
	ds_read2_b32 v[172:173], v97 offset0:8 offset1:9
	ds_read2_b32 v[174:175], v97 offset0:10 offset1:11
	ds_read2_b32 v[176:177], v97 offset0:0 offset1:1
	ds_read2_b32 v[178:179], v97 offset0:2 offset1:3
	v_mfma_f32_16x16x32_bf16 v[56:59], v[132:135], v[188:191], v[56:59]
	v_mfma_f32_16x16x32_bf16 v[52:55], v[132:135], v[192:195], v[52:55]
	v_mfma_f32_16x16x32_bf16 v[56:59], v[136:139], v[180:183], v[56:59]
	v_mfma_f32_16x16x32_bf16 v[52:55], v[136:139], v[184:187], v[52:55]
	s_waitcnt lgkmcnt(0)
	v_add_u32_e32 v97, 0xffffff80, v97
	v_add_u32_e32 v96, 0xffffff70, v96
	v_add_u32_e32 v95, -1, v95
	ds_read2_b32 v[180:181], v97 offset0:24 offset1:25
	ds_read2_b32 v[182:183], v97 offset0:26 offset1:27
	ds_read2_b32 v[184:185], v97 offset0:16 offset1:17
	ds_read2_b32 v[186:187], v97 offset0:18 offset1:19
	v_add_u32_e32 v72, 0xffffffd0, v95
	v_cmp_gt_u32_e64 s[0:1], 64, v72
	v_mfma_f32_16x16x32_bf16 v[64:67], v[100:103], v[164:167], v[64:67]
	v_mfma_f32_16x16x32_bf16 v[60:63], v[100:103], v[168:171], v[60:63]
	v_mfma_f32_16x16x32_bf16 v[64:67], v[104:107], v[188:191], v[64:67]
	v_mfma_f32_16x16x32_bf16 v[60:63], v[104:107], v[192:195], v[60:63]
	v_cndmask_b32_e64 v76, v68, v96, s[0:1]
	ds_read_b128 v[132:135], v76 offset:0
	ds_read_b128 v[136:139], v76 offset:64
	ds_read2_b32 v[188:189], v97 offset0:8 offset1:9
	ds_read2_b32 v[190:191], v97 offset0:10 offset1:11
	ds_read2_b32 v[192:193], v97 offset0:0 offset1:1
	ds_read2_b32 v[194:195], v97 offset0:2 offset1:3
	v_mfma_f32_16x16x32_bf16 v[56:59], v[100:103], v[172:175], v[56:59]
	v_mfma_f32_16x16x32_bf16 v[52:55], v[100:103], v[176:179], v[52:55]
	v_mfma_f32_16x16x32_bf16 v[56:59], v[104:107], v[164:167], v[56:59]
	v_mfma_f32_16x16x32_bf16 v[52:55], v[104:107], v[168:171], v[52:55]
	s_sub_u32 s24, s24, 1
	s_cmp_lg_u32 s24, 0
	s_cbranch_scc1 .Lconv_seg0
	s_waitcnt lgkmcnt(0)
	v_add_u32_e32 v97, 0xffffff80, v97
	v_add_u32_e32 v96, 0xffffff70, v96
	v_add_u32_e32 v95, -1, v95
	ds_read2_b32 v[164:165], v97 offset0:24 offset1:25
	ds_read2_b32 v[166:167], v97 offset0:26 offset1:27
	ds_read2_b32 v[168:169], v97 offset0:16 offset1:17
	ds_read2_b32 v[170:171], v97 offset0:18 offset1:19
	v_add_u32_e32 v72, 0xffffffd0, v95
	v_cmp_gt_u32_e64 s[0:1], 64, v72
	v_mfma_f32_16x16x32_bf16 v[64:67], v[132:135], v[180:183], v[64:67]
	v_mfma_f32_16x16x32_bf16 v[60:63], v[132:135], v[184:187], v[60:63]
	v_mfma_f32_16x16x32_bf16 v[64:67], v[136:139], v[172:175], v[64:67]
	v_mfma_f32_16x16x32_bf16 v[60:63], v[136:139], v[176:179], v[60:63]
	v_cndmask_b32_e64 v76, v68, v96, s[0:1]
	ds_read_b128 v[100:103], v76 offset:0
	ds_read_b128 v[104:107], v76 offset:64
	ds_read2_b32 v[172:173], v97 offset0:8 offset1:9
	ds_read2_b32 v[174:175], v97 offset0:10 offset1:11
	ds_read2_b32 v[176:177], v97 offset0:0 offset1:1
	ds_read2_b32 v[178:179], v97 offset0:2 offset1:3
	v_mfma_f32_16x16x32_bf16 v[56:59], v[132:135], v[188:191], v[56:59]
	v_mfma_f32_16x16x32_bf16 v[52:55], v[132:135], v[192:195], v[52:55]
	v_mfma_f32_16x16x32_bf16 v[56:59], v[136:139], v[180:183], v[56:59]
	v_mfma_f32_16x16x32_bf16 v[52:55], v[136:139], v[184:187], v[52:55]
	s_waitcnt lgkmcnt(0)
	v_add_u32_e32 v97, 0xffffff80, v97
	v_add_u32_e32 v96, 0xffffff70, v96
	v_add_u32_e32 v95, -1, v95
	ds_read2_b32 v[180:181], v97 offset0:24 offset1:25
	ds_read2_b32 v[182:183], v97 offset0:26 offset1:27
	ds_read2_b32 v[184:185], v97 offset0:16 offset1:17
	ds_read2_b32 v[186:187], v97 offset0:18 offset1:19
	v_add_u32_e32 v72, 0xffffffd0, v95
	v_cmp_gt_u32_e64 s[0:1], 64, v72
	v_add_u32_e32 v73, 0xffffffe0, v95
	v_cmp_gt_u32_e64 s[4:5], 64, v73
	v_mfma_f32_16x16x32_bf16 v[64:67], v[100:103], v[164:167], v[64:67]
	v_mfma_f32_16x16x32_bf16 v[60:63], v[100:103], v[168:171], v[60:63]
	v_mfma_f32_16x16x32_bf16 v[64:67], v[104:107], v[188:191], v[64:67]
	v_mfma_f32_16x16x32_bf16 v[60:63], v[104:107], v[192:195], v[60:63]
	v_cndmask_b32_e64 v76, v68, v96, s[0:1]
	ds_read_b128 v[132:135], v76 offset:0
	ds_read_b128 v[136:139], v76 offset:64
	v_cndmask_b32_e64 v77, v69, v96, s[4:5]
	ds_read_b128 v[140:143], v77 offset:2304
	ds_read_b128 v[144:147], v77 offset:2368
	ds_read2_b32 v[188:189], v97 offset0:8 offset1:9
	ds_read2_b32 v[190:191], v97 offset0:10 offset1:11
	ds_read2_b32 v[192:193], v97 offset0:0 offset1:1
	ds_read2_b32 v[194:195], v97 offset0:2 offset1:3
	v_mfma_f32_16x16x32_bf16 v[56:59], v[100:103], v[172:175], v[56:59]
	v_mfma_f32_16x16x32_bf16 v[52:55], v[100:103], v[176:179], v[52:55]
	v_mfma_f32_16x16x32_bf16 v[56:59], v[104:107], v[164:167], v[56:59]
	v_mfma_f32_16x16x32_bf16 v[52:55], v[104:107], v[168:171], v[52:55]
	s_mov_b32 s24, 7
; #define MFMA16(a, b, c) __builtin_amdgcn_mfma_f32_16x16x32_bf16(__builtin_bit_cast(bf16x8, (a)), __builtin_bit_cast(bf16x8, (b)), (c), 0, 0, 0)
; DI void hyena_conv_unit(const Params& p, int item, char* smem) {
;     ...
;   for (int d = -63; d <= 63; ++d) {
; #pragma unroll
;     for (int kk = 0; kk < 2; ++kk) {
;       u32x4 bfr[4];
; #pragma unroll
;       for (int nn = 0; nn < 4; ++nn) bfr[nn] = bfrag(4 * d + nn - 2 * kk);
; #pragma unroll
;       for (int rb = 0; rb < 4; ++rb) {
;         if (d >= 16 * rb - 63 && d <= 16 * rb + 15) {
;           int t1 = 16 * rb + n, s1 = t1 - d;
;           u32x4 a = zero4();
;           if (s1 >= 0 && s1 < 64) a = *(const u32x4*)(su + s1 * 72 + 32 * kk + 8 * g);
; #pragma unroll
;           for (int nn = 0; nn < 4; ++nn) acc[rb][nn] = MFMA16(a, bfr[nn], acc[rb][nn]);
;         }
;       }
;     }
;   }
.Lconv_seg1:
	s_waitcnt lgkmcnt(0)
	v_add_u32_e32 v97, 0xffffff80, v97
	v_add_u32_e32 v96, 0xffffff70, v96
	v_add_u32_e32 v95, -1, v95
	ds_read2_b32 v[164:165], v97 offset0:24 offset1:25
	ds_read2_b32 v[166:167], v97 offset0:26 offset1:27
	ds_read2_b32 v[168:169], v97 offset0:16 offset1:17
	ds_read2_b32 v[170:171], v97 offset0:18 offset1:19
	v_add_u32_e32 v72, 0xffffffd0, v95
	v_cmp_gt_u32_e64 s[0:1], 64, v72
	v_add_u32_e32 v73, 0xffffffe0, v95
	v_cmp_gt_u32_e64 s[4:5], 64, v73
	v_mfma_f32_16x16x32_bf16 v[64:67], v[132:135], v[180:183], v[64:67]
	v_mfma_f32_16x16x32_bf16 v[60:63], v[132:135], v[184:187], v[60:63]
	v_mfma_f32_16x16x32_bf16 v[64:67], v[136:139], v[172:175], v[64:67]
	v_mfma_f32_16x16x32_bf16 v[60:63], v[136:139], v[176:179], v[60:63]
	v_cndmask_b32_e64 v76, v68, v96, s[0:1]
	ds_read_b128 v[100:103], v76 offset:0
	ds_read_b128 v[104:107], v76 offset:64
	v_mfma_f32_16x16x32_bf16 v[48:51], v[140:143], v[180:183], v[48:51]
	v_mfma_f32_16x16x32_bf16 v[44:47], v[140:143], v[184:187], v[44:47]
	v_mfma_f32_16x16x32_bf16 v[48:51], v[144:147], v[172:175], v[48:51]
	v_mfma_f32_16x16x32_bf16 v[44:47], v[144:147], v[176:179], v[44:47]
	v_cndmask_b32_e64 v77, v69, v96, s[4:5]
	ds_read_b128 v[108:111], v77 offset:2304
	ds_read_b128 v[112:115], v77 offset:2368
	ds_read2_b32 v[172:173], v97 offset0:8 offset1:9
	ds_read2_b32 v[174:175], v97 offset0:10 offset1:11
	ds_read2_b32 v[176:177], v97 offset0:0 offset1:1
	ds_read2_b32 v[178:179], v97 offset0:2 offset1:3
	v_mfma_f32_16x16x32_bf16 v[56:59], v[132:135], v[188:191], v[56:59]
	v_mfma_f32_16x16x32_bf16 v[52:55], v[132:135], v[192:195], v[52:55]
	v_mfma_f32_16x16x32_bf16 v[56:59], v[136:139], v[180:183], v[56:59]
	v_mfma_f32_16x16x32_bf16 v[52:55], v[136:139], v[184:187], v[52:55]
	v_mfma_f32_16x16x32_bf16 v[40:43], v[140:143], v[188:191], v[40:43]
	v_mfma_f32_16x16x32_bf16 v[36:39], v[140:143], v[192:195], v[36:39]
	v_mfma_f32_16x16x32_bf16 v[40:43], v[144:147], v[180:183], v[40:43]
	v_mfma_f32_16x16x32_bf16 v[36:39], v[144:147], v[184:187], v[36:39]
	s_waitcnt lgkmcnt(0)
	v_add_u32_e32 v97, 0xffffff80, v97
	v_add_u32_e32 v96, 0xffffff70, v96
	v_add_u32_e32 v95, -1, v95
	ds_read2_b32 v[180:181], v97 offset0:24 offset1:25
	ds_read2_b32 v[182:183], v97 offset0:26 offset1:27
	ds_read2_b32 v[184:185], v97 offset0:16 offset1:17
	ds_read2_b32 v[186:187], v97 offset0:18 offset1:19
	v_add_u32_e32 v72, 0xffffffd0, v95
	v_cmp_gt_u32_e64 s[0:1], 64, v72
	v_add_u32_e32 v73, 0xffffffe0, v95
	v_cmp_gt_u32_e64 s[4:5], 64, v73
	v_mfma_f32_16x16x32_bf16 v[64:67], v[100:103], v[164:167], v[64:67]
	v_mfma_f32_16x16x32_bf16 v[60:63], v[100:103], v[168:171], v[60:63]
	v_mfma_f32_16x16x32_bf16 v[64:67], v[104:107], v[188:191], v[64:67]
	v_mfma_f32_16x16x32_bf16 v[60:63], v[104:107], v[192:195], v[60:63]
	v_cndmask_b32_e64 v76, v68, v96, s[0:1]
	ds_read_b128 v[132:135], v76 offset:0
	ds_read_b128 v[136:139], v76 offset:64
	v_mfma_f32_16x16x32_bf16 v[48:51], v[108:111], v[164:167], v[48:51]
	v_mfma_f32_16x16x32_bf16 v[44:47], v[108:111], v[168:171], v[44:47]
	v_mfma_f32_16x16x32_bf16 v[48:51], v[112:115], v[188:191], v[48:51]
	v_mfma_f32_16x16x32_bf16 v[44:47], v[112:115], v[192:195], v[44:47]
	v_cndmask_b32_e64 v77, v69, v96, s[4:5]
	ds_read_b128 v[140:143], v77 offset:2304
	ds_read_b128 v[144:147], v77 offset:2368
	ds_read2_b32 v[188:189], v97 offset0:8 offset1:9
	ds_read2_b32 v[190:191], v97 offset0:10 offset1:11
	ds_read2_b32 v[192:193], v97 offset0:0 offset1:1
	ds_read2_b32 v[194:195], v97 offset0:2 offset1:3
	v_mfma_f32_16x16x32_bf16 v[56:59], v[100:103], v[172:175], v[56:59]
	v_mfma_f32_16x16x32_bf16 v[52:55], v[100:103], v[176:179], v[52:55]
	v_mfma_f32_16x16x32_bf16 v[56:59], v[104:107], v[164:167], v[56:59]
	v_mfma_f32_16x16x32_bf16 v[52:55], v[104:107], v[168:171], v[52:55]
	v_mfma_f32_16x16x32_bf16 v[40:43], v[108:111], v[172:175], v[40:43]
	v_mfma_f32_16x16x32_bf16 v[36:39], v[108:111], v[176:179], v[36:39]
	v_mfma_f32_16x16x32_bf16 v[40:43], v[112:115], v[164:167], v[40:43]
	v_mfma_f32_16x16x32_bf16 v[36:39], v[112:115], v[168:171], v[36:39]
	s_sub_u32 s24, s24, 1
	s_cmp_lg_u32 s24, 0
	s_cbranch_scc1 .Lconv_seg1
	s_waitcnt lgkmcnt(0)
	v_add_u32_e32 v97, 0xffffff80, v97
	v_add_u32_e32 v96, 0xffffff70, v96
	v_add_u32_e32 v95, -1, v95
	ds_read2_b32 v[164:165], v97 offset0:24 offset1:25
	ds_read2_b32 v[166:167], v97 offset0:26 offset1:27
	ds_read2_b32 v[168:169], v97 offset0:16 offset1:17
	ds_read2_b32 v[170:171], v97 offset0:18 offset1:19
	v_add_u32_e32 v72, 0xffffffd0, v95
	v_cmp_gt_u32_e64 s[0:1], 64, v72
	v_add_u32_e32 v73, 0xffffffe0, v95
	v_cmp_gt_u32_e64 s[4:5], 64, v73
	v_mfma_f32_16x16x32_bf16 v[64:67], v[132:135], v[180:183], v[64:67]
	v_mfma_f32_16x16x32_bf16 v[60:63], v[132:135], v[184:187], v[60:63]
	v_mfma_f32_16x16x32_bf16 v[64:67], v[136:139], v[172:175], v[64:67]
	v_mfma_f32_16x16x32_bf16 v[60:63], v[136:139], v[176:179], v[60:63]
	v_cndmask_b32_e64 v76, v68, v96, s[0:1]
	ds_read_b128 v[100:103], v76 offset:0
	ds_read_b128 v[104:107], v76 offset:64
	v_mfma_f32_16x16x32_bf16 v[48:51], v[140:143], v[180:183], v[48:51]
	v_mfma_f32_16x16x32_bf16 v[44:47], v[140:143], v[184:187], v[44:47]
	v_mfma_f32_16x16x32_bf16 v[48:51], v[144:147], v[172:175], v[48:51]
	v_mfma_f32_16x16x32_bf16 v[44:47], v[144:147], v[176:179], v[44:47]
	v_cndmask_b32_e64 v77, v69, v96, s[4:5]
	ds_read_b128 v[108:111], v77 offset:2304
	ds_read_b128 v[112:115], v77 offset:2368
	ds_read2_b32 v[172:173], v97 offset0:8 offset1:9
	ds_read2_b32 v[174:175], v97 offset0:10 offset1:11
	ds_read2_b32 v[176:177], v97 offset0:0 offset1:1
	ds_read2_b32 v[178:179], v97 offset0:2 offset1:3
	v_mfma_f32_16x16x32_bf16 v[56:59], v[132:135], v[188:191], v[56:59]
	v_mfma_f32_16x16x32_bf16 v[52:55], v[132:135], v[192:195], v[52:55]
	v_mfma_f32_16x16x32_bf16 v[56:59], v[136:139], v[180:183], v[56:59]
	v_mfma_f32_16x16x32_bf16 v[52:55], v[136:139], v[184:187], v[52:55]
	v_mfma_f32_16x16x32_bf16 v[40:43], v[140:143], v[188:191], v[40:43]
	v_mfma_f32_16x16x32_bf16 v[36:39], v[140:143], v[192:195], v[36:39]
	v_mfma_f32_16x16x32_bf16 v[40:43], v[144:147], v[180:183], v[40:43]
	v_mfma_f32_16x16x32_bf16 v[36:39], v[144:147], v[184:187], v[36:39]
	s_waitcnt lgkmcnt(0)
; #define MFMA16(a, b, c) __builtin_amdgcn_mfma_f32_16x16x32_bf16(__builtin_bit_cast(bf16x8, (a)), __builtin_bit_cast(bf16x8, (b)), (c), 0, 0, 0)
; DI void hyena_conv_unit(const Params& p, int item, char* smem) {
;     ...
;   for (int d = -63; d <= 63; ++d) {
; #pragma unroll
;     for (int kk = 0; kk < 2; ++kk) {
;       u32x4 bfr[4];
; #pragma unroll
;       for (int nn = 0; nn < 4; ++nn) bfr[nn] = bfrag(4 * d + nn - 2 * kk);
; #pragma unroll
;       for (int rb = 0; rb < 4; ++rb) {
;         if (d >= 16 * rb - 63 && d <= 16 * rb + 15) {
;           int t1 = 16 * rb + n, s1 = t1 - d;
;           u32x4 a = zero4();
;           if (s1 >= 0 && s1 < 64) a = *(const u32x4*)(su + s1 * 72 + 32 * kk + 8 * g);
; #pragma unroll
;           for (int nn = 0; nn < 4; ++nn) acc[rb][nn] = MFMA16(a, bfr[nn], acc[rb][nn]);
;         }
;       }
;     }
;   }
	v_add_u32_e32 v97, 0xffffff80, v97
	v_add_u32_e32 v96, 0xffffff70, v96
	v_add_u32_e32 v95, -1, v95
	ds_read2_b32 v[180:181], v97 offset0:24 offset1:25
	ds_read2_b32 v[182:183], v97 offset0:26 offset1:27
	ds_read2_b32 v[184:185], v97 offset0:16 offset1:17
	ds_read2_b32 v[186:187], v97 offset0:18 offset1:19
	v_add_u32_e32 v72, 0xffffffd0, v95
	v_cmp_gt_u32_e64 s[0:1], 64, v72
	v_add_u32_e32 v73, 0xffffffe0, v95
	v_cmp_gt_u32_e64 s[4:5], 64, v73
	v_add_u32_e32 v74, 0xfffffff0, v95
	v_cmp_gt_u32_e64 s[6:7], 64, v74
	v_mfma_f32_16x16x32_bf16 v[64:67], v[100:103], v[164:167], v[64:67]
	v_mfma_f32_16x16x32_bf16 v[60:63], v[100:103], v[168:171], v[60:63]
	v_mfma_f32_16x16x32_bf16 v[64:67], v[104:107], v[188:191], v[64:67]
	v_mfma_f32_16x16x32_bf16 v[60:63], v[104:107], v[192:195], v[60:63]
	v_cndmask_b32_e64 v76, v68, v96, s[0:1]
	ds_read_b128 v[132:135], v76 offset:0
	ds_read_b128 v[136:139], v76 offset:64
	v_mfma_f32_16x16x32_bf16 v[48:51], v[108:111], v[164:167], v[48:51]
	v_mfma_f32_16x16x32_bf16 v[44:47], v[108:111], v[168:171], v[44:47]
	v_mfma_f32_16x16x32_bf16 v[48:51], v[112:115], v[188:191], v[48:51]
	v_mfma_f32_16x16x32_bf16 v[44:47], v[112:115], v[192:195], v[44:47]
	v_cndmask_b32_e64 v77, v69, v96, s[4:5]
	ds_read_b128 v[140:143], v77 offset:2304
	ds_read_b128 v[144:147], v77 offset:2368
	v_cndmask_b32_e64 v78, v70, v96, s[6:7]
	ds_read_b128 v[148:151], v78 offset:4608
	ds_read_b128 v[152:155], v78 offset:4672
	ds_read2_b32 v[188:189], v97 offset0:8 offset1:9
	ds_read2_b32 v[190:191], v97 offset0:10 offset1:11
	ds_read2_b32 v[192:193], v97 offset0:0 offset1:1
	ds_read2_b32 v[194:195], v97 offset0:2 offset1:3
	v_mfma_f32_16x16x32_bf16 v[56:59], v[100:103], v[172:175], v[56:59]
	v_mfma_f32_16x16x32_bf16 v[52:55], v[100:103], v[176:179], v[52:55]
	v_mfma_f32_16x16x32_bf16 v[56:59], v[104:107], v[164:167], v[56:59]
	v_mfma_f32_16x16x32_bf16 v[52:55], v[104:107], v[168:171], v[52:55]
	v_mfma_f32_16x16x32_bf16 v[40:43], v[108:111], v[172:175], v[40:43]
	v_mfma_f32_16x16x32_bf16 v[36:39], v[108:111], v[176:179], v[36:39]
	v_mfma_f32_16x16x32_bf16 v[40:43], v[112:115], v[164:167], v[40:43]
	v_mfma_f32_16x16x32_bf16 v[36:39], v[112:115], v[168:171], v[36:39]
	s_mov_b32 s24, 7
.Lconv_seg2:
	s_waitcnt lgkmcnt(0)
	v_add_u32_e32 v97, 0xffffff80, v97
	v_add_u32_e32 v96, 0xffffff70, v96
	v_add_u32_e32 v95, -1, v95
	ds_read2_b32 v[164:165], v97 offset0:24 offset1:25
	ds_read2_b32 v[166:167], v97 offset0:26 offset1:27
	ds_read2_b32 v[168:169], v97 offset0:16 offset1:17
	ds_read2_b32 v[170:171], v97 offset0:18 offset1:19
	v_add_u32_e32 v72, 0xffffffd0, v95
	v_cmp_gt_u32_e64 s[0:1], 64, v72
	v_add_u32_e32 v73, 0xffffffe0, v95
	v_cmp_gt_u32_e64 s[4:5], 64, v73
	v_add_u32_e32 v74, 0xfffffff0, v95
	v_cmp_gt_u32_e64 s[6:7], 64, v74
	v_mfma_f32_16x16x32_bf16 v[64:67], v[132:135], v[180:183], v[64:67]
	v_mfma_f32_16x16x32_bf16 v[60:63], v[132:135], v[184:187], v[60:63]
	v_mfma_f32_16x16x32_bf16 v[64:67], v[136:139], v[172:175], v[64:67]
	v_mfma_f32_16x16x32_bf16 v[60:63], v[136:139], v[176:179], v[60:63]
	v_cndmask_b32_e64 v76, v68, v96, s[0:1]
	ds_read_b128 v[100:103], v76 offset:0
	ds_read_b128 v[104:107], v76 offset:64
	v_mfma_f32_16x16x32_bf16 v[48:51], v[140:143], v[180:183], v[48:51]
	v_mfma_f32_16x16x32_bf16 v[44:47], v[140:143], v[184:187], v[44:47]
	v_mfma_f32_16x16x32_bf16 v[48:51], v[144:147], v[172:175], v[48:51]
	v_mfma_f32_16x16x32_bf16 v[44:47], v[144:147], v[176:179], v[44:47]
	v_cndmask_b32_e64 v77, v69, v96, s[4:5]
	ds_read_b128 v[108:111], v77 offset:2304
	ds_read_b128 v[112:115], v77 offset:2368
	v_mfma_f32_16x16x32_bf16 v[32:35], v[148:151], v[180:183], v[32:35]
	v_mfma_f32_16x16x32_bf16 v[28:31], v[148:151], v[184:187], v[28:31]
	v_mfma_f32_16x16x32_bf16 v[32:35], v[152:155], v[172:175], v[32:35]
	v_mfma_f32_16x16x32_bf16 v[28:31], v[152:155], v[176:179], v[28:31]
	v_cndmask_b32_e64 v78, v70, v96, s[6:7]
	ds_read_b128 v[116:119], v78 offset:4608
	ds_read_b128 v[120:123], v78 offset:4672
	ds_read2_b32 v[172:173], v97 offset0:8 offset1:9
	ds_read2_b32 v[174:175], v97 offset0:10 offset1:11
	ds_read2_b32 v[176:177], v97 offset0:0 offset1:1
	ds_read2_b32 v[178:179], v97 offset0:2 offset1:3
	v_mfma_f32_16x16x32_bf16 v[56:59], v[132:135], v[188:191], v[56:59]
	v_mfma_f32_16x16x32_bf16 v[52:55], v[132:135], v[192:195], v[52:55]
	v_mfma_f32_16x16x32_bf16 v[56:59], v[136:139], v[180:183], v[56:59]
	v_mfma_f32_16x16x32_bf16 v[52:55], v[136:139], v[184:187], v[52:55]
	v_mfma_f32_16x16x32_bf16 v[40:43], v[140:143], v[188:191], v[40:43]
	v_mfma_f32_16x16x32_bf16 v[36:39], v[140:143], v[192:195], v[36:39]
	v_mfma_f32_16x16x32_bf16 v[40:43], v[144:147], v[180:183], v[40:43]
	v_mfma_f32_16x16x32_bf16 v[36:39], v[144:147], v[184:187], v[36:39]
	v_mfma_f32_16x16x32_bf16 v[24:27], v[148:151], v[188:191], v[24:27]
	v_mfma_f32_16x16x32_bf16 v[20:23], v[148:151], v[192:195], v[20:23]
	v_mfma_f32_16x16x32_bf16 v[24:27], v[152:155], v[180:183], v[24:27]
	v_mfma_f32_16x16x32_bf16 v[20:23], v[152:155], v[184:187], v[20:23]
	s_waitcnt lgkmcnt(0)
; #define MFMA16(a, b, c) __builtin_amdgcn_mfma_f32_16x16x32_bf16(__builtin_bit_cast(bf16x8, (a)), __builtin_bit_cast(bf16x8, (b)), (c), 0, 0, 0)
; DI void hyena_conv_unit(const Params& p, int item, char* smem) {
;     ...
;   for (int d = -63; d <= 63; ++d) {
; #pragma unroll
;     for (int kk = 0; kk < 2; ++kk) {
;       u32x4 bfr[4];
; #pragma unroll
;       for (int nn = 0; nn < 4; ++nn) bfr[nn] = bfrag(4 * d + nn - 2 * kk);
; #pragma unroll
;       for (int rb = 0; rb < 4; ++rb) {
;         if (d >= 16 * rb - 63 && d <= 16 * rb + 15) {
;           int t1 = 16 * rb + n, s1 = t1 - d;
;           u32x4 a = zero4();
;           if (s1 >= 0 && s1 < 64) a = *(const u32x4*)(su + s1 * 72 + 32 * kk + 8 * g);
; #pragma unroll
;           for (int nn = 0; nn < 4; ++nn) acc[rb][nn] = MFMA16(a, bfr[nn], acc[rb][nn]);
;         }
;       }
;     }
;   }
	v_add_u32_e32 v97, 0xffffff80, v97
	v_add_u32_e32 v96, 0xffffff70, v96
	v_add_u32_e32 v95, -1, v95
	ds_read2_b32 v[180:181], v97 offset0:24 offset1:25
	ds_read2_b32 v[182:183], v97 offset0:26 offset1:27
	ds_read2_b32 v[184:185], v97 offset0:16 offset1:17
	ds_read2_b32 v[186:187], v97 offset0:18 offset1:19
	v_add_u32_e32 v72, 0xffffffd0, v95
	v_cmp_gt_u32_e64 s[0:1], 64, v72
	v_add_u32_e32 v73, 0xffffffe0, v95
	v_cmp_gt_u32_e64 s[4:5], 64, v73
	v_add_u32_e32 v74, 0xfffffff0, v95
	v_cmp_gt_u32_e64 s[6:7], 64, v74
	v_mfma_f32_16x16x32_bf16 v[64:67], v[100:103], v[164:167], v[64:67]
	v_mfma_f32_16x16x32_bf16 v[60:63], v[100:103], v[168:171], v[60:63]
	v_mfma_f32_16x16x32_bf16 v[64:67], v[104:107], v[188:191], v[64:67]
	v_mfma_f32_16x16x32_bf16 v[60:63], v[104:107], v[192:195], v[60:63]
	v_cndmask_b32_e64 v76, v68, v96, s[0:1]
	ds_read_b128 v[132:135], v76 offset:0
	ds_read_b128 v[136:139], v76 offset:64
	v_mfma_f32_16x16x32_bf16 v[48:51], v[108:111], v[164:167], v[48:51]
	v_mfma_f32_16x16x32_bf16 v[44:47], v[108:111], v[168:171], v[44:47]
	v_mfma_f32_16x16x32_bf16 v[48:51], v[112:115], v[188:191], v[48:51]
	v_mfma_f32_16x16x32_bf16 v[44:47], v[112:115], v[192:195], v[44:47]
	v_cndmask_b32_e64 v77, v69, v96, s[4:5]
	ds_read_b128 v[140:143], v77 offset:2304
	ds_read_b128 v[144:147], v77 offset:2368
	v_mfma_f32_16x16x32_bf16 v[32:35], v[116:119], v[164:167], v[32:35]
	v_mfma_f32_16x16x32_bf16 v[28:31], v[116:119], v[168:171], v[28:31]
	v_mfma_f32_16x16x32_bf16 v[32:35], v[120:123], v[188:191], v[32:35]
	v_mfma_f32_16x16x32_bf16 v[28:31], v[120:123], v[192:195], v[28:31]
	v_cndmask_b32_e64 v78, v70, v96, s[6:7]
	ds_read_b128 v[148:151], v78 offset:4608
	ds_read_b128 v[152:155], v78 offset:4672
	ds_read2_b32 v[188:189], v97 offset0:8 offset1:9
	ds_read2_b32 v[190:191], v97 offset0:10 offset1:11
	ds_read2_b32 v[192:193], v97 offset0:0 offset1:1
	ds_read2_b32 v[194:195], v97 offset0:2 offset1:3
	v_mfma_f32_16x16x32_bf16 v[56:59], v[100:103], v[172:175], v[56:59]
	v_mfma_f32_16x16x32_bf16 v[52:55], v[100:103], v[176:179], v[52:55]
	v_mfma_f32_16x16x32_bf16 v[56:59], v[104:107], v[164:167], v[56:59]
	v_mfma_f32_16x16x32_bf16 v[52:55], v[104:107], v[168:171], v[52:55]
	v_mfma_f32_16x16x32_bf16 v[40:43], v[108:111], v[172:175], v[40:43]
	v_mfma_f32_16x16x32_bf16 v[36:39], v[108:111], v[176:179], v[36:39]
	v_mfma_f32_16x16x32_bf16 v[40:43], v[112:115], v[164:167], v[40:43]
	v_mfma_f32_16x16x32_bf16 v[36:39], v[112:115], v[168:171], v[36:39]
	v_mfma_f32_16x16x32_bf16 v[24:27], v[116:119], v[172:175], v[24:27]
	v_mfma_f32_16x16x32_bf16 v[20:23], v[116:119], v[176:179], v[20:23]
	v_mfma_f32_16x16x32_bf16 v[24:27], v[120:123], v[164:167], v[24:27]
	v_mfma_f32_16x16x32_bf16 v[20:23], v[120:123], v[168:171], v[20:23]
	s_sub_u32 s24, s24, 1
	s_cmp_lg_u32 s24, 0
	s_cbranch_scc1 .Lconv_seg2
	s_waitcnt lgkmcnt(0)
	v_add_u32_e32 v97, 0xffffff80, v97
	v_add_u32_e32 v96, 0xffffff70, v96
	v_add_u32_e32 v95, -1, v95
	ds_read2_b32 v[164:165], v97 offset0:24 offset1:25
	ds_read2_b32 v[166:167], v97 offset0:26 offset1:27
	ds_read2_b32 v[168:169], v97 offset0:16 offset1:17
	ds_read2_b32 v[170:171], v97 offset0:18 offset1:19
	v_add_u32_e32 v72, 0xffffffd0, v95
	v_cmp_gt_u32_e64 s[0:1], 64, v72
	v_add_u32_e32 v73, 0xffffffe0, v95
	v_cmp_gt_u32_e64 s[4:5], 64, v73
	v_add_u32_e32 v74, 0xfffffff0, v95
	v_cmp_gt_u32_e64 s[6:7], 64, v74
	v_mfma_f32_16x16x32_bf16 v[64:67], v[132:135], v[180:183], v[64:67]
	v_mfma_f32_16x16x32_bf16 v[60:63], v[132:135], v[184:187], v[60:63]
	v_mfma_f32_16x16x32_bf16 v[64:67], v[136:139], v[172:175], v[64:67]
	v_mfma_f32_16x16x32_bf16 v[60:63], v[136:139], v[176:179], v[60:63]
	v_cndmask_b32_e64 v76, v68, v96, s[0:1]
	ds_read_b128 v[100:103], v76 offset:0
	ds_read_b128 v[104:107], v76 offset:64
	v_mfma_f32_16x16x32_bf16 v[48:51], v[140:143], v[180:183], v[48:51]
	v_mfma_f32_16x16x32_bf16 v[44:47], v[140:143], v[184:187], v[44:47]
	v_mfma_f32_16x16x32_bf16 v[48:51], v[144:147], v[172:175], v[48:51]
	v_mfma_f32_16x16x32_bf16 v[44:47], v[144:147], v[176:179], v[44:47]
	v_cndmask_b32_e64 v77, v69, v96, s[4:5]
	ds_read_b128 v[108:111], v77 offset:2304
	ds_read_b128 v[112:115], v77 offset:2368
	v_mfma_f32_16x16x32_bf16 v[32:35], v[148:151], v[180:183], v[32:35]
	v_mfma_f32_16x16x32_bf16 v[28:31], v[148:151], v[184:187], v[28:31]
	v_mfma_f32_16x16x32_bf16 v[32:35], v[152:155], v[172:175], v[32:35]
	v_mfma_f32_16x16x32_bf16 v[28:31], v[152:155], v[176:179], v[28:31]
	v_cndmask_b32_e64 v78, v70, v96, s[6:7]
	ds_read_b128 v[116:119], v78 offset:4608
	ds_read_b128 v[120:123], v78 offset:4672
	ds_read2_b32 v[172:173], v97 offset0:8 offset1:9
	ds_read2_b32 v[174:175], v97 offset0:10 offset1:11
	ds_read2_b32 v[176:177], v97 offset0:0 offset1:1
	ds_read2_b32 v[178:179], v97 offset0:2 offset1:3
	v_mfma_f32_16x16x32_bf16 v[56:59], v[132:135], v[188:191], v[56:59]
	v_mfma_f32_16x16x32_bf16 v[52:55], v[132:135], v[192:195], v[52:55]
	v_mfma_f32_16x16x32_bf16 v[56:59], v[136:139], v[180:183], v[56:59]
	v_mfma_f32_16x16x32_bf16 v[52:55], v[136:139], v[184:187], v[52:55]
	v_mfma_f32_16x16x32_bf16 v[40:43], v[140:143], v[188:191], v[40:43]
	v_mfma_f32_16x16x32_bf16 v[36:39], v[140:143], v[192:195], v[36:39]
	v_mfma_f32_16x16x32_bf16 v[40:43], v[144:147], v[180:183], v[40:43]
	v_mfma_f32_16x16x32_bf16 v[36:39], v[144:147], v[184:187], v[36:39]
	v_mfma_f32_16x16x32_bf16 v[24:27], v[148:151], v[188:191], v[24:27]
	v_mfma_f32_16x16x32_bf16 v[20:23], v[148:151], v[192:195], v[20:23]
	v_mfma_f32_16x16x32_bf16 v[24:27], v[152:155], v[180:183], v[24:27]
	v_mfma_f32_16x16x32_bf16 v[20:23], v[152:155], v[184:187], v[20:23]
	s_waitcnt lgkmcnt(0)
; #define MFMA16(a, b, c) __builtin_amdgcn_mfma_f32_16x16x32_bf16(__builtin_bit_cast(bf16x8, (a)), __builtin_bit_cast(bf16x8, (b)), (c), 0, 0, 0)
; DI void hyena_conv_unit(const Params& p, int item, char* smem) {
;     ...
;   for (int d = -63; d <= 63; ++d) {
; #pragma unroll
;     for (int kk = 0; kk < 2; ++kk) {
;       u32x4 bfr[4];
; #pragma unroll
;       for (int nn = 0; nn < 4; ++nn) bfr[nn] = bfrag(4 * d + nn - 2 * kk);
; #pragma unroll
;       for (int rb = 0; rb < 4; ++rb) {
;         if (d >= 16 * rb - 63 && d <= 16 * rb + 15) {
;           int t1 = 16 * rb + n, s1 = t1 - d;
;           u32x4 a = zero4();
;           if (s1 >= 0 && s1 < 64) a = *(const u32x4*)(su + s1 * 72 + 32 * kk + 8 * g);
; #pragma unroll
;           for (int nn = 0; nn < 4; ++nn) acc[rb][nn] = MFMA16(a, bfr[nn], acc[rb][nn]);
;         }
;       }
;     }
;   }
	v_add_u32_e32 v97, 0xffffff80, v97
	v_add_u32_e32 v96, 0xffffff70, v96
	v_add_u32_e32 v95, -1, v95
	ds_read2_b32 v[180:181], v97 offset0:24 offset1:25
	ds_read2_b32 v[182:183], v97 offset0:26 offset1:27
	ds_read2_b32 v[184:185], v97 offset0:16 offset1:17
	ds_read2_b32 v[186:187], v97 offset0:18 offset1:19
	v_add_u32_e32 v72, 0xffffffd0, v95
	v_cmp_gt_u32_e64 s[0:1], 64, v72
	v_add_u32_e32 v73, 0xffffffe0, v95
	v_cmp_gt_u32_e64 s[4:5], 64, v73
	v_add_u32_e32 v74, 0xfffffff0, v95
	v_cmp_gt_u32_e64 s[6:7], 64, v74
	v_cmp_gt_u32_e64 s[20:21], 64, v95
	v_mfma_f32_16x16x32_bf16 v[64:67], v[100:103], v[164:167], v[64:67]
	v_mfma_f32_16x16x32_bf16 v[60:63], v[100:103], v[168:171], v[60:63]
	v_mfma_f32_16x16x32_bf16 v[64:67], v[104:107], v[188:191], v[64:67]
	v_mfma_f32_16x16x32_bf16 v[60:63], v[104:107], v[192:195], v[60:63]
	v_cndmask_b32_e64 v76, v68, v96, s[0:1]
	ds_read_b128 v[132:135], v76 offset:0
	ds_read_b128 v[136:139], v76 offset:64
	v_mfma_f32_16x16x32_bf16 v[48:51], v[108:111], v[164:167], v[48:51]
	v_mfma_f32_16x16x32_bf16 v[44:47], v[108:111], v[168:171], v[44:47]
	v_mfma_f32_16x16x32_bf16 v[48:51], v[112:115], v[188:191], v[48:51]
	v_mfma_f32_16x16x32_bf16 v[44:47], v[112:115], v[192:195], v[44:47]
	v_cndmask_b32_e64 v77, v69, v96, s[4:5]
	ds_read_b128 v[140:143], v77 offset:2304
	ds_read_b128 v[144:147], v77 offset:2368
	v_mfma_f32_16x16x32_bf16 v[32:35], v[116:119], v[164:167], v[32:35]
	v_mfma_f32_16x16x32_bf16 v[28:31], v[116:119], v[168:171], v[28:31]
	v_mfma_f32_16x16x32_bf16 v[32:35], v[120:123], v[188:191], v[32:35]
	v_mfma_f32_16x16x32_bf16 v[28:31], v[120:123], v[192:195], v[28:31]
	v_cndmask_b32_e64 v78, v70, v96, s[6:7]
	ds_read_b128 v[148:151], v78 offset:4608
	ds_read_b128 v[152:155], v78 offset:4672
	v_cndmask_b32_e64 v79, v71, v96, s[20:21]
	ds_read_b128 v[156:159], v79 offset:6912
	ds_read_b128 v[160:163], v79 offset:6976
	ds_read2_b32 v[188:189], v97 offset0:8 offset1:9
	ds_read2_b32 v[190:191], v97 offset0:10 offset1:11
	ds_read2_b32 v[192:193], v97 offset0:0 offset1:1
	ds_read2_b32 v[194:195], v97 offset0:2 offset1:3
	v_mfma_f32_16x16x32_bf16 v[56:59], v[100:103], v[172:175], v[56:59]
	v_mfma_f32_16x16x32_bf16 v[52:55], v[100:103], v[176:179], v[52:55]
	v_mfma_f32_16x16x32_bf16 v[56:59], v[104:107], v[164:167], v[56:59]
	v_mfma_f32_16x16x32_bf16 v[52:55], v[104:107], v[168:171], v[52:55]
	v_mfma_f32_16x16x32_bf16 v[40:43], v[108:111], v[172:175], v[40:43]
	v_mfma_f32_16x16x32_bf16 v[36:39], v[108:111], v[176:179], v[36:39]
	v_mfma_f32_16x16x32_bf16 v[40:43], v[112:115], v[164:167], v[40:43]
	v_mfma_f32_16x16x32_bf16 v[36:39], v[112:115], v[168:171], v[36:39]
	v_mfma_f32_16x16x32_bf16 v[24:27], v[116:119], v[172:175], v[24:27]
	v_mfma_f32_16x16x32_bf16 v[20:23], v[116:119], v[176:179], v[20:23]
	v_mfma_f32_16x16x32_bf16 v[24:27], v[120:123], v[164:167], v[24:27]
	v_mfma_f32_16x16x32_bf16 v[20:23], v[120:123], v[168:171], v[20:23]
	s_mov_b32 s24, 15
.Lconv_seg3:
	s_waitcnt lgkmcnt(0)
	v_add_u32_e32 v97, 0xffffff80, v97
	v_add_u32_e32 v96, 0xffffff70, v96
	v_add_u32_e32 v95, -1, v95
	ds_read2_b32 v[164:165], v97 offset0:24 offset1:25
	ds_read2_b32 v[166:167], v97 offset0:26 offset1:27
	ds_read2_b32 v[168:169], v97 offset0:16 offset1:17
	ds_read2_b32 v[170:171], v97 offset0:18 offset1:19
	v_add_u32_e32 v72, 0xffffffd0, v95
	v_cmp_gt_u32_e64 s[0:1], 64, v72
	v_add_u32_e32 v73, 0xffffffe0, v95
	v_cmp_gt_u32_e64 s[4:5], 64, v73
	v_add_u32_e32 v74, 0xfffffff0, v95
	v_cmp_gt_u32_e64 s[6:7], 64, v74
	v_cmp_gt_u32_e64 s[20:21], 64, v95
	v_mfma_f32_16x16x32_bf16 v[64:67], v[132:135], v[180:183], v[64:67]
	v_mfma_f32_16x16x32_bf16 v[60:63], v[132:135], v[184:187], v[60:63]
	v_mfma_f32_16x16x32_bf16 v[64:67], v[136:139], v[172:175], v[64:67]
	v_mfma_f32_16x16x32_bf16 v[60:63], v[136:139], v[176:179], v[60:63]
	v_cndmask_b32_e64 v76, v68, v96, s[0:1]
	ds_read_b128 v[100:103], v76 offset:0
	ds_read_b128 v[104:107], v76 offset:64
	v_mfma_f32_16x16x32_bf16 v[48:51], v[140:143], v[180:183], v[48:51]
	v_mfma_f32_16x16x32_bf16 v[44:47], v[140:143], v[184:187], v[44:47]
	v_mfma_f32_16x16x32_bf16 v[48:51], v[144:147], v[172:175], v[48:51]
	v_mfma_f32_16x16x32_bf16 v[44:47], v[144:147], v[176:179], v[44:47]
	v_cndmask_b32_e64 v77, v69, v96, s[4:5]
	ds_read_b128 v[108:111], v77 offset:2304
	ds_read_b128 v[112:115], v77 offset:2368
	v_mfma_f32_16x16x32_bf16 v[32:35], v[148:151], v[180:183], v[32:35]
	v_mfma_f32_16x16x32_bf16 v[28:31], v[148:151], v[184:187], v[28:31]
	v_mfma_f32_16x16x32_bf16 v[32:35], v[152:155], v[172:175], v[32:35]
	v_mfma_f32_16x16x32_bf16 v[28:31], v[152:155], v[176:179], v[28:31]
	v_cndmask_b32_e64 v78, v70, v96, s[6:7]
	ds_read_b128 v[116:119], v78 offset:4608
	ds_read_b128 v[120:123], v78 offset:4672
	v_mfma_f32_16x16x32_bf16 v[16:19], v[156:159], v[180:183], v[16:19]
	v_mfma_f32_16x16x32_bf16 v[12:15], v[156:159], v[184:187], v[12:15]
	v_mfma_f32_16x16x32_bf16 v[16:19], v[160:163], v[172:175], v[16:19]
	v_mfma_f32_16x16x32_bf16 v[12:15], v[160:163], v[176:179], v[12:15]
	v_cndmask_b32_e64 v79, v71, v96, s[20:21]
	ds_read_b128 v[124:127], v79 offset:6912
	ds_read_b128 v[128:131], v79 offset:6976
	ds_read2_b32 v[172:173], v97 offset0:8 offset1:9
	ds_read2_b32 v[174:175], v97 offset0:10 offset1:11
	ds_read2_b32 v[176:177], v97 offset0:0 offset1:1
	ds_read2_b32 v[178:179], v97 offset0:2 offset1:3
	v_mfma_f32_16x16x32_bf16 v[56:59], v[132:135], v[188:191], v[56:59]
	v_mfma_f32_16x16x32_bf16 v[52:55], v[132:135], v[192:195], v[52:55]
	v_mfma_f32_16x16x32_bf16 v[56:59], v[136:139], v[180:183], v[56:59]
	v_mfma_f32_16x16x32_bf16 v[52:55], v[136:139], v[184:187], v[52:55]
	v_mfma_f32_16x16x32_bf16 v[40:43], v[140:143], v[188:191], v[40:43]
	v_mfma_f32_16x16x32_bf16 v[36:39], v[140:143], v[192:195], v[36:39]
	v_mfma_f32_16x16x32_bf16 v[40:43], v[144:147], v[180:183], v[40:43]
	v_mfma_f32_16x16x32_bf16 v[36:39], v[144:147], v[184:187], v[36:39]
	v_mfma_f32_16x16x32_bf16 v[24:27], v[148:151], v[188:191], v[24:27]
	v_mfma_f32_16x16x32_bf16 v[20:23], v[148:151], v[192:195], v[20:23]
	v_mfma_f32_16x16x32_bf16 v[24:27], v[152:155], v[180:183], v[24:27]
	v_mfma_f32_16x16x32_bf16 v[20:23], v[152:155], v[184:187], v[20:23]
	v_mfma_f32_16x16x32_bf16 v[8:11], v[156:159], v[188:191], v[8:11]
	v_mfma_f32_16x16x32_bf16 v[4:7], v[156:159], v[192:195], v[4:7]
	v_mfma_f32_16x16x32_bf16 v[8:11], v[160:163], v[180:183], v[8:11]
	v_mfma_f32_16x16x32_bf16 v[4:7], v[160:163], v[184:187], v[4:7]
	s_waitcnt lgkmcnt(0)
; #define MFMA16(a, b, c) __builtin_amdgcn_mfma_f32_16x16x32_bf16(__builtin_bit_cast(bf16x8, (a)), __builtin_bit_cast(bf16x8, (b)), (c), 0, 0, 0)
; DI void hyena_conv_unit(const Params& p, int item, char* smem) {
;     ...
;   for (int d = -63; d <= 63; ++d) {
; #pragma unroll
;     for (int kk = 0; kk < 2; ++kk) {
;       u32x4 bfr[4];
; #pragma unroll
;       for (int nn = 0; nn < 4; ++nn) bfr[nn] = bfrag(4 * d + nn - 2 * kk);
; #pragma unroll
;       for (int rb = 0; rb < 4; ++rb) {
;         if (d >= 16 * rb - 63 && d <= 16 * rb + 15) {
;           int t1 = 16 * rb + n, s1 = t1 - d;
;           u32x4 a = zero4();
;           if (s1 >= 0 && s1 < 64) a = *(const u32x4*)(su + s1 * 72 + 32 * kk + 8 * g);
; #pragma unroll
;           for (int nn = 0; nn < 4; ++nn) acc[rb][nn] = MFMA16(a, bfr[nn], acc[rb][nn]);
;         }
;       }
;     }
;   }
	v_add_u32_e32 v97, 0xffffff80, v97
	v_add_u32_e32 v96, 0xffffff70, v96
	v_add_u32_e32 v95, -1, v95
	ds_read2_b32 v[180:181], v97 offset0:24 offset1:25
	ds_read2_b32 v[182:183], v97 offset0:26 offset1:27
	ds_read2_b32 v[184:185], v97 offset0:16 offset1:17
	ds_read2_b32 v[186:187], v97 offset0:18 offset1:19
	v_add_u32_e32 v72, 0xffffffd0, v95
	v_cmp_gt_u32_e64 s[0:1], 64, v72
	v_add_u32_e32 v73, 0xffffffe0, v95
	v_cmp_gt_u32_e64 s[4:5], 64, v73
	v_add_u32_e32 v74, 0xfffffff0, v95
	v_cmp_gt_u32_e64 s[6:7], 64, v74
	v_cmp_gt_u32_e64 s[20:21], 64, v95
	v_mfma_f32_16x16x32_bf16 v[64:67], v[100:103], v[164:167], v[64:67]
	v_mfma_f32_16x16x32_bf16 v[60:63], v[100:103], v[168:171], v[60:63]
	v_mfma_f32_16x16x32_bf16 v[64:67], v[104:107], v[188:191], v[64:67]
	v_mfma_f32_16x16x32_bf16 v[60:63], v[104:107], v[192:195], v[60:63]
	v_cndmask_b32_e64 v76, v68, v96, s[0:1]
	ds_read_b128 v[132:135], v76 offset:0
	ds_read_b128 v[136:139], v76 offset:64
	v_mfma_f32_16x16x32_bf16 v[48:51], v[108:111], v[164:167], v[48:51]
	v_mfma_f32_16x16x32_bf16 v[44:47], v[108:111], v[168:171], v[44:47]
	v_mfma_f32_16x16x32_bf16 v[48:51], v[112:115], v[188:191], v[48:51]
	v_mfma_f32_16x16x32_bf16 v[44:47], v[112:115], v[192:195], v[44:47]
	v_cndmask_b32_e64 v77, v69, v96, s[4:5]
	ds_read_b128 v[140:143], v77 offset:2304
	ds_read_b128 v[144:147], v77 offset:2368
	v_mfma_f32_16x16x32_bf16 v[32:35], v[116:119], v[164:167], v[32:35]
	v_mfma_f32_16x16x32_bf16 v[28:31], v[116:119], v[168:171], v[28:31]
	v_mfma_f32_16x16x32_bf16 v[32:35], v[120:123], v[188:191], v[32:35]
	v_mfma_f32_16x16x32_bf16 v[28:31], v[120:123], v[192:195], v[28:31]
	v_cndmask_b32_e64 v78, v70, v96, s[6:7]
	ds_read_b128 v[148:151], v78 offset:4608
	ds_read_b128 v[152:155], v78 offset:4672
	v_mfma_f32_16x16x32_bf16 v[16:19], v[124:127], v[164:167], v[16:19]
	v_mfma_f32_16x16x32_bf16 v[12:15], v[124:127], v[168:171], v[12:15]
	v_mfma_f32_16x16x32_bf16 v[16:19], v[128:131], v[188:191], v[16:19]
	v_mfma_f32_16x16x32_bf16 v[12:15], v[128:131], v[192:195], v[12:15]
	v_cndmask_b32_e64 v79, v71, v96, s[20:21]
	ds_read_b128 v[156:159], v79 offset:6912
	ds_read_b128 v[160:163], v79 offset:6976
	ds_read2_b32 v[188:189], v97 offset0:8 offset1:9
	ds_read2_b32 v[190:191], v97 offset0:10 offset1:11
	ds_read2_b32 v[192:193], v97 offset0:0 offset1:1
	ds_read2_b32 v[194:195], v97 offset0:2 offset1:3
	v_mfma_f32_16x16x32_bf16 v[56:59], v[100:103], v[172:175], v[56:59]
	v_mfma_f32_16x16x32_bf16 v[52:55], v[100:103], v[176:179], v[52:55]
	v_mfma_f32_16x16x32_bf16 v[56:59], v[104:107], v[164:167], v[56:59]
	v_mfma_f32_16x16x32_bf16 v[52:55], v[104:107], v[168:171], v[52:55]
	v_mfma_f32_16x16x32_bf16 v[40:43], v[108:111], v[172:175], v[40:43]
	v_mfma_f32_16x16x32_bf16 v[36:39], v[108:111], v[176:179], v[36:39]
	v_mfma_f32_16x16x32_bf16 v[40:43], v[112:115], v[164:167], v[40:43]
	v_mfma_f32_16x16x32_bf16 v[36:39], v[112:115], v[168:171], v[36:39]
	v_mfma_f32_16x16x32_bf16 v[24:27], v[116:119], v[172:175], v[24:27]
	v_mfma_f32_16x16x32_bf16 v[20:23], v[116:119], v[176:179], v[20:23]
	v_mfma_f32_16x16x32_bf16 v[24:27], v[120:123], v[164:167], v[24:27]
	v_mfma_f32_16x16x32_bf16 v[20:23], v[120:123], v[168:171], v[20:23]
	v_mfma_f32_16x16x32_bf16 v[8:11], v[124:127], v[172:175], v[8:11]
	v_mfma_f32_16x16x32_bf16 v[4:7], v[124:127], v[176:179], v[4:7]
	v_mfma_f32_16x16x32_bf16 v[8:11], v[128:131], v[164:167], v[8:11]
	v_mfma_f32_16x16x32_bf16 v[4:7], v[128:131], v[168:171], v[4:7]
	s_sub_u32 s24, s24, 1
	s_cmp_lg_u32 s24, 0
	s_cbranch_scc1 .Lconv_seg3
	s_waitcnt lgkmcnt(0)
	v_add_u32_e32 v97, 0xffffff80, v97
	v_add_u32_e32 v96, 0xffffff70, v96
	v_add_u32_e32 v95, -1, v95
	ds_read2_b32 v[164:165], v97 offset0:24 offset1:25
	ds_read2_b32 v[166:167], v97 offset0:26 offset1:27
	ds_read2_b32 v[168:169], v97 offset0:16 offset1:17
	ds_read2_b32 v[170:171], v97 offset0:18 offset1:19
	v_add_u32_e32 v72, 0xffffffd0, v95
	v_cmp_gt_u32_e64 s[0:1], 64, v72
	v_add_u32_e32 v73, 0xffffffe0, v95
	v_cmp_gt_u32_e64 s[4:5], 64, v73
	v_add_u32_e32 v74, 0xfffffff0, v95
	v_cmp_gt_u32_e64 s[6:7], 64, v74
	v_cmp_gt_u32_e64 s[20:21], 64, v95
	v_mfma_f32_16x16x32_bf16 v[64:67], v[132:135], v[180:183], v[64:67]
	v_mfma_f32_16x16x32_bf16 v[60:63], v[132:135], v[184:187], v[60:63]
	v_mfma_f32_16x16x32_bf16 v[64:67], v[136:139], v[172:175], v[64:67]
	v_mfma_f32_16x16x32_bf16 v[60:63], v[136:139], v[176:179], v[60:63]
	v_cndmask_b32_e64 v76, v68, v96, s[0:1]
	ds_read_b128 v[100:103], v76 offset:0
	ds_read_b128 v[104:107], v76 offset:64
	v_mfma_f32_16x16x32_bf16 v[48:51], v[140:143], v[180:183], v[48:51]
	v_mfma_f32_16x16x32_bf16 v[44:47], v[140:143], v[184:187], v[44:47]
	v_mfma_f32_16x16x32_bf16 v[48:51], v[144:147], v[172:175], v[48:51]
	v_mfma_f32_16x16x32_bf16 v[44:47], v[144:147], v[176:179], v[44:47]
	v_cndmask_b32_e64 v77, v69, v96, s[4:5]
	ds_read_b128 v[108:111], v77 offset:2304
	ds_read_b128 v[112:115], v77 offset:2368
	v_mfma_f32_16x16x32_bf16 v[32:35], v[148:151], v[180:183], v[32:35]
	v_mfma_f32_16x16x32_bf16 v[28:31], v[148:151], v[184:187], v[28:31]
	v_mfma_f32_16x16x32_bf16 v[32:35], v[152:155], v[172:175], v[32:35]
	v_mfma_f32_16x16x32_bf16 v[28:31], v[152:155], v[176:179], v[28:31]
	v_cndmask_b32_e64 v78, v70, v96, s[6:7]
	ds_read_b128 v[116:119], v78 offset:4608
	ds_read_b128 v[120:123], v78 offset:4672
	v_mfma_f32_16x16x32_bf16 v[16:19], v[156:159], v[180:183], v[16:19]
	v_mfma_f32_16x16x32_bf16 v[12:15], v[156:159], v[184:187], v[12:15]
	v_mfma_f32_16x16x32_bf16 v[16:19], v[160:163], v[172:175], v[16:19]
	v_mfma_f32_16x16x32_bf16 v[12:15], v[160:163], v[176:179], v[12:15]
	v_cndmask_b32_e64 v79, v71, v96, s[20:21]
	ds_read_b128 v[124:127], v79 offset:6912
	ds_read_b128 v[128:131], v79 offset:6976
	ds_read2_b32 v[172:173], v97 offset0:8 offset1:9
	ds_read2_b32 v[174:175], v97 offset0:10 offset1:11
	ds_read2_b32 v[176:177], v97 offset0:0 offset1:1
	ds_read2_b32 v[178:179], v97 offset0:2 offset1:3
	v_mfma_f32_16x16x32_bf16 v[56:59], v[132:135], v[188:191], v[56:59]
	v_mfma_f32_16x16x32_bf16 v[52:55], v[132:135], v[192:195], v[52:55]
	v_mfma_f32_16x16x32_bf16 v[56:59], v[136:139], v[180:183], v[56:59]
	v_mfma_f32_16x16x32_bf16 v[52:55], v[136:139], v[184:187], v[52:55]
	v_mfma_f32_16x16x32_bf16 v[40:43], v[140:143], v[188:191], v[40:43]
	v_mfma_f32_16x16x32_bf16 v[36:39], v[140:143], v[192:195], v[36:39]
	v_mfma_f32_16x16x32_bf16 v[40:43], v[144:147], v[180:183], v[40:43]
	v_mfma_f32_16x16x32_bf16 v[36:39], v[144:147], v[184:187], v[36:39]
	v_mfma_f32_16x16x32_bf16 v[24:27], v[148:151], v[188:191], v[24:27]
	v_mfma_f32_16x16x32_bf16 v[20:23], v[148:151], v[192:195], v[20:23]
	v_mfma_f32_16x16x32_bf16 v[24:27], v[152:155], v[180:183], v[24:27]
	v_mfma_f32_16x16x32_bf16 v[20:23], v[152:155], v[184:187], v[20:23]
	v_mfma_f32_16x16x32_bf16 v[8:11], v[156:159], v[188:191], v[8:11]
	v_mfma_f32_16x16x32_bf16 v[4:7], v[156:159], v[192:195], v[4:7]
	v_mfma_f32_16x16x32_bf16 v[8:11], v[160:163], v[180:183], v[8:11]
	v_mfma_f32_16x16x32_bf16 v[4:7], v[160:163], v[184:187], v[4:7]
	s_waitcnt lgkmcnt(0)
; #define MFMA16(a, b, c) __builtin_amdgcn_mfma_f32_16x16x32_bf16(__builtin_bit_cast(bf16x8, (a)), __builtin_bit_cast(bf16x8, (b)), (c), 0, 0, 0)
; DI void hyena_conv_unit(const Params& p, int item, char* smem) {
;     ...
;   for (int d = -63; d <= 63; ++d) {
; #pragma unroll
;     for (int kk = 0; kk < 2; ++kk) {
;       u32x4 bfr[4];
; #pragma unroll
;       for (int nn = 0; nn < 4; ++nn) bfr[nn] = bfrag(4 * d + nn - 2 * kk);
; #pragma unroll
;       for (int rb = 0; rb < 4; ++rb) {
;         if (d >= 16 * rb - 63 && d <= 16 * rb + 15) {
;           int t1 = 16 * rb + n, s1 = t1 - d;
;           u32x4 a = zero4();
;           if (s1 >= 0 && s1 < 64) a = *(const u32x4*)(su + s1 * 72 + 32 * kk + 8 * g);
; #pragma unroll
;           for (int nn = 0; nn < 4; ++nn) acc[rb][nn] = MFMA16(a, bfr[nn], acc[rb][nn]);
;         }
;       }
;     }
;   }
	v_add_u32_e32 v97, 0xffffff80, v97
	v_add_u32_e32 v96, 0xffffff70, v96
	v_add_u32_e32 v95, -1, v95
	ds_read2_b32 v[180:181], v97 offset0:24 offset1:25
	ds_read2_b32 v[182:183], v97 offset0:26 offset1:27
	ds_read2_b32 v[184:185], v97 offset0:16 offset1:17
	ds_read2_b32 v[186:187], v97 offset0:18 offset1:19
	v_add_u32_e32 v73, 0xffffffe0, v95
	v_cmp_gt_u32_e64 s[4:5], 64, v73
	v_add_u32_e32 v74, 0xfffffff0, v95
	v_cmp_gt_u32_e64 s[6:7], 64, v74
	v_cmp_gt_u32_e64 s[20:21], 64, v95
	v_mfma_f32_16x16x32_bf16 v[64:67], v[100:103], v[164:167], v[64:67]
	v_mfma_f32_16x16x32_bf16 v[60:63], v[100:103], v[168:171], v[60:63]
	v_mfma_f32_16x16x32_bf16 v[64:67], v[104:107], v[188:191], v[64:67]
	v_mfma_f32_16x16x32_bf16 v[60:63], v[104:107], v[192:195], v[60:63]
	v_cndmask_b32_e64 v77, v69, v96, s[4:5]
	ds_read_b128 v[140:143], v77 offset:2304
	ds_read_b128 v[144:147], v77 offset:2368
	v_mfma_f32_16x16x32_bf16 v[48:51], v[108:111], v[164:167], v[48:51]
	v_mfma_f32_16x16x32_bf16 v[44:47], v[108:111], v[168:171], v[44:47]
	v_mfma_f32_16x16x32_bf16 v[48:51], v[112:115], v[188:191], v[48:51]
	v_mfma_f32_16x16x32_bf16 v[44:47], v[112:115], v[192:195], v[44:47]
	v_cndmask_b32_e64 v78, v70, v96, s[6:7]
	ds_read_b128 v[148:151], v78 offset:4608
	ds_read_b128 v[152:155], v78 offset:4672
	v_mfma_f32_16x16x32_bf16 v[32:35], v[116:119], v[164:167], v[32:35]
	v_mfma_f32_16x16x32_bf16 v[28:31], v[116:119], v[168:171], v[28:31]
	v_mfma_f32_16x16x32_bf16 v[32:35], v[120:123], v[188:191], v[32:35]
	v_mfma_f32_16x16x32_bf16 v[28:31], v[120:123], v[192:195], v[28:31]
	v_cndmask_b32_e64 v79, v71, v96, s[20:21]
	ds_read_b128 v[156:159], v79 offset:6912
	ds_read_b128 v[160:163], v79 offset:6976
	v_mfma_f32_16x16x32_bf16 v[16:19], v[124:127], v[164:167], v[16:19]
	v_mfma_f32_16x16x32_bf16 v[12:15], v[124:127], v[168:171], v[12:15]
	v_mfma_f32_16x16x32_bf16 v[16:19], v[128:131], v[188:191], v[16:19]
	v_mfma_f32_16x16x32_bf16 v[12:15], v[128:131], v[192:195], v[12:15]
	ds_read2_b32 v[188:189], v97 offset0:8 offset1:9
	ds_read2_b32 v[190:191], v97 offset0:10 offset1:11
	ds_read2_b32 v[192:193], v97 offset0:0 offset1:1
	ds_read2_b32 v[194:195], v97 offset0:2 offset1:3
	v_mfma_f32_16x16x32_bf16 v[56:59], v[100:103], v[172:175], v[56:59]
	v_mfma_f32_16x16x32_bf16 v[52:55], v[100:103], v[176:179], v[52:55]
	v_mfma_f32_16x16x32_bf16 v[56:59], v[104:107], v[164:167], v[56:59]
	v_mfma_f32_16x16x32_bf16 v[52:55], v[104:107], v[168:171], v[52:55]
	v_mfma_f32_16x16x32_bf16 v[40:43], v[108:111], v[172:175], v[40:43]
	v_mfma_f32_16x16x32_bf16 v[36:39], v[108:111], v[176:179], v[36:39]
	v_mfma_f32_16x16x32_bf16 v[40:43], v[112:115], v[164:167], v[40:43]
	v_mfma_f32_16x16x32_bf16 v[36:39], v[112:115], v[168:171], v[36:39]
	v_mfma_f32_16x16x32_bf16 v[24:27], v[116:119], v[172:175], v[24:27]
	v_mfma_f32_16x16x32_bf16 v[20:23], v[116:119], v[176:179], v[20:23]
	v_mfma_f32_16x16x32_bf16 v[24:27], v[120:123], v[164:167], v[24:27]
	v_mfma_f32_16x16x32_bf16 v[20:23], v[120:123], v[168:171], v[20:23]
	v_mfma_f32_16x16x32_bf16 v[8:11], v[124:127], v[172:175], v[8:11]
	v_mfma_f32_16x16x32_bf16 v[4:7], v[124:127], v[176:179], v[4:7]
	v_mfma_f32_16x16x32_bf16 v[8:11], v[128:131], v[164:167], v[8:11]
	v_mfma_f32_16x16x32_bf16 v[4:7], v[128:131], v[168:171], v[4:7]
	s_mov_b32 s24, 7
.Lconv_seg4:
	s_waitcnt lgkmcnt(0)
	v_add_u32_e32 v97, 0xffffff80, v97
	v_add_u32_e32 v96, 0xffffff70, v96
	v_add_u32_e32 v95, -1, v95
	ds_read2_b32 v[164:165], v97 offset0:24 offset1:25
	ds_read2_b32 v[166:167], v97 offset0:26 offset1:27
	ds_read2_b32 v[168:169], v97 offset0:16 offset1:17
	ds_read2_b32 v[170:171], v97 offset0:18 offset1:19
	v_add_u32_e32 v73, 0xffffffe0, v95
	v_cmp_gt_u32_e64 s[4:5], 64, v73
	v_add_u32_e32 v74, 0xfffffff0, v95
	v_cmp_gt_u32_e64 s[6:7], 64, v74
	v_cmp_gt_u32_e64 s[20:21], 64, v95
	v_mfma_f32_16x16x32_bf16 v[48:51], v[140:143], v[180:183], v[48:51]
	v_mfma_f32_16x16x32_bf16 v[44:47], v[140:143], v[184:187], v[44:47]
	v_mfma_f32_16x16x32_bf16 v[48:51], v[144:147], v[172:175], v[48:51]
	v_mfma_f32_16x16x32_bf16 v[44:47], v[144:147], v[176:179], v[44:47]
	v_cndmask_b32_e64 v77, v69, v96, s[4:5]
	ds_read_b128 v[108:111], v77 offset:2304
	ds_read_b128 v[112:115], v77 offset:2368
	v_mfma_f32_16x16x32_bf16 v[32:35], v[148:151], v[180:183], v[32:35]
	v_mfma_f32_16x16x32_bf16 v[28:31], v[148:151], v[184:187], v[28:31]
	v_mfma_f32_16x16x32_bf16 v[32:35], v[152:155], v[172:175], v[32:35]
	v_mfma_f32_16x16x32_bf16 v[28:31], v[152:155], v[176:179], v[28:31]
	v_cndmask_b32_e64 v78, v70, v96, s[6:7]
	ds_read_b128 v[116:119], v78 offset:4608
	ds_read_b128 v[120:123], v78 offset:4672
	v_mfma_f32_16x16x32_bf16 v[16:19], v[156:159], v[180:183], v[16:19]
	v_mfma_f32_16x16x32_bf16 v[12:15], v[156:159], v[184:187], v[12:15]
	v_mfma_f32_16x16x32_bf16 v[16:19], v[160:163], v[172:175], v[16:19]
	v_mfma_f32_16x16x32_bf16 v[12:15], v[160:163], v[176:179], v[12:15]
	v_cndmask_b32_e64 v79, v71, v96, s[20:21]
	ds_read_b128 v[124:127], v79 offset:6912
	ds_read_b128 v[128:131], v79 offset:6976
	ds_read2_b32 v[172:173], v97 offset0:8 offset1:9
	ds_read2_b32 v[174:175], v97 offset0:10 offset1:11
	ds_read2_b32 v[176:177], v97 offset0:0 offset1:1
	ds_read2_b32 v[178:179], v97 offset0:2 offset1:3
	v_mfma_f32_16x16x32_bf16 v[40:43], v[140:143], v[188:191], v[40:43]
	v_mfma_f32_16x16x32_bf16 v[36:39], v[140:143], v[192:195], v[36:39]
	v_mfma_f32_16x16x32_bf16 v[40:43], v[144:147], v[180:183], v[40:43]
	v_mfma_f32_16x16x32_bf16 v[36:39], v[144:147], v[184:187], v[36:39]
	v_mfma_f32_16x16x32_bf16 v[24:27], v[148:151], v[188:191], v[24:27]
	v_mfma_f32_16x16x32_bf16 v[20:23], v[148:151], v[192:195], v[20:23]
	v_mfma_f32_16x16x32_bf16 v[24:27], v[152:155], v[180:183], v[24:27]
	v_mfma_f32_16x16x32_bf16 v[20:23], v[152:155], v[184:187], v[20:23]
	v_mfma_f32_16x16x32_bf16 v[8:11], v[156:159], v[188:191], v[8:11]
	v_mfma_f32_16x16x32_bf16 v[4:7], v[156:159], v[192:195], v[4:7]
	v_mfma_f32_16x16x32_bf16 v[8:11], v[160:163], v[180:183], v[8:11]
	v_mfma_f32_16x16x32_bf16 v[4:7], v[160:163], v[184:187], v[4:7]
	s_waitcnt lgkmcnt(0)
; #define MFMA16(a, b, c) __builtin_amdgcn_mfma_f32_16x16x32_bf16(__builtin_bit_cast(bf16x8, (a)), __builtin_bit_cast(bf16x8, (b)), (c), 0, 0, 0)
; DI void hyena_conv_unit(const Params& p, int item, char* smem) {
;     ...
;   for (int d = -63; d <= 63; ++d) {
; #pragma unroll
;     for (int kk = 0; kk < 2; ++kk) {
;       u32x4 bfr[4];
; #pragma unroll
;       for (int nn = 0; nn < 4; ++nn) bfr[nn] = bfrag(4 * d + nn - 2 * kk);
; #pragma unroll
;       for (int rb = 0; rb < 4; ++rb) {
;         if (d >= 16 * rb - 63 && d <= 16 * rb + 15) {
;           int t1 = 16 * rb + n, s1 = t1 - d;
;           u32x4 a = zero4();
;           if (s1 >= 0 && s1 < 64) a = *(const u32x4*)(su + s1 * 72 + 32 * kk + 8 * g);
; #pragma unroll
;           for (int nn = 0; nn < 4; ++nn) acc[rb][nn] = MFMA16(a, bfr[nn], acc[rb][nn]);
;         }
;       }
;     }
;   }
	v_add_u32_e32 v97, 0xffffff80, v97
	v_add_u32_e32 v96, 0xffffff70, v96
	v_add_u32_e32 v95, -1, v95
	ds_read2_b32 v[180:181], v97 offset0:24 offset1:25
	ds_read2_b32 v[182:183], v97 offset0:26 offset1:27
	ds_read2_b32 v[184:185], v97 offset0:16 offset1:17
	ds_read2_b32 v[186:187], v97 offset0:18 offset1:19
	v_add_u32_e32 v73, 0xffffffe0, v95
	v_cmp_gt_u32_e64 s[4:5], 64, v73
	v_add_u32_e32 v74, 0xfffffff0, v95
	v_cmp_gt_u32_e64 s[6:7], 64, v74
	v_cmp_gt_u32_e64 s[20:21], 64, v95
	v_mfma_f32_16x16x32_bf16 v[48:51], v[108:111], v[164:167], v[48:51]
	v_mfma_f32_16x16x32_bf16 v[44:47], v[108:111], v[168:171], v[44:47]
	v_mfma_f32_16x16x32_bf16 v[48:51], v[112:115], v[188:191], v[48:51]
	v_mfma_f32_16x16x32_bf16 v[44:47], v[112:115], v[192:195], v[44:47]
	v_cndmask_b32_e64 v77, v69, v96, s[4:5]
	ds_read_b128 v[140:143], v77 offset:2304
	ds_read_b128 v[144:147], v77 offset:2368
	v_mfma_f32_16x16x32_bf16 v[32:35], v[116:119], v[164:167], v[32:35]
	v_mfma_f32_16x16x32_bf16 v[28:31], v[116:119], v[168:171], v[28:31]
	v_mfma_f32_16x16x32_bf16 v[32:35], v[120:123], v[188:191], v[32:35]
	v_mfma_f32_16x16x32_bf16 v[28:31], v[120:123], v[192:195], v[28:31]
	v_cndmask_b32_e64 v78, v70, v96, s[6:7]
	ds_read_b128 v[148:151], v78 offset:4608
	ds_read_b128 v[152:155], v78 offset:4672
	v_mfma_f32_16x16x32_bf16 v[16:19], v[124:127], v[164:167], v[16:19]
	v_mfma_f32_16x16x32_bf16 v[12:15], v[124:127], v[168:171], v[12:15]
	v_mfma_f32_16x16x32_bf16 v[16:19], v[128:131], v[188:191], v[16:19]
	v_mfma_f32_16x16x32_bf16 v[12:15], v[128:131], v[192:195], v[12:15]
	v_cndmask_b32_e64 v79, v71, v96, s[20:21]
	ds_read_b128 v[156:159], v79 offset:6912
	ds_read_b128 v[160:163], v79 offset:6976
	ds_read2_b32 v[188:189], v97 offset0:8 offset1:9
	ds_read2_b32 v[190:191], v97 offset0:10 offset1:11
	ds_read2_b32 v[192:193], v97 offset0:0 offset1:1
	ds_read2_b32 v[194:195], v97 offset0:2 offset1:3
	v_mfma_f32_16x16x32_bf16 v[40:43], v[108:111], v[172:175], v[40:43]
	v_mfma_f32_16x16x32_bf16 v[36:39], v[108:111], v[176:179], v[36:39]
	v_mfma_f32_16x16x32_bf16 v[40:43], v[112:115], v[164:167], v[40:43]
	v_mfma_f32_16x16x32_bf16 v[36:39], v[112:115], v[168:171], v[36:39]
	v_mfma_f32_16x16x32_bf16 v[24:27], v[116:119], v[172:175], v[24:27]
	v_mfma_f32_16x16x32_bf16 v[20:23], v[116:119], v[176:179], v[20:23]
	v_mfma_f32_16x16x32_bf16 v[24:27], v[120:123], v[164:167], v[24:27]
	v_mfma_f32_16x16x32_bf16 v[20:23], v[120:123], v[168:171], v[20:23]
	v_mfma_f32_16x16x32_bf16 v[8:11], v[124:127], v[172:175], v[8:11]
	v_mfma_f32_16x16x32_bf16 v[4:7], v[124:127], v[176:179], v[4:7]
	v_mfma_f32_16x16x32_bf16 v[8:11], v[128:131], v[164:167], v[8:11]
	v_mfma_f32_16x16x32_bf16 v[4:7], v[128:131], v[168:171], v[4:7]
	s_sub_u32 s24, s24, 1
	s_cmp_lg_u32 s24, 0
	s_cbranch_scc1 .Lconv_seg4
	s_waitcnt lgkmcnt(0)
	v_add_u32_e32 v97, 0xffffff80, v97
	v_add_u32_e32 v96, 0xffffff70, v96
	v_add_u32_e32 v95, -1, v95
	ds_read2_b32 v[164:165], v97 offset0:24 offset1:25
	ds_read2_b32 v[166:167], v97 offset0:26 offset1:27
	ds_read2_b32 v[168:169], v97 offset0:16 offset1:17
	ds_read2_b32 v[170:171], v97 offset0:18 offset1:19
	v_add_u32_e32 v73, 0xffffffe0, v95
	v_cmp_gt_u32_e64 s[4:5], 64, v73
	v_add_u32_e32 v74, 0xfffffff0, v95
	v_cmp_gt_u32_e64 s[6:7], 64, v74
	v_cmp_gt_u32_e64 s[20:21], 64, v95
	v_mfma_f32_16x16x32_bf16 v[48:51], v[140:143], v[180:183], v[48:51]
	v_mfma_f32_16x16x32_bf16 v[44:47], v[140:143], v[184:187], v[44:47]
	v_mfma_f32_16x16x32_bf16 v[48:51], v[144:147], v[172:175], v[48:51]
	v_mfma_f32_16x16x32_bf16 v[44:47], v[144:147], v[176:179], v[44:47]
	v_cndmask_b32_e64 v77, v69, v96, s[4:5]
	ds_read_b128 v[108:111], v77 offset:2304
	ds_read_b128 v[112:115], v77 offset:2368
	v_mfma_f32_16x16x32_bf16 v[32:35], v[148:151], v[180:183], v[32:35]
	v_mfma_f32_16x16x32_bf16 v[28:31], v[148:151], v[184:187], v[28:31]
	v_mfma_f32_16x16x32_bf16 v[32:35], v[152:155], v[172:175], v[32:35]
	v_mfma_f32_16x16x32_bf16 v[28:31], v[152:155], v[176:179], v[28:31]
	v_cndmask_b32_e64 v78, v70, v96, s[6:7]
	ds_read_b128 v[116:119], v78 offset:4608
	ds_read_b128 v[120:123], v78 offset:4672
	v_mfma_f32_16x16x32_bf16 v[16:19], v[156:159], v[180:183], v[16:19]
	v_mfma_f32_16x16x32_bf16 v[12:15], v[156:159], v[184:187], v[12:15]
	v_mfma_f32_16x16x32_bf16 v[16:19], v[160:163], v[172:175], v[16:19]
	v_mfma_f32_16x16x32_bf16 v[12:15], v[160:163], v[176:179], v[12:15]
	v_cndmask_b32_e64 v79, v71, v96, s[20:21]
	ds_read_b128 v[124:127], v79 offset:6912
	ds_read_b128 v[128:131], v79 offset:6976
	ds_read2_b32 v[172:173], v97 offset0:8 offset1:9
	ds_read2_b32 v[174:175], v97 offset0:10 offset1:11
	ds_read2_b32 v[176:177], v97 offset0:0 offset1:1
	ds_read2_b32 v[178:179], v97 offset0:2 offset1:3
	v_mfma_f32_16x16x32_bf16 v[40:43], v[140:143], v[188:191], v[40:43]
	v_mfma_f32_16x16x32_bf16 v[36:39], v[140:143], v[192:195], v[36:39]
	v_mfma_f32_16x16x32_bf16 v[40:43], v[144:147], v[180:183], v[40:43]
	v_mfma_f32_16x16x32_bf16 v[36:39], v[144:147], v[184:187], v[36:39]
	v_mfma_f32_16x16x32_bf16 v[24:27], v[148:151], v[188:191], v[24:27]
	v_mfma_f32_16x16x32_bf16 v[20:23], v[148:151], v[192:195], v[20:23]
	v_mfma_f32_16x16x32_bf16 v[24:27], v[152:155], v[180:183], v[24:27]
	v_mfma_f32_16x16x32_bf16 v[20:23], v[152:155], v[184:187], v[20:23]
	v_mfma_f32_16x16x32_bf16 v[8:11], v[156:159], v[188:191], v[8:11]
	v_mfma_f32_16x16x32_bf16 v[4:7], v[156:159], v[192:195], v[4:7]
	v_mfma_f32_16x16x32_bf16 v[8:11], v[160:163], v[180:183], v[8:11]
	v_mfma_f32_16x16x32_bf16 v[4:7], v[160:163], v[184:187], v[4:7]
	s_waitcnt lgkmcnt(0)
; #define MFMA16(a, b, c) __builtin_amdgcn_mfma_f32_16x16x32_bf16(__builtin_bit_cast(bf16x8, (a)), __builtin_bit_cast(bf16x8, (b)), (c), 0, 0, 0)
; DI void hyena_conv_unit(const Params& p, int item, char* smem) {
;     ...
;   for (int d = -63; d <= 63; ++d) {
; #pragma unroll
;     for (int kk = 0; kk < 2; ++kk) {
;       u32x4 bfr[4];
; #pragma unroll
;       for (int nn = 0; nn < 4; ++nn) bfr[nn] = bfrag(4 * d + nn - 2 * kk);
; #pragma unroll
;       for (int rb = 0; rb < 4; ++rb) {
;         if (d >= 16 * rb - 63 && d <= 16 * rb + 15) {
;           int t1 = 16 * rb + n, s1 = t1 - d;
;           u32x4 a = zero4();
;           if (s1 >= 0 && s1 < 64) a = *(const u32x4*)(su + s1 * 72 + 32 * kk + 8 * g);
; #pragma unroll
;           for (int nn = 0; nn < 4; ++nn) acc[rb][nn] = MFMA16(a, bfr[nn], acc[rb][nn]);
;         }
;       }
;     }
;   }
	v_add_u32_e32 v97, 0xffffff80, v97
	v_add_u32_e32 v96, 0xffffff70, v96
	v_add_u32_e32 v95, -1, v95
	ds_read2_b32 v[180:181], v97 offset0:24 offset1:25
	ds_read2_b32 v[182:183], v97 offset0:26 offset1:27
	ds_read2_b32 v[184:185], v97 offset0:16 offset1:17
	ds_read2_b32 v[186:187], v97 offset0:18 offset1:19
	v_add_u32_e32 v74, 0xfffffff0, v95
	v_cmp_gt_u32_e64 s[6:7], 64, v74
	v_cmp_gt_u32_e64 s[20:21], 64, v95
	v_mfma_f32_16x16x32_bf16 v[48:51], v[108:111], v[164:167], v[48:51]
	v_mfma_f32_16x16x32_bf16 v[44:47], v[108:111], v[168:171], v[44:47]
	v_mfma_f32_16x16x32_bf16 v[48:51], v[112:115], v[188:191], v[48:51]
	v_mfma_f32_16x16x32_bf16 v[44:47], v[112:115], v[192:195], v[44:47]
	v_cndmask_b32_e64 v78, v70, v96, s[6:7]
	ds_read_b128 v[148:151], v78 offset:4608
	ds_read_b128 v[152:155], v78 offset:4672
	v_mfma_f32_16x16x32_bf16 v[32:35], v[116:119], v[164:167], v[32:35]
	v_mfma_f32_16x16x32_bf16 v[28:31], v[116:119], v[168:171], v[28:31]
	v_mfma_f32_16x16x32_bf16 v[32:35], v[120:123], v[188:191], v[32:35]
	v_mfma_f32_16x16x32_bf16 v[28:31], v[120:123], v[192:195], v[28:31]
	v_cndmask_b32_e64 v79, v71, v96, s[20:21]
	ds_read_b128 v[156:159], v79 offset:6912
	ds_read_b128 v[160:163], v79 offset:6976
	v_mfma_f32_16x16x32_bf16 v[16:19], v[124:127], v[164:167], v[16:19]
	v_mfma_f32_16x16x32_bf16 v[12:15], v[124:127], v[168:171], v[12:15]
	v_mfma_f32_16x16x32_bf16 v[16:19], v[128:131], v[188:191], v[16:19]
	v_mfma_f32_16x16x32_bf16 v[12:15], v[128:131], v[192:195], v[12:15]
	ds_read2_b32 v[188:189], v97 offset0:8 offset1:9
	ds_read2_b32 v[190:191], v97 offset0:10 offset1:11
	ds_read2_b32 v[192:193], v97 offset0:0 offset1:1
	ds_read2_b32 v[194:195], v97 offset0:2 offset1:3
	v_mfma_f32_16x16x32_bf16 v[40:43], v[108:111], v[172:175], v[40:43]
	v_mfma_f32_16x16x32_bf16 v[36:39], v[108:111], v[176:179], v[36:39]
	v_mfma_f32_16x16x32_bf16 v[40:43], v[112:115], v[164:167], v[40:43]
	v_mfma_f32_16x16x32_bf16 v[36:39], v[112:115], v[168:171], v[36:39]
	v_mfma_f32_16x16x32_bf16 v[24:27], v[116:119], v[172:175], v[24:27]
	v_mfma_f32_16x16x32_bf16 v[20:23], v[116:119], v[176:179], v[20:23]
	v_mfma_f32_16x16x32_bf16 v[24:27], v[120:123], v[164:167], v[24:27]
	v_mfma_f32_16x16x32_bf16 v[20:23], v[120:123], v[168:171], v[20:23]
	v_mfma_f32_16x16x32_bf16 v[8:11], v[124:127], v[172:175], v[8:11]
	v_mfma_f32_16x16x32_bf16 v[4:7], v[124:127], v[176:179], v[4:7]
	v_mfma_f32_16x16x32_bf16 v[8:11], v[128:131], v[164:167], v[8:11]
	v_mfma_f32_16x16x32_bf16 v[4:7], v[128:131], v[168:171], v[4:7]
	s_mov_b32 s24, 7
.Lconv_seg5:
	s_waitcnt lgkmcnt(0)
	v_add_u32_e32 v97, 0xffffff80, v97
	v_add_u32_e32 v96, 0xffffff70, v96
	v_add_u32_e32 v95, -1, v95
	ds_read2_b32 v[164:165], v97 offset0:24 offset1:25
	ds_read2_b32 v[166:167], v97 offset0:26 offset1:27
	ds_read2_b32 v[168:169], v97 offset0:16 offset1:17
	ds_read2_b32 v[170:171], v97 offset0:18 offset1:19
	v_add_u32_e32 v74, 0xfffffff0, v95
	v_cmp_gt_u32_e64 s[6:7], 64, v74
	v_cmp_gt_u32_e64 s[20:21], 64, v95
	v_mfma_f32_16x16x32_bf16 v[32:35], v[148:151], v[180:183], v[32:35]
	v_mfma_f32_16x16x32_bf16 v[28:31], v[148:151], v[184:187], v[28:31]
	v_mfma_f32_16x16x32_bf16 v[32:35], v[152:155], v[172:175], v[32:35]
	v_mfma_f32_16x16x32_bf16 v[28:31], v[152:155], v[176:179], v[28:31]
	v_cndmask_b32_e64 v78, v70, v96, s[6:7]
	ds_read_b128 v[116:119], v78 offset:4608
	ds_read_b128 v[120:123], v78 offset:4672
	v_mfma_f32_16x16x32_bf16 v[16:19], v[156:159], v[180:183], v[16:19]
	v_mfma_f32_16x16x32_bf16 v[12:15], v[156:159], v[184:187], v[12:15]
	v_mfma_f32_16x16x32_bf16 v[16:19], v[160:163], v[172:175], v[16:19]
	v_mfma_f32_16x16x32_bf16 v[12:15], v[160:163], v[176:179], v[12:15]
	v_cndmask_b32_e64 v79, v71, v96, s[20:21]
	ds_read_b128 v[124:127], v79 offset:6912
	ds_read_b128 v[128:131], v79 offset:6976
	ds_read2_b32 v[172:173], v97 offset0:8 offset1:9
	ds_read2_b32 v[174:175], v97 offset0:10 offset1:11
	ds_read2_b32 v[176:177], v97 offset0:0 offset1:1
	ds_read2_b32 v[178:179], v97 offset0:2 offset1:3
	v_mfma_f32_16x16x32_bf16 v[24:27], v[148:151], v[188:191], v[24:27]
	v_mfma_f32_16x16x32_bf16 v[20:23], v[148:151], v[192:195], v[20:23]
	v_mfma_f32_16x16x32_bf16 v[24:27], v[152:155], v[180:183], v[24:27]
	v_mfma_f32_16x16x32_bf16 v[20:23], v[152:155], v[184:187], v[20:23]
	v_mfma_f32_16x16x32_bf16 v[8:11], v[156:159], v[188:191], v[8:11]
	v_mfma_f32_16x16x32_bf16 v[4:7], v[156:159], v[192:195], v[4:7]
	v_mfma_f32_16x16x32_bf16 v[8:11], v[160:163], v[180:183], v[8:11]
	v_mfma_f32_16x16x32_bf16 v[4:7], v[160:163], v[184:187], v[4:7]
	s_waitcnt lgkmcnt(0)
	v_add_u32_e32 v97, 0xffffff80, v97
	v_add_u32_e32 v96, 0xffffff70, v96
	v_add_u32_e32 v95, -1, v95
	ds_read2_b32 v[180:181], v97 offset0:24 offset1:25
	ds_read2_b32 v[182:183], v97 offset0:26 offset1:27
	ds_read2_b32 v[184:185], v97 offset0:16 offset1:17
	ds_read2_b32 v[186:187], v97 offset0:18 offset1:19
	v_add_u32_e32 v74, 0xfffffff0, v95
	v_cmp_gt_u32_e64 s[6:7], 64, v74
	v_cmp_gt_u32_e64 s[20:21], 64, v95
	v_mfma_f32_16x16x32_bf16 v[32:35], v[116:119], v[164:167], v[32:35]
	v_mfma_f32_16x16x32_bf16 v[28:31], v[116:119], v[168:171], v[28:31]
	v_mfma_f32_16x16x32_bf16 v[32:35], v[120:123], v[188:191], v[32:35]
	v_mfma_f32_16x16x32_bf16 v[28:31], v[120:123], v[192:195], v[28:31]
	v_cndmask_b32_e64 v78, v70, v96, s[6:7]
	ds_read_b128 v[148:151], v78 offset:4608
	ds_read_b128 v[152:155], v78 offset:4672
	v_mfma_f32_16x16x32_bf16 v[16:19], v[124:127], v[164:167], v[16:19]
	v_mfma_f32_16x16x32_bf16 v[12:15], v[124:127], v[168:171], v[12:15]
	v_mfma_f32_16x16x32_bf16 v[16:19], v[128:131], v[188:191], v[16:19]
	v_mfma_f32_16x16x32_bf16 v[12:15], v[128:131], v[192:195], v[12:15]
	v_cndmask_b32_e64 v79, v71, v96, s[20:21]
	ds_read_b128 v[156:159], v79 offset:6912
	ds_read_b128 v[160:163], v79 offset:6976
	ds_read2_b32 v[188:189], v97 offset0:8 offset1:9
	ds_read2_b32 v[190:191], v97 offset0:10 offset1:11
	ds_read2_b32 v[192:193], v97 offset0:0 offset1:1
	ds_read2_b32 v[194:195], v97 offset0:2 offset1:3
	v_mfma_f32_16x16x32_bf16 v[24:27], v[116:119], v[172:175], v[24:27]
	v_mfma_f32_16x16x32_bf16 v[20:23], v[116:119], v[176:179], v[20:23]
	v_mfma_f32_16x16x32_bf16 v[24:27], v[120:123], v[164:167], v[24:27]
	v_mfma_f32_16x16x32_bf16 v[20:23], v[120:123], v[168:171], v[20:23]
	v_mfma_f32_16x16x32_bf16 v[8:11], v[124:127], v[172:175], v[8:11]
	v_mfma_f32_16x16x32_bf16 v[4:7], v[124:127], v[176:179], v[4:7]
	v_mfma_f32_16x16x32_bf16 v[8:11], v[128:131], v[164:167], v[8:11]
	v_mfma_f32_16x16x32_bf16 v[4:7], v[128:131], v[168:171], v[4:7]
	s_sub_u32 s24, s24, 1
	s_cmp_lg_u32 s24, 0
	s_cbranch_scc1 .Lconv_seg5
; #define MFMA16(a, b, c) __builtin_amdgcn_mfma_f32_16x16x32_bf16(__builtin_bit_cast(bf16x8, (a)), __builtin_bit_cast(bf16x8, (b)), (c), 0, 0, 0)
; DI void hyena_conv_unit(const Params& p, int item, char* smem) {
;     ...
;   for (int d = -63; d <= 63; ++d) {
; #pragma unroll
;     for (int kk = 0; kk < 2; ++kk) {
;       u32x4 bfr[4];
; #pragma unroll
;       for (int nn = 0; nn < 4; ++nn) bfr[nn] = bfrag(4 * d + nn - 2 * kk);
; #pragma unroll
;       for (int rb = 0; rb < 4; ++rb) {
;         if (d >= 16 * rb - 63 && d <= 16 * rb + 15) {
;           int t1 = 16 * rb + n, s1 = t1 - d;
;           u32x4 a = zero4();
;           if (s1 >= 0 && s1 < 64) a = *(const u32x4*)(su + s1 * 72 + 32 * kk + 8 * g);
; #pragma unroll
;           for (int nn = 0; nn < 4; ++nn) acc[rb][nn] = MFMA16(a, bfr[nn], acc[rb][nn]);
;         }
;       }
;     }
;   }
	s_waitcnt lgkmcnt(0)
	v_add_u32_e32 v97, 0xffffff80, v97
	v_add_u32_e32 v96, 0xffffff70, v96
	v_add_u32_e32 v95, -1, v95
	ds_read2_b32 v[164:165], v97 offset0:24 offset1:25
	ds_read2_b32 v[166:167], v97 offset0:26 offset1:27
	ds_read2_b32 v[168:169], v97 offset0:16 offset1:17
	ds_read2_b32 v[170:171], v97 offset0:18 offset1:19
	v_add_u32_e32 v74, 0xfffffff0, v95
	v_cmp_gt_u32_e64 s[6:7], 64, v74
	v_cmp_gt_u32_e64 s[20:21], 64, v95
	v_mfma_f32_16x16x32_bf16 v[32:35], v[148:151], v[180:183], v[32:35]
	v_mfma_f32_16x16x32_bf16 v[28:31], v[148:151], v[184:187], v[28:31]
	v_mfma_f32_16x16x32_bf16 v[32:35], v[152:155], v[172:175], v[32:35]
	v_mfma_f32_16x16x32_bf16 v[28:31], v[152:155], v[176:179], v[28:31]
	v_cndmask_b32_e64 v78, v70, v96, s[6:7]
	ds_read_b128 v[116:119], v78 offset:4608
	ds_read_b128 v[120:123], v78 offset:4672
	v_mfma_f32_16x16x32_bf16 v[16:19], v[156:159], v[180:183], v[16:19]
	v_mfma_f32_16x16x32_bf16 v[12:15], v[156:159], v[184:187], v[12:15]
	v_mfma_f32_16x16x32_bf16 v[16:19], v[160:163], v[172:175], v[16:19]
	v_mfma_f32_16x16x32_bf16 v[12:15], v[160:163], v[176:179], v[12:15]
	v_cndmask_b32_e64 v79, v71, v96, s[20:21]
	ds_read_b128 v[124:127], v79 offset:6912
	ds_read_b128 v[128:131], v79 offset:6976
	ds_read2_b32 v[172:173], v97 offset0:8 offset1:9
	ds_read2_b32 v[174:175], v97 offset0:10 offset1:11
	ds_read2_b32 v[176:177], v97 offset0:0 offset1:1
	ds_read2_b32 v[178:179], v97 offset0:2 offset1:3
	v_mfma_f32_16x16x32_bf16 v[24:27], v[148:151], v[188:191], v[24:27]
	v_mfma_f32_16x16x32_bf16 v[20:23], v[148:151], v[192:195], v[20:23]
	v_mfma_f32_16x16x32_bf16 v[24:27], v[152:155], v[180:183], v[24:27]
	v_mfma_f32_16x16x32_bf16 v[20:23], v[152:155], v[184:187], v[20:23]
	v_mfma_f32_16x16x32_bf16 v[8:11], v[156:159], v[188:191], v[8:11]
	v_mfma_f32_16x16x32_bf16 v[4:7], v[156:159], v[192:195], v[4:7]
	v_mfma_f32_16x16x32_bf16 v[8:11], v[160:163], v[180:183], v[8:11]
	v_mfma_f32_16x16x32_bf16 v[4:7], v[160:163], v[184:187], v[4:7]
	s_waitcnt lgkmcnt(0)
	v_add_u32_e32 v97, 0xffffff80, v97
	v_add_u32_e32 v96, 0xffffff70, v96
	v_add_u32_e32 v95, -1, v95
	ds_read2_b32 v[180:181], v97 offset0:24 offset1:25
	ds_read2_b32 v[182:183], v97 offset0:26 offset1:27
	ds_read2_b32 v[184:185], v97 offset0:16 offset1:17
	ds_read2_b32 v[186:187], v97 offset0:18 offset1:19
	v_cmp_gt_u32_e64 s[20:21], 64, v95
	v_mfma_f32_16x16x32_bf16 v[32:35], v[116:119], v[164:167], v[32:35]
	v_mfma_f32_16x16x32_bf16 v[28:31], v[116:119], v[168:171], v[28:31]
	v_mfma_f32_16x16x32_bf16 v[32:35], v[120:123], v[188:191], v[32:35]
	v_mfma_f32_16x16x32_bf16 v[28:31], v[120:123], v[192:195], v[28:31]
	v_cndmask_b32_e64 v79, v71, v96, s[20:21]
	ds_read_b128 v[156:159], v79 offset:6912
	ds_read_b128 v[160:163], v79 offset:6976
	v_mfma_f32_16x16x32_bf16 v[16:19], v[124:127], v[164:167], v[16:19]
	v_mfma_f32_16x16x32_bf16 v[12:15], v[124:127], v[168:171], v[12:15]
	v_mfma_f32_16x16x32_bf16 v[16:19], v[128:131], v[188:191], v[16:19]
	v_mfma_f32_16x16x32_bf16 v[12:15], v[128:131], v[192:195], v[12:15]
	ds_read2_b32 v[188:189], v97 offset0:8 offset1:9
	ds_read2_b32 v[190:191], v97 offset0:10 offset1:11
	ds_read2_b32 v[192:193], v97 offset0:0 offset1:1
	ds_read2_b32 v[194:195], v97 offset0:2 offset1:3
	v_mfma_f32_16x16x32_bf16 v[24:27], v[116:119], v[172:175], v[24:27]
	v_mfma_f32_16x16x32_bf16 v[20:23], v[116:119], v[176:179], v[20:23]
	v_mfma_f32_16x16x32_bf16 v[24:27], v[120:123], v[164:167], v[24:27]
	v_mfma_f32_16x16x32_bf16 v[20:23], v[120:123], v[168:171], v[20:23]
	v_mfma_f32_16x16x32_bf16 v[8:11], v[124:127], v[172:175], v[8:11]
	v_mfma_f32_16x16x32_bf16 v[4:7], v[124:127], v[176:179], v[4:7]
	v_mfma_f32_16x16x32_bf16 v[8:11], v[128:131], v[164:167], v[8:11]
	v_mfma_f32_16x16x32_bf16 v[4:7], v[128:131], v[168:171], v[4:7]
	s_mov_b32 s24, 6
; #define MFMA16(a, b, c) __builtin_amdgcn_mfma_f32_16x16x32_bf16(__builtin_bit_cast(bf16x8, (a)), __builtin_bit_cast(bf16x8, (b)), (c), 0, 0, 0)
; DI void hyena_conv_unit(const Params& p, int item, char* smem) {
;     ...
;   for (int d = -63; d <= 63; ++d) {
; #pragma unroll
;     for (int kk = 0; kk < 2; ++kk) {
;       u32x4 bfr[4];
; #pragma unroll
;       for (int nn = 0; nn < 4; ++nn) bfr[nn] = bfrag(4 * d + nn - 2 * kk);
; #pragma unroll
;       for (int rb = 0; rb < 4; ++rb) {
;         if (d >= 16 * rb - 63 && d <= 16 * rb + 15) {
;           int t1 = 16 * rb + n, s1 = t1 - d;
;           u32x4 a = zero4();
;           if (s1 >= 0 && s1 < 64) a = *(const u32x4*)(su + s1 * 72 + 32 * kk + 8 * g);
; #pragma unroll
;           for (int nn = 0; nn < 4; ++nn) acc[rb][nn] = MFMA16(a, bfr[nn], acc[rb][nn]);
;         }
;       }
;     }
;   }
.Lconv_seg6:
	s_waitcnt lgkmcnt(0)
	v_add_u32_e32 v97, 0xffffff80, v97
	v_add_u32_e32 v96, 0xffffff70, v96
	v_add_u32_e32 v95, -1, v95
	ds_read2_b32 v[164:165], v97 offset0:24 offset1:25
	ds_read2_b32 v[166:167], v97 offset0:26 offset1:27
	ds_read2_b32 v[168:169], v97 offset0:16 offset1:17
	ds_read2_b32 v[170:171], v97 offset0:18 offset1:19
	v_cmp_gt_u32_e64 s[20:21], 64, v95
	v_mfma_f32_16x16x32_bf16 v[16:19], v[156:159], v[180:183], v[16:19]
	v_mfma_f32_16x16x32_bf16 v[12:15], v[156:159], v[184:187], v[12:15]
	v_mfma_f32_16x16x32_bf16 v[16:19], v[160:163], v[172:175], v[16:19]
	v_mfma_f32_16x16x32_bf16 v[12:15], v[160:163], v[176:179], v[12:15]
	v_cndmask_b32_e64 v79, v71, v96, s[20:21]
	ds_read_b128 v[124:127], v79 offset:6912
	ds_read_b128 v[128:131], v79 offset:6976
	ds_read2_b32 v[172:173], v97 offset0:8 offset1:9
	ds_read2_b32 v[174:175], v97 offset0:10 offset1:11
	ds_read2_b32 v[176:177], v97 offset0:0 offset1:1
	ds_read2_b32 v[178:179], v97 offset0:2 offset1:3
	v_mfma_f32_16x16x32_bf16 v[8:11], v[156:159], v[188:191], v[8:11]
	v_mfma_f32_16x16x32_bf16 v[4:7], v[156:159], v[192:195], v[4:7]
	v_mfma_f32_16x16x32_bf16 v[8:11], v[160:163], v[180:183], v[8:11]
	v_mfma_f32_16x16x32_bf16 v[4:7], v[160:163], v[184:187], v[4:7]
	s_waitcnt lgkmcnt(0)
	v_add_u32_e32 v97, 0xffffff80, v97
	v_add_u32_e32 v96, 0xffffff70, v96
	v_add_u32_e32 v95, -1, v95
	ds_read2_b32 v[180:181], v97 offset0:24 offset1:25
	ds_read2_b32 v[182:183], v97 offset0:26 offset1:27
	ds_read2_b32 v[184:185], v97 offset0:16 offset1:17
	ds_read2_b32 v[186:187], v97 offset0:18 offset1:19
	v_cmp_gt_u32_e64 s[20:21], 64, v95
	v_mfma_f32_16x16x32_bf16 v[16:19], v[124:127], v[164:167], v[16:19]
	v_mfma_f32_16x16x32_bf16 v[12:15], v[124:127], v[168:171], v[12:15]
	v_mfma_f32_16x16x32_bf16 v[16:19], v[128:131], v[188:191], v[16:19]
	v_mfma_f32_16x16x32_bf16 v[12:15], v[128:131], v[192:195], v[12:15]
	v_cndmask_b32_e64 v79, v71, v96, s[20:21]
	ds_read_b128 v[156:159], v79 offset:6912
	ds_read_b128 v[160:163], v79 offset:6976
	ds_read2_b32 v[188:189], v97 offset0:8 offset1:9
	ds_read2_b32 v[190:191], v97 offset0:10 offset1:11
	ds_read2_b32 v[192:193], v97 offset0:0 offset1:1
	ds_read2_b32 v[194:195], v97 offset0:2 offset1:3
	v_mfma_f32_16x16x32_bf16 v[8:11], v[124:127], v[172:175], v[8:11]
	v_mfma_f32_16x16x32_bf16 v[4:7], v[124:127], v[176:179], v[4:7]
	v_mfma_f32_16x16x32_bf16 v[8:11], v[128:131], v[164:167], v[8:11]
	v_mfma_f32_16x16x32_bf16 v[4:7], v[128:131], v[168:171], v[4:7]
	s_sub_u32 s24, s24, 1
	s_cmp_lg_u32 s24, 0
	s_cbranch_scc1 .Lconv_seg6
	s_waitcnt lgkmcnt(0)
	v_add_u32_e32 v97, 0xffffff80, v97
	v_add_u32_e32 v96, 0xffffff70, v96
	v_add_u32_e32 v95, -1, v95
	ds_read2_b32 v[164:165], v97 offset0:24 offset1:25
	ds_read2_b32 v[166:167], v97 offset0:26 offset1:27
	ds_read2_b32 v[168:169], v97 offset0:16 offset1:17
	ds_read2_b32 v[170:171], v97 offset0:18 offset1:19
	v_cmp_gt_u32_e64 s[20:21], 64, v95
	v_mfma_f32_16x16x32_bf16 v[16:19], v[156:159], v[180:183], v[16:19]
	v_mfma_f32_16x16x32_bf16 v[12:15], v[156:159], v[184:187], v[12:15]
	v_mfma_f32_16x16x32_bf16 v[16:19], v[160:163], v[172:175], v[16:19]
	v_mfma_f32_16x16x32_bf16 v[12:15], v[160:163], v[176:179], v[12:15]
	v_cndmask_b32_e64 v79, v71, v96, s[20:21]
	ds_read_b128 v[124:127], v79 offset:6912
	ds_read_b128 v[128:131], v79 offset:6976
	ds_read2_b32 v[172:173], v97 offset0:8 offset1:9
	ds_read2_b32 v[174:175], v97 offset0:10 offset1:11
	ds_read2_b32 v[176:177], v97 offset0:0 offset1:1
	ds_read2_b32 v[178:179], v97 offset0:2 offset1:3
	v_mfma_f32_16x16x32_bf16 v[8:11], v[156:159], v[188:191], v[8:11]
	v_mfma_f32_16x16x32_bf16 v[4:7], v[156:159], v[192:195], v[4:7]
	v_mfma_f32_16x16x32_bf16 v[8:11], v[160:163], v[180:183], v[8:11]
	v_mfma_f32_16x16x32_bf16 v[4:7], v[160:163], v[184:187], v[4:7]
	s_waitcnt lgkmcnt(0)
	v_add_u32_e32 v97, 0xffffff80, v97
	v_add_u32_e32 v96, 0xffffff70, v96
	v_add_u32_e32 v95, -1, v95
	ds_read2_b32 v[180:181], v97 offset0:24 offset1:25
	ds_read2_b32 v[182:183], v97 offset0:26 offset1:27
	ds_read2_b32 v[184:185], v97 offset0:16 offset1:17
	ds_read2_b32 v[186:187], v97 offset0:18 offset1:19
	v_cmp_gt_u32_e64 s[20:21], 64, v95
	v_mfma_f32_16x16x32_bf16 v[16:19], v[124:127], v[164:167], v[16:19]
	v_mfma_f32_16x16x32_bf16 v[12:15], v[124:127], v[168:171], v[12:15]
	v_mfma_f32_16x16x32_bf16 v[16:19], v[128:131], v[188:191], v[16:19]
	v_mfma_f32_16x16x32_bf16 v[12:15], v[128:131], v[192:195], v[12:15]
	v_cndmask_b32_e64 v79, v71, v96, s[20:21]
	ds_read_b128 v[156:159], v79 offset:6912
	ds_read_b128 v[160:163], v79 offset:6976
	ds_read2_b32 v[188:189], v97 offset0:8 offset1:9
	ds_read2_b32 v[190:191], v97 offset0:10 offset1:11
	ds_read2_b32 v[192:193], v97 offset0:0 offset1:1
	ds_read2_b32 v[194:195], v97 offset0:2 offset1:3
	v_mfma_f32_16x16x32_bf16 v[8:11], v[124:127], v[172:175], v[8:11]
	v_mfma_f32_16x16x32_bf16 v[4:7], v[124:127], v[176:179], v[4:7]
	v_mfma_f32_16x16x32_bf16 v[8:11], v[128:131], v[164:167], v[8:11]
	v_mfma_f32_16x16x32_bf16 v[4:7], v[128:131], v[168:171], v[4:7]
	s_waitcnt lgkmcnt(0)
	v_mfma_f32_16x16x32_bf16 v[16:19], v[156:159], v[180:183], v[16:19]
	v_mfma_f32_16x16x32_bf16 v[12:15], v[156:159], v[184:187], v[12:15]
	v_mfma_f32_16x16x32_bf16 v[16:19], v[160:163], v[172:175], v[16:19]
	v_mfma_f32_16x16x32_bf16 v[12:15], v[160:163], v[176:179], v[12:15]
	v_mfma_f32_16x16x32_bf16 v[8:11], v[156:159], v[188:191], v[8:11]
	v_mfma_f32_16x16x32_bf16 v[4:7], v[156:159], v[192:195], v[4:7]
	v_mfma_f32_16x16x32_bf16 v[8:11], v[160:163], v[180:183], v[8:11]
	v_mfma_f32_16x16x32_bf16 v[4:7], v[160:163], v[184:187], v[4:7]
	s_nop 7
	s_nop 3
	s_branch .LBB0_896

; DI int tid512() { int t = threadIdx_x_raw(); asm volatile("" : "+v"(t)); return t; }
; #define G_LOADA(kt_) { _Pragma("unroll") for (int i = 0; i < 4; ++i) ra[i] = al(lrow + 64 * i, (kt_) * 64 + lck * 8); }
; #define G_LOADB(kt_) { _Pragma("unroll") for (int i = 0; i < 4; ++i) rb[i] = bl(lrow + 64 * i, (kt_) * 64 + lck * 8); }
; #define G_STOREA(buf_) { bf16_t* nA = sA + (buf_) * 256 * GLD; _Pragma("unroll") for (int i = 0; i < 4; ++i) *(u32x4*)(nA + (lrow + 64 * i) * GLD + lck * 8) = ra[i]; }
; #define G_STOREB(buf_) { bf16_t* nB = sB + (buf_) * 256 * GLD; _Pragma("unroll") for (int i = 0; i < 4; ++i) *(u32x4*)(nB + (lrow + 64 * i) * GLD + lck * 8) = rb[i]; }
; template <class AL, class BL, class EP>
; DI void gemm_tile256(AL al, BL bl, EP ep, int K, char* smem) {
;   bf16_t* sA = (bf16_t*)smem;
;   bf16_t* sB = sA + 2 * 256 * GLD;
;   const int tid = tid512(), lane = tid & 63, w = tid >> 6, wm = w >> 2, wn = w & 3, r = lane & 31, h = lane >> 5;
;   const int lrow = tid >> 3, lck = tid & 7;
;   f32x16 acc[4][2];
; #pragma unroll
;   for (int i = 0; i < 4; ++i)
; #pragma unroll
;     for (int j = 0; j < 2; ++j)
; #pragma unroll
;       for (int q = 0; q < 16; ++q) acc[i][j][q] = 0.f;
;   u32x4 ra[4], rb[4];
;   const int KT = K >> 6;
;     ...
;   G_LOADA(0); G_LOADB(0);
;   __syncthreads();
;   G_STOREA(0); G_STOREB(0);
;   if (KT > 1) G_LOADB(1);
;   __syncthreads();
.LBB0_1040:
	s_cmp_lg_u32 s6, 1
	s_mov_b64 s[2:3], -1
	s_cbranch_scc0 .LBB0_1047
	v_mov_b32_e32 v32, v196
	v_readlane_b32 s2, v246, 36
	v_ashrrev_i32_e32 v33, 3, v32
	v_add_u32_e32 v12, s22, v33
	v_add_u32_e32 v28, s21, v33
	v_lshlrev_b32_e32 v0, 4, v32
	v_add_u32_e32 v10, 0x80, v12
	v_add_u32_e32 v26, 0x80, v28
	v_and_b32_e32 v128, 0x70, v0
	v_min_i32_e32 v0, 0x7fff, v12
	v_min_i32_e32 v10, 0x7fff, v10
	v_min_i32_e32 v16, 0x3ff, v28
	v_min_i32_e32 v26, 0x3ff, v26
	v_readlane_b32 s3, v246, 37
	v_ashrrev_i32_e32 v1, 31, v0
	v_ashrrev_i32_e32 v11, 31, v10
	v_ashrrev_i32_e32 v17, 31, v16
	v_ashrrev_i32_e32 v27, 31, v26
	v_lshl_add_u64 v[8:9], s[2:3], 0, v[128:129]
	v_lshlrev_b64 v[0:1], 11, v[0:1]
	v_lshlrev_b64 v[10:11], 11, v[10:11]
	v_lshl_add_u64 v[24:25], s[0:1], 0, v[128:129]
	v_lshlrev_b64 v[16:17], 11, v[16:17]
	v_lshlrev_b64 v[26:27], 11, v[26:27]
	v_lshl_add_u64 v[134:135], v[8:9], 0, v[0:1]
	v_add_u32_e32 v0, 64, v12
	v_lshl_add_u64 v[138:139], v[8:9], 0, v[10:11]
	v_add_u32_e32 v10, 0xc0, v12
	v_lshl_add_u64 v[142:143], v[24:25], 0, v[16:17]
	v_add_u32_e32 v16, 64, v28
	v_lshl_add_u64 v[146:147], v[24:25], 0, v[26:27]
	v_add_u32_e32 v26, 0xc0, v28
	v_min_i32_e32 v0, 0x7fff, v0
	v_min_i32_e32 v10, 0x7fff, v10
	v_min_i32_e32 v16, 0x3ff, v16
	v_min_i32_e32 v26, 0x3ff, v26
	v_ashrrev_i32_e32 v1, 31, v0
	v_ashrrev_i32_e32 v11, 31, v10
	v_ashrrev_i32_e32 v17, 31, v16
	v_ashrrev_i32_e32 v27, 31, v26
	v_lshlrev_b64 v[0:1], 11, v[0:1]
	v_lshlrev_b64 v[10:11], 11, v[10:11]
	v_lshlrev_b64 v[16:17], 11, v[16:17]
	v_lshlrev_b64 v[26:27], 11, v[26:27]
	v_lshl_add_u64 v[136:137], v[8:9], 0, v[0:1]
	v_lshl_add_u64 v[140:141], v[8:9], 0, v[10:11]
	v_lshl_add_u64 v[144:145], v[24:25], 0, v[16:17]
	v_lshl_add_u64 v[148:149], v[24:25], 0, v[26:27]
	v_mad_u64_u32 v[132:133], s[2:3], v33, s15, v[128:129]
	v_add_u32_e32 v153, 0x12000, v132
	v_bfe_u32 v128, v32, 6, 2
	v_add_u32_e32 v152, 0x1b000, v132
	v_and_b32_e32 v1, 31, v32
	v_ashrrev_i32_e32 v0, 1, v32
	v_and_or_b32 v133, v0, s16, v1
	v_lshrrev_b32_e32 v0, 2, v32
	v_and_b32_e32 v150, 8, v0
	v_lshlrev_b32_e32 v0, 1, v150
	v_mad_u64_u32 v[130:131], s[2:3], v133, s15, v[0:1]
	v_lshl_or_b32 v1, v128, 6, v1
	v_mul_u32_u24_e32 v1, 0x48, v1
	v_lshl_add_u32 v0, v1, 1, v0
	v_add_u32_e32 v151, 0x12000, v0
	v_add_u32_e32 v131, 0x1b000, v0
	s_nop 0
	s_nop 0
	s_nop 0
	s_nop 0
	s_nop 0
	s_nop 0
	v_lshrrev_b32_e32 v222, 6, v196
	s_mov_b32 s4, 64
	v_readfirstlane_b32 s23, v222
	s_mov_b32 s5, 0
	s_mov_b32 s6, 0x40000
	s_mov_b32 s7, 0
	v_bfe_u32 v220, v196, 2, 4
	s_lshl_b32 s24, s23, 3
	v_add_u32_e32 v220, s24, v220
	s_mov_b32 s24, 0x800
	v_mul_lo_u32 v220, v220, s24
	v_bfe_u32 v222, v196, 4, 2
	v_and_b32_e32 v221, 3, v196
	v_xor_b32_e32 v222, v221, v222
	v_lshl_add_u32 v220, v222, 4, v220
	v_mov_b32_e32 v221, 0
	v_readlane_b32 s10, v134, 0
	v_readlane_b32 s11, v135, 0
	s_nop 1
	v_lshl_add_u64 v[212:213], s[10:11], 0, v[220:221]
	v_lshl_add_u64 v[214:215], v[212:213], 0, s[6:7]
	v_readlane_b32 s10, v142, 0
	v_readlane_b32 s11, v143, 0
	s_nop 1
	v_lshl_add_u64 v[216:217], s[10:11], 0, v[220:221]
	v_lshl_add_u64 v[218:219], v[216:217], 0, s[6:7]
	v_and_b32_e32 v220, 31, v196
	v_bfe_u32 v222, v196, 2, 2
	v_bfe_u32 v221, v196, 5, 1
	v_xor_b32_e32 v222, v221, v222
	v_lshlrev_b32_e32 v222, 4, v222
	v_lshl_or_b32 v220, v220, 6, v222
	s_lshr_b32 s24, s23, 2
	s_lshl_b32 s24, s24, 13
	v_add_u32_e32 v132, s24, v220
	s_and_b32 s24, s23, 3
	s_lshl_b32 s24, s24, 12
	s_add_u32 s24, s24, 0x4000
	v_add_u32_e32 v198, s24, v220
	v_xor_b32_e32 v151, 0x20, v132
	v_xor_b32_e32 v199, 0x20, v198
	v_add_u32_e32 v204, 0x10000, v132
	v_add_u32_e32 v206, 0x10000, v198
	v_add_u32_e32 v208, 0x20000, v132
	v_add_u32_e32 v210, 0x20000, v198
	v_add_u32_e32 v205, 0x10000, v151
	v_add_u32_e32 v207, 0x10000, v199
	v_add_u32_e32 v209, 0x20000, v151
	v_add_u32_e32 v211, 0x20000, v199
	s_lshl_b32 s23, s23, 10
	s_waitcnt lgkmcnt(0)
	s_barrier
	s_add_u32 m0, s23, 0x0
	s_nop 0
	global_load_lds_dwordx4 v[212:213], off
	v_lshl_add_u64 v[212:213], v[212:213], 0, s[4:5]
	s_add_u32 m0, s23, 0x4000
	s_nop 0
	global_load_lds_dwordx4 v[216:217], off
	v_lshl_add_u64 v[216:217], v[216:217], 0, s[4:5]
	s_add_u32 m0, s23, 0x2000
	s_nop 0
	global_load_lds_dwordx4 v[214:215], off
	v_lshl_add_u64 v[214:215], v[214:215], 0, s[4:5]
	s_add_u32 m0, s23, 0x6000
	s_nop 0
	global_load_lds_dwordx4 v[218:219], off
	v_lshl_add_u64 v[218:219], v[218:219], 0, s[4:5]
	s_add_u32 m0, s23, 0x8000
	s_nop 0
	global_load_lds_dwordx4 v[212:213], off
	v_lshl_add_u64 v[212:213], v[212:213], 0, s[4:5]
	s_add_u32 m0, s23, 0xc000
	s_nop 0
	global_load_lds_dwordx4 v[216:217], off
	v_lshl_add_u64 v[216:217], v[216:217], 0, s[4:5]
	s_add_u32 m0, s23, 0xa000
	s_nop 0
	global_load_lds_dwordx4 v[214:215], off
	v_lshl_add_u64 v[214:215], v[214:215], 0, s[4:5]
	s_add_u32 m0, s23, 0xe000
	s_nop 0
	global_load_lds_dwordx4 v[218:219], off
	v_lshl_add_u64 v[218:219], v[218:219], 0, s[4:5]
	s_add_u32 m0, s23, 0x10000
	s_nop 0
	global_load_lds_dwordx4 v[212:213], off
	v_lshl_add_u64 v[212:213], v[212:213], 0, s[4:5]
	s_add_u32 m0, s23, 0x14000
	s_nop 0
	global_load_lds_dwordx4 v[216:217], off
	v_lshl_add_u64 v[216:217], v[216:217], 0, s[4:5]
	s_add_u32 m0, s23, 0x12000
	s_nop 0
	global_load_lds_dwordx4 v[214:215], off
	v_lshl_add_u64 v[214:215], v[214:215], 0, s[4:5]
	s_add_u32 m0, s23, 0x16000
	s_nop 0
	global_load_lds_dwordx4 v[218:219], off
	v_lshl_add_u64 v[218:219], v[218:219], 0, s[4:5]
	s_add_u32 m0, s23, 0x18000
	s_nop 0
	global_load_lds_dwordx4 v[212:213], off
	v_lshl_add_u64 v[212:213], v[212:213], 0, s[4:5]
	s_add_u32 m0, s23, 0x1c000
	s_nop 0
	global_load_lds_dwordx4 v[216:217], off
; #define G_LOADA(kt_) { _Pragma("unroll") for (int i = 0; i < 4; ++i) ra[i] = al(lrow + 64 * i, (kt_) * 64 + lck * 8); }
; #define G_LOADB(kt_) { _Pragma("unroll") for (int i = 0; i < 4; ++i) rb[i] = bl(lrow + 64 * i, (kt_) * 64 + lck * 8); }
; #define G_STOREA(buf_) { bf16_t* nA = sA + (buf_) * 256 * GLD; _Pragma("unroll") for (int i = 0; i < 4; ++i) *(u32x4*)(nA + (lrow + 64 * i) * GLD + lck * 8) = ra[i]; }
; #define G_STOREB(buf_) { bf16_t* nB = sB + (buf_) * 256 * GLD; _Pragma("unroll") for (int i = 0; i < 4; ++i) *(u32x4*)(nB + (lrow + 64 * i) * GLD + lck * 8) = rb[i]; }
; template <class AL, class BL, class EP>
; DI void gemm_tile256(AL al, BL bl, EP ep, int K, char* smem) {
;     ...
;   const int KT = K >> 6;
;     ...
;   G_LOADA(0); G_LOADB(0);
;   __syncthreads();
;   G_STOREA(0); G_STOREB(0);
;   if (KT > 1) G_LOADB(1);
;   __syncthreads();
;   for (int kt = 0; kt < KT; kt += 2) {
;     G_STEP(0, kt);
;     if (kt + 1 >= KT) break;
;     G_STEP(1, kt + 1);
;   }
	v_lshl_add_u64 v[216:217], v[216:217], 0, s[4:5]
	s_add_u32 m0, s23, 0x1a000
	s_nop 0
	global_load_lds_dwordx4 v[214:215], off
	v_lshl_add_u64 v[214:215], v[214:215], 0, s[4:5]
	s_add_u32 m0, s23, 0x1e000
	s_nop 0
	global_load_lds_dwordx4 v[218:219], off
	v_lshl_add_u64 v[218:219], v[218:219], 0, s[4:5]
	s_add_u32 m0, s23, 0x20000
	s_nop 0
	global_load_lds_dwordx4 v[212:213], off
	v_lshl_add_u64 v[212:213], v[212:213], 0, s[4:5]
	s_add_u32 m0, s23, 0x24000
	s_nop 0
	global_load_lds_dwordx4 v[216:217], off
	v_lshl_add_u64 v[216:217], v[216:217], 0, s[4:5]
	v_mov_b64_e32 v[112:113], 0
	v_mov_b64_e32 v[114:115], 0
	v_mov_b64_e32 v[116:117], 0
	v_mov_b64_e32 v[118:119], 0
	v_mov_b64_e32 v[120:121], 0
	v_mov_b64_e32 v[122:123], 0
	v_mov_b64_e32 v[124:125], 0
	v_mov_b64_e32 v[126:127], 0
	v_mov_b64_e32 v[96:97], 0
	v_mov_b64_e32 v[98:99], 0
	v_mov_b64_e32 v[100:101], 0
	v_mov_b64_e32 v[102:103], 0
	v_mov_b64_e32 v[104:105], 0
	v_mov_b64_e32 v[106:107], 0
	v_mov_b64_e32 v[108:109], 0
	v_mov_b64_e32 v[110:111], 0
	v_mov_b64_e32 v[80:81], 0
	v_mov_b64_e32 v[82:83], 0
	v_mov_b64_e32 v[84:85], 0
	v_mov_b64_e32 v[86:87], 0
	v_mov_b64_e32 v[88:89], 0
	v_mov_b64_e32 v[90:91], 0
	v_mov_b64_e32 v[92:93], 0
	v_mov_b64_e32 v[94:95], 0
	v_mov_b64_e32 v[64:65], 0
	v_mov_b64_e32 v[66:67], 0
	v_mov_b64_e32 v[68:69], 0
	v_mov_b64_e32 v[70:71], 0
	v_mov_b64_e32 v[72:73], 0
	v_mov_b64_e32 v[74:75], 0
	v_mov_b64_e32 v[76:77], 0
	v_mov_b64_e32 v[78:79], 0
	v_mov_b64_e32 v[48:49], 0
	v_mov_b64_e32 v[50:51], 0
	v_mov_b64_e32 v[52:53], 0
	v_mov_b64_e32 v[54:55], 0
	v_mov_b64_e32 v[56:57], 0
	v_mov_b64_e32 v[58:59], 0
	v_mov_b64_e32 v[60:61], 0
	v_mov_b64_e32 v[62:63], 0
	v_mov_b64_e32 v[32:33], 0
	v_mov_b64_e32 v[34:35], 0
	v_mov_b64_e32 v[36:37], 0
	v_mov_b64_e32 v[38:39], 0
	v_mov_b64_e32 v[40:41], 0
	v_mov_b64_e32 v[42:43], 0
	v_mov_b64_e32 v[44:45], 0
	v_mov_b64_e32 v[46:47], 0
	v_mov_b64_e32 v[16:17], 0
	v_mov_b64_e32 v[18:19], 0
	v_mov_b64_e32 v[20:21], 0
	v_mov_b64_e32 v[22:23], 0
	v_mov_b64_e32 v[24:25], 0
	v_mov_b64_e32 v[26:27], 0
	v_mov_b64_e32 v[28:29], 0
	v_mov_b64_e32 v[30:31], 0
	v_mov_b64_e32 v[0:1], 0
	v_mov_b64_e32 v[2:3], 0
	v_mov_b64_e32 v[4:5], 0
	v_mov_b64_e32 v[6:7], 0
	v_mov_b64_e32 v[8:9], 0
	v_mov_b64_e32 v[10:11], 0
	v_mov_b64_e32 v[12:13], 0
	v_mov_b64_e32 v[14:15], 0
	s_mov_b32 s24, 5
	s_waitcnt vmcnt(14)
	s_barrier
	ds_read_b128 v[184:187], v198
	ds_read_b128 v[152:155], v132
	ds_read_b128 v[188:191], v198 offset:2048
	ds_read_b128 v[156:159], v132 offset:2048
	ds_read_b128 v[160:163], v132 offset:4096
	ds_read_b128 v[164:167], v132 offset:6144
.Lgk_ph13_loop:
	s_waitcnt lgkmcnt(0)
	v_mfma_f32_32x32x16_bf16 v[112:127], v[184:187], v[152:155], v[112:127]
	ds_read_b128 v[192:195], v199
	ds_read_b128 v[168:171], v151
	v_mfma_f32_32x32x16_bf16 v[96:111], v[188:191], v[152:155], v[96:111]
	ds_read_b128 v[200:203], v199 offset:2048
	ds_read_b128 v[172:175], v151 offset:2048
	v_mfma_f32_32x32x16_bf16 v[80:95], v[184:187], v[156:159], v[80:95]
	ds_read_b128 v[176:179], v151 offset:4096
	ds_read_b128 v[180:183], v151 offset:6144
	v_mfma_f32_32x32x16_bf16 v[64:79], v[188:191], v[156:159], v[64:79]
	s_add_u32 m0, s23, 0x22000
	s_nop 0
	global_load_lds_dwordx4 v[214:215], off
	v_lshl_add_u64 v[214:215], v[214:215], 0, s[4:5]
	v_mfma_f32_32x32x16_bf16 v[48:63], v[184:187], v[160:163], v[48:63]
	v_mfma_f32_32x32x16_bf16 v[32:47], v[188:191], v[160:163], v[32:47]
	v_mfma_f32_32x32x16_bf16 v[16:31], v[184:187], v[164:167], v[16:31]
	v_mfma_f32_32x32x16_bf16 v[0:15], v[188:191], v[164:167], v[0:15]
	s_add_u32 m0, s23, 0x26000
	s_nop 0
	global_load_lds_dwordx4 v[218:219], off
	v_lshl_add_u64 v[218:219], v[218:219], 0, s[4:5]
	s_waitcnt lgkmcnt(0)
	s_waitcnt vmcnt(12)
	s_barrier
	s_waitcnt lgkmcnt(0)
	v_mfma_f32_32x32x16_bf16 v[112:127], v[192:195], v[168:171], v[112:127]
	ds_read_b128 v[184:187], v198 offset:32768
	ds_read_b128 v[152:155], v132 offset:32768
	v_mfma_f32_32x32x16_bf16 v[96:111], v[200:203], v[168:171], v[96:111]
	ds_read_b128 v[188:191], v198 offset:34816
	ds_read_b128 v[156:159], v132 offset:34816
	v_mfma_f32_32x32x16_bf16 v[80:95], v[192:195], v[172:175], v[80:95]
	ds_read_b128 v[160:163], v132 offset:36864
	ds_read_b128 v[164:167], v132 offset:38912
	v_mfma_f32_32x32x16_bf16 v[64:79], v[200:203], v[172:175], v[64:79]
	s_add_u32 m0, s23, 0x0
	s_nop 0
	global_load_lds_dwordx4 v[212:213], off
	v_lshl_add_u64 v[212:213], v[212:213], 0, s[4:5]
	v_mfma_f32_32x32x16_bf16 v[48:63], v[192:195], v[176:179], v[48:63]
	v_mfma_f32_32x32x16_bf16 v[32:47], v[200:203], v[176:179], v[32:47]
	v_mfma_f32_32x32x16_bf16 v[16:31], v[192:195], v[180:183], v[16:31]
	v_mfma_f32_32x32x16_bf16 v[0:15], v[200:203], v[180:183], v[0:15]
	s_add_u32 m0, s23, 0x4000
	s_nop 0
	global_load_lds_dwordx4 v[216:217], off
	v_lshl_add_u64 v[216:217], v[216:217], 0, s[4:5]
	s_waitcnt lgkmcnt(0)
	v_mfma_f32_32x32x16_bf16 v[112:127], v[184:187], v[152:155], v[112:127]
	ds_read_b128 v[192:195], v199 offset:32768
	ds_read_b128 v[168:171], v151 offset:32768
	v_mfma_f32_32x32x16_bf16 v[96:111], v[188:191], v[152:155], v[96:111]
	ds_read_b128 v[200:203], v199 offset:34816
	ds_read_b128 v[172:175], v151 offset:34816
	v_mfma_f32_32x32x16_bf16 v[80:95], v[184:187], v[156:159], v[80:95]
	ds_read_b128 v[176:179], v151 offset:36864
	ds_read_b128 v[180:183], v151 offset:38912
	v_mfma_f32_32x32x16_bf16 v[64:79], v[188:191], v[156:159], v[64:79]
	s_add_u32 m0, s23, 0x2000
	s_nop 0
	global_load_lds_dwordx4 v[214:215], off
	v_lshl_add_u64 v[214:215], v[214:215], 0, s[4:5]
	v_mfma_f32_32x32x16_bf16 v[48:63], v[184:187], v[160:163], v[48:63]
	v_mfma_f32_32x32x16_bf16 v[32:47], v[188:191], v[160:163], v[32:47]
	v_mfma_f32_32x32x16_bf16 v[16:31], v[184:187], v[164:167], v[16:31]
	v_mfma_f32_32x32x16_bf16 v[0:15], v[188:191], v[164:167], v[0:15]
	s_add_u32 m0, s23, 0x6000
	s_nop 0
	global_load_lds_dwordx4 v[218:219], off
	v_lshl_add_u64 v[218:219], v[218:219], 0, s[4:5]
	s_waitcnt lgkmcnt(0)
	s_waitcnt vmcnt(12)
	s_barrier
; #define G_LOADA(kt_) { _Pragma("unroll") for (int i = 0; i < 4; ++i) ra[i] = al(lrow + 64 * i, (kt_) * 64 + lck * 8); }
; #define G_LOADB(kt_) { _Pragma("unroll") for (int i = 0; i < 4; ++i) rb[i] = bl(lrow + 64 * i, (kt_) * 64 + lck * 8); }
; #define G_STOREA(buf_) { bf16_t* nA = sA + (buf_) * 256 * GLD; _Pragma("unroll") for (int i = 0; i < 4; ++i) *(u32x4*)(nA + (lrow + 64 * i) * GLD + lck * 8) = ra[i]; }
; #define G_STOREB(buf_) { bf16_t* nB = sB + (buf_) * 256 * GLD; _Pragma("unroll") for (int i = 0; i < 4; ++i) *(u32x4*)(nB + (lrow + 64 * i) * GLD + lck * 8) = rb[i]; }
; template <class AL, class BL, class EP>
; DI void gemm_tile256(AL al, BL bl, EP ep, int K, char* smem) {
;     ...
;   const int KT = K >> 6;
;     ...
;   G_LOADA(0); G_LOADB(0);
;   __syncthreads();
;   G_STOREA(0); G_STOREB(0);
;   if (KT > 1) G_LOADB(1);
;   __syncthreads();
;   for (int kt = 0; kt < KT; kt += 2) {
;     G_STEP(0, kt);
;     if (kt + 1 >= KT) break;
;     G_STEP(1, kt + 1);
;   }
	s_waitcnt lgkmcnt(0)
	v_mfma_f32_32x32x16_bf16 v[112:127], v[192:195], v[168:171], v[112:127]
	ds_read_b128 v[184:187], v206
	ds_read_b128 v[152:155], v204
	v_mfma_f32_32x32x16_bf16 v[96:111], v[200:203], v[168:171], v[96:111]
	ds_read_b128 v[188:191], v206 offset:2048
	ds_read_b128 v[156:159], v204 offset:2048
	v_mfma_f32_32x32x16_bf16 v[80:95], v[192:195], v[172:175], v[80:95]
	ds_read_b128 v[160:163], v204 offset:4096
	ds_read_b128 v[164:167], v204 offset:6144
	v_mfma_f32_32x32x16_bf16 v[64:79], v[200:203], v[172:175], v[64:79]
	s_add_u32 m0, s23, 0x8000
	s_nop 0
	global_load_lds_dwordx4 v[212:213], off
	v_lshl_add_u64 v[212:213], v[212:213], 0, s[4:5]
	v_mfma_f32_32x32x16_bf16 v[48:63], v[192:195], v[176:179], v[48:63]
	v_mfma_f32_32x32x16_bf16 v[32:47], v[200:203], v[176:179], v[32:47]
	v_mfma_f32_32x32x16_bf16 v[16:31], v[192:195], v[180:183], v[16:31]
	v_mfma_f32_32x32x16_bf16 v[0:15], v[200:203], v[180:183], v[0:15]
	s_add_u32 m0, s23, 0xc000
	s_nop 0
	global_load_lds_dwordx4 v[216:217], off
	v_lshl_add_u64 v[216:217], v[216:217], 0, s[4:5]
	s_waitcnt lgkmcnt(0)
	v_mfma_f32_32x32x16_bf16 v[112:127], v[184:187], v[152:155], v[112:127]
	ds_read_b128 v[192:195], v207
	ds_read_b128 v[168:171], v205
	v_mfma_f32_32x32x16_bf16 v[96:111], v[188:191], v[152:155], v[96:111]
	ds_read_b128 v[200:203], v207 offset:2048
	ds_read_b128 v[172:175], v205 offset:2048
	v_mfma_f32_32x32x16_bf16 v[80:95], v[184:187], v[156:159], v[80:95]
	ds_read_b128 v[176:179], v205 offset:4096
	ds_read_b128 v[180:183], v205 offset:6144
	v_mfma_f32_32x32x16_bf16 v[64:79], v[188:191], v[156:159], v[64:79]
	s_add_u32 m0, s23, 0xa000
	s_nop 0
	global_load_lds_dwordx4 v[214:215], off
	v_lshl_add_u64 v[214:215], v[214:215], 0, s[4:5]
	v_mfma_f32_32x32x16_bf16 v[48:63], v[184:187], v[160:163], v[48:63]
	v_mfma_f32_32x32x16_bf16 v[32:47], v[188:191], v[160:163], v[32:47]
	v_mfma_f32_32x32x16_bf16 v[16:31], v[184:187], v[164:167], v[16:31]
	v_mfma_f32_32x32x16_bf16 v[0:15], v[188:191], v[164:167], v[0:15]
	s_add_u32 m0, s23, 0xe000
	s_nop 0
	global_load_lds_dwordx4 v[218:219], off
	v_lshl_add_u64 v[218:219], v[218:219], 0, s[4:5]
	s_waitcnt lgkmcnt(0)
	s_waitcnt vmcnt(12)
	s_barrier
	s_waitcnt lgkmcnt(0)
	v_mfma_f32_32x32x16_bf16 v[112:127], v[192:195], v[168:171], v[112:127]
	ds_read_b128 v[184:187], v206 offset:32768
	ds_read_b128 v[152:155], v204 offset:32768
	v_mfma_f32_32x32x16_bf16 v[96:111], v[200:203], v[168:171], v[96:111]
	ds_read_b128 v[188:191], v206 offset:34816
	ds_read_b128 v[156:159], v204 offset:34816
	v_mfma_f32_32x32x16_bf16 v[80:95], v[192:195], v[172:175], v[80:95]
	ds_read_b128 v[160:163], v204 offset:36864
	ds_read_b128 v[164:167], v204 offset:38912
	v_mfma_f32_32x32x16_bf16 v[64:79], v[200:203], v[172:175], v[64:79]
	s_add_u32 m0, s23, 0x10000
	s_nop 0
	global_load_lds_dwordx4 v[212:213], off
	v_lshl_add_u64 v[212:213], v[212:213], 0, s[4:5]
	v_mfma_f32_32x32x16_bf16 v[48:63], v[192:195], v[176:179], v[48:63]
	v_mfma_f32_32x32x16_bf16 v[32:47], v[200:203], v[176:179], v[32:47]
	v_mfma_f32_32x32x16_bf16 v[16:31], v[192:195], v[180:183], v[16:31]
	v_mfma_f32_32x32x16_bf16 v[0:15], v[200:203], v[180:183], v[0:15]
	s_add_u32 m0, s23, 0x14000
	s_nop 0
	global_load_lds_dwordx4 v[216:217], off
	v_lshl_add_u64 v[216:217], v[216:217], 0, s[4:5]
	s_waitcnt lgkmcnt(0)
	v_mfma_f32_32x32x16_bf16 v[112:127], v[184:187], v[152:155], v[112:127]
	ds_read_b128 v[192:195], v207 offset:32768
	ds_read_b128 v[168:171], v205 offset:32768
	v_mfma_f32_32x32x16_bf16 v[96:111], v[188:191], v[152:155], v[96:111]
	ds_read_b128 v[200:203], v207 offset:34816
	ds_read_b128 v[172:175], v205 offset:34816
	v_mfma_f32_32x32x16_bf16 v[80:95], v[184:187], v[156:159], v[80:95]
	ds_read_b128 v[176:179], v205 offset:36864
	ds_read_b128 v[180:183], v205 offset:38912
	v_mfma_f32_32x32x16_bf16 v[64:79], v[188:191], v[156:159], v[64:79]
	s_add_u32 m0, s23, 0x12000
	s_nop 0
	global_load_lds_dwordx4 v[214:215], off
	v_lshl_add_u64 v[214:215], v[214:215], 0, s[4:5]
	v_mfma_f32_32x32x16_bf16 v[48:63], v[184:187], v[160:163], v[48:63]
	v_mfma_f32_32x32x16_bf16 v[32:47], v[188:191], v[160:163], v[32:47]
	v_mfma_f32_32x32x16_bf16 v[16:31], v[184:187], v[164:167], v[16:31]
	v_mfma_f32_32x32x16_bf16 v[0:15], v[188:191], v[164:167], v[0:15]
	s_add_u32 m0, s23, 0x16000
	s_nop 0
	global_load_lds_dwordx4 v[218:219], off
	v_lshl_add_u64 v[218:219], v[218:219], 0, s[4:5]
	s_waitcnt lgkmcnt(0)
	s_waitcnt vmcnt(12)
	s_barrier
	s_waitcnt lgkmcnt(0)
	v_mfma_f32_32x32x16_bf16 v[112:127], v[192:195], v[168:171], v[112:127]
	ds_read_b128 v[184:187], v210
	ds_read_b128 v[152:155], v208
	v_mfma_f32_32x32x16_bf16 v[96:111], v[200:203], v[168:171], v[96:111]
	ds_read_b128 v[188:191], v210 offset:2048
	ds_read_b128 v[156:159], v208 offset:2048
	v_mfma_f32_32x32x16_bf16 v[80:95], v[192:195], v[172:175], v[80:95]
	ds_read_b128 v[160:163], v208 offset:4096
	ds_read_b128 v[164:167], v208 offset:6144
	v_mfma_f32_32x32x16_bf16 v[64:79], v[200:203], v[172:175], v[64:79]
	s_add_u32 m0, s23, 0x18000
	s_nop 0
	global_load_lds_dwordx4 v[212:213], off
	v_lshl_add_u64 v[212:213], v[212:213], 0, s[4:5]
	v_mfma_f32_32x32x16_bf16 v[48:63], v[192:195], v[176:179], v[48:63]
	v_mfma_f32_32x32x16_bf16 v[32:47], v[200:203], v[176:179], v[32:47]
	v_mfma_f32_32x32x16_bf16 v[16:31], v[192:195], v[180:183], v[16:31]
	v_mfma_f32_32x32x16_bf16 v[0:15], v[200:203], v[180:183], v[0:15]
	s_add_u32 m0, s23, 0x1c000
	s_nop 0
	global_load_lds_dwordx4 v[216:217], off
	v_lshl_add_u64 v[216:217], v[216:217], 0, s[4:5]
	s_waitcnt lgkmcnt(0)
	v_mfma_f32_32x32x16_bf16 v[112:127], v[184:187], v[152:155], v[112:127]
	ds_read_b128 v[192:195], v211
	ds_read_b128 v[168:171], v209
	v_mfma_f32_32x32x16_bf16 v[96:111], v[188:191], v[152:155], v[96:111]
	ds_read_b128 v[200:203], v211 offset:2048
	ds_read_b128 v[172:175], v209 offset:2048
	v_mfma_f32_32x32x16_bf16 v[80:95], v[184:187], v[156:159], v[80:95]
	ds_read_b128 v[176:179], v209 offset:4096
	ds_read_b128 v[180:183], v209 offset:6144
	v_mfma_f32_32x32x16_bf16 v[64:79], v[188:191], v[156:159], v[64:79]
	s_add_u32 m0, s23, 0x1a000
	s_nop 0
	global_load_lds_dwordx4 v[214:215], off
	v_lshl_add_u64 v[214:215], v[214:215], 0, s[4:5]
	v_mfma_f32_32x32x16_bf16 v[48:63], v[184:187], v[160:163], v[48:63]
	v_mfma_f32_32x32x16_bf16 v[32:47], v[188:191], v[160:163], v[32:47]
	v_mfma_f32_32x32x16_bf16 v[16:31], v[184:187], v[164:167], v[16:31]
	v_mfma_f32_32x32x16_bf16 v[0:15], v[188:191], v[164:167], v[0:15]
	s_add_u32 m0, s23, 0x1e000
	s_nop 0
	global_load_lds_dwordx4 v[218:219], off
	v_lshl_add_u64 v[218:219], v[218:219], 0, s[4:5]
	s_waitcnt lgkmcnt(0)
	s_waitcnt vmcnt(12)
	s_barrier
; #define G_LOADA(kt_) { _Pragma("unroll") for (int i = 0; i < 4; ++i) ra[i] = al(lrow + 64 * i, (kt_) * 64 + lck * 8); }
; #define G_LOADB(kt_) { _Pragma("unroll") for (int i = 0; i < 4; ++i) rb[i] = bl(lrow + 64 * i, (kt_) * 64 + lck * 8); }
; #define G_STOREA(buf_) { bf16_t* nA = sA + (buf_) * 256 * GLD; _Pragma("unroll") for (int i = 0; i < 4; ++i) *(u32x4*)(nA + (lrow + 64 * i) * GLD + lck * 8) = ra[i]; }
; #define G_STOREB(buf_) { bf16_t* nB = sB + (buf_) * 256 * GLD; _Pragma("unroll") for (int i = 0; i < 4; ++i) *(u32x4*)(nB + (lrow + 64 * i) * GLD + lck * 8) = rb[i]; }
; template <class AL, class BL, class EP>
; DI void gemm_tile256(AL al, BL bl, EP ep, int K, char* smem) {
;     ...
;   const int KT = K >> 6;
;     ...
;   G_LOADA(0); G_LOADB(0);
;   __syncthreads();
;   G_STOREA(0); G_STOREB(0);
;   if (KT > 1) G_LOADB(1);
;   __syncthreads();
;   for (int kt = 0; kt < KT; kt += 2) {
;     G_STEP(0, kt);
;     if (kt + 1 >= KT) break;
;     G_STEP(1, kt + 1);
;   }
	s_waitcnt lgkmcnt(0)
	v_mfma_f32_32x32x16_bf16 v[112:127], v[192:195], v[168:171], v[112:127]
	ds_read_b128 v[184:187], v198
	ds_read_b128 v[152:155], v132
	v_mfma_f32_32x32x16_bf16 v[96:111], v[200:203], v[168:171], v[96:111]
	ds_read_b128 v[188:191], v198 offset:2048
	ds_read_b128 v[156:159], v132 offset:2048
	v_mfma_f32_32x32x16_bf16 v[80:95], v[192:195], v[172:175], v[80:95]
	ds_read_b128 v[160:163], v132 offset:4096
	ds_read_b128 v[164:167], v132 offset:6144
	v_mfma_f32_32x32x16_bf16 v[64:79], v[200:203], v[172:175], v[64:79]
	s_add_u32 m0, s23, 0x20000
	s_nop 0
	global_load_lds_dwordx4 v[212:213], off
	v_lshl_add_u64 v[212:213], v[212:213], 0, s[4:5]
	v_mfma_f32_32x32x16_bf16 v[48:63], v[192:195], v[176:179], v[48:63]
	v_mfma_f32_32x32x16_bf16 v[32:47], v[200:203], v[176:179], v[32:47]
	v_mfma_f32_32x32x16_bf16 v[16:31], v[192:195], v[180:183], v[16:31]
	v_mfma_f32_32x32x16_bf16 v[0:15], v[200:203], v[180:183], v[0:15]
	s_add_u32 m0, s23, 0x24000
	s_nop 0
	global_load_lds_dwordx4 v[216:217], off
	v_lshl_add_u64 v[216:217], v[216:217], 0, s[4:5]
	s_sub_u32 s24, s24, 1
	s_cmp_lg_u32 s24, 0
	s_cbranch_scc1 .Lgk_ph13_loop
	s_waitcnt lgkmcnt(0)
	v_mfma_f32_32x32x16_bf16 v[112:127], v[184:187], v[152:155], v[112:127]
	ds_read_b128 v[192:195], v199
	ds_read_b128 v[168:171], v151
	v_mfma_f32_32x32x16_bf16 v[96:111], v[188:191], v[152:155], v[96:111]
	ds_read_b128 v[200:203], v199 offset:2048
	ds_read_b128 v[172:175], v151 offset:2048
	v_mfma_f32_32x32x16_bf16 v[80:95], v[184:187], v[156:159], v[80:95]
	ds_read_b128 v[176:179], v151 offset:4096
	ds_read_b128 v[180:183], v151 offset:6144
	v_mfma_f32_32x32x16_bf16 v[64:79], v[188:191], v[156:159], v[64:79]
	s_add_u32 m0, s23, 0x22000
	s_nop 0
	global_load_lds_dwordx4 v[214:215], off
	v_lshl_add_u64 v[214:215], v[214:215], 0, s[4:5]
	v_mfma_f32_32x32x16_bf16 v[48:63], v[184:187], v[160:163], v[48:63]
	v_mfma_f32_32x32x16_bf16 v[32:47], v[188:191], v[160:163], v[32:47]
	v_mfma_f32_32x32x16_bf16 v[16:31], v[184:187], v[164:167], v[16:31]
	v_mfma_f32_32x32x16_bf16 v[0:15], v[188:191], v[164:167], v[0:15]
	s_add_u32 m0, s23, 0x26000
	s_nop 0
	global_load_lds_dwordx4 v[218:219], off
	v_lshl_add_u64 v[218:219], v[218:219], 0, s[4:5]
	s_waitcnt lgkmcnt(0)
	s_waitcnt vmcnt(12)
	s_barrier
	s_waitcnt lgkmcnt(0)
	v_mfma_f32_32x32x16_bf16 v[112:127], v[192:195], v[168:171], v[112:127]
	ds_read_b128 v[184:187], v198 offset:32768
	ds_read_b128 v[152:155], v132 offset:32768
	v_mfma_f32_32x32x16_bf16 v[96:111], v[200:203], v[168:171], v[96:111]
	ds_read_b128 v[188:191], v198 offset:34816
	ds_read_b128 v[156:159], v132 offset:34816
	v_mfma_f32_32x32x16_bf16 v[80:95], v[192:195], v[172:175], v[80:95]
	ds_read_b128 v[160:163], v132 offset:36864
	ds_read_b128 v[164:167], v132 offset:38912
	v_mfma_f32_32x32x16_bf16 v[64:79], v[200:203], v[172:175], v[64:79]
	s_add_u32 m0, s23, 0x0
	s_nop 0
	global_load_lds_dwordx4 v[212:213], off
	v_lshl_add_u64 v[212:213], v[212:213], 0, s[4:5]
	v_mfma_f32_32x32x16_bf16 v[48:63], v[192:195], v[176:179], v[48:63]
	v_mfma_f32_32x32x16_bf16 v[32:47], v[200:203], v[176:179], v[32:47]
	v_mfma_f32_32x32x16_bf16 v[16:31], v[192:195], v[180:183], v[16:31]
	v_mfma_f32_32x32x16_bf16 v[0:15], v[200:203], v[180:183], v[0:15]
	s_add_u32 m0, s23, 0x4000
	s_nop 0
	global_load_lds_dwordx4 v[216:217], off
	v_lshl_add_u64 v[216:217], v[216:217], 0, s[4:5]
	s_waitcnt lgkmcnt(0)
	v_mfma_f32_32x32x16_bf16 v[112:127], v[184:187], v[152:155], v[112:127]
	ds_read_b128 v[192:195], v199 offset:32768
	ds_read_b128 v[168:171], v151 offset:32768
	v_mfma_f32_32x32x16_bf16 v[96:111], v[188:191], v[152:155], v[96:111]
	ds_read_b128 v[200:203], v199 offset:34816
	ds_read_b128 v[172:175], v151 offset:34816
	v_mfma_f32_32x32x16_bf16 v[80:95], v[184:187], v[156:159], v[80:95]
	ds_read_b128 v[176:179], v151 offset:36864
	ds_read_b128 v[180:183], v151 offset:38912
	v_mfma_f32_32x32x16_bf16 v[64:79], v[188:191], v[156:159], v[64:79]
	s_add_u32 m0, s23, 0x2000
	s_nop 0
	global_load_lds_dwordx4 v[214:215], off
	v_lshl_add_u64 v[214:215], v[214:215], 0, s[4:5]
	v_mfma_f32_32x32x16_bf16 v[48:63], v[184:187], v[160:163], v[48:63]
	v_mfma_f32_32x32x16_bf16 v[32:47], v[188:191], v[160:163], v[32:47]
	v_mfma_f32_32x32x16_bf16 v[16:31], v[184:187], v[164:167], v[16:31]
	v_mfma_f32_32x32x16_bf16 v[0:15], v[188:191], v[164:167], v[0:15]
	s_add_u32 m0, s23, 0x6000
	s_nop 0
	global_load_lds_dwordx4 v[218:219], off
	v_lshl_add_u64 v[218:219], v[218:219], 0, s[4:5]
	s_waitcnt lgkmcnt(0)
	s_waitcnt vmcnt(12)
	s_barrier
	s_waitcnt lgkmcnt(0)
	v_mfma_f32_32x32x16_bf16 v[112:127], v[192:195], v[168:171], v[112:127]
	ds_read_b128 v[184:187], v206
	ds_read_b128 v[152:155], v204
	v_mfma_f32_32x32x16_bf16 v[96:111], v[200:203], v[168:171], v[96:111]
	ds_read_b128 v[188:191], v206 offset:2048
	ds_read_b128 v[156:159], v204 offset:2048
	v_mfma_f32_32x32x16_bf16 v[80:95], v[192:195], v[172:175], v[80:95]
	ds_read_b128 v[160:163], v204 offset:4096
	ds_read_b128 v[164:167], v204 offset:6144
	v_mfma_f32_32x32x16_bf16 v[64:79], v[200:203], v[172:175], v[64:79]
	s_add_u32 m0, s23, 0x8000
	s_nop 0
	global_load_lds_dwordx4 v[212:213], off
	v_lshl_add_u64 v[212:213], v[212:213], 0, s[4:5]
	v_mfma_f32_32x32x16_bf16 v[48:63], v[192:195], v[176:179], v[48:63]
	v_mfma_f32_32x32x16_bf16 v[32:47], v[200:203], v[176:179], v[32:47]
	v_mfma_f32_32x32x16_bf16 v[16:31], v[192:195], v[180:183], v[16:31]
	v_mfma_f32_32x32x16_bf16 v[0:15], v[200:203], v[180:183], v[0:15]
	s_add_u32 m0, s23, 0xc000
	s_nop 0
	global_load_lds_dwordx4 v[216:217], off
	v_lshl_add_u64 v[216:217], v[216:217], 0, s[4:5]
	s_waitcnt lgkmcnt(0)
	v_mfma_f32_32x32x16_bf16 v[112:127], v[184:187], v[152:155], v[112:127]
	ds_read_b128 v[192:195], v207
	ds_read_b128 v[168:171], v205
	v_mfma_f32_32x32x16_bf16 v[96:111], v[188:191], v[152:155], v[96:111]
	ds_read_b128 v[200:203], v207 offset:2048
	ds_read_b128 v[172:175], v205 offset:2048
	v_mfma_f32_32x32x16_bf16 v[80:95], v[184:187], v[156:159], v[80:95]
	ds_read_b128 v[176:179], v205 offset:4096
	ds_read_b128 v[180:183], v205 offset:6144
	v_mfma_f32_32x32x16_bf16 v[64:79], v[188:191], v[156:159], v[64:79]
	s_add_u32 m0, s23, 0xa000
	s_nop 0
	global_load_lds_dwordx4 v[214:215], off
	v_lshl_add_u64 v[214:215], v[214:215], 0, s[4:5]
	v_mfma_f32_32x32x16_bf16 v[48:63], v[184:187], v[160:163], v[48:63]
	v_mfma_f32_32x32x16_bf16 v[32:47], v[188:191], v[160:163], v[32:47]
	v_mfma_f32_32x32x16_bf16 v[16:31], v[184:187], v[164:167], v[16:31]
	v_mfma_f32_32x32x16_bf16 v[0:15], v[188:191], v[164:167], v[0:15]
	s_add_u32 m0, s23, 0xe000
	s_nop 0
	global_load_lds_dwordx4 v[218:219], off
	v_lshl_add_u64 v[218:219], v[218:219], 0, s[4:5]
	s_waitcnt lgkmcnt(0)
	s_waitcnt vmcnt(12)
	s_barrier
; #define G_LOADA(kt_) { _Pragma("unroll") for (int i = 0; i < 4; ++i) ra[i] = al(lrow + 64 * i, (kt_) * 64 + lck * 8); }
; #define G_LOADB(kt_) { _Pragma("unroll") for (int i = 0; i < 4; ++i) rb[i] = bl(lrow + 64 * i, (kt_) * 64 + lck * 8); }
; #define G_STOREA(buf_) { bf16_t* nA = sA + (buf_) * 256 * GLD; _Pragma("unroll") for (int i = 0; i < 4; ++i) *(u32x4*)(nA + (lrow + 64 * i) * GLD + lck * 8) = ra[i]; }
; #define G_STOREB(buf_) { bf16_t* nB = sB + (buf_) * 256 * GLD; _Pragma("unroll") for (int i = 0; i < 4; ++i) *(u32x4*)(nB + (lrow + 64 * i) * GLD + lck * 8) = rb[i]; }
; template <class AL, class BL, class EP>
; DI void gemm_tile256(AL al, BL bl, EP ep, int K, char* smem) {
;     ...
;   const int KT = K >> 6;
;     ...
;   G_LOADA(0); G_LOADB(0);
;   __syncthreads();
;   G_STOREA(0); G_STOREB(0);
;   if (KT > 1) G_LOADB(1);
;   __syncthreads();
;   for (int kt = 0; kt < KT; kt += 2) {
;     G_STEP(0, kt);
;     if (kt + 1 >= KT) break;
;     G_STEP(1, kt + 1);
;   }
	s_waitcnt lgkmcnt(0)
	v_mfma_f32_32x32x16_bf16 v[112:127], v[192:195], v[168:171], v[112:127]
	ds_read_b128 v[184:187], v206 offset:32768
	ds_read_b128 v[152:155], v204 offset:32768
	v_mfma_f32_32x32x16_bf16 v[96:111], v[200:203], v[168:171], v[96:111]
	ds_read_b128 v[188:191], v206 offset:34816
	ds_read_b128 v[156:159], v204 offset:34816
	v_mfma_f32_32x32x16_bf16 v[80:95], v[192:195], v[172:175], v[80:95]
	ds_read_b128 v[160:163], v204 offset:36864
	ds_read_b128 v[164:167], v204 offset:38912
	v_mfma_f32_32x32x16_bf16 v[64:79], v[200:203], v[172:175], v[64:79]
	v_mfma_f32_32x32x16_bf16 v[48:63], v[192:195], v[176:179], v[48:63]
	v_mfma_f32_32x32x16_bf16 v[32:47], v[200:203], v[176:179], v[32:47]
	v_mfma_f32_32x32x16_bf16 v[16:31], v[192:195], v[180:183], v[16:31]
	v_mfma_f32_32x32x16_bf16 v[0:15], v[200:203], v[180:183], v[0:15]
	s_waitcnt lgkmcnt(0)
	v_mfma_f32_32x32x16_bf16 v[112:127], v[184:187], v[152:155], v[112:127]
	ds_read_b128 v[192:195], v207 offset:32768
	ds_read_b128 v[168:171], v205 offset:32768
	v_mfma_f32_32x32x16_bf16 v[96:111], v[188:191], v[152:155], v[96:111]
	ds_read_b128 v[200:203], v207 offset:34816
	ds_read_b128 v[172:175], v205 offset:34816
	v_mfma_f32_32x32x16_bf16 v[80:95], v[184:187], v[156:159], v[80:95]
	ds_read_b128 v[176:179], v205 offset:36864
	ds_read_b128 v[180:183], v205 offset:38912
	v_mfma_f32_32x32x16_bf16 v[64:79], v[188:191], v[156:159], v[64:79]
	v_mfma_f32_32x32x16_bf16 v[48:63], v[184:187], v[160:163], v[48:63]
	v_mfma_f32_32x32x16_bf16 v[32:47], v[188:191], v[160:163], v[32:47]
	v_mfma_f32_32x32x16_bf16 v[16:31], v[184:187], v[164:167], v[16:31]
	v_mfma_f32_32x32x16_bf16 v[0:15], v[188:191], v[164:167], v[0:15]
	s_waitcnt lgkmcnt(0)
	s_waitcnt vmcnt(8)
	s_barrier
	s_waitcnt lgkmcnt(0)
	v_mfma_f32_32x32x16_bf16 v[112:127], v[192:195], v[168:171], v[112:127]
	ds_read_b128 v[184:187], v210
	ds_read_b128 v[152:155], v208
	v_mfma_f32_32x32x16_bf16 v[96:111], v[200:203], v[168:171], v[96:111]
	ds_read_b128 v[188:191], v210 offset:2048
	ds_read_b128 v[156:159], v208 offset:2048
	v_mfma_f32_32x32x16_bf16 v[80:95], v[192:195], v[172:175], v[80:95]
	ds_read_b128 v[160:163], v208 offset:4096
	ds_read_b128 v[164:167], v208 offset:6144
	v_mfma_f32_32x32x16_bf16 v[64:79], v[200:203], v[172:175], v[64:79]
	v_mfma_f32_32x32x16_bf16 v[48:63], v[192:195], v[176:179], v[48:63]
	v_mfma_f32_32x32x16_bf16 v[32:47], v[200:203], v[176:179], v[32:47]
	v_mfma_f32_32x32x16_bf16 v[16:31], v[192:195], v[180:183], v[16:31]
	v_mfma_f32_32x32x16_bf16 v[0:15], v[200:203], v[180:183], v[0:15]
	s_waitcnt lgkmcnt(0)
	v_mfma_f32_32x32x16_bf16 v[112:127], v[184:187], v[152:155], v[112:127]
	ds_read_b128 v[192:195], v211
	ds_read_b128 v[168:171], v209
	v_mfma_f32_32x32x16_bf16 v[96:111], v[188:191], v[152:155], v[96:111]
	ds_read_b128 v[200:203], v211 offset:2048
	ds_read_b128 v[172:175], v209 offset:2048
	v_mfma_f32_32x32x16_bf16 v[80:95], v[184:187], v[156:159], v[80:95]
	ds_read_b128 v[176:179], v209 offset:4096
	ds_read_b128 v[180:183], v209 offset:6144
	v_mfma_f32_32x32x16_bf16 v[64:79], v[188:191], v[156:159], v[64:79]
	v_mfma_f32_32x32x16_bf16 v[48:63], v[184:187], v[160:163], v[48:63]
	v_mfma_f32_32x32x16_bf16 v[32:47], v[188:191], v[160:163], v[32:47]
	v_mfma_f32_32x32x16_bf16 v[16:31], v[184:187], v[164:167], v[16:31]
	v_mfma_f32_32x32x16_bf16 v[0:15], v[188:191], v[164:167], v[0:15]
	s_waitcnt lgkmcnt(0)
	s_waitcnt vmcnt(4)
	s_barrier
	s_waitcnt lgkmcnt(0)
	v_mfma_f32_32x32x16_bf16 v[112:127], v[192:195], v[168:171], v[112:127]
	ds_read_b128 v[184:187], v198
	ds_read_b128 v[152:155], v132
	v_mfma_f32_32x32x16_bf16 v[96:111], v[200:203], v[168:171], v[96:111]
	ds_read_b128 v[188:191], v198 offset:2048
	ds_read_b128 v[156:159], v132 offset:2048
	v_mfma_f32_32x32x16_bf16 v[80:95], v[192:195], v[172:175], v[80:95]
	ds_read_b128 v[160:163], v132 offset:4096
	ds_read_b128 v[164:167], v132 offset:6144
	v_mfma_f32_32x32x16_bf16 v[64:79], v[200:203], v[172:175], v[64:79]
	v_mfma_f32_32x32x16_bf16 v[48:63], v[192:195], v[176:179], v[48:63]
	v_mfma_f32_32x32x16_bf16 v[32:47], v[200:203], v[176:179], v[32:47]
	v_mfma_f32_32x32x16_bf16 v[16:31], v[192:195], v[180:183], v[16:31]
	v_mfma_f32_32x32x16_bf16 v[0:15], v[200:203], v[180:183], v[0:15]
	s_waitcnt lgkmcnt(0)
	v_mfma_f32_32x32x16_bf16 v[112:127], v[184:187], v[152:155], v[112:127]
	ds_read_b128 v[192:195], v199
	ds_read_b128 v[168:171], v151
	v_mfma_f32_32x32x16_bf16 v[96:111], v[188:191], v[152:155], v[96:111]
	ds_read_b128 v[200:203], v199 offset:2048
	ds_read_b128 v[172:175], v151 offset:2048
	v_mfma_f32_32x32x16_bf16 v[80:95], v[184:187], v[156:159], v[80:95]
	ds_read_b128 v[176:179], v151 offset:4096
	ds_read_b128 v[180:183], v151 offset:6144
	v_mfma_f32_32x32x16_bf16 v[64:79], v[188:191], v[156:159], v[64:79]
	v_mfma_f32_32x32x16_bf16 v[48:63], v[184:187], v[160:163], v[48:63]
	v_mfma_f32_32x32x16_bf16 v[32:47], v[188:191], v[160:163], v[32:47]
	v_mfma_f32_32x32x16_bf16 v[16:31], v[184:187], v[164:167], v[16:31]
	v_mfma_f32_32x32x16_bf16 v[0:15], v[188:191], v[164:167], v[0:15]
	s_waitcnt lgkmcnt(0)
	s_waitcnt vmcnt(0)
	s_barrier
; DI unsigned pack2(float a, float b) { f2_t f = {a, b}; bf2_t r = __builtin_convertvector(f, bf2_t); return __builtin_bit_cast(unsigned, r); }
; template <class AL, class BL, class EP>
; DI void gemm_tile256(AL al, BL bl, EP ep, int K, char* smem) {
;     ...
;   for (int kt = 0; kt < KT; kt += 2) {
;     G_STEP(0, kt);
;     if (kt + 1 >= KT) break;
;     G_STEP(1, kt + 1);
;   }
;     ...
;   if constexpr (EP::kBf16) {
;     bf16_t* sCb = (bf16_t*)smem;
; #pragma unroll
;     for (int i = 0; i < 4; ++i)
; #pragma unroll
;       for (int j = 0; j < 2; ++j)
; #pragma unroll
;         for (int g = 0; g < 4; ++g) {
;           u32x2 v = {pack2(acc[i][j][4 * g], acc[i][j][4 * g + 1]), pack2(acc[i][j][4 * g + 2], acc[i][j][4 * g + 3])};
;           *(u32x2*)(sCb + (128 * wm + 32 * i + r) * BLD + 64 * wn + 32 * j + 8 * g + 4 * h) = v;
;         }
;     __syncthreads();
;     ep(sCb);
	s_waitcnt lgkmcnt(0)
	v_mfma_f32_32x32x16_bf16 v[112:127], v[192:195], v[168:171], v[112:127]
	ds_read_b128 v[184:187], v198 offset:32768
	ds_read_b128 v[152:155], v132 offset:32768
	v_mfma_f32_32x32x16_bf16 v[96:111], v[200:203], v[168:171], v[96:111]
	ds_read_b128 v[188:191], v198 offset:34816
	ds_read_b128 v[156:159], v132 offset:34816
	v_mfma_f32_32x32x16_bf16 v[80:95], v[192:195], v[172:175], v[80:95]
	ds_read_b128 v[160:163], v132 offset:36864
	ds_read_b128 v[164:167], v132 offset:38912
	v_mfma_f32_32x32x16_bf16 v[64:79], v[200:203], v[172:175], v[64:79]
	v_mfma_f32_32x32x16_bf16 v[48:63], v[192:195], v[176:179], v[48:63]
	v_mfma_f32_32x32x16_bf16 v[32:47], v[200:203], v[176:179], v[32:47]
	v_mfma_f32_32x32x16_bf16 v[16:31], v[192:195], v[180:183], v[16:31]
	v_mfma_f32_32x32x16_bf16 v[0:15], v[200:203], v[180:183], v[0:15]
	s_waitcnt lgkmcnt(0)
	v_mfma_f32_32x32x16_bf16 v[112:127], v[184:187], v[152:155], v[112:127]
	ds_read_b128 v[192:195], v199 offset:32768
	ds_read_b128 v[168:171], v151 offset:32768
	v_mfma_f32_32x32x16_bf16 v[96:111], v[188:191], v[152:155], v[96:111]
	ds_read_b128 v[200:203], v199 offset:34816
	ds_read_b128 v[172:175], v151 offset:34816
	v_mfma_f32_32x32x16_bf16 v[80:95], v[184:187], v[156:159], v[80:95]
	ds_read_b128 v[176:179], v151 offset:36864
	ds_read_b128 v[180:183], v151 offset:38912
	v_mfma_f32_32x32x16_bf16 v[64:79], v[188:191], v[156:159], v[64:79]
	v_mfma_f32_32x32x16_bf16 v[48:63], v[184:187], v[160:163], v[48:63]
	v_mfma_f32_32x32x16_bf16 v[32:47], v[188:191], v[160:163], v[32:47]
	v_mfma_f32_32x32x16_bf16 v[16:31], v[184:187], v[164:167], v[16:31]
	v_mfma_f32_32x32x16_bf16 v[0:15], v[188:191], v[164:167], v[0:15]
	s_waitcnt lgkmcnt(0)
	s_waitcnt lgkmcnt(0)
	v_mfma_f32_32x32x16_bf16 v[112:127], v[192:195], v[168:171], v[112:127]
	v_mfma_f32_32x32x16_bf16 v[96:111], v[200:203], v[168:171], v[96:111]
	v_mfma_f32_32x32x16_bf16 v[80:95], v[192:195], v[172:175], v[80:95]
	v_mfma_f32_32x32x16_bf16 v[64:79], v[200:203], v[172:175], v[64:79]
	v_mfma_f32_32x32x16_bf16 v[48:63], v[192:195], v[176:179], v[48:63]
	v_mfma_f32_32x32x16_bf16 v[32:47], v[200:203], v[176:179], v[32:47]
	v_mfma_f32_32x32x16_bf16 v[16:31], v[192:195], v[180:183], v[16:31]
	v_mfma_f32_32x32x16_bf16 v[0:15], v[200:203], v[180:183], v[0:15]
	s_nop 15
	s_nop 3
	v_lshl_or_b32 v128, v128, 7, v150
	s_waitcnt lgkmcnt(4)
	v_mad_u64_u32 v[130:131], s[2:3], v133, s17, v[128:129]
	s_waitcnt lgkmcnt(0)
	s_barrier
	s_nop 8
	v_cvt_pk_bf16_f32 v112, v112, v113
	v_cvt_pk_bf16_f32 v113, v114, v115
	v_cvt_pk_bf16_f32 v114, v116, v117
	v_cvt_pk_bf16_f32 v115, v118, v119
	ds_write2_b64 v130, v[112:113], v[114:115] offset1:2
	v_cvt_pk_bf16_f32 v112, v120, v121
	v_cvt_pk_bf16_f32 v113, v122, v123
	v_cvt_pk_bf16_f32 v114, v124, v125
	s_nop 3
	v_cvt_pk_bf16_f32 v16, v16, v17
	v_cvt_pk_bf16_f32 v17, v18, v19
	v_cvt_pk_bf16_f32 v18, v20, v21
	v_add_u32_e32 v20, 0xc000, v130
	v_cvt_pk_bf16_f32 v19, v22, v23
	v_cvt_pk_bf16_f32 v115, v126, v127
	ds_write2_b64 v20, v[16:17], v[18:19] offset0:192 offset1:194
	v_cvt_pk_bf16_f32 v0, v0, v1
	v_cvt_pk_bf16_f32 v1, v2, v3
	v_cvt_pk_bf16_f32 v2, v4, v5
	v_cvt_pk_bf16_f32 v3, v6, v7
	ds_write2_b64 v20, v[0:1], v[2:3] offset0:200 offset1:202
	v_cvt_pk_bf16_f32 v0, v8, v9
	v_cvt_pk_bf16_f32 v1, v10, v11
	s_nop 3
	v_cvt_pk_bf16_f32 v96, v96, v97
	v_cvt_pk_bf16_f32 v97, v98, v99
	v_cvt_pk_bf16_f32 v98, v100, v101
	v_cvt_pk_bf16_f32 v99, v102, v103
	v_cvt_pk_bf16_f32 v2, v12, v13
	v_cvt_pk_bf16_f32 v3, v14, v15
	ds_write2_b64 v130, v[96:97], v[98:99] offset0:8 offset1:10
	v_cvt_pk_bf16_f32 v80, v80, v81
	v_cvt_pk_bf16_f32 v81, v82, v83
	v_cvt_pk_bf16_f32 v82, v84, v85
	v_cvt_pk_bf16_f32 v83, v86, v87
	v_add_u32_e32 v84, 0x4000, v130
	v_cvt_pk_bf16_f32 v96, v104, v105
	v_cvt_pk_bf16_f32 v97, v106, v107
	s_nop 3
	v_cvt_pk_bf16_f32 v64, v64, v65
	v_cvt_pk_bf16_f32 v65, v66, v67
	v_cvt_pk_bf16_f32 v66, v68, v69
	v_cvt_pk_bf16_f32 v67, v70, v71
	v_cvt_pk_bf16_f32 v98, v108, v109
	v_cvt_pk_bf16_f32 v99, v110, v111
	ds_write2_b64 v84, v[80:81], v[82:83] offset0:64 offset1:66
	v_cvt_pk_bf16_f32 v48, v48, v49
	v_cvt_pk_bf16_f32 v49, v50, v51
	v_cvt_pk_bf16_f32 v50, v52, v53
	v_cvt_pk_bf16_f32 v51, v54, v55
	v_add_u32_e32 v52, 0x8000, v130
	v_cvt_pk_bf16_f32 v80, v88, v89
	v_cvt_pk_bf16_f32 v81, v90, v91
	s_nop 4
	v_cvt_pk_bf16_f32 v32, v32, v33
	v_cvt_pk_bf16_f32 v33, v34, v35
	v_cvt_pk_bf16_f32 v34, v36, v37
	v_cvt_pk_bf16_f32 v35, v38, v39
	v_cvt_pk_bf16_f32 v82, v92, v93
	v_cvt_pk_bf16_f32 v83, v94, v95
	ds_write2_b64 v84, v[64:65], v[66:67] offset0:72 offset1:74
	v_cvt_pk_bf16_f32 v64, v72, v73
	v_cvt_pk_bf16_f32 v65, v74, v75
	v_cvt_pk_bf16_f32 v66, v76, v77
	v_cvt_pk_bf16_f32 v67, v78, v79
	ds_write2_b64 v52, v[48:49], v[50:51] offset0:128 offset1:130
	v_cvt_pk_bf16_f32 v48, v56, v57
	v_cvt_pk_bf16_f32 v49, v58, v59
	v_cvt_pk_bf16_f32 v50, v60, v61
	v_cvt_pk_bf16_f32 v51, v62, v63
	ds_write2_b64 v52, v[32:33], v[34:35] offset0:136 offset1:138
	v_cvt_pk_bf16_f32 v32, v40, v41
	v_cvt_pk_bf16_f32 v33, v42, v43
	v_cvt_pk_bf16_f32 v34, v44, v45
	v_cvt_pk_bf16_f32 v35, v46, v47
	v_cvt_pk_bf16_f32 v16, v24, v25
	v_cvt_pk_bf16_f32 v17, v26, v27
	v_cvt_pk_bf16_f32 v18, v28, v29
	v_cvt_pk_bf16_f32 v19, v30, v31
	ds_write2_b64 v20, v[0:1], v[2:3] offset0:204 offset1:206
	v_mov_b32_e32 v2, v196
	ds_write2_b64 v130, v[112:113], v[114:115] offset0:4 offset1:6
	ds_write2_b64 v130, v[96:97], v[98:99] offset0:12 offset1:14
	ds_write2_b64 v84, v[80:81], v[82:83] offset0:68 offset1:70
	ds_write2_b64 v84, v[64:65], v[66:67] offset0:76 offset1:78
	ds_write2_b64 v52, v[48:49], v[50:51] offset0:132 offset1:134
	ds_write2_b64 v52, v[32:33], v[34:35] offset0:140 offset1:142
	ds_write2_b64 v20, v[16:17], v[18:19] offset0:196 offset1:198
	s_waitcnt lgkmcnt(0)
	s_barrier
	s_nop 0
	v_cmp_gt_i32_e32 vcc, s18, v2
	s_and_saveexec_b64 s[2:3], vcc
	s_cbranch_execz .LBB0_1046
	v_lshlrev_b32_e32 v3, 3, v2
	s_mov_b64 s[4:5], 0
	s_branch .LBB0_1044

; DI int tid512() { int t = threadIdx_x_raw(); asm volatile("" : "+v"(t)); return t; }
; #define G_LOADA(kt_) { _Pragma("unroll") for (int i = 0; i < 4; ++i) ra[i] = al(lrow + 64 * i, (kt_) * 64 + lck * 8); }
; #define G_LOADB(kt_) { _Pragma("unroll") for (int i = 0; i < 4; ++i) rb[i] = bl(lrow + 64 * i, (kt_) * 64 + lck * 8); }
; #define G_STOREA(buf_) { bf16_t* nA = sA + (buf_) * 256 * GLD; _Pragma("unroll") for (int i = 0; i < 4; ++i) *(u32x4*)(nA + (lrow + 64 * i) * GLD + lck * 8) = ra[i]; }
; #define G_STOREB(buf_) { bf16_t* nB = sB + (buf_) * 256 * GLD; _Pragma("unroll") for (int i = 0; i < 4; ++i) *(u32x4*)(nB + (lrow + 64 * i) * GLD + lck * 8) = rb[i]; }
; template <class AL, class BL, class EP>
; DI void gemm_tile256(AL al, BL bl, EP ep, int K, char* smem) {
;   bf16_t* sA = (bf16_t*)smem;
;   bf16_t* sB = sA + 2 * 256 * GLD;
;   const int tid = tid512(), lane = tid & 63, w = tid >> 6, wm = w >> 2, wn = w & 3, r = lane & 31, h = lane >> 5;
;   const int lrow = tid >> 3, lck = tid & 7;
;   f32x16 acc[4][2];
; #pragma unroll
;   for (int i = 0; i < 4; ++i)
; #pragma unroll
;     for (int j = 0; j < 2; ++j)
; #pragma unroll
;       for (int q = 0; q < 16; ++q) acc[i][j][q] = 0.f;
;   u32x4 ra[4], rb[4];
;   const int KT = K >> 6;
;     ...
;   G_LOADA(0); G_LOADB(0);
;   __syncthreads();
;   G_STOREA(0); G_STOREB(0);
;   if (KT > 1) G_LOADB(1);
;   __syncthreads();
; DI void phase_ffn_up256(const Sched& sc, const Params& p, int layer, char* smem) {
;   const bf16_t* H = (const bf16_t*)(p.hbuf);
;   const bf16_t* Wt = (const bf16_t*)(p.ws + (layer ? OFF_WT_GU1 : OFF_WT_GU0));
;   for (int round = 0;; ++round) {
;     int mt = 0, nt = 0;
;     const int st = sched_tile(sc, round, 128, 22, mt, nt);
;     if (st == 2) break;
;     if (st == 1) continue;
;     LoadRows al{H, 1024, mt * 256, T};
;     LoadRows bl{Wt, 1024, nt * 256, 5632};
;     EpFfnUp256 ep{p.ffn_conv + (size_t)layer * 3 * DFF, (bf16_t*)(p.ws + OFF_HID), (bf16_t*)(p.ws + OFF_HG), (bf16_t*)(p.ws + OFF_HU), mt, nt * 128};
;     gemm_tile256(al, bl, ep, 1024, smem);
.LBB0_1143:
	v_cmp_ne_u32_e32 vcc, 1, v0
	s_mov_b64 s[0:1], -1
	s_cbranch_vccz .LBB0_1158
	v_mov_b32_e32 v32, v196
	s_nop 0
	v_ashrrev_i32_e32 v33, 3, v32
	v_lshl_add_u32 v12, v130, 8, v33
	v_lshlrev_b32_e32 v0, 4, v32
	v_add_u32_e32 v10, 0x80, v12
	v_lshl_add_u32 v28, v131, 8, v33
	v_and_b32_e32 v128, 0x70, v0
	v_min_i32_e32 v0, 0x7fff, v12
	v_min_i32_e32 v10, 0x7fff, v10
	v_add_u32_e32 v26, 0x80, v28
	v_ashrrev_i32_e32 v1, 31, v0
	v_ashrrev_i32_e32 v11, 31, v10
	v_min_i32_e32 v16, 0x15ff, v28
	v_min_i32_e32 v26, 0x15ff, v26
	v_lshl_add_u64 v[8:9], s[84:85], 0, v[128:129]
	v_lshlrev_b64 v[0:1], 11, v[0:1]
	v_lshlrev_b64 v[10:11], 11, v[10:11]
	v_ashrrev_i32_e32 v17, 31, v16
	v_ashrrev_i32_e32 v27, 31, v26
	v_lshl_add_u64 v[136:137], v[8:9], 0, v[0:1]
	v_add_u32_e32 v0, 64, v12
	v_lshl_add_u64 v[140:141], v[8:9], 0, v[10:11]
	v_add_u32_e32 v10, 0xc0, v12
	v_lshlrev_b64 v[190:191], 11, v[16:17]
	v_add_u32_e32 v16, 64, v28
	v_lshlrev_b64 v[194:195], 11, v[26:27]
	v_add_u32_e32 v26, 0xc0, v28
	v_min_i32_e32 v0, 0x7fff, v0
	v_min_i32_e32 v10, 0x7fff, v10
	v_min_i32_e32 v16, 0x15ff, v16
	v_min_i32_e32 v26, 0x15ff, v26
	v_ashrrev_i32_e32 v1, 31, v0
	v_ashrrev_i32_e32 v11, 31, v10
	v_lshl_add_u64 v[24:25], s[2:3], 0, v[128:129]
	v_ashrrev_i32_e32 v17, 31, v16
	v_ashrrev_i32_e32 v27, 31, v26
	v_lshlrev_b64 v[0:1], 11, v[0:1]
	v_lshlrev_b64 v[10:11], 11, v[10:11]
	v_lshl_add_u64 v[144:145], v[24:25], 0, v[190:191]
	v_lshlrev_b64 v[192:193], 11, v[16:17]
	v_lshl_add_u64 v[148:149], v[24:25], 0, v[194:195]
	v_lshlrev_b64 v[198:199], 11, v[26:27]
	v_lshl_add_u64 v[138:139], v[8:9], 0, v[0:1]
	v_lshl_add_u64 v[142:143], v[8:9], 0, v[10:11]
	v_lshl_add_u64 v[146:147], v[24:25], 0, v[192:193]
	v_lshl_add_u64 v[150:151], v[24:25], 0, v[198:199]
	v_mad_u64_u32 v[134:135], s[0:1], v33, s23, v[128:129]
	v_add_u32_e32 v157, 0x12000, v134
	v_bfe_u32 v135, v32, 6, 2
	v_add_u32_e32 v156, 0x1b000, v134
	v_and_b32_e32 v1, 31, v32
	v_ashrrev_i32_e32 v0, 1, v32
	v_and_or_b32 v153, v0, s24, v1
	v_lshrrev_b32_e32 v0, 2, v32
	v_and_b32_e32 v154, 8, v0
	v_lshlrev_b32_e32 v0, 1, v154
	v_mad_u64_u32 v[132:133], s[0:1], v153, s23, v[0:1]
	v_lshl_or_b32 v1, v135, 6, v1
	v_mul_u32_u24_e32 v1, 0x48, v1
	v_lshl_add_u32 v0, v1, 1, v0
	v_add_u32_e32 v155, 0x12000, v0
	v_add_u32_e32 v133, 0x1b000, v0
	v_lshl_add_u64 v[198:199], s[2:3], 0, v[198:199]
	v_or_b32_e32 v128, 0x100, v128
	v_lshl_add_u64 v[192:193], s[2:3], 0, v[192:193]
	v_lshl_add_u64 v[190:191], s[2:3], 0, v[190:191]
	v_lshl_add_u64 v[206:207], v[198:199], 0, v[128:129]
	v_lshl_add_u64 v[194:195], s[2:3], 0, v[194:195]
	v_lshl_add_u64 v[198:199], v[192:193], 0, v[128:129]
	v_lshl_add_u64 v[190:191], v[190:191], 0, v[128:129]
	v_lshl_add_u64 v[194:195], v[194:195], 0, v[128:129]
	s_nop 0
	s_nop 0
	s_nop 0
	s_nop 0
	s_nop 0
	s_nop 0
	s_nop 0
	s_nop 0
	s_nop 0
	v_lshrrev_b32_e32 v226, 6, v196
	s_mov_b32 s10, 64
	v_readfirstlane_b32 s32, v226
	s_mov_b32 s11, 0
	s_mov_b32 s18, 0x40000
	s_mov_b32 s19, 0
	v_bfe_u32 v224, v196, 2, 4
	s_lshl_b32 s33, s32, 3
	v_add_u32_e32 v224, s33, v224
	s_mov_b32 s33, 0x800
	v_mul_lo_u32 v224, v224, s33
	v_bfe_u32 v226, v196, 4, 2
	v_and_b32_e32 v225, 3, v196
	v_xor_b32_e32 v226, v225, v226
	v_lshl_add_u32 v224, v226, 4, v224
	v_mov_b32_e32 v225, 0
	v_readlane_b32 s20, v136, 0
	v_readlane_b32 s21, v137, 0
	s_nop 1
	v_lshl_add_u64 v[216:217], s[20:21], 0, v[224:225]
	v_lshl_add_u64 v[218:219], v[216:217], 0, s[18:19]
	v_readlane_b32 s20, v144, 0
	v_readlane_b32 s21, v145, 0
	s_nop 1
	v_lshl_add_u64 v[220:221], s[20:21], 0, v[224:225]
	v_lshl_add_u64 v[222:223], v[220:221], 0, s[18:19]
	v_and_b32_e32 v224, 31, v196
	v_bfe_u32 v226, v196, 2, 2
	v_bfe_u32 v225, v196, 5, 1
	v_xor_b32_e32 v226, v225, v226
	v_lshlrev_b32_e32 v226, 4, v226
	v_lshl_or_b32 v224, v224, 6, v226
	s_lshr_b32 s33, s32, 2
	s_lshl_b32 s33, s33, 13
	v_add_u32_e32 v134, s33, v224
	s_and_b32 s33, s32, 3
	s_lshl_b32 s33, s33, 12
	s_add_u32 s33, s33, 0x4000
	v_add_u32_e32 v198, s33, v224
	v_xor_b32_e32 v155, 0x20, v134
	v_xor_b32_e32 v199, 0x20, v198
	v_add_u32_e32 v208, 0x10000, v134
	v_add_u32_e32 v210, 0x10000, v198
	v_add_u32_e32 v212, 0x20000, v134
	v_add_u32_e32 v214, 0x20000, v198
	v_add_u32_e32 v209, 0x10000, v155
	v_add_u32_e32 v211, 0x10000, v199
	v_add_u32_e32 v213, 0x20000, v155
	v_add_u32_e32 v215, 0x20000, v199
	s_lshl_b32 s32, s32, 10
	s_waitcnt lgkmcnt(0)
	s_barrier
; #define G_LOADA(kt_) { _Pragma("unroll") for (int i = 0; i < 4; ++i) ra[i] = al(lrow + 64 * i, (kt_) * 64 + lck * 8); }
; #define G_LOADB(kt_) { _Pragma("unroll") for (int i = 0; i < 4; ++i) rb[i] = bl(lrow + 64 * i, (kt_) * 64 + lck * 8); }
; #define G_STOREA(buf_) { bf16_t* nA = sA + (buf_) * 256 * GLD; _Pragma("unroll") for (int i = 0; i < 4; ++i) *(u32x4*)(nA + (lrow + 64 * i) * GLD + lck * 8) = ra[i]; }
; #define G_STOREB(buf_) { bf16_t* nB = sB + (buf_) * 256 * GLD; _Pragma("unroll") for (int i = 0; i < 4; ++i) *(u32x4*)(nB + (lrow + 64 * i) * GLD + lck * 8) = rb[i]; }
; template <class AL, class BL, class EP>
; DI void gemm_tile256(AL al, BL bl, EP ep, int K, char* smem) {
;     ...
;   const int KT = K >> 6;
;     ...
;   G_LOADA(0); G_LOADB(0);
;   __syncthreads();
;   G_STOREA(0); G_STOREB(0);
;   if (KT > 1) G_LOADB(1);
;   __syncthreads();
	s_add_u32 m0, s32, 0x0
	s_nop 0
	global_load_lds_dwordx4 v[216:217], off
	v_lshl_add_u64 v[216:217], v[216:217], 0, s[10:11]
	s_add_u32 m0, s32, 0x4000
	s_nop 0
	global_load_lds_dwordx4 v[220:221], off
	v_lshl_add_u64 v[220:221], v[220:221], 0, s[10:11]
	s_add_u32 m0, s32, 0x2000
	s_nop 0
	global_load_lds_dwordx4 v[218:219], off
	v_lshl_add_u64 v[218:219], v[218:219], 0, s[10:11]
	s_add_u32 m0, s32, 0x6000
	s_nop 0
	global_load_lds_dwordx4 v[222:223], off
	v_lshl_add_u64 v[222:223], v[222:223], 0, s[10:11]
	s_add_u32 m0, s32, 0x8000
	s_nop 0
	global_load_lds_dwordx4 v[216:217], off
	v_lshl_add_u64 v[216:217], v[216:217], 0, s[10:11]
	s_add_u32 m0, s32, 0xc000
	s_nop 0
	global_load_lds_dwordx4 v[220:221], off
	v_lshl_add_u64 v[220:221], v[220:221], 0, s[10:11]
	s_add_u32 m0, s32, 0xa000
	s_nop 0
	global_load_lds_dwordx4 v[218:219], off
	v_lshl_add_u64 v[218:219], v[218:219], 0, s[10:11]
	s_add_u32 m0, s32, 0xe000
	s_nop 0
	global_load_lds_dwordx4 v[222:223], off
	v_lshl_add_u64 v[222:223], v[222:223], 0, s[10:11]
	s_add_u32 m0, s32, 0x10000
	s_nop 0
	global_load_lds_dwordx4 v[216:217], off
	v_lshl_add_u64 v[216:217], v[216:217], 0, s[10:11]
	s_add_u32 m0, s32, 0x14000
	s_nop 0
	global_load_lds_dwordx4 v[220:221], off
	v_lshl_add_u64 v[220:221], v[220:221], 0, s[10:11]
	s_add_u32 m0, s32, 0x12000
	s_nop 0
	global_load_lds_dwordx4 v[218:219], off
	v_lshl_add_u64 v[218:219], v[218:219], 0, s[10:11]
	s_add_u32 m0, s32, 0x16000
	s_nop 0
	global_load_lds_dwordx4 v[222:223], off
	v_lshl_add_u64 v[222:223], v[222:223], 0, s[10:11]
	s_add_u32 m0, s32, 0x18000
	s_nop 0
	global_load_lds_dwordx4 v[216:217], off
	v_lshl_add_u64 v[216:217], v[216:217], 0, s[10:11]
	s_add_u32 m0, s32, 0x1c000
	s_nop 0
	global_load_lds_dwordx4 v[220:221], off
	v_lshl_add_u64 v[220:221], v[220:221], 0, s[10:11]
	s_add_u32 m0, s32, 0x1a000
	s_nop 0
	global_load_lds_dwordx4 v[218:219], off
	v_lshl_add_u64 v[218:219], v[218:219], 0, s[10:11]
	s_add_u32 m0, s32, 0x1e000
	s_nop 0
	global_load_lds_dwordx4 v[222:223], off
	v_lshl_add_u64 v[222:223], v[222:223], 0, s[10:11]
	s_add_u32 m0, s32, 0x20000
	s_nop 0
	global_load_lds_dwordx4 v[216:217], off
	v_lshl_add_u64 v[216:217], v[216:217], 0, s[10:11]
	s_add_u32 m0, s32, 0x24000
	s_nop 0
	global_load_lds_dwordx4 v[220:221], off
	v_lshl_add_u64 v[220:221], v[220:221], 0, s[10:11]
	v_mov_b64_e32 v[112:113], 0
	v_mov_b64_e32 v[114:115], 0
	v_mov_b64_e32 v[116:117], 0
	v_mov_b64_e32 v[118:119], 0
	v_mov_b64_e32 v[120:121], 0
	v_mov_b64_e32 v[122:123], 0
	v_mov_b64_e32 v[124:125], 0
	v_mov_b64_e32 v[126:127], 0
	v_mov_b64_e32 v[96:97], 0
	v_mov_b64_e32 v[98:99], 0
	v_mov_b64_e32 v[100:101], 0
	v_mov_b64_e32 v[102:103], 0
	v_mov_b64_e32 v[104:105], 0
	v_mov_b64_e32 v[106:107], 0
	v_mov_b64_e32 v[108:109], 0
	v_mov_b64_e32 v[110:111], 0
	v_mov_b64_e32 v[80:81], 0
	v_mov_b64_e32 v[82:83], 0
	v_mov_b64_e32 v[84:85], 0
	v_mov_b64_e32 v[86:87], 0
	v_mov_b64_e32 v[88:89], 0
	v_mov_b64_e32 v[90:91], 0
	v_mov_b64_e32 v[92:93], 0
	v_mov_b64_e32 v[94:95], 0
	v_mov_b64_e32 v[64:65], 0
	v_mov_b64_e32 v[66:67], 0
	v_mov_b64_e32 v[68:69], 0
	v_mov_b64_e32 v[70:71], 0
	v_mov_b64_e32 v[72:73], 0
	v_mov_b64_e32 v[74:75], 0
	v_mov_b64_e32 v[76:77], 0
	v_mov_b64_e32 v[78:79], 0
	v_mov_b64_e32 v[48:49], 0
	v_mov_b64_e32 v[50:51], 0
	v_mov_b64_e32 v[52:53], 0
	v_mov_b64_e32 v[54:55], 0
	v_mov_b64_e32 v[56:57], 0
	v_mov_b64_e32 v[58:59], 0
	v_mov_b64_e32 v[60:61], 0
	v_mov_b64_e32 v[62:63], 0
	v_mov_b64_e32 v[32:33], 0
	v_mov_b64_e32 v[34:35], 0
	v_mov_b64_e32 v[36:37], 0
	v_mov_b64_e32 v[38:39], 0
	v_mov_b64_e32 v[40:41], 0
	v_mov_b64_e32 v[42:43], 0
	v_mov_b64_e32 v[44:45], 0
	v_mov_b64_e32 v[46:47], 0
	v_mov_b64_e32 v[16:17], 0
	v_mov_b64_e32 v[18:19], 0
	v_mov_b64_e32 v[20:21], 0
	v_mov_b64_e32 v[22:23], 0
	v_mov_b64_e32 v[24:25], 0
	v_mov_b64_e32 v[26:27], 0
	v_mov_b64_e32 v[28:29], 0
	v_mov_b64_e32 v[30:31], 0
	v_mov_b64_e32 v[0:1], 0
	v_mov_b64_e32 v[2:3], 0
	v_mov_b64_e32 v[4:5], 0
	v_mov_b64_e32 v[6:7], 0
	v_mov_b64_e32 v[8:9], 0
	v_mov_b64_e32 v[10:11], 0
	v_mov_b64_e32 v[12:13], 0
	v_mov_b64_e32 v[14:15], 0
	s_mov_b32 s33, 5
	s_waitcnt vmcnt(14)
	s_barrier
	ds_read_b128 v[188:191], v198
	ds_read_b128 v[156:159], v134
	ds_read_b128 v[192:195], v198 offset:2048
	ds_read_b128 v[160:163], v134 offset:2048
	ds_read_b128 v[164:167], v134 offset:4096
	ds_read_b128 v[168:171], v134 offset:6144
; #define G_LOADA(kt_) { _Pragma("unroll") for (int i = 0; i < 4; ++i) ra[i] = al(lrow + 64 * i, (kt_) * 64 + lck * 8); }
; #define G_LOADB(kt_) { _Pragma("unroll") for (int i = 0; i < 4; ++i) rb[i] = bl(lrow + 64 * i, (kt_) * 64 + lck * 8); }
; #define G_STOREA(buf_) { bf16_t* nA = sA + (buf_) * 256 * GLD; _Pragma("unroll") for (int i = 0; i < 4; ++i) *(u32x4*)(nA + (lrow + 64 * i) * GLD + lck * 8) = ra[i]; }
; #define G_STOREB(buf_) { bf16_t* nB = sB + (buf_) * 256 * GLD; _Pragma("unroll") for (int i = 0; i < 4; ++i) *(u32x4*)(nB + (lrow + 64 * i) * GLD + lck * 8) = rb[i]; }
; template <class AL, class BL, class EP>
; DI void gemm_tile256(AL al, BL bl, EP ep, int K, char* smem) {
;     ...
;   const int KT = K >> 6;
;     ...
;   G_LOADA(0); G_LOADB(0);
;   __syncthreads();
;   G_STOREA(0); G_STOREB(0);
;   if (KT > 1) G_LOADB(1);
;   __syncthreads();
;   for (int kt = 0; kt < KT; kt += 2) {
;     G_STEP(0, kt);
;     if (kt + 1 >= KT) break;
;     G_STEP(1, kt + 1);
;   }
.Lgk_ph15_loop:
	s_waitcnt lgkmcnt(0)
	v_mfma_f32_32x32x16_bf16 v[112:127], v[188:191], v[156:159], v[112:127]
	ds_read_b128 v[200:203], v199
	ds_read_b128 v[172:175], v155
	v_mfma_f32_32x32x16_bf16 v[96:111], v[192:195], v[156:159], v[96:111]
	ds_read_b128 v[204:207], v199 offset:2048
	ds_read_b128 v[176:179], v155 offset:2048
	v_mfma_f32_32x32x16_bf16 v[80:95], v[188:191], v[160:163], v[80:95]
	ds_read_b128 v[180:183], v155 offset:4096
	ds_read_b128 v[184:187], v155 offset:6144
	v_mfma_f32_32x32x16_bf16 v[64:79], v[192:195], v[160:163], v[64:79]
	s_add_u32 m0, s32, 0x22000
	s_nop 0
	global_load_lds_dwordx4 v[218:219], off
	v_lshl_add_u64 v[218:219], v[218:219], 0, s[10:11]
	v_mfma_f32_32x32x16_bf16 v[48:63], v[188:191], v[164:167], v[48:63]
	v_mfma_f32_32x32x16_bf16 v[32:47], v[192:195], v[164:167], v[32:47]
	v_mfma_f32_32x32x16_bf16 v[16:31], v[188:191], v[168:171], v[16:31]
	v_mfma_f32_32x32x16_bf16 v[0:15], v[192:195], v[168:171], v[0:15]
	s_add_u32 m0, s32, 0x26000
	s_nop 0
	global_load_lds_dwordx4 v[222:223], off
	v_lshl_add_u64 v[222:223], v[222:223], 0, s[10:11]
	s_waitcnt lgkmcnt(0)
	s_waitcnt vmcnt(12)
	s_barrier
	s_waitcnt lgkmcnt(0)
	v_mfma_f32_32x32x16_bf16 v[112:127], v[200:203], v[172:175], v[112:127]
	ds_read_b128 v[188:191], v198 offset:32768
	ds_read_b128 v[156:159], v134 offset:32768
	v_mfma_f32_32x32x16_bf16 v[96:111], v[204:207], v[172:175], v[96:111]
	ds_read_b128 v[192:195], v198 offset:34816
	ds_read_b128 v[160:163], v134 offset:34816
	v_mfma_f32_32x32x16_bf16 v[80:95], v[200:203], v[176:179], v[80:95]
	ds_read_b128 v[164:167], v134 offset:36864
	ds_read_b128 v[168:171], v134 offset:38912
	v_mfma_f32_32x32x16_bf16 v[64:79], v[204:207], v[176:179], v[64:79]
	s_add_u32 m0, s32, 0x0
	s_nop 0
	global_load_lds_dwordx4 v[216:217], off
	v_lshl_add_u64 v[216:217], v[216:217], 0, s[10:11]
	v_mfma_f32_32x32x16_bf16 v[48:63], v[200:203], v[180:183], v[48:63]
	v_mfma_f32_32x32x16_bf16 v[32:47], v[204:207], v[180:183], v[32:47]
	v_mfma_f32_32x32x16_bf16 v[16:31], v[200:203], v[184:187], v[16:31]
	v_mfma_f32_32x32x16_bf16 v[0:15], v[204:207], v[184:187], v[0:15]
	s_add_u32 m0, s32, 0x4000
	s_nop 0
	global_load_lds_dwordx4 v[220:221], off
	v_lshl_add_u64 v[220:221], v[220:221], 0, s[10:11]
	s_waitcnt lgkmcnt(0)
	v_mfma_f32_32x32x16_bf16 v[112:127], v[188:191], v[156:159], v[112:127]
	ds_read_b128 v[200:203], v199 offset:32768
	ds_read_b128 v[172:175], v155 offset:32768
	v_mfma_f32_32x32x16_bf16 v[96:111], v[192:195], v[156:159], v[96:111]
	ds_read_b128 v[204:207], v199 offset:34816
	ds_read_b128 v[176:179], v155 offset:34816
	v_mfma_f32_32x32x16_bf16 v[80:95], v[188:191], v[160:163], v[80:95]
	ds_read_b128 v[180:183], v155 offset:36864
	ds_read_b128 v[184:187], v155 offset:38912
	v_mfma_f32_32x32x16_bf16 v[64:79], v[192:195], v[160:163], v[64:79]
	s_add_u32 m0, s32, 0x2000
	s_nop 0
	global_load_lds_dwordx4 v[218:219], off
	v_lshl_add_u64 v[218:219], v[218:219], 0, s[10:11]
	v_mfma_f32_32x32x16_bf16 v[48:63], v[188:191], v[164:167], v[48:63]
	v_mfma_f32_32x32x16_bf16 v[32:47], v[192:195], v[164:167], v[32:47]
	v_mfma_f32_32x32x16_bf16 v[16:31], v[188:191], v[168:171], v[16:31]
	v_mfma_f32_32x32x16_bf16 v[0:15], v[192:195], v[168:171], v[0:15]
	s_add_u32 m0, s32, 0x6000
	s_nop 0
	global_load_lds_dwordx4 v[222:223], off
	v_lshl_add_u64 v[222:223], v[222:223], 0, s[10:11]
	s_waitcnt lgkmcnt(0)
	s_waitcnt vmcnt(12)
	s_barrier
	s_waitcnt lgkmcnt(0)
	v_mfma_f32_32x32x16_bf16 v[112:127], v[200:203], v[172:175], v[112:127]
	ds_read_b128 v[188:191], v210
	ds_read_b128 v[156:159], v208
	v_mfma_f32_32x32x16_bf16 v[96:111], v[204:207], v[172:175], v[96:111]
	ds_read_b128 v[192:195], v210 offset:2048
	ds_read_b128 v[160:163], v208 offset:2048
	v_mfma_f32_32x32x16_bf16 v[80:95], v[200:203], v[176:179], v[80:95]
	ds_read_b128 v[164:167], v208 offset:4096
	ds_read_b128 v[168:171], v208 offset:6144
	v_mfma_f32_32x32x16_bf16 v[64:79], v[204:207], v[176:179], v[64:79]
	s_add_u32 m0, s32, 0x8000
	s_nop 0
	global_load_lds_dwordx4 v[216:217], off
	v_lshl_add_u64 v[216:217], v[216:217], 0, s[10:11]
	v_mfma_f32_32x32x16_bf16 v[48:63], v[200:203], v[180:183], v[48:63]
	v_mfma_f32_32x32x16_bf16 v[32:47], v[204:207], v[180:183], v[32:47]
	v_mfma_f32_32x32x16_bf16 v[16:31], v[200:203], v[184:187], v[16:31]
	v_mfma_f32_32x32x16_bf16 v[0:15], v[204:207], v[184:187], v[0:15]
	s_add_u32 m0, s32, 0xc000
	s_nop 0
	global_load_lds_dwordx4 v[220:221], off
	v_lshl_add_u64 v[220:221], v[220:221], 0, s[10:11]
	s_waitcnt lgkmcnt(0)
	v_mfma_f32_32x32x16_bf16 v[112:127], v[188:191], v[156:159], v[112:127]
	ds_read_b128 v[200:203], v211
	ds_read_b128 v[172:175], v209
	v_mfma_f32_32x32x16_bf16 v[96:111], v[192:195], v[156:159], v[96:111]
	ds_read_b128 v[204:207], v211 offset:2048
	ds_read_b128 v[176:179], v209 offset:2048
	v_mfma_f32_32x32x16_bf16 v[80:95], v[188:191], v[160:163], v[80:95]
	ds_read_b128 v[180:183], v209 offset:4096
	ds_read_b128 v[184:187], v209 offset:6144
	v_mfma_f32_32x32x16_bf16 v[64:79], v[192:195], v[160:163], v[64:79]
	s_add_u32 m0, s32, 0xa000
	s_nop 0
	global_load_lds_dwordx4 v[218:219], off
	v_lshl_add_u64 v[218:219], v[218:219], 0, s[10:11]
	v_mfma_f32_32x32x16_bf16 v[48:63], v[188:191], v[164:167], v[48:63]
	v_mfma_f32_32x32x16_bf16 v[32:47], v[192:195], v[164:167], v[32:47]
	v_mfma_f32_32x32x16_bf16 v[16:31], v[188:191], v[168:171], v[16:31]
	v_mfma_f32_32x32x16_bf16 v[0:15], v[192:195], v[168:171], v[0:15]
	s_add_u32 m0, s32, 0xe000
	s_nop 0
	global_load_lds_dwordx4 v[222:223], off
	v_lshl_add_u64 v[222:223], v[222:223], 0, s[10:11]
	s_waitcnt lgkmcnt(0)
	s_waitcnt vmcnt(12)
	s_barrier
; #define G_LOADA(kt_) { _Pragma("unroll") for (int i = 0; i < 4; ++i) ra[i] = al(lrow + 64 * i, (kt_) * 64 + lck * 8); }
; #define G_LOADB(kt_) { _Pragma("unroll") for (int i = 0; i < 4; ++i) rb[i] = bl(lrow + 64 * i, (kt_) * 64 + lck * 8); }
; #define G_STOREA(buf_) { bf16_t* nA = sA + (buf_) * 256 * GLD; _Pragma("unroll") for (int i = 0; i < 4; ++i) *(u32x4*)(nA + (lrow + 64 * i) * GLD + lck * 8) = ra[i]; }
; #define G_STOREB(buf_) { bf16_t* nB = sB + (buf_) * 256 * GLD; _Pragma("unroll") for (int i = 0; i < 4; ++i) *(u32x4*)(nB + (lrow + 64 * i) * GLD + lck * 8) = rb[i]; }
; template <class AL, class BL, class EP>
; DI void gemm_tile256(AL al, BL bl, EP ep, int K, char* smem) {
;     ...
;   const int KT = K >> 6;
;     ...
;   G_LOADA(0); G_LOADB(0);
;   __syncthreads();
;   G_STOREA(0); G_STOREB(0);
;   if (KT > 1) G_LOADB(1);
;   __syncthreads();
;   for (int kt = 0; kt < KT; kt += 2) {
;     G_STEP(0, kt);
;     if (kt + 1 >= KT) break;
;     G_STEP(1, kt + 1);
;   }
	s_waitcnt lgkmcnt(0)
	v_mfma_f32_32x32x16_bf16 v[112:127], v[200:203], v[172:175], v[112:127]
	ds_read_b128 v[188:191], v210 offset:32768
	ds_read_b128 v[156:159], v208 offset:32768
	v_mfma_f32_32x32x16_bf16 v[96:111], v[204:207], v[172:175], v[96:111]
	ds_read_b128 v[192:195], v210 offset:34816
	ds_read_b128 v[160:163], v208 offset:34816
	v_mfma_f32_32x32x16_bf16 v[80:95], v[200:203], v[176:179], v[80:95]
	ds_read_b128 v[164:167], v208 offset:36864
	ds_read_b128 v[168:171], v208 offset:38912
	v_mfma_f32_32x32x16_bf16 v[64:79], v[204:207], v[176:179], v[64:79]
	s_add_u32 m0, s32, 0x10000
	s_nop 0
	global_load_lds_dwordx4 v[216:217], off
	v_lshl_add_u64 v[216:217], v[216:217], 0, s[10:11]
	v_mfma_f32_32x32x16_bf16 v[48:63], v[200:203], v[180:183], v[48:63]
	v_mfma_f32_32x32x16_bf16 v[32:47], v[204:207], v[180:183], v[32:47]
	v_mfma_f32_32x32x16_bf16 v[16:31], v[200:203], v[184:187], v[16:31]
	v_mfma_f32_32x32x16_bf16 v[0:15], v[204:207], v[184:187], v[0:15]
	s_add_u32 m0, s32, 0x14000
	s_nop 0
	global_load_lds_dwordx4 v[220:221], off
	v_lshl_add_u64 v[220:221], v[220:221], 0, s[10:11]
	s_waitcnt lgkmcnt(0)
	v_mfma_f32_32x32x16_bf16 v[112:127], v[188:191], v[156:159], v[112:127]
	ds_read_b128 v[200:203], v211 offset:32768
	ds_read_b128 v[172:175], v209 offset:32768
	v_mfma_f32_32x32x16_bf16 v[96:111], v[192:195], v[156:159], v[96:111]
	ds_read_b128 v[204:207], v211 offset:34816
	ds_read_b128 v[176:179], v209 offset:34816
	v_mfma_f32_32x32x16_bf16 v[80:95], v[188:191], v[160:163], v[80:95]
	ds_read_b128 v[180:183], v209 offset:36864
	ds_read_b128 v[184:187], v209 offset:38912
	v_mfma_f32_32x32x16_bf16 v[64:79], v[192:195], v[160:163], v[64:79]
	s_add_u32 m0, s32, 0x12000
	s_nop 0
	global_load_lds_dwordx4 v[218:219], off
	v_lshl_add_u64 v[218:219], v[218:219], 0, s[10:11]
	v_mfma_f32_32x32x16_bf16 v[48:63], v[188:191], v[164:167], v[48:63]
	v_mfma_f32_32x32x16_bf16 v[32:47], v[192:195], v[164:167], v[32:47]
	v_mfma_f32_32x32x16_bf16 v[16:31], v[188:191], v[168:171], v[16:31]
	v_mfma_f32_32x32x16_bf16 v[0:15], v[192:195], v[168:171], v[0:15]
	s_add_u32 m0, s32, 0x16000
	s_nop 0
	global_load_lds_dwordx4 v[222:223], off
	v_lshl_add_u64 v[222:223], v[222:223], 0, s[10:11]
	s_waitcnt lgkmcnt(0)
	s_waitcnt vmcnt(12)
	s_barrier
	s_waitcnt lgkmcnt(0)
	v_mfma_f32_32x32x16_bf16 v[112:127], v[200:203], v[172:175], v[112:127]
	ds_read_b128 v[188:191], v214
	ds_read_b128 v[156:159], v212
	v_mfma_f32_32x32x16_bf16 v[96:111], v[204:207], v[172:175], v[96:111]
	ds_read_b128 v[192:195], v214 offset:2048
	ds_read_b128 v[160:163], v212 offset:2048
	v_mfma_f32_32x32x16_bf16 v[80:95], v[200:203], v[176:179], v[80:95]
	ds_read_b128 v[164:167], v212 offset:4096
	ds_read_b128 v[168:171], v212 offset:6144
	v_mfma_f32_32x32x16_bf16 v[64:79], v[204:207], v[176:179], v[64:79]
	s_add_u32 m0, s32, 0x18000
	s_nop 0
	global_load_lds_dwordx4 v[216:217], off
	v_lshl_add_u64 v[216:217], v[216:217], 0, s[10:11]
	v_mfma_f32_32x32x16_bf16 v[48:63], v[200:203], v[180:183], v[48:63]
	v_mfma_f32_32x32x16_bf16 v[32:47], v[204:207], v[180:183], v[32:47]
	v_mfma_f32_32x32x16_bf16 v[16:31], v[200:203], v[184:187], v[16:31]
	v_mfma_f32_32x32x16_bf16 v[0:15], v[204:207], v[184:187], v[0:15]
	s_add_u32 m0, s32, 0x1c000
	s_nop 0
	global_load_lds_dwordx4 v[220:221], off
	v_lshl_add_u64 v[220:221], v[220:221], 0, s[10:11]
	s_waitcnt lgkmcnt(0)
	v_mfma_f32_32x32x16_bf16 v[112:127], v[188:191], v[156:159], v[112:127]
	ds_read_b128 v[200:203], v215
	ds_read_b128 v[172:175], v213
	v_mfma_f32_32x32x16_bf16 v[96:111], v[192:195], v[156:159], v[96:111]
	ds_read_b128 v[204:207], v215 offset:2048
	ds_read_b128 v[176:179], v213 offset:2048
	v_mfma_f32_32x32x16_bf16 v[80:95], v[188:191], v[160:163], v[80:95]
	ds_read_b128 v[180:183], v213 offset:4096
	ds_read_b128 v[184:187], v213 offset:6144
	v_mfma_f32_32x32x16_bf16 v[64:79], v[192:195], v[160:163], v[64:79]
	s_add_u32 m0, s32, 0x1a000
	s_nop 0
	global_load_lds_dwordx4 v[218:219], off
	v_lshl_add_u64 v[218:219], v[218:219], 0, s[10:11]
	v_mfma_f32_32x32x16_bf16 v[48:63], v[188:191], v[164:167], v[48:63]
	v_mfma_f32_32x32x16_bf16 v[32:47], v[192:195], v[164:167], v[32:47]
	v_mfma_f32_32x32x16_bf16 v[16:31], v[188:191], v[168:171], v[16:31]
	v_mfma_f32_32x32x16_bf16 v[0:15], v[192:195], v[168:171], v[0:15]
	s_add_u32 m0, s32, 0x1e000
	s_nop 0
	global_load_lds_dwordx4 v[222:223], off
	v_lshl_add_u64 v[222:223], v[222:223], 0, s[10:11]
	s_waitcnt lgkmcnt(0)
	s_waitcnt vmcnt(12)
	s_barrier
	s_waitcnt lgkmcnt(0)
	v_mfma_f32_32x32x16_bf16 v[112:127], v[200:203], v[172:175], v[112:127]
	ds_read_b128 v[188:191], v198
	ds_read_b128 v[156:159], v134
	v_mfma_f32_32x32x16_bf16 v[96:111], v[204:207], v[172:175], v[96:111]
	ds_read_b128 v[192:195], v198 offset:2048
	ds_read_b128 v[160:163], v134 offset:2048
	v_mfma_f32_32x32x16_bf16 v[80:95], v[200:203], v[176:179], v[80:95]
	ds_read_b128 v[164:167], v134 offset:4096
	ds_read_b128 v[168:171], v134 offset:6144
	v_mfma_f32_32x32x16_bf16 v[64:79], v[204:207], v[176:179], v[64:79]
	s_add_u32 m0, s32, 0x20000
	s_nop 0
	global_load_lds_dwordx4 v[216:217], off
	v_lshl_add_u64 v[216:217], v[216:217], 0, s[10:11]
	v_mfma_f32_32x32x16_bf16 v[48:63], v[200:203], v[180:183], v[48:63]
	v_mfma_f32_32x32x16_bf16 v[32:47], v[204:207], v[180:183], v[32:47]
	v_mfma_f32_32x32x16_bf16 v[16:31], v[200:203], v[184:187], v[16:31]
	v_mfma_f32_32x32x16_bf16 v[0:15], v[204:207], v[184:187], v[0:15]
	s_add_u32 m0, s32, 0x24000
	s_nop 0
	global_load_lds_dwordx4 v[220:221], off
	v_lshl_add_u64 v[220:221], v[220:221], 0, s[10:11]
	s_sub_u32 s33, s33, 1
	s_cmp_lg_u32 s33, 0
	s_cbranch_scc1 .Lgk_ph15_loop
; #define G_LOADA(kt_) { _Pragma("unroll") for (int i = 0; i < 4; ++i) ra[i] = al(lrow + 64 * i, (kt_) * 64 + lck * 8); }
; #define G_LOADB(kt_) { _Pragma("unroll") for (int i = 0; i < 4; ++i) rb[i] = bl(lrow + 64 * i, (kt_) * 64 + lck * 8); }
; #define G_STOREA(buf_) { bf16_t* nA = sA + (buf_) * 256 * GLD; _Pragma("unroll") for (int i = 0; i < 4; ++i) *(u32x4*)(nA + (lrow + 64 * i) * GLD + lck * 8) = ra[i]; }
; #define G_STOREB(buf_) { bf16_t* nB = sB + (buf_) * 256 * GLD; _Pragma("unroll") for (int i = 0; i < 4; ++i) *(u32x4*)(nB + (lrow + 64 * i) * GLD + lck * 8) = rb[i]; }
; template <class AL, class BL, class EP>
; DI void gemm_tile256(AL al, BL bl, EP ep, int K, char* smem) {
;     ...
;   const int KT = K >> 6;
;     ...
;   G_LOADA(0); G_LOADB(0);
;   __syncthreads();
;   G_STOREA(0); G_STOREB(0);
;   if (KT > 1) G_LOADB(1);
;   __syncthreads();
;   for (int kt = 0; kt < KT; kt += 2) {
;     G_STEP(0, kt);
;     if (kt + 1 >= KT) break;
;     G_STEP(1, kt + 1);
;   }
	s_waitcnt lgkmcnt(0)
	v_mfma_f32_32x32x16_bf16 v[112:127], v[188:191], v[156:159], v[112:127]
	ds_read_b128 v[200:203], v199
	ds_read_b128 v[172:175], v155
	v_mfma_f32_32x32x16_bf16 v[96:111], v[192:195], v[156:159], v[96:111]
	ds_read_b128 v[204:207], v199 offset:2048
	ds_read_b128 v[176:179], v155 offset:2048
	v_mfma_f32_32x32x16_bf16 v[80:95], v[188:191], v[160:163], v[80:95]
	ds_read_b128 v[180:183], v155 offset:4096
	ds_read_b128 v[184:187], v155 offset:6144
	v_mfma_f32_32x32x16_bf16 v[64:79], v[192:195], v[160:163], v[64:79]
	s_add_u32 m0, s32, 0x22000
	s_nop 0
	global_load_lds_dwordx4 v[218:219], off
	v_lshl_add_u64 v[218:219], v[218:219], 0, s[10:11]
	v_mfma_f32_32x32x16_bf16 v[48:63], v[188:191], v[164:167], v[48:63]
	v_mfma_f32_32x32x16_bf16 v[32:47], v[192:195], v[164:167], v[32:47]
	v_mfma_f32_32x32x16_bf16 v[16:31], v[188:191], v[168:171], v[16:31]
	v_mfma_f32_32x32x16_bf16 v[0:15], v[192:195], v[168:171], v[0:15]
	s_add_u32 m0, s32, 0x26000
	s_nop 0
	global_load_lds_dwordx4 v[222:223], off
	v_lshl_add_u64 v[222:223], v[222:223], 0, s[10:11]
	s_waitcnt lgkmcnt(0)
	s_waitcnt vmcnt(12)
	s_barrier
	s_waitcnt lgkmcnt(0)
	v_mfma_f32_32x32x16_bf16 v[112:127], v[200:203], v[172:175], v[112:127]
	ds_read_b128 v[188:191], v198 offset:32768
	ds_read_b128 v[156:159], v134 offset:32768
	v_mfma_f32_32x32x16_bf16 v[96:111], v[204:207], v[172:175], v[96:111]
	ds_read_b128 v[192:195], v198 offset:34816
	ds_read_b128 v[160:163], v134 offset:34816
	v_mfma_f32_32x32x16_bf16 v[80:95], v[200:203], v[176:179], v[80:95]
	ds_read_b128 v[164:167], v134 offset:36864
	ds_read_b128 v[168:171], v134 offset:38912
	v_mfma_f32_32x32x16_bf16 v[64:79], v[204:207], v[176:179], v[64:79]
	s_add_u32 m0, s32, 0x0
	s_nop 0
	global_load_lds_dwordx4 v[216:217], off
	v_lshl_add_u64 v[216:217], v[216:217], 0, s[10:11]
	v_mfma_f32_32x32x16_bf16 v[48:63], v[200:203], v[180:183], v[48:63]
	v_mfma_f32_32x32x16_bf16 v[32:47], v[204:207], v[180:183], v[32:47]
	v_mfma_f32_32x32x16_bf16 v[16:31], v[200:203], v[184:187], v[16:31]
	v_mfma_f32_32x32x16_bf16 v[0:15], v[204:207], v[184:187], v[0:15]
	s_add_u32 m0, s32, 0x4000
	s_nop 0
	global_load_lds_dwordx4 v[220:221], off
	v_lshl_add_u64 v[220:221], v[220:221], 0, s[10:11]
	s_waitcnt lgkmcnt(0)
	v_mfma_f32_32x32x16_bf16 v[112:127], v[188:191], v[156:159], v[112:127]
	ds_read_b128 v[200:203], v199 offset:32768
	ds_read_b128 v[172:175], v155 offset:32768
	v_mfma_f32_32x32x16_bf16 v[96:111], v[192:195], v[156:159], v[96:111]
	ds_read_b128 v[204:207], v199 offset:34816
	ds_read_b128 v[176:179], v155 offset:34816
	v_mfma_f32_32x32x16_bf16 v[80:95], v[188:191], v[160:163], v[80:95]
	ds_read_b128 v[180:183], v155 offset:36864
	ds_read_b128 v[184:187], v155 offset:38912
	v_mfma_f32_32x32x16_bf16 v[64:79], v[192:195], v[160:163], v[64:79]
	s_add_u32 m0, s32, 0x2000
	s_nop 0
	global_load_lds_dwordx4 v[218:219], off
	v_lshl_add_u64 v[218:219], v[218:219], 0, s[10:11]
	v_mfma_f32_32x32x16_bf16 v[48:63], v[188:191], v[164:167], v[48:63]
	v_mfma_f32_32x32x16_bf16 v[32:47], v[192:195], v[164:167], v[32:47]
	v_mfma_f32_32x32x16_bf16 v[16:31], v[188:191], v[168:171], v[16:31]
	v_mfma_f32_32x32x16_bf16 v[0:15], v[192:195], v[168:171], v[0:15]
	s_add_u32 m0, s32, 0x6000
	s_nop 0
	global_load_lds_dwordx4 v[222:223], off
	v_lshl_add_u64 v[222:223], v[222:223], 0, s[10:11]
	s_waitcnt lgkmcnt(0)
	s_waitcnt vmcnt(12)
	s_barrier
	s_waitcnt lgkmcnt(0)
	v_mfma_f32_32x32x16_bf16 v[112:127], v[200:203], v[172:175], v[112:127]
	ds_read_b128 v[188:191], v210
	ds_read_b128 v[156:159], v208
	v_mfma_f32_32x32x16_bf16 v[96:111], v[204:207], v[172:175], v[96:111]
	ds_read_b128 v[192:195], v210 offset:2048
	ds_read_b128 v[160:163], v208 offset:2048
	v_mfma_f32_32x32x16_bf16 v[80:95], v[200:203], v[176:179], v[80:95]
	ds_read_b128 v[164:167], v208 offset:4096
	ds_read_b128 v[168:171], v208 offset:6144
	v_mfma_f32_32x32x16_bf16 v[64:79], v[204:207], v[176:179], v[64:79]
	s_add_u32 m0, s32, 0x8000
	s_nop 0
	global_load_lds_dwordx4 v[216:217], off
	v_lshl_add_u64 v[216:217], v[216:217], 0, s[10:11]
	v_mfma_f32_32x32x16_bf16 v[48:63], v[200:203], v[180:183], v[48:63]
	v_mfma_f32_32x32x16_bf16 v[32:47], v[204:207], v[180:183], v[32:47]
	v_mfma_f32_32x32x16_bf16 v[16:31], v[200:203], v[184:187], v[16:31]
	v_mfma_f32_32x32x16_bf16 v[0:15], v[204:207], v[184:187], v[0:15]
	s_add_u32 m0, s32, 0xc000
	s_nop 0
	global_load_lds_dwordx4 v[220:221], off
	v_lshl_add_u64 v[220:221], v[220:221], 0, s[10:11]
	s_waitcnt lgkmcnt(0)
	v_mfma_f32_32x32x16_bf16 v[112:127], v[188:191], v[156:159], v[112:127]
	ds_read_b128 v[200:203], v211
	ds_read_b128 v[172:175], v209
	v_mfma_f32_32x32x16_bf16 v[96:111], v[192:195], v[156:159], v[96:111]
	ds_read_b128 v[204:207], v211 offset:2048
	ds_read_b128 v[176:179], v209 offset:2048
	v_mfma_f32_32x32x16_bf16 v[80:95], v[188:191], v[160:163], v[80:95]
	ds_read_b128 v[180:183], v209 offset:4096
	ds_read_b128 v[184:187], v209 offset:6144
	v_mfma_f32_32x32x16_bf16 v[64:79], v[192:195], v[160:163], v[64:79]
	s_add_u32 m0, s32, 0xa000
	s_nop 0
	global_load_lds_dwordx4 v[218:219], off
	v_lshl_add_u64 v[218:219], v[218:219], 0, s[10:11]
	v_mfma_f32_32x32x16_bf16 v[48:63], v[188:191], v[164:167], v[48:63]
	v_mfma_f32_32x32x16_bf16 v[32:47], v[192:195], v[164:167], v[32:47]
	v_mfma_f32_32x32x16_bf16 v[16:31], v[188:191], v[168:171], v[16:31]
	v_mfma_f32_32x32x16_bf16 v[0:15], v[192:195], v[168:171], v[0:15]
	s_add_u32 m0, s32, 0xe000
	s_nop 0
	global_load_lds_dwordx4 v[222:223], off
	v_lshl_add_u64 v[222:223], v[222:223], 0, s[10:11]
	s_waitcnt lgkmcnt(0)
	s_waitcnt vmcnt(12)
	s_barrier
; #define G_LOADA(kt_) { _Pragma("unroll") for (int i = 0; i < 4; ++i) ra[i] = al(lrow + 64 * i, (kt_) * 64 + lck * 8); }
; #define G_LOADB(kt_) { _Pragma("unroll") for (int i = 0; i < 4; ++i) rb[i] = bl(lrow + 64 * i, (kt_) * 64 + lck * 8); }
; #define G_STOREA(buf_) { bf16_t* nA = sA + (buf_) * 256 * GLD; _Pragma("unroll") for (int i = 0; i < 4; ++i) *(u32x4*)(nA + (lrow + 64 * i) * GLD + lck * 8) = ra[i]; }
; #define G_STOREB(buf_) { bf16_t* nB = sB + (buf_) * 256 * GLD; _Pragma("unroll") for (int i = 0; i < 4; ++i) *(u32x4*)(nB + (lrow + 64 * i) * GLD + lck * 8) = rb[i]; }
; template <class AL, class BL, class EP>
; DI void gemm_tile256(AL al, BL bl, EP ep, int K, char* smem) {
;     ...
;   const int KT = K >> 6;
;     ...
;   G_LOADA(0); G_LOADB(0);
;   __syncthreads();
;   G_STOREA(0); G_STOREB(0);
;   if (KT > 1) G_LOADB(1);
;   __syncthreads();
;   for (int kt = 0; kt < KT; kt += 2) {
;     G_STEP(0, kt);
;     if (kt + 1 >= KT) break;
;     G_STEP(1, kt + 1);
;   }
	s_waitcnt lgkmcnt(0)
	v_mfma_f32_32x32x16_bf16 v[112:127], v[200:203], v[172:175], v[112:127]
	ds_read_b128 v[188:191], v210 offset:32768
	ds_read_b128 v[156:159], v208 offset:32768
	v_mfma_f32_32x32x16_bf16 v[96:111], v[204:207], v[172:175], v[96:111]
	ds_read_b128 v[192:195], v210 offset:34816
	ds_read_b128 v[160:163], v208 offset:34816
	v_mfma_f32_32x32x16_bf16 v[80:95], v[200:203], v[176:179], v[80:95]
	ds_read_b128 v[164:167], v208 offset:36864
	ds_read_b128 v[168:171], v208 offset:38912
	v_mfma_f32_32x32x16_bf16 v[64:79], v[204:207], v[176:179], v[64:79]
	v_mfma_f32_32x32x16_bf16 v[48:63], v[200:203], v[180:183], v[48:63]
	v_mfma_f32_32x32x16_bf16 v[32:47], v[204:207], v[180:183], v[32:47]
	v_mfma_f32_32x32x16_bf16 v[16:31], v[200:203], v[184:187], v[16:31]
	v_mfma_f32_32x32x16_bf16 v[0:15], v[204:207], v[184:187], v[0:15]
	s_waitcnt lgkmcnt(0)
	v_mfma_f32_32x32x16_bf16 v[112:127], v[188:191], v[156:159], v[112:127]
	ds_read_b128 v[200:203], v211 offset:32768
	ds_read_b128 v[172:175], v209 offset:32768
	v_mfma_f32_32x32x16_bf16 v[96:111], v[192:195], v[156:159], v[96:111]
	ds_read_b128 v[204:207], v211 offset:34816
	ds_read_b128 v[176:179], v209 offset:34816
	v_mfma_f32_32x32x16_bf16 v[80:95], v[188:191], v[160:163], v[80:95]
	ds_read_b128 v[180:183], v209 offset:36864
	ds_read_b128 v[184:187], v209 offset:38912
	v_mfma_f32_32x32x16_bf16 v[64:79], v[192:195], v[160:163], v[64:79]
	v_mfma_f32_32x32x16_bf16 v[48:63], v[188:191], v[164:167], v[48:63]
	v_mfma_f32_32x32x16_bf16 v[32:47], v[192:195], v[164:167], v[32:47]
	v_mfma_f32_32x32x16_bf16 v[16:31], v[188:191], v[168:171], v[16:31]
	v_mfma_f32_32x32x16_bf16 v[0:15], v[192:195], v[168:171], v[0:15]
	s_waitcnt lgkmcnt(0)
	s_waitcnt vmcnt(8)
	s_barrier
	s_waitcnt lgkmcnt(0)
	v_mfma_f32_32x32x16_bf16 v[112:127], v[200:203], v[172:175], v[112:127]
	ds_read_b128 v[188:191], v214
	ds_read_b128 v[156:159], v212
	v_mfma_f32_32x32x16_bf16 v[96:111], v[204:207], v[172:175], v[96:111]
	ds_read_b128 v[192:195], v214 offset:2048
	ds_read_b128 v[160:163], v212 offset:2048
	v_mfma_f32_32x32x16_bf16 v[80:95], v[200:203], v[176:179], v[80:95]
	ds_read_b128 v[164:167], v212 offset:4096
	ds_read_b128 v[168:171], v212 offset:6144
	v_mfma_f32_32x32x16_bf16 v[64:79], v[204:207], v[176:179], v[64:79]
	v_mfma_f32_32x32x16_bf16 v[48:63], v[200:203], v[180:183], v[48:63]
	v_mfma_f32_32x32x16_bf16 v[32:47], v[204:207], v[180:183], v[32:47]
	v_mfma_f32_32x32x16_bf16 v[16:31], v[200:203], v[184:187], v[16:31]
	v_mfma_f32_32x32x16_bf16 v[0:15], v[204:207], v[184:187], v[0:15]
	s_waitcnt lgkmcnt(0)
	v_mfma_f32_32x32x16_bf16 v[112:127], v[188:191], v[156:159], v[112:127]
	ds_read_b128 v[200:203], v215
	ds_read_b128 v[172:175], v213
	v_mfma_f32_32x32x16_bf16 v[96:111], v[192:195], v[156:159], v[96:111]
	ds_read_b128 v[204:207], v215 offset:2048
	ds_read_b128 v[176:179], v213 offset:2048
	v_mfma_f32_32x32x16_bf16 v[80:95], v[188:191], v[160:163], v[80:95]
	ds_read_b128 v[180:183], v213 offset:4096
	ds_read_b128 v[184:187], v213 offset:6144
	v_mfma_f32_32x32x16_bf16 v[64:79], v[192:195], v[160:163], v[64:79]
	v_mfma_f32_32x32x16_bf16 v[48:63], v[188:191], v[164:167], v[48:63]
	v_mfma_f32_32x32x16_bf16 v[32:47], v[192:195], v[164:167], v[32:47]
	v_mfma_f32_32x32x16_bf16 v[16:31], v[188:191], v[168:171], v[16:31]
	v_mfma_f32_32x32x16_bf16 v[0:15], v[192:195], v[168:171], v[0:15]
	s_waitcnt lgkmcnt(0)
	s_waitcnt vmcnt(4)
	s_barrier
	s_waitcnt lgkmcnt(0)
	v_mfma_f32_32x32x16_bf16 v[112:127], v[200:203], v[172:175], v[112:127]
	ds_read_b128 v[188:191], v198
	ds_read_b128 v[156:159], v134
	v_mfma_f32_32x32x16_bf16 v[96:111], v[204:207], v[172:175], v[96:111]
	ds_read_b128 v[192:195], v198 offset:2048
	ds_read_b128 v[160:163], v134 offset:2048
	v_mfma_f32_32x32x16_bf16 v[80:95], v[200:203], v[176:179], v[80:95]
	ds_read_b128 v[164:167], v134 offset:4096
	ds_read_b128 v[168:171], v134 offset:6144
	v_mfma_f32_32x32x16_bf16 v[64:79], v[204:207], v[176:179], v[64:79]
	v_mfma_f32_32x32x16_bf16 v[48:63], v[200:203], v[180:183], v[48:63]
	v_mfma_f32_32x32x16_bf16 v[32:47], v[204:207], v[180:183], v[32:47]
	v_mfma_f32_32x32x16_bf16 v[16:31], v[200:203], v[184:187], v[16:31]
	v_mfma_f32_32x32x16_bf16 v[0:15], v[204:207], v[184:187], v[0:15]
	s_waitcnt lgkmcnt(0)
	v_mfma_f32_32x32x16_bf16 v[112:127], v[188:191], v[156:159], v[112:127]
	ds_read_b128 v[200:203], v199
	ds_read_b128 v[172:175], v155
	v_mfma_f32_32x32x16_bf16 v[96:111], v[192:195], v[156:159], v[96:111]
	ds_read_b128 v[204:207], v199 offset:2048
	ds_read_b128 v[176:179], v155 offset:2048
	v_mfma_f32_32x32x16_bf16 v[80:95], v[188:191], v[160:163], v[80:95]
	ds_read_b128 v[180:183], v155 offset:4096
	ds_read_b128 v[184:187], v155 offset:6144
	v_mfma_f32_32x32x16_bf16 v[64:79], v[192:195], v[160:163], v[64:79]
	v_mfma_f32_32x32x16_bf16 v[48:63], v[188:191], v[164:167], v[48:63]
	v_mfma_f32_32x32x16_bf16 v[32:47], v[192:195], v[164:167], v[32:47]
	v_mfma_f32_32x32x16_bf16 v[16:31], v[188:191], v[168:171], v[16:31]
	v_mfma_f32_32x32x16_bf16 v[0:15], v[192:195], v[168:171], v[0:15]
	s_waitcnt lgkmcnt(0)
	s_waitcnt vmcnt(0)
	s_barrier
; DI unsigned pack2(float a, float b) { f2_t f = {a, b}; bf2_t r = __builtin_convertvector(f, bf2_t); return __builtin_bit_cast(unsigned, r); }
; #define G_LOADA(kt_) { _Pragma("unroll") for (int i = 0; i < 4; ++i) ra[i] = al(lrow + 64 * i, (kt_) * 64 + lck * 8); }
; #define G_LOADB(kt_) { _Pragma("unroll") for (int i = 0; i < 4; ++i) rb[i] = bl(lrow + 64 * i, (kt_) * 64 + lck * 8); }
; #define G_STOREA(buf_) { bf16_t* nA = sA + (buf_) * 256 * GLD; _Pragma("unroll") for (int i = 0; i < 4; ++i) *(u32x4*)(nA + (lrow + 64 * i) * GLD + lck * 8) = ra[i]; }
; #define G_STOREB(buf_) { bf16_t* nB = sB + (buf_) * 256 * GLD; _Pragma("unroll") for (int i = 0; i < 4; ++i) *(u32x4*)(nB + (lrow + 64 * i) * GLD + lck * 8) = rb[i]; }
; template <class AL, class BL, class EP>
; DI void gemm_tile256(AL al, BL bl, EP ep, int K, char* smem) {
;     ...
;   const int KT = K >> 6;
;     ...
;   G_LOADA(0); G_LOADB(0);
;   __syncthreads();
;   G_STOREA(0); G_STOREB(0);
;   if (KT > 1) G_LOADB(1);
;   __syncthreads();
;   for (int kt = 0; kt < KT; kt += 2) {
;     G_STEP(0, kt);
;     if (kt + 1 >= KT) break;
;     G_STEP(1, kt + 1);
;   }
;     ...
;   if constexpr (EP::kBf16) {
;     bf16_t* sCb = (bf16_t*)smem;
; #pragma unroll
;     for (int i = 0; i < 4; ++i)
; #pragma unroll
;       for (int j = 0; j < 2; ++j)
; #pragma unroll
;         for (int g = 0; g < 4; ++g) {
;           u32x2 v = {pack2(acc[i][j][4 * g], acc[i][j][4 * g + 1]), pack2(acc[i][j][4 * g + 2], acc[i][j][4 * g + 3])};
;           *(u32x2*)(sCb + (128 * wm + 32 * i + r) * BLD + 64 * wn + 32 * j + 8 * g + 4 * h) = v;
;         }
;     __syncthreads();
;     ep(sCb);
	s_waitcnt lgkmcnt(0)
	v_mfma_f32_32x32x16_bf16 v[112:127], v[200:203], v[172:175], v[112:127]
	ds_read_b128 v[188:191], v198 offset:32768
	ds_read_b128 v[156:159], v134 offset:32768
	v_mfma_f32_32x32x16_bf16 v[96:111], v[204:207], v[172:175], v[96:111]
	ds_read_b128 v[192:195], v198 offset:34816
	ds_read_b128 v[160:163], v134 offset:34816
	v_mfma_f32_32x32x16_bf16 v[80:95], v[200:203], v[176:179], v[80:95]
	ds_read_b128 v[164:167], v134 offset:36864
	ds_read_b128 v[168:171], v134 offset:38912
	v_mfma_f32_32x32x16_bf16 v[64:79], v[204:207], v[176:179], v[64:79]
	v_mfma_f32_32x32x16_bf16 v[48:63], v[200:203], v[180:183], v[48:63]
	v_mfma_f32_32x32x16_bf16 v[32:47], v[204:207], v[180:183], v[32:47]
	v_mfma_f32_32x32x16_bf16 v[16:31], v[200:203], v[184:187], v[16:31]
	v_mfma_f32_32x32x16_bf16 v[0:15], v[204:207], v[184:187], v[0:15]
	s_waitcnt lgkmcnt(0)
	v_mfma_f32_32x32x16_bf16 v[112:127], v[188:191], v[156:159], v[112:127]
	ds_read_b128 v[200:203], v199 offset:32768
	ds_read_b128 v[172:175], v155 offset:32768
	v_mfma_f32_32x32x16_bf16 v[96:111], v[192:195], v[156:159], v[96:111]
	ds_read_b128 v[204:207], v199 offset:34816
	ds_read_b128 v[176:179], v155 offset:34816
	v_mfma_f32_32x32x16_bf16 v[80:95], v[188:191], v[160:163], v[80:95]
	ds_read_b128 v[180:183], v155 offset:36864
	ds_read_b128 v[184:187], v155 offset:38912
	v_mfma_f32_32x32x16_bf16 v[64:79], v[192:195], v[160:163], v[64:79]
	v_mfma_f32_32x32x16_bf16 v[48:63], v[188:191], v[164:167], v[48:63]
	v_mfma_f32_32x32x16_bf16 v[32:47], v[192:195], v[164:167], v[32:47]
	v_mfma_f32_32x32x16_bf16 v[16:31], v[188:191], v[168:171], v[16:31]
	v_mfma_f32_32x32x16_bf16 v[0:15], v[192:195], v[168:171], v[0:15]
	s_waitcnt lgkmcnt(0)
	s_waitcnt lgkmcnt(0)
	v_mfma_f32_32x32x16_bf16 v[112:127], v[200:203], v[172:175], v[112:127]
	v_mfma_f32_32x32x16_bf16 v[96:111], v[204:207], v[172:175], v[96:111]
	v_mfma_f32_32x32x16_bf16 v[80:95], v[200:203], v[176:179], v[80:95]
	v_mfma_f32_32x32x16_bf16 v[64:79], v[204:207], v[176:179], v[64:79]
	v_mfma_f32_32x32x16_bf16 v[48:63], v[200:203], v[180:183], v[48:63]
	v_mfma_f32_32x32x16_bf16 v[32:47], v[204:207], v[180:183], v[32:47]
	v_mfma_f32_32x32x16_bf16 v[16:31], v[200:203], v[184:187], v[16:31]
	v_mfma_f32_32x32x16_bf16 v[0:15], v[204:207], v[184:187], v[0:15]
	s_nop 15
	s_nop 3
	s_waitcnt lgkmcnt(4)
	v_lshl_or_b32 v128, v135, 7, v154
	v_mad_u64_u32 v[132:133], s[0:1], v153, s25, v[128:129]
	s_waitcnt lgkmcnt(0)
	s_barrier
; DI unsigned pack2(float a, float b) { f2_t f = {a, b}; bf2_t r = __builtin_convertvector(f, bf2_t); return __builtin_bit_cast(unsigned, r); }
; DI int tid512() { int t = threadIdx_x_raw(); asm volatile("" : "+v"(t)); return t; }
; template <class AL, class BL, class EP>
; DI void gemm_tile256(AL al, BL bl, EP ep, int K, char* smem) {
;     ...
;   if constexpr (EP::kBf16) {
;     bf16_t* sCb = (bf16_t*)smem;
; #pragma unroll
;     for (int i = 0; i < 4; ++i)
; #pragma unroll
;       for (int j = 0; j < 2; ++j)
; #pragma unroll
;         for (int g = 0; g < 4; ++g) {
;           u32x2 v = {pack2(acc[i][j][4 * g], acc[i][j][4 * g + 1]), pack2(acc[i][j][4 * g + 2], acc[i][j][4 * g + 3])};
;           *(u32x2*)(sCb + (128 * wm + 32 * i + r) * BLD + 64 * wn + 32 * j + 8 * g + 4 * h) = v;
;         }
;     __syncthreads();
;     ep(sCb);
;   DI void operator()(const bf16_t* sCb) const {
;     const int t = tid512(), hf = (t >> 3) & 1, c8 = (t & 7) * 8;
;     const int cb = c0 + 64 * hf;
;     const bf16_t* base = sCb + 128 * hf;
;     float w0[8], w1[8], w2[8];
;     ld8f(conv + cb + c8, w0); ld8f(conv + DFF + cb + c8, w1); ld8f(conv + 2 * DFF + cb + c8, w2);
;     for (int rr = t >> 4; rr < 254; rr += 32) {
;       const int row = rr + 1;
;       float gm[8], g0[8], gp[8], uu[8], v[8];
;       ld8b(base + (row - 1) * BLD + c8, gm); ld8b(base + row * BLD + c8, g0); ld8b(base + (row + 1) * BLD + c8, gp); ld8b(base + row * BLD + 64 + c8, uu);
	v_lshlrev_b32_e32 v131, 7, v131
	s_nop 5
	v_cvt_pk_bf16_f32 v112, v112, v113
	v_cvt_pk_bf16_f32 v113, v114, v115
	v_cvt_pk_bf16_f32 v114, v116, v117
	v_cvt_pk_bf16_f32 v115, v118, v119
	ds_write2_b64 v132, v[112:113], v[114:115] offset1:2
	v_cvt_pk_bf16_f32 v112, v120, v121
	v_cvt_pk_bf16_f32 v113, v122, v123
	v_cvt_pk_bf16_f32 v96, v96, v97
	v_cvt_pk_bf16_f32 v97, v98, v99
	v_cvt_pk_bf16_f32 v98, v100, v101
	v_cvt_pk_bf16_f32 v99, v102, v103
	v_cvt_pk_bf16_f32 v114, v124, v125
	v_cvt_pk_bf16_f32 v115, v126, v127
	ds_write2_b64 v132, v[96:97], v[98:99] offset0:8 offset1:10
	s_nop 3
	v_cvt_pk_bf16_f32 v80, v80, v81
	v_cvt_pk_bf16_f32 v81, v82, v83
	v_cvt_pk_bf16_f32 v82, v84, v85
	v_cvt_pk_bf16_f32 v83, v86, v87
	v_add_u32_e32 v84, 0x4000, v132
	v_cvt_pk_bf16_f32 v96, v104, v105
	v_cvt_pk_bf16_f32 v97, v106, v107
	v_cvt_pk_bf16_f32 v64, v64, v65
	v_cvt_pk_bf16_f32 v65, v66, v67
	v_cvt_pk_bf16_f32 v66, v68, v69
	v_cvt_pk_bf16_f32 v67, v70, v71
	v_cvt_pk_bf16_f32 v98, v108, v109
	v_cvt_pk_bf16_f32 v99, v110, v111
	ds_write2_b64 v84, v[80:81], v[82:83] offset0:64 offset1:66
	s_nop 3
	v_cvt_pk_bf16_f32 v48, v48, v49
	v_cvt_pk_bf16_f32 v49, v50, v51
	v_cvt_pk_bf16_f32 v50, v52, v53
	v_cvt_pk_bf16_f32 v51, v54, v55
	v_add_u32_e32 v52, 0x8000, v132
	v_cvt_pk_bf16_f32 v80, v88, v89
	v_cvt_pk_bf16_f32 v81, v90, v91
	v_cvt_pk_bf16_f32 v32, v32, v33
	v_cvt_pk_bf16_f32 v33, v34, v35
	v_cvt_pk_bf16_f32 v34, v36, v37
	v_cvt_pk_bf16_f32 v35, v38, v39
	v_cvt_pk_bf16_f32 v82, v92, v93
	v_cvt_pk_bf16_f32 v83, v94, v95
	ds_write2_b64 v84, v[64:65], v[66:67] offset0:72 offset1:74
	s_nop 3
	v_cvt_pk_bf16_f32 v16, v16, v17
	v_cvt_pk_bf16_f32 v17, v18, v19
	v_cvt_pk_bf16_f32 v18, v20, v21
	v_cvt_pk_bf16_f32 v19, v22, v23
	v_add_u32_e32 v20, 0xc000, v132
	v_cvt_pk_bf16_f32 v64, v72, v73
	v_cvt_pk_bf16_f32 v65, v74, v75
	s_nop 0
	v_cvt_pk_bf16_f32 v0, v0, v1
	v_cvt_pk_bf16_f32 v1, v2, v3
	v_cvt_pk_bf16_f32 v2, v4, v5
	v_cvt_pk_bf16_f32 v3, v6, v7
	v_cvt_pk_bf16_f32 v66, v76, v77
	v_cvt_pk_bf16_f32 v67, v78, v79
	ds_write2_b64 v52, v[48:49], v[50:51] offset0:128 offset1:130
	v_cvt_pk_bf16_f32 v48, v56, v57
	v_cvt_pk_bf16_f32 v49, v58, v59
	v_cvt_pk_bf16_f32 v50, v60, v61
	v_cvt_pk_bf16_f32 v51, v62, v63
	ds_write2_b64 v52, v[32:33], v[34:35] offset0:136 offset1:138
	v_cvt_pk_bf16_f32 v32, v40, v41
	v_cvt_pk_bf16_f32 v33, v42, v43
	v_cvt_pk_bf16_f32 v34, v44, v45
	v_cvt_pk_bf16_f32 v35, v46, v47
	ds_write2_b64 v20, v[16:17], v[18:19] offset0:192 offset1:194
	v_cvt_pk_bf16_f32 v16, v24, v25
	v_cvt_pk_bf16_f32 v17, v26, v27
	v_cvt_pk_bf16_f32 v18, v28, v29
	v_cvt_pk_bf16_f32 v19, v30, v31
	ds_write2_b64 v20, v[0:1], v[2:3] offset0:200 offset1:202
	v_cvt_pk_bf16_f32 v0, v8, v9
	v_cvt_pk_bf16_f32 v1, v10, v11
	v_cvt_pk_bf16_f32 v2, v12, v13
	v_cvt_pk_bf16_f32 v3, v14, v15
	v_mov_b32_e32 v29, v196
	ds_write2_b64 v132, v[112:113], v[114:115] offset0:4 offset1:6
	ds_write2_b64 v132, v[96:97], v[98:99] offset0:12 offset1:14
	ds_write2_b64 v84, v[80:81], v[82:83] offset0:68 offset1:70
	ds_write2_b64 v84, v[64:65], v[66:67] offset0:76 offset1:78
	ds_write2_b64 v52, v[48:49], v[50:51] offset0:132 offset1:134
	ds_write2_b64 v52, v[32:33], v[34:35] offset0:140 offset1:142
	ds_write2_b64 v20, v[16:17], v[18:19] offset0:196 offset1:198
	ds_write2_b64 v20, v[0:1], v[2:3] offset0:204 offset1:206
	s_waitcnt lgkmcnt(0)
	s_barrier
	s_nop 0
	v_bfe_u32 v0, v29, 3, 1
	v_lshlrev_b32_e32 v30, 6, v0
	v_lshlrev_b32_e32 v1, 3, v29
	v_or_b32_e32 v24, v30, v131
	v_ashrrev_i32_e32 v26, 4, v29
	v_and_b32_e32 v27, 56, v1
	v_lshlrev_b32_e32 v28, 8, v0
	v_ashrrev_i32_e32 v25, 31, v24
	v_cmp_gt_i32_e32 vcc, s26, v26
	s_and_saveexec_b64 s[0:1], vcc
	s_cbranch_execz .LBB0_1147
	v_lshlrev_b64 v[16:17], 2, v[24:25]
	v_lshl_add_u64 v[0:1], s[14:15], 0, v[16:17]
	v_lshlrev_b32_e32 v128, 2, v27
	v_lshl_add_u64 v[8:9], s[6:7], 0, v[16:17]
	v_lshl_add_u64 v[16:17], s[4:5], 0, v[16:17]
	v_lshl_add_u64 v[4:5], v[0:1], 0, v[128:129]
	v_lshl_add_u64 v[12:13], v[8:9], 0, v[128:129]
	v_lshl_add_u64 v[20:21], v[16:17], 0, v[128:129]
	global_load_dwordx4 v[0:3], v[4:5], off
	s_nop 0
	global_load_dwordx4 v[4:7], v[4:5], off offset:16
	s_nop 0
	global_load_dwordx4 v[8:11], v[12:13], off
	s_nop 0
	global_load_dwordx4 v[12:15], v[12:13], off offset:16
	s_nop 0
	global_load_dwordx4 v[16:19], v[20:21], off
	s_nop 0
	global_load_dwordx4 v[20:23], v[20:21], off offset:16
	v_lshlrev_b32_e32 v33, 4, v29
	v_mad_i64_i32 v[34:35], s[18:19], v26, s27, 0
	v_mul_lo_u32 v31, v26, s25
	v_and_b32_e32 v36, 0x70, v33
	v_mad_i64_i32 v[34:35], s[18:19], v130, s28, v[34:35]
	v_add_u32_e32 v30, v131, v30
	v_add3_u32 v33, v31, v28, v36
	v_or_b32_e32 v34, v34, v36
	v_ashrrev_i32_e32 v31, 31, v30
	v_readlane_b32 s10, v246, 51
	v_lshl_add_u64 v[30:31], v[30:31], 1, v[34:35]
	v_readlane_b32 s11, v246, 52
	v_subrev_u32_e32 v32, 32, v26
	s_mov_b64 s[18:19], 0
	v_lshl_add_u64 v[30:31], s[10:11], 0, v[30:31]
	s_waitcnt vmcnt(0)

; __global__ void __launch_bounds__(512, 2) k_mega(Params p) {
;   __shared__ __attribute__((aligned(16))) char smem[SMEM_TOTAL];
	.amdhsa_kernel _Z6k_mega6Params
		.amdhsa_group_segment_fixed_size 163840
		.amdhsa_private_segment_fixed_size 0
		.amdhsa_kernarg_size 520
		.amdhsa_user_sgpr_count 2
		.amdhsa_user_sgpr_dispatch_ptr 0
		.amdhsa_user_sgpr_queue_ptr 0
		.amdhsa_user_sgpr_kernarg_segment_ptr 1
		.amdhsa_user_sgpr_dispatch_id 0
		.amdhsa_user_sgpr_kernarg_preload_length 0
		.amdhsa_user_sgpr_kernarg_preload_offset 0
		.amdhsa_user_sgpr_private_segment_size 0
		.amdhsa_uses_dynamic_stack 0
		.amdhsa_enable_private_segment 0
		.amdhsa_system_sgpr_workgroup_id_x 1
		.amdhsa_system_sgpr_workgroup_id_y 0
		.amdhsa_system_sgpr_workgroup_id_z 0
		.amdhsa_system_sgpr_workgroup_info 0
		.amdhsa_system_vgpr_workitem_id 2
		.amdhsa_next_free_vgpr 256
		.amdhsa_next_free_sgpr 98
		.amdhsa_accum_offset 256
		.amdhsa_reserve_vcc 1
		.amdhsa_float_round_mode_32 0
		.amdhsa_float_round_mode_16_64 0
		.amdhsa_float_denorm_mode_32 3
		.amdhsa_float_denorm_mode_16_64 3
		.amdhsa_dx10_clamp 1
		.amdhsa_ieee_mode 1
		.amdhsa_fp16_overflow 0
		.amdhsa_tg_split 0
		.amdhsa_exception_fp_ieee_invalid_op 0
		.amdhsa_exception_fp_denorm_src 0
		.amdhsa_exception_fp_ieee_div_zero 0
		.amdhsa_exception_fp_ieee_overflow 0
		.amdhsa_exception_fp_ieee_underflow 0
		.amdhsa_exception_fp_ieee_inexact 0
		.amdhsa_exception_int_div_zero 0
	.end_amdhsa_kernel

; __global__ void __launch_bounds__(512, 2) k_mega(Params p) {
;   __shared__ __attribute__((aligned(16))) char smem[SMEM_TOTAL];
amdhsa.kernels:
  - .agpr_count:     0
    .args:
      - .offset:         0
        .size:           264
        .value_kind:     by_value
      - .offset:         264
        .size:           4
        .value_kind:     hidden_block_count_x
      - .offset:         268
        .size:           4
        .value_kind:     hidden_block_count_y
      - .offset:         272
        .size:           4
        .value_kind:     hidden_block_count_z
      - .offset:         276
        .size:           2
        .value_kind:     hidden_group_size_x
      - .offset:         278
        .size:           2
        .value_kind:     hidden_group_size_y
      - .offset:         280
        .size:           2
        .value_kind:     hidden_group_size_z
      - .offset:         282
        .size:           2
        .value_kind:     hidden_remainder_x
      - .offset:         284
        .size:           2
        .value_kind:     hidden_remainder_y
      - .offset:         286
        .size:           2
        .value_kind:     hidden_remainder_z
      - .offset:         304
        .size:           8
        .value_kind:     hidden_global_offset_x
      - .offset:         312
        .size:           8
        .value_kind:     hidden_global_offset_y
      - .offset:         320
        .size:           8
        .value_kind:     hidden_global_offset_z
      - .offset:         328
        .size:           2
        .value_kind:     hidden_grid_dims
      - .offset:         352
        .size:           8
        .value_kind:     hidden_multigrid_sync_arg
    .group_segment_fixed_size: 163840
    .kernarg_segment_align: 8
    .kernarg_segment_size: 520
    .language:       OpenCL C
    .language_version:
      - 2
      - 0
    .max_flat_workgroup_size: 512
    .name:           _Z6k_mega6Params
    .private_segment_fixed_size: 0
    .sgpr_count:     104
    .sgpr_spill_count: 120
    .symbol:         _Z6k_mega6Params.kd
    .uniform_work_group_size: 1
    .uses_dynamic_stack: false
    .vgpr_count:     256
    .vgpr_spill_count: 0
    .wavefront_size: 64
